# post-MMA s_barrier moved up by two MFMAs with s_setprio 2 for the tail MFMAs (all GEMM loops) + final RMSNorm next-row prefetch
# speedup vs baseline: 1.0143x; 1.0098x over previous
; #define PG8_STAGE(bufoff, gbase, voff) do { _Pragma("unroll") for (int _i = 0; _i < 2; ++_i) \
;         __builtin_amdgcn_global_load_lds((const unsigned*)((const char*)(gbase) + (voff)[_i]), (LAS unsigned*)(lds + (bufoff) + ldsw + _i * 8192), 16, 0, 0); } while (0)
; #define PG8_LDA(dst, b, h) do { _Pragma("unroll") for (int m = 0; m < 4; ++m) _Pragma("unroll") for (int k = 0; k < 2; ++k) dst[m][k] = *(const LAS bf16x8*)(lds + PG8_SA(b, h) + aoff + m * 2048 + k * 1024); } while (0)
; #define PG8_LDB(dst, b, h) do { _Pragma("unroll") for (int n = 0; n < 2; ++n) _Pragma("unroll") for (int k = 0; k < 2; ++k) dst[n][k] = *(const LAS bf16x8*)(lds + PG8_SB(b, h) + boff + n * 2048 + k * 1024); } while (0)
; #define PG8_MMA(ai, bj, At, Bt) do { __builtin_amdgcn_s_setprio(1); _Pragma("unroll") for (int m = 0; m < 4; ++m) _Pragma("unroll") for (int n = 0; n < 2; ++n) _Pragma("unroll") for (int k = 0; k < 2; ++k) \
;         acc[ai][bj][m][n] = __builtin_amdgcn_mfma_f32_16x16x32_bf16(Bt[n][k], At[m][k], acc[ai][bj][m][n], 0, 0, 0); __builtin_amdgcn_s_setprio(0); } while (0)
; #define PG8_WAIT_L(n) asm volatile("s_waitcnt lgkmcnt(" #n ")" ::: "memory")
; #define PG8_BAR __builtin_amdgcn_s_barrier()
; #define PG8_SCHED __builtin_amdgcn_sched_barrier(0)
; #define PG8_WAIT_L(n) asm volatile("s_waitcnt lgkmcnt(" #n ")" ::: "memory")
; #define PG8_BAR __builtin_amdgcn_s_barrier()
; #define PG8_SCHED __builtin_amdgcn_sched_barrier(0)
; template <class Epi>
; DI void gemm_phase(LAS unsigned char* lds, const Gemm g, const StaticOrder S, const Epi E) {
;     ...
;             const bool last = (t == nt - 2);
;             const char* a1 = cA + (size_t)(t + 1) * kstep;
;             const char* a2 = last ? nA : cA + (size_t)(t + 2) * kstep; const char* b2 = last ? nB : cB + (size_t)(t + 2) * kstep;
;             const char* a3 = a2 + kstep; const char* b3 = b2 + kstep;
;             PG8_LDB(B0, 0, 0); PG8_SCHED; PG8_LDA(At, 0, 0); PG8_STAGE(PG8_SA(1, 1), a1 + hstep, voffA);
;             PG8_WAIT_L(8); PG8_BAR; PG8_WAIT_L(0); PG8_MMA(0, 0, At, B0); PG8_BAR; PG8_SCHED;
;             PG8_LDB(B1, 0, 1); PG8_STAGE(PG8_SB(0, 0), b2, voffB);
;             PG8_BAR; PG8_WAIT_L(0); PG8_MMA(0, 1, At, B1); PG8_BAR;
;             PG8_LDA(At, 0, 1); PG8_STAGE(PG8_SA(0, 0), a2, voffA);
;             PG8_BAR; PG8_WAIT_L(0); PG8_MMA(1, 0, At, B0); PG8_BAR; PG8_SCHED;
.LBB0_107:
	ds_read_b128 v[152:155], v149
	ds_read_b128 v[156:159], v149 offset:1024
	ds_read_b128 v[160:163], v149 offset:2048
	ds_read_b128 v[164:167], v149 offset:3072
	s_add_u32 s14, s76, 0xfffc0080
	s_addc_u32 s15, s77, -1
	s_cmp_eq_u32 s97, 12
	s_cselect_b32 s81, s11, s15
	s_cselect_b32 s80, s93, s14
	s_cselect_b32 s79, s9, s96
	s_cselect_b32 s78, s94, s95
	v_lshl_add_u64 v[144:145], s[76:77], 0, v[136:137]
	s_add_i32 m0, s29, 0xc000
	ds_read_b128 v[168:171], v150
	ds_read_b128 v[172:175], v150 offset:1024
	ds_read_b128 v[176:179], v150 offset:2048
	ds_read_b128 v[180:183], v150 offset:3072
	ds_read_b128 v[184:187], v150 offset:4096
	ds_read_b128 v[188:191], v150 offset:5120
	ds_read_b128 v[192:195], v150 offset:6144
	ds_read_b128 v[196:199], v150 offset:7168
	global_load_lds_dwordx4 v[144:145], off
	v_lshl_add_u64 v[144:145], s[76:77], 0, v[138:139]
	s_add_i32 m0, s29, 0xe000
	s_nop 0
	global_load_lds_dwordx4 v[144:145], off
	s_waitcnt lgkmcnt(8)
	s_barrier
	s_waitcnt lgkmcnt(0)
	s_setprio 1
	s_waitcnt lgkmcnt(0)
	v_mfma_f32_16x16x32_bf16 v[124:127], v[152:155], v[168:171], v[124:127]
	v_mfma_f32_16x16x32_bf16 v[116:119], v[160:163], v[168:171], v[116:119]
	v_mfma_f32_16x16x32_bf16 v[108:111], v[152:155], v[176:179], v[108:111]
	v_mfma_f32_16x16x32_bf16 v[100:103], v[160:163], v[176:179], v[100:103]
	v_mfma_f32_16x16x32_bf16 v[92:95], v[152:155], v[184:187], v[92:95]
	v_mfma_f32_16x16x32_bf16 v[84:87], v[160:163], v[184:187], v[84:87]
	v_mfma_f32_16x16x32_bf16 v[76:79], v[152:155], v[192:195], v[76:79]
	v_mfma_f32_16x16x32_bf16 v[68:71], v[160:163], v[192:195], v[68:71]
	v_mfma_f32_16x16x32_bf16 v[124:127], v[156:159], v[172:175], v[124:127]
	v_mfma_f32_16x16x32_bf16 v[116:119], v[164:167], v[172:175], v[116:119]
	v_mfma_f32_16x16x32_bf16 v[108:111], v[156:159], v[180:183], v[108:111]
	v_mfma_f32_16x16x32_bf16 v[100:103], v[164:167], v[180:183], v[100:103]
	v_mfma_f32_16x16x32_bf16 v[92:95], v[156:159], v[188:191], v[92:95]
	v_mfma_f32_16x16x32_bf16 v[84:87], v[164:167], v[188:191], v[84:87]
	s_setprio 2
	s_barrier
	v_mfma_f32_16x16x32_bf16 v[76:79], v[156:159], v[196:199], v[76:79]
	v_mfma_f32_16x16x32_bf16 v[68:71], v[164:167], v[196:199], v[68:71]
	s_setprio 0
	s_add_i32 s14, s89, s7
	v_lshl_add_u64 v[144:145], s[78:79], 0, v[132:133]
	s_mov_b32 m0, s14
	ds_read_b128 v[200:203], v151
	ds_read_b128 v[204:207], v151 offset:1024
	ds_read_b128 v[208:211], v151 offset:2048
	ds_read_b128 v[212:215], v151 offset:3072
	global_load_lds_dwordx4 v[144:145], off
	v_lshl_add_u64 v[216:217], s[78:79], 0, v[128:129]
	s_add_i32 m0, s14, 0x2000
	s_nop 0
	global_load_lds_dwordx4 v[216:217], off
	s_barrier
	s_waitcnt lgkmcnt(0)
	s_setprio 1
	s_waitcnt lgkmcnt(0)
	v_mfma_f32_16x16x32_bf16 v[120:123], v[200:203], v[168:171], v[120:123]
	v_mfma_f32_16x16x32_bf16 v[112:115], v[208:211], v[168:171], v[112:115]
	v_mfma_f32_16x16x32_bf16 v[104:107], v[200:203], v[176:179], v[104:107]
	v_mfma_f32_16x16x32_bf16 v[96:99], v[208:211], v[176:179], v[96:99]
	v_mfma_f32_16x16x32_bf16 v[88:91], v[200:203], v[184:187], v[88:91]
	v_mfma_f32_16x16x32_bf16 v[80:83], v[208:211], v[184:187], v[80:83]
	v_mfma_f32_16x16x32_bf16 v[72:75], v[200:203], v[192:195], v[72:75]
	v_mfma_f32_16x16x32_bf16 v[64:67], v[208:211], v[192:195], v[64:67]
	v_mfma_f32_16x16x32_bf16 v[120:123], v[204:207], v[172:175], v[120:123]
	v_mfma_f32_16x16x32_bf16 v[112:115], v[212:215], v[172:175], v[112:115]
	v_mfma_f32_16x16x32_bf16 v[104:107], v[204:207], v[180:183], v[104:107]
	v_mfma_f32_16x16x32_bf16 v[96:99], v[212:215], v[180:183], v[96:99]
	v_mfma_f32_16x16x32_bf16 v[88:91], v[204:207], v[188:191], v[88:91]
	v_mfma_f32_16x16x32_bf16 v[80:83], v[212:215], v[188:191], v[80:83]
	s_setprio 2
	s_barrier
	v_mfma_f32_16x16x32_bf16 v[72:75], v[204:207], v[196:199], v[72:75]
	v_mfma_f32_16x16x32_bf16 v[64:67], v[212:215], v[196:199], v[64:67]
	s_setprio 0
	s_mov_b32 m0, s29
	v_lshl_add_u64 v[218:219], s[80:81], 0, v[134:135]
	ds_read_b128 v[168:171], v150 offset:16384
	ds_read_b128 v[172:175], v150 offset:17408
	ds_read_b128 v[176:179], v150 offset:18432
	ds_read_b128 v[180:183], v150 offset:19456
	ds_read_b128 v[184:187], v150 offset:20480
	ds_read_b128 v[188:191], v150 offset:21504
	ds_read_b128 v[192:195], v150 offset:22528
	ds_read_b128 v[196:199], v150 offset:23552
	global_load_lds_dwordx4 v[218:219], off
	v_lshl_add_u64 v[220:221], s[80:81], 0, v[130:131]
	s_mov_b32 m0, s59
	s_nop 0
	global_load_lds_dwordx4 v[220:221], off
	s_barrier
	s_waitcnt lgkmcnt(0)
	s_setprio 1
	s_waitcnt lgkmcnt(0)
	v_mfma_f32_16x16x32_bf16 v[60:63], v[152:155], v[168:171], v[60:63]
	v_mfma_f32_16x16x32_bf16 v[52:55], v[160:163], v[168:171], v[52:55]
	v_mfma_f32_16x16x32_bf16 v[44:47], v[152:155], v[176:179], v[44:47]
	v_mfma_f32_16x16x32_bf16 v[36:39], v[160:163], v[176:179], v[36:39]
	v_mfma_f32_16x16x32_bf16 v[28:31], v[152:155], v[184:187], v[28:31]
	v_mfma_f32_16x16x32_bf16 v[20:23], v[160:163], v[184:187], v[20:23]
	v_mfma_f32_16x16x32_bf16 v[12:15], v[152:155], v[192:195], v[12:15]
	v_mfma_f32_16x16x32_bf16 v[4:7], v[160:163], v[192:195], v[4:7]
	v_mfma_f32_16x16x32_bf16 v[60:63], v[156:159], v[172:175], v[60:63]
	v_mfma_f32_16x16x32_bf16 v[52:55], v[164:167], v[172:175], v[52:55]
	v_mfma_f32_16x16x32_bf16 v[44:47], v[156:159], v[180:183], v[44:47]
	v_mfma_f32_16x16x32_bf16 v[36:39], v[164:167], v[180:183], v[36:39]
	v_mfma_f32_16x16x32_bf16 v[28:31], v[156:159], v[188:191], v[28:31]
	v_mfma_f32_16x16x32_bf16 v[20:23], v[164:167], v[188:191], v[20:23]
	s_setprio 2
	s_barrier
; #define PG8_STAGE(bufoff, gbase, voff) do { _Pragma("unroll") for (int _i = 0; _i < 2; ++_i) \
;         __builtin_amdgcn_global_load_lds((const unsigned*)((const char*)(gbase) + (voff)[_i]), (LAS unsigned*)(lds + (bufoff) + ldsw + _i * 8192), 16, 0, 0); } while (0)
; #define PG8_LDA(dst, b, h) do { _Pragma("unroll") for (int m = 0; m < 4; ++m) _Pragma("unroll") for (int k = 0; k < 2; ++k) dst[m][k] = *(const LAS bf16x8*)(lds + PG8_SA(b, h) + aoff + m * 2048 + k * 1024); } while (0)
; #define PG8_LDB(dst, b, h) do { _Pragma("unroll") for (int n = 0; n < 2; ++n) _Pragma("unroll") for (int k = 0; k < 2; ++k) dst[n][k] = *(const LAS bf16x8*)(lds + PG8_SB(b, h) + boff + n * 2048 + k * 1024); } while (0)
; #define PG8_MMA(ai, bj, At, Bt) do { __builtin_amdgcn_s_setprio(1); _Pragma("unroll") for (int m = 0; m < 4; ++m) _Pragma("unroll") for (int n = 0; n < 2; ++n) _Pragma("unroll") for (int k = 0; k < 2; ++k) \
;         acc[ai][bj][m][n] = __builtin_amdgcn_mfma_f32_16x16x32_bf16(Bt[n][k], At[m][k], acc[ai][bj][m][n], 0, 0, 0); __builtin_amdgcn_s_setprio(0); } while (0)
; #define PG8_WAIT_V(n) asm volatile("s_waitcnt vmcnt(" #n ")" ::: "memory")
; #define PG8_WAIT_L(n) asm volatile("s_waitcnt lgkmcnt(" #n ")" ::: "memory")
; #define PG8_BAR __builtin_amdgcn_s_barrier()
; #define PG8_SCHED __builtin_amdgcn_sched_barrier(0)
; #define PG8_STAGE(bufoff, gbase, voff) do { _Pragma("unroll") for (int _i = 0; _i < 2; ++_i) \
;         __builtin_amdgcn_global_load_lds((const unsigned*)((const char*)(gbase) + (voff)[_i]), (LAS unsigned*)(lds + (bufoff) + ldsw + _i * 8192), 16, 0, 0); } while (0)
; #define PG8_BAR __builtin_amdgcn_s_barrier()
; template <class Epi>
; DI void gemm_phase(LAS unsigned char* lds, const Gemm g, const StaticOrder S, const Epi E) {
;     ...
;             PG8_BAR; PG8_WAIT_L(0); PG8_MMA(1, 0, At, B0); PG8_BAR; PG8_SCHED;
;             PG8_STAGE(PG8_SB(0, 1), b2 + hstep, voffB);
;             PG8_WAIT_V(6); PG8_BAR; PG8_MMA(1, 1, At, B1); PG8_BAR;
;             PG8_LDB(B0, 1, 0); PG8_SCHED; PG8_LDA(At, 1, 0); PG8_STAGE(PG8_SA(0, 1), a2 + hstep, voffA);
;             PG8_WAIT_L(8); PG8_BAR; PG8_WAIT_L(0); PG8_MMA(0, 0, At, B0); PG8_BAR; PG8_SCHED;
;             PG8_LDB(B1, 1, 1); PG8_STAGE(PG8_SB(1, 0), b3, voffB);
;             PG8_BAR; PG8_WAIT_L(0); PG8_MMA(0, 1, At, B1); PG8_BAR;
;             PG8_LDA(At, 1, 1); PG8_STAGE(PG8_SA(1, 0), a3, voffA);
	v_mfma_f32_16x16x32_bf16 v[12:15], v[156:159], v[196:199], v[12:15]
	v_mfma_f32_16x16x32_bf16 v[4:7], v[164:167], v[196:199], v[4:7]
	s_setprio 0
	s_add_u32 s14, s78, 0x40000
	s_addc_u32 s15, s79, 0
	s_add_i32 s35, s90, s7
	v_lshl_add_u64 v[152:153], s[14:15], 0, v[132:133]
	s_mov_b32 m0, s35
	s_nop 0
	global_load_lds_dwordx4 v[152:153], off
	v_lshl_add_u64 v[152:153], s[14:15], 0, v[128:129]
	s_add_i32 m0, s35, 0x2000
	s_nop 0
	global_load_lds_dwordx4 v[152:153], off
	s_waitcnt vmcnt(6)
	s_barrier
	s_setprio 1
	v_mfma_f32_16x16x32_bf16 v[56:59], v[200:203], v[168:171], v[56:59]
	v_mfma_f32_16x16x32_bf16 v[48:51], v[208:211], v[168:171], v[48:51]
	v_mfma_f32_16x16x32_bf16 v[40:43], v[200:203], v[176:179], v[40:43]
	v_mfma_f32_16x16x32_bf16 v[32:35], v[208:211], v[176:179], v[32:35]
	v_mfma_f32_16x16x32_bf16 v[24:27], v[200:203], v[184:187], v[24:27]
	v_mfma_f32_16x16x32_bf16 v[16:19], v[208:211], v[184:187], v[16:19]
	v_mfma_f32_16x16x32_bf16 v[8:11], v[200:203], v[192:195], v[8:11]
	v_mfma_f32_16x16x32_bf16 v[0:3], v[208:211], v[192:195], v[0:3]
	v_mfma_f32_16x16x32_bf16 v[56:59], v[204:207], v[172:175], v[56:59]
	v_mfma_f32_16x16x32_bf16 v[48:51], v[212:215], v[172:175], v[48:51]
	v_mfma_f32_16x16x32_bf16 v[40:43], v[204:207], v[180:183], v[40:43]
	v_mfma_f32_16x16x32_bf16 v[32:35], v[212:215], v[180:183], v[32:35]
	v_mfma_f32_16x16x32_bf16 v[24:27], v[204:207], v[188:191], v[24:27]
	v_mfma_f32_16x16x32_bf16 v[16:19], v[212:215], v[188:191], v[16:19]
	s_setprio 2
	s_barrier
	v_mfma_f32_16x16x32_bf16 v[8:11], v[204:207], v[196:199], v[8:11]
	v_mfma_f32_16x16x32_bf16 v[0:3], v[212:215], v[196:199], v[0:3]
	s_setprio 0
	s_add_i32 s35, 0, 0x18000
	v_add_u32_e32 v164, s35, v147
	ds_read_b128 v[152:155], v164
	ds_read_b128 v[156:159], v164 offset:1024
	ds_read_b128 v[160:163], v164 offset:2048
	ds_read_b128 v[164:167], v164 offset:3072
	s_add_u32 s14, s80, 0x40000
	s_addc_u32 s15, s81, 0
	s_mov_b32 m0, s82
	v_lshl_add_u64 v[200:201], s[14:15], 0, v[134:135]
	ds_read_b128 v[168:171], v150 offset:32768
	ds_read_b128 v[172:175], v150 offset:33792
	ds_read_b128 v[176:179], v150 offset:34816
	ds_read_b128 v[180:183], v150 offset:35840
	ds_read_b128 v[184:187], v150 offset:36864
	ds_read_b128 v[188:191], v150 offset:37888
	ds_read_b128 v[192:195], v150 offset:38912
	ds_read_b128 v[196:199], v150 offset:39936
	global_load_lds_dwordx4 v[200:201], off
	v_lshl_add_u64 v[200:201], s[14:15], 0, v[130:131]
	s_mov_b32 m0, s83
	s_nop 0
	global_load_lds_dwordx4 v[200:201], off
	s_waitcnt lgkmcnt(8)
	s_barrier
	s_waitcnt lgkmcnt(0)
	s_setprio 1
	s_waitcnt lgkmcnt(0)
	v_mfma_f32_16x16x32_bf16 v[124:127], v[152:155], v[168:171], v[124:127]
	v_mfma_f32_16x16x32_bf16 v[116:119], v[160:163], v[168:171], v[116:119]
	v_mfma_f32_16x16x32_bf16 v[108:111], v[152:155], v[176:179], v[108:111]
	v_mfma_f32_16x16x32_bf16 v[100:103], v[160:163], v[176:179], v[100:103]
	v_mfma_f32_16x16x32_bf16 v[92:95], v[152:155], v[184:187], v[92:95]
	v_mfma_f32_16x16x32_bf16 v[84:87], v[160:163], v[184:187], v[84:87]
	v_mfma_f32_16x16x32_bf16 v[76:79], v[152:155], v[192:195], v[76:79]
	v_mfma_f32_16x16x32_bf16 v[68:71], v[160:163], v[192:195], v[68:71]
	v_mfma_f32_16x16x32_bf16 v[124:127], v[156:159], v[172:175], v[124:127]
	v_mfma_f32_16x16x32_bf16 v[116:119], v[164:167], v[172:175], v[116:119]
	v_mfma_f32_16x16x32_bf16 v[108:111], v[156:159], v[180:183], v[108:111]
	v_mfma_f32_16x16x32_bf16 v[100:103], v[164:167], v[180:183], v[100:103]
	v_mfma_f32_16x16x32_bf16 v[92:95], v[156:159], v[188:191], v[92:95]
	v_mfma_f32_16x16x32_bf16 v[84:87], v[164:167], v[188:191], v[84:87]
	s_setprio 2
	s_barrier
	v_mfma_f32_16x16x32_bf16 v[76:79], v[156:159], v[196:199], v[76:79]
	v_mfma_f32_16x16x32_bf16 v[68:71], v[164:167], v[196:199], v[68:71]
	s_setprio 0
	s_add_i32 s80, 0, 0x1c000
	s_add_i32 s14, s35, s7
	v_add_u32_e32 v212, s80, v147
	v_lshl_add_u64 v[144:145], v[144:145], 0, s[4:5]
	s_mov_b32 m0, s14
	ds_read_b128 v[200:203], v212
	ds_read_b128 v[204:207], v212 offset:1024
	ds_read_b128 v[208:211], v212 offset:2048
	ds_read_b128 v[212:215], v212 offset:3072
	global_load_lds_dwordx4 v[144:145], off
	v_lshl_add_u64 v[144:145], v[216:217], 0, s[4:5]
	s_add_i32 m0, s14, 0x2000
	s_nop 0
	global_load_lds_dwordx4 v[144:145], off
	s_barrier
	s_waitcnt lgkmcnt(0)
	s_setprio 1
	s_waitcnt lgkmcnt(0)
	v_mfma_f32_16x16x32_bf16 v[120:123], v[200:203], v[168:171], v[120:123]
	v_mfma_f32_16x16x32_bf16 v[112:115], v[208:211], v[168:171], v[112:115]
	v_mfma_f32_16x16x32_bf16 v[104:107], v[200:203], v[176:179], v[104:107]
	v_mfma_f32_16x16x32_bf16 v[96:99], v[208:211], v[176:179], v[96:99]
	v_mfma_f32_16x16x32_bf16 v[88:91], v[200:203], v[184:187], v[88:91]
	v_mfma_f32_16x16x32_bf16 v[80:83], v[208:211], v[184:187], v[80:83]
	v_mfma_f32_16x16x32_bf16 v[72:75], v[200:203], v[192:195], v[72:75]
	v_mfma_f32_16x16x32_bf16 v[64:67], v[208:211], v[192:195], v[64:67]
	v_mfma_f32_16x16x32_bf16 v[120:123], v[204:207], v[172:175], v[120:123]
	v_mfma_f32_16x16x32_bf16 v[112:115], v[212:215], v[172:175], v[112:115]
	v_mfma_f32_16x16x32_bf16 v[104:107], v[204:207], v[180:183], v[104:107]
	v_mfma_f32_16x16x32_bf16 v[96:99], v[212:215], v[180:183], v[96:99]
	v_mfma_f32_16x16x32_bf16 v[88:91], v[204:207], v[188:191], v[88:91]
	v_mfma_f32_16x16x32_bf16 v[80:83], v[212:215], v[188:191], v[80:83]
	s_setprio 2
	s_barrier
; DI unsigned pk_bf16(float lo, float hi) { f32x2 v = {lo, hi}; return __builtin_bit_cast(unsigned, __builtin_convertvector(v, bf16v2)); }
; DI float fast_silu(float x) { return x * fast_sigmoid(x); }
; #define PG8_STAGE(bufoff, gbase, voff) do { _Pragma("unroll") for (int _i = 0; _i < 2; ++_i) \
;         __builtin_amdgcn_global_load_lds((const unsigned*)((const char*)(gbase) + (voff)[_i]), (LAS unsigned*)(lds + (bufoff) + ldsw + _i * 8192), 16, 0, 0); } while (0)
; #define PG8_LDA(dst, b, h) do { _Pragma("unroll") for (int m = 0; m < 4; ++m) _Pragma("unroll") for (int k = 0; k < 2; ++k) dst[m][k] = *(const LAS bf16x8*)(lds + PG8_SA(b, h) + aoff + m * 2048 + k * 1024); } while (0)
; #define PG8_MMA(ai, bj, At, Bt) do { __builtin_amdgcn_s_setprio(1); _Pragma("unroll") for (int m = 0; m < 4; ++m) _Pragma("unroll") for (int n = 0; n < 2; ++n) _Pragma("unroll") for (int k = 0; k < 2; ++k) \
;         acc[ai][bj][m][n] = __builtin_amdgcn_mfma_f32_16x16x32_bf16(Bt[n][k], At[m][k], acc[ai][bj][m][n], 0, 0, 0); __builtin_amdgcn_s_setprio(0); } while (0)
; #define PG8_WAIT_V(n) asm volatile("s_waitcnt vmcnt(" #n ")" ::: "memory")
; template <class Epi>
; DI void gemm_phase(LAS unsigned char* lds, const Gemm g, const StaticOrder S, const Epi E) {
;     ...
;             PG8_BAR; PG8_WAIT_L(0); PG8_MMA(0, 1, At, B1); PG8_BAR;
;             PG8_LDA(At, 1, 1); PG8_STAGE(PG8_SA(1, 0), a3, voffA);
;             PG8_BAR; PG8_WAIT_L(0); PG8_MMA(1, 0, At, B0); PG8_BAR; PG8_SCHED;
;             PG8_STAGE(PG8_SB(1, 1), b3 + hstep, voffB);
;             PG8_WAIT_V(6); PG8_BAR; PG8_MMA(1, 1, At, B1); PG8_BAR;
;     DI void operator()(AccRef acc, const Unit& u, int wr, int wc, int fr, int fq) const {
;     ...
;             for (int m = 0; m < 4; ++m) {
;                 const int row = row0 + ai * 128 + m * 16;
;                 const float r = RS ? rsc.r[ai][m] : 1.0f;
;                 const f32x4 a0 = acc[ai][0][m][0] * r, a1 = acc[ai][0][m][1] * r, b0 = acc[ai][1][m][0] * r, b1 = acc[ai][1][m][1] * r;
;                 u32x4 w;
;                 w.x = pk_bf16(fast_silu(a0[0]) * b0[0], fast_silu(a0[1]) * b0[1]); w.y = pk_bf16(fast_silu(a0[2]) * b0[2], fast_silu(a0[3]) * b0[3]);
;                 w.z = pk_bf16(fast_silu(a1[0]) * b1[0], fast_silu(a1[1]) * b1[1]); w.w = pk_bf16(fast_silu(a1[2]) * b1[2], fast_silu(a1[3]) * b1[3]);
;                 *(u32x4*)(G + (size_t)row * DFF + col) = w;
	v_mfma_f32_16x16x32_bf16 v[72:75], v[204:207], v[196:199], v[72:75]
	v_mfma_f32_16x16x32_bf16 v[64:67], v[212:215], v[196:199], v[64:67]
	s_setprio 0
	s_mov_b32 m0, s85
	v_lshl_add_u64 v[144:145], v[218:219], 0, s[4:5]
	ds_read_b128 v[168:171], v150 offset:49152
	ds_read_b128 v[172:175], v150 offset:50176
	ds_read_b128 v[176:179], v150 offset:51200
	ds_read_b128 v[180:183], v150 offset:52224
	ds_read_b128 v[184:187], v150 offset:53248
	ds_read_b128 v[188:191], v150 offset:54272
	ds_read_b128 v[192:195], v150 offset:55296
	ds_read_b128 v[196:199], v150 offset:56320
	global_load_lds_dwordx4 v[144:145], off
	v_lshl_add_u64 v[144:145], v[220:221], 0, s[4:5]
	s_mov_b32 m0, s86
	s_nop 0
	global_load_lds_dwordx4 v[144:145], off
	s_barrier
	s_waitcnt lgkmcnt(0)
	s_setprio 1
	s_waitcnt lgkmcnt(0)
	v_mfma_f32_16x16x32_bf16 v[60:63], v[152:155], v[168:171], v[60:63]
	v_mfma_f32_16x16x32_bf16 v[52:55], v[160:163], v[168:171], v[52:55]
	v_mfma_f32_16x16x32_bf16 v[44:47], v[152:155], v[176:179], v[44:47]
	v_mfma_f32_16x16x32_bf16 v[36:39], v[160:163], v[176:179], v[36:39]
	v_mfma_f32_16x16x32_bf16 v[28:31], v[152:155], v[184:187], v[28:31]
	v_mfma_f32_16x16x32_bf16 v[20:23], v[160:163], v[184:187], v[20:23]
	v_mfma_f32_16x16x32_bf16 v[12:15], v[152:155], v[192:195], v[12:15]
	v_mfma_f32_16x16x32_bf16 v[4:7], v[160:163], v[192:195], v[4:7]
	v_mfma_f32_16x16x32_bf16 v[60:63], v[156:159], v[172:175], v[60:63]
	v_mfma_f32_16x16x32_bf16 v[52:55], v[164:167], v[172:175], v[52:55]
	v_mfma_f32_16x16x32_bf16 v[44:47], v[156:159], v[180:183], v[44:47]
	v_mfma_f32_16x16x32_bf16 v[36:39], v[164:167], v[180:183], v[36:39]
	v_mfma_f32_16x16x32_bf16 v[28:31], v[156:159], v[188:191], v[28:31]
	v_mfma_f32_16x16x32_bf16 v[20:23], v[164:167], v[188:191], v[20:23]
	s_setprio 2
	s_barrier
	v_mfma_f32_16x16x32_bf16 v[12:15], v[156:159], v[196:199], v[12:15]
	v_mfma_f32_16x16x32_bf16 v[4:7], v[164:167], v[196:199], v[4:7]
	s_setprio 0
	s_add_u32 s14, s78, 0x40080
	s_addc_u32 s15, s79, 0
	s_add_i32 s35, s80, s7
	v_lshl_add_u64 v[144:145], s[14:15], 0, v[132:133]
	s_mov_b32 m0, s35
	s_nop 0
	global_load_lds_dwordx4 v[144:145], off
	v_lshl_add_u64 v[144:145], s[14:15], 0, v[128:129]
	s_add_i32 m0, s35, 0x2000
	s_nop 0
	global_load_lds_dwordx4 v[144:145], off
	s_waitcnt vmcnt(6)
	s_barrier
	s_setprio 1
	v_mfma_f32_16x16x32_bf16 v[56:59], v[200:203], v[168:171], v[56:59]
	v_mfma_f32_16x16x32_bf16 v[48:51], v[208:211], v[168:171], v[48:51]
	v_mfma_f32_16x16x32_bf16 v[40:43], v[200:203], v[176:179], v[40:43]
	v_mfma_f32_16x16x32_bf16 v[32:35], v[208:211], v[176:179], v[32:35]
	v_mfma_f32_16x16x32_bf16 v[24:27], v[200:203], v[184:187], v[24:27]
	v_mfma_f32_16x16x32_bf16 v[16:19], v[208:211], v[184:187], v[16:19]
	v_mfma_f32_16x16x32_bf16 v[8:11], v[200:203], v[192:195], v[8:11]
	v_mfma_f32_16x16x32_bf16 v[0:3], v[208:211], v[192:195], v[0:3]
	v_mfma_f32_16x16x32_bf16 v[56:59], v[204:207], v[172:175], v[56:59]
	v_mfma_f32_16x16x32_bf16 v[48:51], v[212:215], v[172:175], v[48:51]
	v_mfma_f32_16x16x32_bf16 v[40:43], v[204:207], v[180:183], v[40:43]
	v_mfma_f32_16x16x32_bf16 v[32:35], v[212:215], v[180:183], v[32:35]
	v_mfma_f32_16x16x32_bf16 v[24:27], v[204:207], v[188:191], v[24:27]
	v_mfma_f32_16x16x32_bf16 v[16:19], v[212:215], v[188:191], v[16:19]
	s_setprio 2
	s_barrier
	v_mfma_f32_16x16x32_bf16 v[8:11], v[204:207], v[196:199], v[8:11]
	v_mfma_f32_16x16x32_bf16 v[0:3], v[212:215], v[196:199], v[0:3]
	s_setprio 0
	s_add_i32 s97, s97, 2
	s_add_u32 s76, s76, 0x100
	s_addc_u32 s77, s77, 0
	s_add_u32 s95, s95, 0x100
	s_addc_u32 s96, s96, 0
	s_cmp_gt_u32 s97, 13
	s_cbranch_scc0 .LBB0_107
	v_mul_f32_e32 v153, 0xbfb8aa3b, v124
	v_exp_f32_e32 v153, v153
	v_mul_f32_e32 v154, 0xbfb8aa3b, v125
	v_exp_f32_e32 v155, v154
	v_lshl_or_b32 v144, s92, 7, v148
	v_add_f32_e32 v153, 1.0, v153
	v_rcp_f32_e32 v154, v153
	v_add_f32_e32 v153, 1.0, v155
	v_mul_f32_e32 v155, 0xbfb8aa3b, v126
	v_exp_f32_e32 v156, v155
	v_mul_f32_e32 v155, 0xbfb8aa3b, v127
	v_exp_f32_e32 v157, v155
	v_rcp_f32_e32 v155, v153
	v_add_f32_e32 v153, 1.0, v156
	v_rcp_f32_e32 v156, v153
	v_add_f32_e32 v153, 1.0, v157
	v_rcp_f32_e32 v157, v153
	v_pk_mul_f32 v[124:125], v[124:125], v[154:155]
	v_ashrrev_i32_e32 v145, 31, v144
	v_pk_mul_f32 v[120:121], v[124:125], v[120:121]
	v_pk_mul_f32 v[124:125], v[126:127], v[156:157]
	v_cvt_pk_bf16_f32 v120, v120, v121
	v_mul_f32_e32 v121, 0xbfb8aa3b, v116
	v_pk_mul_f32 v[122:123], v[124:125], v[122:123]
	v_exp_f32_e32 v124, v121
	v_mul_f32_e32 v121, 0xbfb8aa3b, v117
	v_exp_f32_e32 v125, v121
	v_cvt_pk_bf16_f32 v121, v122, v123
	v_add_f32_e32 v122, 1.0, v124
	v_mul_f32_e32 v124, 0xbfb8aa3b, v118
	v_add_f32_e32 v123, 1.0, v125
	v_mul_f32_e32 v125, 0xbfb8aa3b, v119
	v_exp_f32_e32 v124, v124
	v_exp_f32_e32 v125, v125
	v_rcp_f32_e32 v122, v122
	v_rcp_f32_e32 v123, v123
	v_add_f32_e32 v124, 1.0, v124
	v_add_f32_e32 v125, 1.0, v125
	v_rcp_f32_e32 v124, v124
	v_rcp_f32_e32 v125, v125
	v_pk_mul_f32 v[116:117], v[116:117], v[122:123]
	v_lshl_add_u32 v152, s28, 8, v146
	v_pk_mul_f32 v[112:113], v[116:117], v[112:113]
	v_lshl_add_u64 v[144:145], v[144:145], 1, s[54:55]
	v_cvt_pk_bf16_f32 v122, v112, v113
	v_pk_mul_f32 v[112:113], v[118:119], v[124:125]
	v_or_b32_e32 v116, 16, v152
	v_pk_mul_f32 v[112:113], v[112:113], v[114:115]
	v_mul_f32_e32 v114, 0xbfb8aa3b, v110
	v_cvt_pk_bf16_f32 v123, v112, v113
	v_mad_i64_i32 v[112:113], s[14:15], v152, s91, v[144:145]
	global_store_dwordx4 v[112:113], v[120:123], off
	v_mul_f32_e32 v112, 0xbfb8aa3b, v108
	v_mul_f32_e32 v113, 0xbfb8aa3b, v109
	v_exp_f32_e32 v112, v112
	v_exp_f32_e32 v113, v113
	v_mul_f32_e32 v115, 0xbfb8aa3b, v111
	v_exp_f32_e32 v114, v114
; DI unsigned pk_bf16(float lo, float hi) { f32x2 v = {lo, hi}; return __builtin_bit_cast(unsigned, __builtin_convertvector(v, bf16v2)); }
; DI float fast_silu(float x) { return x * fast_sigmoid(x); }
;     DI void operator()(AccRef acc, const Unit& u, int wr, int wc, int fr, int fq) const {
;     ...
;             for (int m = 0; m < 4; ++m) {
;                 const int row = row0 + ai * 128 + m * 16;
;                 const float r = RS ? rsc.r[ai][m] : 1.0f;
;                 const f32x4 a0 = acc[ai][0][m][0] * r, a1 = acc[ai][0][m][1] * r, b0 = acc[ai][1][m][0] * r, b1 = acc[ai][1][m][1] * r;
;                 u32x4 w;
;                 w.x = pk_bf16(fast_silu(a0[0]) * b0[0], fast_silu(a0[1]) * b0[1]); w.y = pk_bf16(fast_silu(a0[2]) * b0[2], fast_silu(a0[3]) * b0[3]);
;                 w.z = pk_bf16(fast_silu(a1[0]) * b1[0], fast_silu(a1[1]) * b1[1]); w.w = pk_bf16(fast_silu(a1[2]) * b1[2], fast_silu(a1[3]) * b1[3]);
;                 *(u32x4*)(G + (size_t)row * DFF + col) = w;
	v_exp_f32_e32 v115, v115
	v_add_f32_e32 v112, 1.0, v112
	v_add_f32_e32 v113, 1.0, v113
	v_rcp_f32_e32 v112, v112
	v_rcp_f32_e32 v113, v113
	v_add_f32_e32 v114, 1.0, v114
	v_add_f32_e32 v115, 1.0, v115
	v_rcp_f32_e32 v114, v114
	v_rcp_f32_e32 v115, v115
	v_pk_mul_f32 v[108:109], v[108:109], v[112:113]
	s_and_b64 vcc, exec, s[0:1]
	v_pk_mul_f32 v[104:105], v[108:109], v[104:105]
	v_pk_mul_f32 v[108:109], v[110:111], v[114:115]
	v_cvt_pk_bf16_f32 v104, v104, v105
	v_mul_f32_e32 v105, 0xbfb8aa3b, v100
	v_pk_mul_f32 v[106:107], v[108:109], v[106:107]
	v_exp_f32_e32 v108, v105
	v_mul_f32_e32 v105, 0xbfb8aa3b, v101
	v_exp_f32_e32 v109, v105
	v_cvt_pk_bf16_f32 v105, v106, v107
	v_add_f32_e32 v106, 1.0, v108
	v_mul_f32_e32 v108, 0xbfb8aa3b, v102
	v_add_f32_e32 v107, 1.0, v109
	v_mul_f32_e32 v109, 0xbfb8aa3b, v103
	v_exp_f32_e32 v108, v108
	v_exp_f32_e32 v109, v109
	v_rcp_f32_e32 v106, v106
	v_rcp_f32_e32 v107, v107
	v_add_f32_e32 v108, 1.0, v108
	v_add_f32_e32 v109, 1.0, v109
	v_rcp_f32_e32 v108, v108
	v_rcp_f32_e32 v109, v109
	v_pk_mul_f32 v[100:101], v[100:101], v[106:107]
	s_mov_b32 s92, s8
	v_pk_mul_f32 v[96:97], v[100:101], v[96:97]
	v_or_b32_e32 v100, 32, v152
	v_cvt_pk_bf16_f32 v106, v96, v97
	v_pk_mul_f32 v[96:97], v[102:103], v[108:109]
	s_mov_b32 s28, s10
	v_pk_mul_f32 v[96:97], v[96:97], v[98:99]
	v_mul_f32_e32 v98, 0xbfb8aa3b, v94
	v_cvt_pk_bf16_f32 v107, v96, v97
	v_mad_i64_i32 v[96:97], s[14:15], v116, s91, v[144:145]
	global_store_dwordx4 v[96:97], v[104:107], off
	v_mul_f32_e32 v96, 0xbfb8aa3b, v92
	v_mul_f32_e32 v97, 0xbfb8aa3b, v93
	v_exp_f32_e32 v96, v96
	v_exp_f32_e32 v97, v97
	v_mul_f32_e32 v99, 0xbfb8aa3b, v95
	v_exp_f32_e32 v98, v98
	v_exp_f32_e32 v99, v99
	v_add_f32_e32 v96, 1.0, v96
	v_add_f32_e32 v97, 1.0, v97
	v_rcp_f32_e32 v96, v96
	v_rcp_f32_e32 v97, v97
	v_add_f32_e32 v98, 1.0, v98
	v_add_f32_e32 v99, 1.0, v99
	v_rcp_f32_e32 v98, v98
	v_rcp_f32_e32 v99, v99
	v_pk_mul_f32 v[92:93], v[92:93], v[96:97]
	s_mov_b64 s[78:79], s[26:27]
	v_pk_mul_f32 v[88:89], v[92:93], v[88:89]
	v_pk_mul_f32 v[92:93], v[94:95], v[98:99]
	v_cvt_pk_bf16_f32 v88, v88, v89
	v_mul_f32_e32 v89, 0xbfb8aa3b, v84
	v_pk_mul_f32 v[90:91], v[92:93], v[90:91]
	v_exp_f32_e32 v92, v89
	v_mul_f32_e32 v89, 0xbfb8aa3b, v85
	v_exp_f32_e32 v93, v89
	v_cvt_pk_bf16_f32 v89, v90, v91
	v_add_f32_e32 v90, 1.0, v92
	v_mul_f32_e32 v92, 0xbfb8aa3b, v86
	v_add_f32_e32 v91, 1.0, v93
	v_mul_f32_e32 v93, 0xbfb8aa3b, v87
	v_exp_f32_e32 v92, v92
	v_exp_f32_e32 v93, v93
	v_rcp_f32_e32 v90, v90
	v_rcp_f32_e32 v91, v91
	v_add_f32_e32 v92, 1.0, v92
	v_add_f32_e32 v93, 1.0, v93
	v_rcp_f32_e32 v92, v92
	v_rcp_f32_e32 v93, v93
	v_pk_mul_f32 v[84:85], v[84:85], v[90:91]
	s_mov_b64 s[76:77], s[24:25]
	v_pk_mul_f32 v[80:81], v[84:85], v[80:81]
	v_or_b32_e32 v84, 48, v152
	v_cvt_pk_bf16_f32 v90, v80, v81
	v_pk_mul_f32 v[80:81], v[86:87], v[92:93]
	s_nop 0
	v_pk_mul_f32 v[80:81], v[80:81], v[82:83]
	v_mul_f32_e32 v82, 0xbfb8aa3b, v78
	v_cvt_pk_bf16_f32 v91, v80, v81
	v_mad_i64_i32 v[80:81], s[14:15], v100, s91, v[144:145]
	global_store_dwordx4 v[80:81], v[88:91], off
	v_mul_f32_e32 v80, 0xbfb8aa3b, v76
	v_mul_f32_e32 v81, 0xbfb8aa3b, v77
	v_exp_f32_e32 v80, v80
	v_exp_f32_e32 v81, v81
	v_mul_f32_e32 v83, 0xbfb8aa3b, v79
	v_exp_f32_e32 v82, v82
	v_exp_f32_e32 v83, v83
	v_add_f32_e32 v80, 1.0, v80
	v_add_f32_e32 v81, 1.0, v81
	v_rcp_f32_e32 v80, v80
	v_rcp_f32_e32 v81, v81
	v_add_f32_e32 v82, 1.0, v82
	v_add_f32_e32 v83, 1.0, v83
	v_rcp_f32_e32 v82, v82
	v_rcp_f32_e32 v83, v83
	v_pk_mul_f32 v[76:77], v[76:77], v[80:81]
	s_nop 0
	v_pk_mul_f32 v[72:73], v[76:77], v[72:73]
	v_pk_mul_f32 v[76:77], v[78:79], v[82:83]
	v_cvt_pk_bf16_f32 v72, v72, v73
	v_mul_f32_e32 v73, 0xbfb8aa3b, v68
	v_pk_mul_f32 v[74:75], v[76:77], v[74:75]
	v_exp_f32_e32 v76, v73
	v_mul_f32_e32 v73, 0xbfb8aa3b, v69
	v_exp_f32_e32 v77, v73
	v_cvt_pk_bf16_f32 v73, v74, v75
	v_add_f32_e32 v74, 1.0, v76
	v_mul_f32_e32 v76, 0xbfb8aa3b, v70
	v_add_f32_e32 v75, 1.0, v77
	v_mul_f32_e32 v77, 0xbfb8aa3b, v71
	v_exp_f32_e32 v76, v76
	v_exp_f32_e32 v77, v77
	v_rcp_f32_e32 v74, v74
	v_rcp_f32_e32 v75, v75
	v_add_f32_e32 v76, 1.0, v76
	v_add_f32_e32 v77, 1.0, v77
	v_rcp_f32_e32 v76, v76
	v_rcp_f32_e32 v77, v77
	v_pk_mul_f32 v[68:69], v[68:69], v[74:75]
	s_nop 0
	v_pk_mul_f32 v[64:65], v[68:69], v[64:65]
	v_add_u32_e32 v68, 0x80, v152
	v_cvt_pk_bf16_f32 v74, v64, v65
	v_pk_mul_f32 v[64:65], v[70:71], v[76:77]
	s_nop 0
	v_pk_mul_f32 v[64:65], v[64:65], v[66:67]
	v_mul_f32_e32 v66, 0xbfb8aa3b, v62
	v_cvt_pk_bf16_f32 v75, v64, v65
	v_mad_i64_i32 v[64:65], s[14:15], v84, s91, v[144:145]
	global_store_dwordx4 v[64:65], v[72:75], off
	v_mul_f32_e32 v64, 0xbfb8aa3b, v60
	v_mul_f32_e32 v65, 0xbfb8aa3b, v61
	v_exp_f32_e32 v64, v64
	v_exp_f32_e32 v65, v65
	v_mul_f32_e32 v67, 0xbfb8aa3b, v63
	v_exp_f32_e32 v66, v66
	v_exp_f32_e32 v67, v67
	v_add_f32_e32 v64, 1.0, v64
	v_add_f32_e32 v65, 1.0, v65
	v_rcp_f32_e32 v64, v64
	v_rcp_f32_e32 v65, v65
	v_add_f32_e32 v66, 1.0, v66
	v_add_f32_e32 v67, 1.0, v67
	v_rcp_f32_e32 v66, v66
	v_rcp_f32_e32 v67, v67
	v_pk_mul_f32 v[60:61], v[60:61], v[64:65]
	s_nop 0
	v_pk_mul_f32 v[56:57], v[60:61], v[56:57]
	v_pk_mul_f32 v[60:61], v[62:63], v[66:67]
	v_cvt_pk_bf16_f32 v56, v56, v57
	v_mul_f32_e32 v57, 0xbfb8aa3b, v52
	v_pk_mul_f32 v[58:59], v[60:61], v[58:59]
	v_exp_f32_e32 v60, v57
	v_mul_f32_e32 v57, 0xbfb8aa3b, v53
	v_exp_f32_e32 v61, v57
	v_cvt_pk_bf16_f32 v57, v58, v59
	v_add_f32_e32 v58, 1.0, v60
; DI unsigned pk_bf16(float lo, float hi) { f32x2 v = {lo, hi}; return __builtin_bit_cast(unsigned, __builtin_convertvector(v, bf16v2)); }
; DI float fast_silu(float x) { return x * fast_sigmoid(x); }
; #define PG8_WAIT_V(n) asm volatile("s_waitcnt vmcnt(" #n ")" ::: "memory")
; #define PG8_BAR __builtin_amdgcn_s_barrier()
; #define PG8_WAIT_V(n) asm volatile("s_waitcnt vmcnt(" #n ")" ::: "memory")
; #define PG8_BAR __builtin_amdgcn_s_barrier()
; template <class Epi>
; DI void gemm_phase(LAS unsigned char* lds, const Gemm g, const StaticOrder S, const Epi E) {
;     ...
;         if (!has_next) break;
; #pragma unroll
;         for (int a = 0; a < 2; ++a)
; #pragma unroll
;             for (int b = 0; b < 2; ++b)
; #pragma unroll
;                 for (int m = 0; m < 4; ++m)
; #pragma unroll
;                     for (int n = 0; n < 2; ++n) acc[a][b][m][n] = (f32x4){0.f, 0.f, 0.f, 0.f};
;         cur = nxt; cA = nA; cB = nB; ++ui;
;     }
;     PG8_WAIT_V(0);
;     if (wr == 0) PG8_BAR;
;     PG8_BAR;
;     DI void operator()(AccRef acc, const Unit& u, int wr, int wc, int fr, int fq) const {
;     ...
;             for (int m = 0; m < 4; ++m) {
;                 const int row = row0 + ai * 128 + m * 16;
;                 const float r = RS ? rsc.r[ai][m] : 1.0f;
;                 const f32x4 a0 = acc[ai][0][m][0] * r, a1 = acc[ai][0][m][1] * r, b0 = acc[ai][1][m][0] * r, b1 = acc[ai][1][m][1] * r;
;                 u32x4 w;
;                 w.x = pk_bf16(fast_silu(a0[0]) * b0[0], fast_silu(a0[1]) * b0[1]); w.y = pk_bf16(fast_silu(a0[2]) * b0[2], fast_silu(a0[3]) * b0[3]);
;                 w.z = pk_bf16(fast_silu(a1[0]) * b1[0], fast_silu(a1[1]) * b1[1]); w.w = pk_bf16(fast_silu(a1[2]) * b1[2], fast_silu(a1[3]) * b1[3]);
;                 *(u32x4*)(G + (size_t)row * DFF + col) = w;
	v_mul_f32_e32 v60, 0xbfb8aa3b, v54
	v_add_f32_e32 v59, 1.0, v61
	v_mul_f32_e32 v61, 0xbfb8aa3b, v55
	v_exp_f32_e32 v60, v60
	v_exp_f32_e32 v61, v61
	v_rcp_f32_e32 v58, v58
	v_rcp_f32_e32 v59, v59
	v_add_f32_e32 v60, 1.0, v60
	v_add_f32_e32 v61, 1.0, v61
	v_rcp_f32_e32 v60, v60
	v_rcp_f32_e32 v61, v61
	v_pk_mul_f32 v[52:53], v[52:53], v[58:59]
	s_nop 0
	v_pk_mul_f32 v[48:49], v[52:53], v[48:49]
	v_add_u32_e32 v52, 0x90, v152
	v_cvt_pk_bf16_f32 v58, v48, v49
	v_pk_mul_f32 v[48:49], v[54:55], v[60:61]
	s_nop 0
	v_pk_mul_f32 v[48:49], v[48:49], v[50:51]
	v_mul_f32_e32 v50, 0xbfb8aa3b, v46
	v_cvt_pk_bf16_f32 v59, v48, v49
	v_mad_i64_i32 v[48:49], s[14:15], v68, s91, v[144:145]
	global_store_dwordx4 v[48:49], v[56:59], off
	v_mul_f32_e32 v48, 0xbfb8aa3b, v44
	v_mul_f32_e32 v49, 0xbfb8aa3b, v45
	v_exp_f32_e32 v48, v48
	v_exp_f32_e32 v49, v49
	v_mul_f32_e32 v51, 0xbfb8aa3b, v47
	v_exp_f32_e32 v50, v50
	v_exp_f32_e32 v51, v51
	v_add_f32_e32 v48, 1.0, v48
	v_add_f32_e32 v49, 1.0, v49
	v_rcp_f32_e32 v48, v48
	v_rcp_f32_e32 v49, v49
	v_add_f32_e32 v50, 1.0, v50
	v_add_f32_e32 v51, 1.0, v51
	v_rcp_f32_e32 v50, v50
	v_rcp_f32_e32 v51, v51
	v_pk_mul_f32 v[44:45], v[44:45], v[48:49]
	s_nop 0
	v_pk_mul_f32 v[40:41], v[44:45], v[40:41]
	v_pk_mul_f32 v[44:45], v[46:47], v[50:51]
	v_cvt_pk_bf16_f32 v40, v40, v41
	v_mul_f32_e32 v41, 0xbfb8aa3b, v36
	v_pk_mul_f32 v[42:43], v[44:45], v[42:43]
	v_exp_f32_e32 v44, v41
	v_mul_f32_e32 v41, 0xbfb8aa3b, v37
	v_exp_f32_e32 v45, v41
	v_cvt_pk_bf16_f32 v41, v42, v43
	v_add_f32_e32 v42, 1.0, v44
	v_mul_f32_e32 v44, 0xbfb8aa3b, v38
	v_add_f32_e32 v43, 1.0, v45
	v_mul_f32_e32 v45, 0xbfb8aa3b, v39
	v_exp_f32_e32 v44, v44
	v_exp_f32_e32 v45, v45
	v_rcp_f32_e32 v42, v42
	v_rcp_f32_e32 v43, v43
	v_add_f32_e32 v44, 1.0, v44
	v_add_f32_e32 v45, 1.0, v45
	v_rcp_f32_e32 v44, v44
	v_rcp_f32_e32 v45, v45
	v_pk_mul_f32 v[36:37], v[36:37], v[42:43]
	s_nop 0
	v_pk_mul_f32 v[32:33], v[36:37], v[32:33]
	v_add_u32_e32 v36, 0xa0, v152
	v_cvt_pk_bf16_f32 v42, v32, v33
	v_pk_mul_f32 v[32:33], v[38:39], v[44:45]
	s_nop 0
	v_pk_mul_f32 v[32:33], v[32:33], v[34:35]
	v_mul_f32_e32 v34, 0xbfb8aa3b, v30
	v_cvt_pk_bf16_f32 v43, v32, v33
	v_mad_i64_i32 v[32:33], s[14:15], v52, s91, v[144:145]
	global_store_dwordx4 v[32:33], v[40:43], off
	v_mul_f32_e32 v32, 0xbfb8aa3b, v28
	v_mul_f32_e32 v33, 0xbfb8aa3b, v29
	v_exp_f32_e32 v32, v32
	v_exp_f32_e32 v33, v33
	v_mul_f32_e32 v35, 0xbfb8aa3b, v31
	v_exp_f32_e32 v34, v34
	v_exp_f32_e32 v35, v35
	v_add_f32_e32 v32, 1.0, v32
	v_add_f32_e32 v33, 1.0, v33
	v_rcp_f32_e32 v32, v32
	v_rcp_f32_e32 v33, v33
	v_add_f32_e32 v34, 1.0, v34
	v_add_f32_e32 v35, 1.0, v35
	v_rcp_f32_e32 v34, v34
	v_rcp_f32_e32 v35, v35
	v_pk_mul_f32 v[28:29], v[28:29], v[32:33]
	s_nop 0
	v_pk_mul_f32 v[24:25], v[28:29], v[24:25]
	v_pk_mul_f32 v[28:29], v[30:31], v[34:35]
	v_cvt_pk_bf16_f32 v24, v24, v25
	v_mul_f32_e32 v25, 0xbfb8aa3b, v20
	v_pk_mul_f32 v[26:27], v[28:29], v[26:27]
	v_exp_f32_e32 v28, v25
	v_mul_f32_e32 v25, 0xbfb8aa3b, v21
	v_exp_f32_e32 v29, v25
	v_cvt_pk_bf16_f32 v25, v26, v27
	v_add_f32_e32 v26, 1.0, v28
	v_mul_f32_e32 v28, 0xbfb8aa3b, v22
	v_add_f32_e32 v27, 1.0, v29
	v_mul_f32_e32 v29, 0xbfb8aa3b, v23
	v_exp_f32_e32 v28, v28
	v_exp_f32_e32 v29, v29
	v_rcp_f32_e32 v26, v26
	v_rcp_f32_e32 v27, v27
	v_add_f32_e32 v28, 1.0, v28
	v_add_f32_e32 v29, 1.0, v29
	v_rcp_f32_e32 v28, v28
	v_rcp_f32_e32 v29, v29
	v_pk_mul_f32 v[20:21], v[20:21], v[26:27]
	s_nop 0
	v_pk_mul_f32 v[16:17], v[20:21], v[16:17]
	v_add_u32_e32 v20, 0xb0, v152
	v_cvt_pk_bf16_f32 v26, v16, v17
	v_pk_mul_f32 v[16:17], v[22:23], v[28:29]
	s_nop 0
	v_pk_mul_f32 v[16:17], v[16:17], v[18:19]
	v_mul_f32_e32 v18, 0xbfb8aa3b, v14
	v_cvt_pk_bf16_f32 v27, v16, v17
	v_mad_i64_i32 v[16:17], s[14:15], v36, s91, v[144:145]
	global_store_dwordx4 v[16:17], v[24:27], off
	v_mul_f32_e32 v16, 0xbfb8aa3b, v12
	v_mul_f32_e32 v17, 0xbfb8aa3b, v13
	v_exp_f32_e32 v16, v16
	v_exp_f32_e32 v17, v17
	v_mul_f32_e32 v19, 0xbfb8aa3b, v15
	v_exp_f32_e32 v18, v18
	v_exp_f32_e32 v19, v19
	v_add_f32_e32 v16, 1.0, v16
	v_add_f32_e32 v17, 1.0, v17
	v_rcp_f32_e32 v16, v16
	v_rcp_f32_e32 v17, v17
	v_add_f32_e32 v18, 1.0, v18
	v_add_f32_e32 v19, 1.0, v19
	v_rcp_f32_e32 v18, v18
	v_rcp_f32_e32 v19, v19
	v_pk_mul_f32 v[12:13], v[12:13], v[16:17]
	s_nop 0
	v_pk_mul_f32 v[8:9], v[12:13], v[8:9]
	v_pk_mul_f32 v[12:13], v[14:15], v[18:19]
	v_cvt_pk_bf16_f32 v8, v8, v9
	v_mul_f32_e32 v9, 0xbfb8aa3b, v4
	v_pk_mul_f32 v[10:11], v[12:13], v[10:11]
	v_exp_f32_e32 v12, v9
	v_mul_f32_e32 v9, 0xbfb8aa3b, v5
	v_exp_f32_e32 v13, v9
	v_cvt_pk_bf16_f32 v9, v10, v11
	v_add_f32_e32 v10, 1.0, v12
	v_mul_f32_e32 v12, 0xbfb8aa3b, v6
	v_add_f32_e32 v11, 1.0, v13
	v_mul_f32_e32 v13, 0xbfb8aa3b, v7
	v_exp_f32_e32 v12, v12
	v_exp_f32_e32 v13, v13
	v_rcp_f32_e32 v10, v10
	v_rcp_f32_e32 v11, v11
	v_add_f32_e32 v12, 1.0, v12
	v_add_f32_e32 v13, 1.0, v13
	v_rcp_f32_e32 v12, v12
	v_rcp_f32_e32 v13, v13
	v_pk_mul_f32 v[4:5], v[4:5], v[10:11]
	s_nop 0
	v_pk_mul_f32 v[0:1], v[4:5], v[0:1]
	s_nop 0
	v_cvt_pk_bf16_f32 v10, v0, v1
	v_pk_mul_f32 v[0:1], v[6:7], v[12:13]
	s_nop 0
	v_pk_mul_f32 v[0:1], v[0:1], v[2:3]
	s_nop 0
	v_cvt_pk_bf16_f32 v11, v0, v1
	v_mad_i64_i32 v[0:1], s[14:15], v20, s91, v[144:145]
	global_store_dwordx4 v[0:1], v[8:11], off
	s_cbranch_vccz .LBB0_104
	s_waitcnt vmcnt(0)
	v_readlane_b32 s92, v243, 8
	s_cmpk_gt_u32 s6, 0xff
	v_readlane_b32 s93, v243, 9
	s_cbranch_scc1 .LBB0_111
	s_barrier

; #define PG8_STAGE(bufoff, gbase, voff) do { _Pragma("unroll") for (int _i = 0; _i < 2; ++_i) \
;         __builtin_amdgcn_global_load_lds((const unsigned*)((const char*)(gbase) + (voff)[_i]), (LAS unsigned*)(lds + (bufoff) + ldsw + _i * 8192), 16, 0, 0); } while (0)
; #define PG8_LDA(dst, b, h) do { _Pragma("unroll") for (int m = 0; m < 4; ++m) _Pragma("unroll") for (int k = 0; k < 2; ++k) dst[m][k] = *(const LAS bf16x8*)(lds + PG8_SA(b, h) + aoff + m * 2048 + k * 1024); } while (0)
; #define PG8_LDB(dst, b, h) do { _Pragma("unroll") for (int n = 0; n < 2; ++n) _Pragma("unroll") for (int k = 0; k < 2; ++k) dst[n][k] = *(const LAS bf16x8*)(lds + PG8_SB(b, h) + boff + n * 2048 + k * 1024); } while (0)
; #define PG8_MMA(ai, bj, At, Bt) do { __builtin_amdgcn_s_setprio(1); _Pragma("unroll") for (int m = 0; m < 4; ++m) _Pragma("unroll") for (int n = 0; n < 2; ++n) _Pragma("unroll") for (int k = 0; k < 2; ++k) \
;         acc[ai][bj][m][n] = __builtin_amdgcn_mfma_f32_16x16x32_bf16(Bt[n][k], At[m][k], acc[ai][bj][m][n], 0, 0, 0); __builtin_amdgcn_s_setprio(0); } while (0)
; #define PG8_WAIT_L(n) asm volatile("s_waitcnt lgkmcnt(" #n ")" ::: "memory")
; #define PG8_BAR __builtin_amdgcn_s_barrier()
; #define PG8_SCHED __builtin_amdgcn_sched_barrier(0)
; #define PG8_WAIT_L(n) asm volatile("s_waitcnt lgkmcnt(" #n ")" ::: "memory")
; #define PG8_BAR __builtin_amdgcn_s_barrier()
; #define PG8_SCHED __builtin_amdgcn_sched_barrier(0)
; template <class Epi>
; DI void gemm_phase(LAS unsigned char* lds, const Gemm g, const StaticOrder S, const Epi E) {
;     ...
;             const bool last = (t == nt - 2);
;             const char* a1 = cA + (size_t)(t + 1) * kstep;
;             const char* a2 = last ? nA : cA + (size_t)(t + 2) * kstep; const char* b2 = last ? nB : cB + (size_t)(t + 2) * kstep;
;             const char* a3 = a2 + kstep; const char* b3 = b2 + kstep;
;             PG8_LDB(B0, 0, 0); PG8_SCHED; PG8_LDA(At, 0, 0); PG8_STAGE(PG8_SA(1, 1), a1 + hstep, voffA);
;             PG8_WAIT_L(8); PG8_BAR; PG8_WAIT_L(0); PG8_MMA(0, 0, At, B0); PG8_BAR; PG8_SCHED;
;             PG8_LDB(B1, 0, 1); PG8_STAGE(PG8_SB(0, 0), b2, voffB);
;             PG8_BAR; PG8_WAIT_L(0); PG8_MMA(0, 1, At, B1); PG8_BAR;
;             PG8_LDA(At, 0, 1); PG8_STAGE(PG8_SA(0, 0), a2, voffA);
;             PG8_BAR; PG8_WAIT_L(0); PG8_MMA(1, 0, At, B0); PG8_BAR; PG8_SCHED;
.LBB0_186:
	ds_read_b128 v[128:131], v207
	ds_read_b128 v[132:135], v207 offset:1024
	ds_read_b128 v[136:139], v207 offset:2048
	ds_read_b128 v[140:143], v207 offset:3072
	s_add_u32 s76, s28, 0x100
	s_addc_u32 s77, s29, 0
	s_cmp_eq_u32 s97, 40
	s_cselect_b32 s81, s9, s77
	s_cselect_b32 s80, s8, s76
	s_cselect_b32 s79, s11, s7
	s_cselect_b32 s78, s10, s6
	v_lshl_add_u64 v[192:193], s[28:29], 0, v[184:185]
	s_add_i32 m0, s82, 0xc000
	ds_read_b128 v[144:147], v208
	ds_read_b128 v[148:151], v208 offset:1024
	ds_read_b128 v[152:155], v208 offset:2048
	ds_read_b128 v[156:159], v208 offset:3072
	ds_read_b128 v[160:163], v208 offset:4096
	ds_read_b128 v[164:167], v208 offset:5120
	ds_read_b128 v[168:171], v208 offset:6144
	ds_read_b128 v[172:175], v208 offset:7168
	global_load_lds_dwordx4 v[192:193], off
	v_lshl_add_u64 v[192:193], s[28:29], 0, v[186:187]
	s_add_i32 m0, s82, 0xe000
	s_nop 0
	global_load_lds_dwordx4 v[192:193], off
	s_waitcnt lgkmcnt(8)
	s_barrier
	s_waitcnt lgkmcnt(0)
	s_setprio 1
	s_waitcnt lgkmcnt(0)
	v_mfma_f32_16x16x32_bf16 v[124:127], v[128:131], v[144:147], v[124:127]
	v_mfma_f32_16x16x32_bf16 v[120:123], v[136:139], v[144:147], v[120:123]
	v_mfma_f32_16x16x32_bf16 v[108:111], v[128:131], v[152:155], v[108:111]
	v_mfma_f32_16x16x32_bf16 v[104:107], v[136:139], v[152:155], v[104:107]
	v_mfma_f32_16x16x32_bf16 v[92:95], v[128:131], v[160:163], v[92:95]
	v_mfma_f32_16x16x32_bf16 v[88:91], v[136:139], v[160:163], v[88:91]
	v_mfma_f32_16x16x32_bf16 v[76:79], v[128:131], v[168:171], v[76:79]
	v_mfma_f32_16x16x32_bf16 v[72:75], v[136:139], v[168:171], v[72:75]
	v_mfma_f32_16x16x32_bf16 v[124:127], v[132:135], v[148:151], v[124:127]
	v_mfma_f32_16x16x32_bf16 v[120:123], v[140:143], v[148:151], v[120:123]
	v_mfma_f32_16x16x32_bf16 v[108:111], v[132:135], v[156:159], v[108:111]
	v_mfma_f32_16x16x32_bf16 v[104:107], v[140:143], v[156:159], v[104:107]
	v_mfma_f32_16x16x32_bf16 v[92:95], v[132:135], v[164:167], v[92:95]
	v_mfma_f32_16x16x32_bf16 v[88:91], v[140:143], v[164:167], v[88:91]
	s_setprio 2
	s_barrier
	v_mfma_f32_16x16x32_bf16 v[76:79], v[132:135], v[172:175], v[76:79]
	v_mfma_f32_16x16x32_bf16 v[72:75], v[140:143], v[172:175], v[72:75]
	s_setprio 0
	s_add_i32 s14, s91, s59
	v_lshl_add_u64 v[216:217], s[78:79], 0, v[178:179]
	s_mov_b32 m0, s14
	ds_read_b128 v[192:195], v209
	ds_read_b128 v[196:199], v209 offset:1024
	ds_read_b128 v[200:203], v209 offset:2048
	ds_read_b128 v[212:215], v209 offset:3072
	global_load_lds_dwordx4 v[216:217], off
	v_lshl_add_u64 v[218:219], s[78:79], 0, v[182:183]
	s_add_i32 m0, s14, 0x2000
	s_nop 0
	global_load_lds_dwordx4 v[218:219], off
	s_barrier
	s_waitcnt lgkmcnt(0)
	s_setprio 1
	s_waitcnt lgkmcnt(0)
	v_mfma_f32_16x16x32_bf16 v[116:119], v[192:195], v[144:147], v[116:119]
	v_mfma_f32_16x16x32_bf16 v[112:115], v[200:203], v[144:147], v[112:115]
	v_mfma_f32_16x16x32_bf16 v[100:103], v[192:195], v[152:155], v[100:103]
	v_mfma_f32_16x16x32_bf16 v[96:99], v[200:203], v[152:155], v[96:99]
	v_mfma_f32_16x16x32_bf16 v[84:87], v[192:195], v[160:163], v[84:87]
	v_mfma_f32_16x16x32_bf16 v[80:83], v[200:203], v[160:163], v[80:83]
	v_mfma_f32_16x16x32_bf16 v[68:71], v[192:195], v[168:171], v[68:71]
	v_mfma_f32_16x16x32_bf16 v[64:67], v[200:203], v[168:171], v[64:67]
	v_mfma_f32_16x16x32_bf16 v[116:119], v[196:199], v[148:151], v[116:119]
	v_mfma_f32_16x16x32_bf16 v[112:115], v[212:215], v[148:151], v[112:115]
	v_mfma_f32_16x16x32_bf16 v[100:103], v[196:199], v[156:159], v[100:103]
	v_mfma_f32_16x16x32_bf16 v[96:99], v[212:215], v[156:159], v[96:99]
	v_mfma_f32_16x16x32_bf16 v[84:87], v[196:199], v[164:167], v[84:87]
	v_mfma_f32_16x16x32_bf16 v[80:83], v[212:215], v[164:167], v[80:83]
	s_setprio 2
	s_barrier
	v_mfma_f32_16x16x32_bf16 v[68:71], v[196:199], v[172:175], v[68:71]
	v_mfma_f32_16x16x32_bf16 v[64:67], v[212:215], v[172:175], v[64:67]
	s_setprio 0
	s_mov_b32 m0, s82
	v_lshl_add_u64 v[220:221], s[80:81], 0, v[176:177]
	ds_read_b128 v[144:147], v208 offset:16384
	ds_read_b128 v[148:151], v208 offset:17408
	ds_read_b128 v[152:155], v208 offset:18432
	ds_read_b128 v[156:159], v208 offset:19456
	ds_read_b128 v[160:163], v208 offset:20480
	ds_read_b128 v[164:167], v208 offset:21504
	ds_read_b128 v[168:171], v208 offset:22528
	ds_read_b128 v[172:175], v208 offset:23552
	global_load_lds_dwordx4 v[220:221], off
	v_lshl_add_u64 v[224:225], s[80:81], 0, v[180:181]
	s_mov_b32 m0, s83
	s_nop 0
	global_load_lds_dwordx4 v[224:225], off
	s_barrier
	s_waitcnt lgkmcnt(0)
	s_setprio 1
	s_waitcnt lgkmcnt(0)
	v_mfma_f32_16x16x32_bf16 v[60:63], v[128:131], v[144:147], v[60:63]
	v_mfma_f32_16x16x32_bf16 v[56:59], v[136:139], v[144:147], v[56:59]
	v_mfma_f32_16x16x32_bf16 v[44:47], v[128:131], v[152:155], v[44:47]
	v_mfma_f32_16x16x32_bf16 v[40:43], v[136:139], v[152:155], v[40:43]
	v_mfma_f32_16x16x32_bf16 v[28:31], v[128:131], v[160:163], v[28:31]
	v_mfma_f32_16x16x32_bf16 v[24:27], v[136:139], v[160:163], v[24:27]
	v_mfma_f32_16x16x32_bf16 v[12:15], v[128:131], v[168:171], v[12:15]
	v_mfma_f32_16x16x32_bf16 v[8:11], v[136:139], v[168:171], v[8:11]
	v_mfma_f32_16x16x32_bf16 v[60:63], v[132:135], v[148:151], v[60:63]
	v_mfma_f32_16x16x32_bf16 v[56:59], v[140:143], v[148:151], v[56:59]
	v_mfma_f32_16x16x32_bf16 v[44:47], v[132:135], v[156:159], v[44:47]
	v_mfma_f32_16x16x32_bf16 v[40:43], v[140:143], v[156:159], v[40:43]
	v_mfma_f32_16x16x32_bf16 v[28:31], v[132:135], v[164:167], v[28:31]
	v_mfma_f32_16x16x32_bf16 v[24:27], v[140:143], v[164:167], v[24:27]
	s_setprio 2
	s_barrier
; #define PG8_STAGE(bufoff, gbase, voff) do { _Pragma("unroll") for (int _i = 0; _i < 2; ++_i) \
;         __builtin_amdgcn_global_load_lds((const unsigned*)((const char*)(gbase) + (voff)[_i]), (LAS unsigned*)(lds + (bufoff) + ldsw + _i * 8192), 16, 0, 0); } while (0)
; #define PG8_LDA(dst, b, h) do { _Pragma("unroll") for (int m = 0; m < 4; ++m) _Pragma("unroll") for (int k = 0; k < 2; ++k) dst[m][k] = *(const LAS bf16x8*)(lds + PG8_SA(b, h) + aoff + m * 2048 + k * 1024); } while (0)
; #define PG8_LDB(dst, b, h) do { _Pragma("unroll") for (int n = 0; n < 2; ++n) _Pragma("unroll") for (int k = 0; k < 2; ++k) dst[n][k] = *(const LAS bf16x8*)(lds + PG8_SB(b, h) + boff + n * 2048 + k * 1024); } while (0)
; #define PG8_MMA(ai, bj, At, Bt) do { __builtin_amdgcn_s_setprio(1); _Pragma("unroll") for (int m = 0; m < 4; ++m) _Pragma("unroll") for (int n = 0; n < 2; ++n) _Pragma("unroll") for (int k = 0; k < 2; ++k) \
;         acc[ai][bj][m][n] = __builtin_amdgcn_mfma_f32_16x16x32_bf16(Bt[n][k], At[m][k], acc[ai][bj][m][n], 0, 0, 0); __builtin_amdgcn_s_setprio(0); } while (0)
; #define PG8_WAIT_V(n) asm volatile("s_waitcnt vmcnt(" #n ")" ::: "memory")
; #define PG8_WAIT_L(n) asm volatile("s_waitcnt lgkmcnt(" #n ")" ::: "memory")
; #define PG8_BAR __builtin_amdgcn_s_barrier()
; #define PG8_SCHED __builtin_amdgcn_sched_barrier(0)
; #define PG8_STAGE(bufoff, gbase, voff) do { _Pragma("unroll") for (int _i = 0; _i < 2; ++_i) \
;         __builtin_amdgcn_global_load_lds((const unsigned*)((const char*)(gbase) + (voff)[_i]), (LAS unsigned*)(lds + (bufoff) + ldsw + _i * 8192), 16, 0, 0); } while (0)
; #define PG8_BAR __builtin_amdgcn_s_barrier()
; template <class Epi>
; DI void gemm_phase(LAS unsigned char* lds, const Gemm g, const StaticOrder S, const Epi E) {
;     ...
;             PG8_BAR; PG8_WAIT_L(0); PG8_MMA(1, 0, At, B0); PG8_BAR; PG8_SCHED;
;             PG8_STAGE(PG8_SB(0, 1), b2 + hstep, voffB);
;             PG8_WAIT_V(6); PG8_BAR; PG8_MMA(1, 1, At, B1); PG8_BAR;
;             PG8_LDB(B0, 1, 0); PG8_SCHED; PG8_LDA(At, 1, 0); PG8_STAGE(PG8_SA(0, 1), a2 + hstep, voffA);
;             PG8_WAIT_L(8); PG8_BAR; PG8_WAIT_L(0); PG8_MMA(0, 0, At, B0); PG8_BAR; PG8_SCHED;
;             PG8_LDB(B1, 1, 1); PG8_STAGE(PG8_SB(1, 0), b3, voffB);
;             PG8_BAR; PG8_WAIT_L(0); PG8_MMA(0, 1, At, B1); PG8_BAR;
;             PG8_LDA(At, 1, 1); PG8_STAGE(PG8_SA(1, 0), a3, voffA);
	v_mfma_f32_16x16x32_bf16 v[12:15], v[132:135], v[172:175], v[12:15]
	v_mfma_f32_16x16x32_bf16 v[8:11], v[140:143], v[172:175], v[8:11]
	s_setprio 0
	s_add_u32 s14, s78, 0xb0000
	s_addc_u32 s15, s79, 0
	s_add_i32 s28, s92, s59
	v_lshl_add_u64 v[128:129], s[14:15], 0, v[178:179]
	s_mov_b32 m0, s28
	s_nop 0
	global_load_lds_dwordx4 v[128:129], off
	v_lshl_add_u64 v[128:129], s[14:15], 0, v[182:183]
	s_add_i32 m0, s28, 0x2000
	s_nop 0
	global_load_lds_dwordx4 v[128:129], off
	s_waitcnt vmcnt(6)
	s_barrier
	s_setprio 1
	v_mfma_f32_16x16x32_bf16 v[52:55], v[192:195], v[144:147], v[52:55]
	v_mfma_f32_16x16x32_bf16 v[48:51], v[200:203], v[144:147], v[48:51]
	v_mfma_f32_16x16x32_bf16 v[36:39], v[192:195], v[152:155], v[36:39]
	v_mfma_f32_16x16x32_bf16 v[32:35], v[200:203], v[152:155], v[32:35]
	v_mfma_f32_16x16x32_bf16 v[20:23], v[192:195], v[160:163], v[20:23]
	v_mfma_f32_16x16x32_bf16 v[16:19], v[200:203], v[160:163], v[16:19]
	v_mfma_f32_16x16x32_bf16 v[4:7], v[192:195], v[168:171], v[4:7]
	v_mfma_f32_16x16x32_bf16 v[0:3], v[200:203], v[168:171], v[0:3]
	v_mfma_f32_16x16x32_bf16 v[52:55], v[196:199], v[148:151], v[52:55]
	v_mfma_f32_16x16x32_bf16 v[48:51], v[212:215], v[148:151], v[48:51]
	v_mfma_f32_16x16x32_bf16 v[36:39], v[196:199], v[156:159], v[36:39]
	v_mfma_f32_16x16x32_bf16 v[32:35], v[212:215], v[156:159], v[32:35]
	v_mfma_f32_16x16x32_bf16 v[20:23], v[196:199], v[164:167], v[20:23]
	v_mfma_f32_16x16x32_bf16 v[16:19], v[212:215], v[164:167], v[16:19]
	s_setprio 2
	s_barrier
	v_mfma_f32_16x16x32_bf16 v[4:7], v[196:199], v[172:175], v[4:7]
	v_mfma_f32_16x16x32_bf16 v[0:3], v[212:215], v[172:175], v[0:3]
	s_setprio 0
	s_add_i32 s28, 0, 0x18000
	v_add_u32_e32 v140, s28, v205
	ds_read_b128 v[128:131], v140
	ds_read_b128 v[132:135], v140 offset:1024
	ds_read_b128 v[136:139], v140 offset:2048
	ds_read_b128 v[140:143], v140 offset:3072
	s_add_u32 s14, s80, 0xb0000
	s_addc_u32 s15, s81, 0
	s_mov_b32 m0, s84
	v_lshl_add_u64 v[192:193], s[14:15], 0, v[176:177]
	ds_read_b128 v[144:147], v208 offset:32768
	ds_read_b128 v[148:151], v208 offset:33792
	ds_read_b128 v[152:155], v208 offset:34816
	ds_read_b128 v[156:159], v208 offset:35840
	ds_read_b128 v[160:163], v208 offset:36864
	ds_read_b128 v[164:167], v208 offset:37888
	ds_read_b128 v[168:171], v208 offset:38912
	ds_read_b128 v[172:175], v208 offset:39936
	global_load_lds_dwordx4 v[192:193], off
	v_lshl_add_u64 v[192:193], s[14:15], 0, v[180:181]
	s_mov_b32 m0, s85
	s_nop 0
	global_load_lds_dwordx4 v[192:193], off
	s_waitcnt lgkmcnt(8)
	s_barrier
	s_waitcnt lgkmcnt(0)
	s_setprio 1
	s_waitcnt lgkmcnt(0)
	v_mfma_f32_16x16x32_bf16 v[124:127], v[128:131], v[144:147], v[124:127]
	v_mfma_f32_16x16x32_bf16 v[120:123], v[136:139], v[144:147], v[120:123]
	v_mfma_f32_16x16x32_bf16 v[108:111], v[128:131], v[152:155], v[108:111]
	v_mfma_f32_16x16x32_bf16 v[104:107], v[136:139], v[152:155], v[104:107]
	v_mfma_f32_16x16x32_bf16 v[92:95], v[128:131], v[160:163], v[92:95]
	v_mfma_f32_16x16x32_bf16 v[88:91], v[136:139], v[160:163], v[88:91]
	v_mfma_f32_16x16x32_bf16 v[76:79], v[128:131], v[168:171], v[76:79]
	v_mfma_f32_16x16x32_bf16 v[72:75], v[136:139], v[168:171], v[72:75]
	v_mfma_f32_16x16x32_bf16 v[124:127], v[132:135], v[148:151], v[124:127]
	v_mfma_f32_16x16x32_bf16 v[120:123], v[140:143], v[148:151], v[120:123]
	v_mfma_f32_16x16x32_bf16 v[108:111], v[132:135], v[156:159], v[108:111]
	v_mfma_f32_16x16x32_bf16 v[104:107], v[140:143], v[156:159], v[104:107]
	v_mfma_f32_16x16x32_bf16 v[92:95], v[132:135], v[164:167], v[92:95]
	v_mfma_f32_16x16x32_bf16 v[88:91], v[140:143], v[164:167], v[88:91]
	s_setprio 2
	s_barrier
	v_mfma_f32_16x16x32_bf16 v[76:79], v[132:135], v[172:175], v[76:79]
	v_mfma_f32_16x16x32_bf16 v[72:75], v[140:143], v[172:175], v[72:75]
	s_setprio 0
	s_add_i32 s29, 0, 0x1c000
	s_add_i32 s14, s28, s59
	v_add_u32_e32 v211, s29, v205
	v_lshl_add_u64 v[216:217], v[216:217], 0, s[24:25]
	s_mov_b32 m0, s14
	ds_read_b128 v[192:195], v211
	ds_read_b128 v[196:199], v211 offset:1024
	ds_read_b128 v[200:203], v211 offset:2048
	ds_read_b128 v[212:215], v211 offset:3072
	global_load_lds_dwordx4 v[216:217], off
	v_lshl_add_u64 v[216:217], v[218:219], 0, s[24:25]
	s_add_i32 m0, s14, 0x2000
	s_nop 0
	global_load_lds_dwordx4 v[216:217], off
	s_barrier
	s_waitcnt lgkmcnt(0)
	s_setprio 1
	s_waitcnt lgkmcnt(0)
	v_mfma_f32_16x16x32_bf16 v[116:119], v[192:195], v[144:147], v[116:119]
	v_mfma_f32_16x16x32_bf16 v[112:115], v[200:203], v[144:147], v[112:115]
	v_mfma_f32_16x16x32_bf16 v[100:103], v[192:195], v[152:155], v[100:103]
	v_mfma_f32_16x16x32_bf16 v[96:99], v[200:203], v[152:155], v[96:99]
	v_mfma_f32_16x16x32_bf16 v[84:87], v[192:195], v[160:163], v[84:87]
	v_mfma_f32_16x16x32_bf16 v[80:83], v[200:203], v[160:163], v[80:83]
	v_mfma_f32_16x16x32_bf16 v[68:71], v[192:195], v[168:171], v[68:71]
	v_mfma_f32_16x16x32_bf16 v[64:67], v[200:203], v[168:171], v[64:67]
	v_mfma_f32_16x16x32_bf16 v[116:119], v[196:199], v[148:151], v[116:119]
	v_mfma_f32_16x16x32_bf16 v[112:115], v[212:215], v[148:151], v[112:115]
	v_mfma_f32_16x16x32_bf16 v[100:103], v[196:199], v[156:159], v[100:103]
	v_mfma_f32_16x16x32_bf16 v[96:99], v[212:215], v[156:159], v[96:99]
	v_mfma_f32_16x16x32_bf16 v[84:87], v[196:199], v[164:167], v[84:87]
	v_mfma_f32_16x16x32_bf16 v[80:83], v[212:215], v[164:167], v[80:83]
	s_setprio 2
	s_barrier
; #define PG8_STAGE(bufoff, gbase, voff) do { _Pragma("unroll") for (int _i = 0; _i < 2; ++_i) \
;         __builtin_amdgcn_global_load_lds((const unsigned*)((const char*)(gbase) + (voff)[_i]), (LAS unsigned*)(lds + (bufoff) + ldsw + _i * 8192), 16, 0, 0); } while (0)
; #define PG8_LDA(dst, b, h) do { _Pragma("unroll") for (int m = 0; m < 4; ++m) _Pragma("unroll") for (int k = 0; k < 2; ++k) dst[m][k] = *(const LAS bf16x8*)(lds + PG8_SA(b, h) + aoff + m * 2048 + k * 1024); } while (0)
; #define PG8_MMA(ai, bj, At, Bt) do { __builtin_amdgcn_s_setprio(1); _Pragma("unroll") for (int m = 0; m < 4; ++m) _Pragma("unroll") for (int n = 0; n < 2; ++n) _Pragma("unroll") for (int k = 0; k < 2; ++k) \
;         acc[ai][bj][m][n] = __builtin_amdgcn_mfma_f32_16x16x32_bf16(Bt[n][k], At[m][k], acc[ai][bj][m][n], 0, 0, 0); __builtin_amdgcn_s_setprio(0); } while (0)
; #define PG8_WAIT_V(n) asm volatile("s_waitcnt vmcnt(" #n ")" ::: "memory")
; #define PG8_WAIT_L(n) asm volatile("s_waitcnt lgkmcnt(" #n ")" ::: "memory")
; #define PG8_BAR __builtin_amdgcn_s_barrier()
; #define PG8_SCHED __builtin_amdgcn_sched_barrier(0)
; #define PG8_STAGE(bufoff, gbase, voff) do { _Pragma("unroll") for (int _i = 0; _i < 2; ++_i) \
;         __builtin_amdgcn_global_load_lds((const unsigned*)((const char*)(gbase) + (voff)[_i]), (LAS unsigned*)(lds + (bufoff) + ldsw + _i * 8192), 16, 0, 0); } while (0)
; #define PG8_LDA(dst, b, h) do { _Pragma("unroll") for (int m = 0; m < 4; ++m) _Pragma("unroll") for (int k = 0; k < 2; ++k) dst[m][k] = *(const LAS bf16x8*)(lds + PG8_SA(b, h) + aoff + m * 2048 + k * 1024); } while (0)
; #define PG8_WAIT_V(n) asm volatile("s_waitcnt vmcnt(" #n ")" ::: "memory")
; #define PG8_WAIT_L(n) asm volatile("s_waitcnt lgkmcnt(" #n ")" ::: "memory")
; #define PG8_BAR __builtin_amdgcn_s_barrier()
; #define PG8_SCHED __builtin_amdgcn_sched_barrier(0)
; template <class Epi>
; DI void gemm_phase(LAS unsigned char* lds, const Gemm g, const StaticOrder S, const Epi E) {
;     ...
;             PG8_BAR; PG8_WAIT_L(0); PG8_MMA(0, 1, At, B1); PG8_BAR;
;             PG8_LDA(At, 1, 1); PG8_STAGE(PG8_SA(1, 0), a3, voffA);
;             PG8_BAR; PG8_WAIT_L(0); PG8_MMA(1, 0, At, B0); PG8_BAR; PG8_SCHED;
;             PG8_STAGE(PG8_SB(1, 1), b3 + hstep, voffB);
;             PG8_WAIT_V(6); PG8_BAR; PG8_MMA(1, 1, At, B1); PG8_BAR;
	v_mfma_f32_16x16x32_bf16 v[68:71], v[196:199], v[172:175], v[68:71]
	v_mfma_f32_16x16x32_bf16 v[64:67], v[212:215], v[172:175], v[64:67]
	s_setprio 0
	s_mov_b32 m0, s87
	v_lshl_add_u64 v[216:217], v[220:221], 0, s[24:25]
	ds_read_b128 v[144:147], v208 offset:49152
	ds_read_b128 v[148:151], v208 offset:50176
	ds_read_b128 v[152:155], v208 offset:51200
	ds_read_b128 v[156:159], v208 offset:52224
	ds_read_b128 v[160:163], v208 offset:53248
	ds_read_b128 v[164:167], v208 offset:54272
	ds_read_b128 v[168:171], v208 offset:55296
	ds_read_b128 v[172:175], v208 offset:56320
	global_load_lds_dwordx4 v[216:217], off
	v_lshl_add_u64 v[216:217], v[224:225], 0, s[24:25]
	s_mov_b32 m0, s88
	s_nop 0
	global_load_lds_dwordx4 v[216:217], off
	s_barrier
	s_waitcnt lgkmcnt(0)
	s_setprio 1
	s_waitcnt lgkmcnt(0)
	v_mfma_f32_16x16x32_bf16 v[60:63], v[128:131], v[144:147], v[60:63]
	v_mfma_f32_16x16x32_bf16 v[56:59], v[136:139], v[144:147], v[56:59]
	v_mfma_f32_16x16x32_bf16 v[44:47], v[128:131], v[152:155], v[44:47]
	v_mfma_f32_16x16x32_bf16 v[40:43], v[136:139], v[152:155], v[40:43]
	v_mfma_f32_16x16x32_bf16 v[28:31], v[128:131], v[160:163], v[28:31]
	v_mfma_f32_16x16x32_bf16 v[24:27], v[136:139], v[160:163], v[24:27]
	v_mfma_f32_16x16x32_bf16 v[12:15], v[128:131], v[168:171], v[12:15]
	v_mfma_f32_16x16x32_bf16 v[8:11], v[136:139], v[168:171], v[8:11]
	v_mfma_f32_16x16x32_bf16 v[60:63], v[132:135], v[148:151], v[60:63]
	v_mfma_f32_16x16x32_bf16 v[56:59], v[140:143], v[148:151], v[56:59]
	v_mfma_f32_16x16x32_bf16 v[44:47], v[132:135], v[156:159], v[44:47]
	v_mfma_f32_16x16x32_bf16 v[40:43], v[140:143], v[156:159], v[40:43]
	v_mfma_f32_16x16x32_bf16 v[28:31], v[132:135], v[164:167], v[28:31]
	v_mfma_f32_16x16x32_bf16 v[24:27], v[140:143], v[164:167], v[24:27]
	s_setprio 2
	s_barrier
	v_mfma_f32_16x16x32_bf16 v[12:15], v[132:135], v[172:175], v[12:15]
	v_mfma_f32_16x16x32_bf16 v[8:11], v[140:143], v[172:175], v[8:11]
	s_setprio 0
	s_add_u32 s14, s78, 0xb0080
	s_addc_u32 s15, s79, 0
	s_add_i32 s28, s29, s59
	v_lshl_add_u64 v[128:129], s[14:15], 0, v[178:179]
	s_mov_b32 m0, s28
	s_nop 0
	global_load_lds_dwordx4 v[128:129], off
	v_lshl_add_u64 v[128:129], s[14:15], 0, v[182:183]
	s_add_i32 m0, s28, 0x2000
	s_nop 0
	global_load_lds_dwordx4 v[128:129], off
	s_waitcnt vmcnt(6)
	s_barrier
	s_setprio 1
	v_mfma_f32_16x16x32_bf16 v[52:55], v[192:195], v[144:147], v[52:55]
	v_mfma_f32_16x16x32_bf16 v[48:51], v[200:203], v[144:147], v[48:51]
	v_mfma_f32_16x16x32_bf16 v[36:39], v[192:195], v[152:155], v[36:39]
	v_mfma_f32_16x16x32_bf16 v[32:35], v[200:203], v[152:155], v[32:35]
	v_mfma_f32_16x16x32_bf16 v[20:23], v[192:195], v[160:163], v[20:23]
	v_mfma_f32_16x16x32_bf16 v[16:19], v[200:203], v[160:163], v[16:19]
	v_mfma_f32_16x16x32_bf16 v[4:7], v[192:195], v[168:171], v[4:7]
	v_mfma_f32_16x16x32_bf16 v[0:3], v[200:203], v[168:171], v[0:3]
	v_mfma_f32_16x16x32_bf16 v[52:55], v[196:199], v[148:151], v[52:55]
	v_mfma_f32_16x16x32_bf16 v[48:51], v[212:215], v[148:151], v[48:51]
	v_mfma_f32_16x16x32_bf16 v[36:39], v[196:199], v[156:159], v[36:39]
	v_mfma_f32_16x16x32_bf16 v[32:35], v[212:215], v[156:159], v[32:35]
	v_mfma_f32_16x16x32_bf16 v[20:23], v[196:199], v[164:167], v[20:23]
	v_mfma_f32_16x16x32_bf16 v[16:19], v[212:215], v[164:167], v[16:19]
	s_setprio 2
	s_barrier
	v_mfma_f32_16x16x32_bf16 v[4:7], v[196:199], v[172:175], v[4:7]
	v_mfma_f32_16x16x32_bf16 v[0:3], v[212:215], v[172:175], v[0:3]
	s_setprio 0
	s_add_i32 s97, s97, 2
	s_add_u32 s6, s6, 0x100
	s_addc_u32 s7, s7, 0
	s_cmp_gt_u32 s97, 41
	s_mov_b64 s[28:29], s[76:77]
	s_cbranch_scc0 .LBB0_186
; DI unsigned pk_bf16(float lo, float hi) { f32x2 v = {lo, hi}; return __builtin_bit_cast(unsigned, __builtin_convertvector(v, bf16v2)); }
; DI f32x4 bf_lo4(u32x4 w) { f32x4 r; r[0] = bf_lo(w.x); r[1] = bf_hi(w.x); r[2] = bf_lo(w.y); r[3] = bf_hi(w.y); return r; }
; DI f32x4 bf_hi4(u32x4 w) { f32x4 r; r[0] = bf_lo(w.z); r[1] = bf_hi(w.z); r[2] = bf_lo(w.w); r[3] = bf_hi(w.w); return r; }
;     DI void operator()(AccRef acc, const Unit& u, int wr, int wc, int fr, int fq) const {
;     ...
;         const int row0 = u.pm * 256 + wr * 64 + fr, col0 = u.pn * 256 + wc * 32 + 8 * fq;
; #pragma unroll
;         for (int ai = 0; ai < 2; ++ai) {
;             f32x4 bv[4][2][2];
; #pragma unroll
;             for (int m = 0; m < 4; ++m)
; #pragma unroll
;                 for (int bj = 0; bj < 2; ++bj) {
;                     const size_t o = (size_t)(row0 + ai * 128 + m * 16) * DM + col0 + bj * 128;
;                     if (BASEF32) { bv[m][bj][0] = *(const f32x4*)(basef + o); bv[m][bj][1] = *(const f32x4*)(basef + o + 4); }
;                     else { const u32x4 h = *(const u32x4*)(xnb + o); bv[m][bj][0] = bf_lo4(h); bv[m][bj][1] = bf_hi4(h); }
;                 }
; #pragma unroll
;             for (int m = 0; m < 4; ++m) {
;                 const int row = row0 + ai * 128 + m * 16;
;                 float q = 0.f;
; #pragma unroll
;                 for (int bj = 0; bj < 2; ++bj) {
;                     const size_t o = (size_t)row * DM + col0 + bj * 128;
;                     const f32x4 r0 = bv[m][bj][0] + scale * acc[ai][bj][m][0], r1 = bv[m][bj][1] + scale * acc[ai][bj][m][1];
;                     u32x4 w; w.x = pk_bf16(r0[0], r0[1]); w.y = pk_bf16(r0[2], r0[3]); w.z = pk_bf16(r1[0], r1[1]); w.w = pk_bf16(r1[2], r1[3]);
;                     *(u32x4*)(xnb + o) = w;
;                     if (STATS) q += r0[0] * r0[0] + r0[1] * r0[1] + r0[2] * r0[2] + r0[3] * r0[3] + r1[0] * r1[0] + r1[1] * r1[1] + r1[2] * r1[2] + r1[3] * r1[3];
;                 }
;                 if (STATS) { q += __shfl_xor(q, 16); q += __shfl_xor(q, 32); if (fq == 0) atomicAdd(ss + row, q); }
	v_lshl_add_u32 v194, s96, 8, v204
	v_lshl_or_b32 v192, s95, 8, v206
	v_ashrrev_i32_e32 v193, 31, v192
	v_ashrrev_i32_e32 v195, 31, v194
	v_lshl_add_u64 v[196:197], v[192:193], 2, s[52:53]
	v_lshlrev_b64 v[128:129], 12, v[194:195]
	v_lshl_add_u64 v[128:129], v[196:197], 0, v[128:129]
	global_load_dwordx4 v[214:217], v[128:129], off
	global_load_dwordx4 v[218:221], v[128:129], off offset:16
	global_load_dwordx4 v[224:227], v[128:129], off offset:512
	global_load_dwordx4 v[228:231], v[128:129], off offset:528
	v_or_b32_e32 v202, 16, v194
	v_or_b32_e32 v200, 32, v194
	v_or_b32_e32 v198, 48, v194
	v_ashrrev_i32_e32 v203, 31, v202
	v_ashrrev_i32_e32 v201, 31, v200
	v_ashrrev_i32_e32 v199, 31, v198
	v_lshlrev_b64 v[128:129], 12, v[202:203]
	v_lshlrev_b64 v[130:131], 12, v[200:201]
	v_lshlrev_b64 v[132:133], 12, v[198:199]
	v_lshl_add_u64 v[128:129], v[196:197], 0, v[128:129]
	v_lshl_add_u64 v[130:131], v[196:197], 0, v[130:131]
	v_lshl_add_u64 v[132:133], v[196:197], 0, v[132:133]
	global_load_dwordx4 v[168:171], v[128:129], off offset:16
	global_load_dwordx4 v[172:175], v[128:129], off
	global_load_dwordx4 v[160:163], v[128:129], off offset:528
	global_load_dwordx4 v[164:167], v[128:129], off offset:512
	global_load_dwordx4 v[152:155], v[130:131], off offset:16
	global_load_dwordx4 v[156:159], v[130:131], off
	global_load_dwordx4 v[144:147], v[130:131], off offset:528
	global_load_dwordx4 v[148:151], v[130:131], off offset:512
	global_load_dwordx4 v[136:139], v[132:133], off offset:16
	global_load_dwordx4 v[140:143], v[132:133], off
	s_nop 0
	global_load_dwordx4 v[128:131], v[132:133], off offset:528
	s_nop 0
	global_load_dwordx4 v[132:135], v[132:133], off offset:512
	v_and_b32_e32 v212, 64, v210
	v_xor_b32_e32 v211, 16, v210
	v_add_u32_e32 v212, 64, v212
	v_xor_b32_e32 v213, 32, v210
	v_cmp_lt_i32_e32 vcc, v211, v212
	v_lshlrev_b64 v[232:233], 11, v[194:195]
	s_waitcnt vmcnt(0)
	v_pk_fma_f32 v[124:125], v[124:125], 0.5, v[214:215] op_sel_hi:[1,0,1]
	v_cndmask_b32_e32 v211, v210, v211, vcc
	v_cmp_lt_i32_e32 vcc, v213, v212
	v_pk_fma_f32 v[116:117], v[116:117], 0.5, v[224:225] op_sel_hi:[1,0,1]
	v_lshlrev_b32_e32 v212, 2, v211
	v_cndmask_b32_e32 v213, v210, v213, vcc
	v_lshlrev_b32_e32 v211, 2, v213
	v_pk_fma_f32 v[126:127], v[126:127], 0.5, v[216:217] op_sel_hi:[1,0,1]
	v_pk_fma_f32 v[216:217], v[112:113], 0.5, v[228:229] op_sel_hi:[1,0,1]
	v_cvt_pk_bf16_f32 v112, v124, v125
	v_mul_f32_e32 v125, v125, v125
	v_mul_f32_e32 v213, v117, v117
	v_pk_fma_f32 v[118:119], v[118:119], 0.5, v[226:227] op_sel_hi:[1,0,1]
	v_fmac_f32_e32 v125, v124, v124
	v_fmac_f32_e32 v213, v116, v116
	v_fmac_f32_e32 v125, v126, v126
	v_fmac_f32_e32 v213, v118, v118
	v_pk_fma_f32 v[120:121], v[120:121], 0.5, v[218:219] op_sel_hi:[1,0,1]
	v_fmac_f32_e32 v125, v127, v127
	v_fmac_f32_e32 v213, v119, v119
	v_fmac_f32_e32 v125, v120, v120
	v_fmac_f32_e32 v213, v216, v216
	v_pk_fma_f32 v[122:123], v[122:123], 0.5, v[220:221] op_sel_hi:[1,0,1]
	v_pk_fma_f32 v[214:215], v[114:115], 0.5, v[230:231] op_sel_hi:[1,0,1]
	v_fmac_f32_e32 v125, v121, v121
	v_fmac_f32_e32 v213, v217, v217
	v_fmac_f32_e32 v125, v122, v122
	v_fmac_f32_e32 v213, v214, v214
	v_fmac_f32_e32 v125, v123, v123
	v_fmac_f32_e32 v213, v215, v215
	v_cvt_pk_bf16_f32 v115, v122, v123
	v_add_f32_e32 v122, v125, v213
	ds_bpermute_b32 v123, v212, v122
	v_cvt_pk_bf16_f32 v114, v120, v121
	v_lshl_add_u64 v[120:121], s[56:57], 0, v[232:233]
	v_cvt_pk_bf16_f32 v113, v126, v127
	v_lshl_add_u64 v[120:121], v[192:193], 1, v[120:121]
	global_store_dwordx4 v[120:121], v[112:115], off
	s_waitcnt lgkmcnt(0)
	s_nop 0
	v_add_f32_e32 v112, v122, v123
	ds_bpermute_b32 v113, v211, v112
	v_cvt_pk_bf16_f32 v114, v116, v117
	v_cvt_pk_bf16_f32 v115, v118, v119
	v_cvt_pk_bf16_f32 v116, v216, v217
	v_cvt_pk_bf16_f32 v117, v214, v215
	global_store_dwordx4 v[120:121], v[114:117], off offset:256
	s_and_saveexec_b64 s[6:7], s[0:1]
	s_cbranch_execz .LBB0_189
	v_lshl_add_u64 v[114:115], v[194:195], 2, s[60:61]
	s_waitcnt lgkmcnt(0)
	v_add_f32_e32 v112, v112, v113
	global_atomic_add_f32 v[114:115], v112, off

; #define PG8_STAGE(bufoff, gbase, voff) do { _Pragma("unroll") for (int _i = 0; _i < 2; ++_i) \
;         __builtin_amdgcn_global_load_lds((const unsigned*)((const char*)(gbase) + (voff)[_i]), (LAS unsigned*)(lds + (bufoff) + ldsw + _i * 8192), 16, 0, 0); } while (0)
; #define PG8_LDA(dst, b, h) do { _Pragma("unroll") for (int m = 0; m < 4; ++m) _Pragma("unroll") for (int k = 0; k < 2; ++k) dst[m][k] = *(const LAS bf16x8*)(lds + PG8_SA(b, h) + aoff + m * 2048 + k * 1024); } while (0)
; #define PG8_LDB(dst, b, h) do { _Pragma("unroll") for (int n = 0; n < 2; ++n) _Pragma("unroll") for (int k = 0; k < 2; ++k) dst[n][k] = *(const LAS bf16x8*)(lds + PG8_SB(b, h) + boff + n * 2048 + k * 1024); } while (0)
; #define PG8_MMA(ai, bj, At, Bt) do { __builtin_amdgcn_s_setprio(1); _Pragma("unroll") for (int m = 0; m < 4; ++m) _Pragma("unroll") for (int n = 0; n < 2; ++n) _Pragma("unroll") for (int k = 0; k < 2; ++k) \
;         acc[ai][bj][m][n] = __builtin_amdgcn_mfma_f32_16x16x32_bf16(Bt[n][k], At[m][k], acc[ai][bj][m][n], 0, 0, 0); __builtin_amdgcn_s_setprio(0); } while (0)
; #define PG8_WAIT_L(n) asm volatile("s_waitcnt lgkmcnt(" #n ")" ::: "memory")
; #define PG8_BAR __builtin_amdgcn_s_barrier()
; #define PG8_SCHED __builtin_amdgcn_sched_barrier(0)
; #define PG8_WAIT_L(n) asm volatile("s_waitcnt lgkmcnt(" #n ")" ::: "memory")
; #define PG8_BAR __builtin_amdgcn_s_barrier()
; #define PG8_SCHED __builtin_amdgcn_sched_barrier(0)
; template <class Epi>
; DI void gemm_phase(LAS unsigned char* lds, const Gemm g, const StaticOrder S, const Epi E) {
;     ...
;             const bool last = (t == nt - 2);
;             const char* a1 = cA + (size_t)(t + 1) * kstep;
;             const char* a2 = last ? nA : cA + (size_t)(t + 2) * kstep; const char* b2 = last ? nB : cB + (size_t)(t + 2) * kstep;
;             const char* a3 = a2 + kstep; const char* b3 = b2 + kstep;
;             PG8_LDB(B0, 0, 0); PG8_SCHED; PG8_LDA(At, 0, 0); PG8_STAGE(PG8_SA(1, 1), a1 + hstep, voffA);
;             PG8_WAIT_L(8); PG8_BAR; PG8_WAIT_L(0); PG8_MMA(0, 0, At, B0); PG8_BAR; PG8_SCHED;
;             PG8_LDB(B1, 0, 1); PG8_STAGE(PG8_SB(0, 0), b2, voffB);
;             PG8_BAR; PG8_WAIT_L(0); PG8_MMA(0, 1, At, B1); PG8_BAR;
;             PG8_LDA(At, 0, 1); PG8_STAGE(PG8_SA(0, 0), a2, voffA);
;             PG8_BAR; PG8_WAIT_L(0); PG8_MMA(1, 0, At, B0); PG8_BAR; PG8_SCHED;
.LBB0_274:
	ds_read_b128 v[100:103], v227
	ds_read_b128 v[134:137], v227 offset:1024
	ds_read_b128 v[138:141], v227 offset:2048
	ds_read_b128 v[142:145], v227 offset:3072
	s_add_u32 s14, s8, 0xfffc0080
	s_addc_u32 s15, s9, -1
	s_cmp_eq_u32 s95, 12
	s_cselect_b32 s77, s1, s15
	s_cselect_b32 s76, s6, s14
	s_cselect_b32 s53, s7, s94
	s_cselect_b32 s52, s21, s23
	v_lshl_add_u64 v[104:105], s[8:9], 0, v[212:213]
	s_add_i32 m0, s78, 0xc000
	ds_read_b128 v[146:149], v228
	ds_read_b128 v[150:153], v228 offset:1024
	ds_read_b128 v[154:157], v228 offset:2048
	ds_read_b128 v[158:161], v228 offset:3072
	ds_read_b128 v[162:165], v228 offset:4096
	ds_read_b128 v[166:169], v228 offset:5120
	ds_read_b128 v[170:173], v228 offset:6144
	ds_read_b128 v[174:177], v228 offset:7168
	global_load_lds_dwordx4 v[104:105], off
	v_lshl_add_u64 v[104:105], s[8:9], 0, v[214:215]
	s_add_i32 m0, s78, 0xe000
	s_nop 0
	global_load_lds_dwordx4 v[104:105], off
	s_waitcnt lgkmcnt(8)
	s_barrier
	s_waitcnt lgkmcnt(0)
	s_setprio 1
	s_waitcnt lgkmcnt(0)
	v_mfma_f32_16x16x32_bf16 v[130:133], v[100:103], v[146:149], v[130:133]
	v_mfma_f32_16x16x32_bf16 v[126:129], v[138:141], v[146:149], v[126:129]
	v_mfma_f32_16x16x32_bf16 v[114:117], v[100:103], v[154:157], v[114:117]
	v_mfma_f32_16x16x32_bf16 v[110:113], v[138:141], v[154:157], v[110:113]
	v_mfma_f32_16x16x32_bf16 v[92:95], v[100:103], v[162:165], v[92:95]
	v_mfma_f32_16x16x32_bf16 v[88:91], v[138:141], v[162:165], v[88:91]
	v_mfma_f32_16x16x32_bf16 v[76:79], v[100:103], v[170:173], v[76:79]
	v_mfma_f32_16x16x32_bf16 v[72:75], v[138:141], v[170:173], v[72:75]
	v_mfma_f32_16x16x32_bf16 v[130:133], v[134:137], v[150:153], v[130:133]
	v_mfma_f32_16x16x32_bf16 v[126:129], v[142:145], v[150:153], v[126:129]
	v_mfma_f32_16x16x32_bf16 v[114:117], v[134:137], v[158:161], v[114:117]
	v_mfma_f32_16x16x32_bf16 v[110:113], v[142:145], v[158:161], v[110:113]
	v_mfma_f32_16x16x32_bf16 v[92:95], v[134:137], v[166:169], v[92:95]
	v_mfma_f32_16x16x32_bf16 v[88:91], v[142:145], v[166:169], v[88:91]
	s_setprio 2
	s_barrier
	v_mfma_f32_16x16x32_bf16 v[76:79], v[134:137], v[174:177], v[76:79]
	v_mfma_f32_16x16x32_bf16 v[72:75], v[142:145], v[174:177], v[72:75]
	s_setprio 0
	s_add_i32 s14, s87, s59
	v_lshl_add_u64 v[194:195], s[52:53], 0, v[200:201]
	s_mov_b32 m0, s14
	ds_read_b128 v[178:181], v229
	ds_read_b128 v[182:185], v229 offset:1024
	ds_read_b128 v[186:189], v229 offset:2048
	ds_read_b128 v[190:193], v229 offset:3072
	global_load_lds_dwordx4 v[194:195], off
	v_lshl_add_u64 v[196:197], s[52:53], 0, v[204:205]
	s_add_i32 m0, s14, 0x2000
	s_nop 0
	global_load_lds_dwordx4 v[196:197], off
	s_barrier
	s_waitcnt lgkmcnt(0)
	s_setprio 1
	s_waitcnt lgkmcnt(0)
	v_mfma_f32_16x16x32_bf16 v[122:125], v[178:181], v[146:149], v[122:125]
	v_mfma_f32_16x16x32_bf16 v[118:121], v[186:189], v[146:149], v[118:121]
	v_mfma_f32_16x16x32_bf16 v[104:107], v[178:181], v[154:157], v[106:109]
	v_mfma_f32_16x16x32_bf16 v[96:99], v[186:189], v[154:157], v[96:99]
	v_mfma_f32_16x16x32_bf16 v[84:87], v[178:181], v[162:165], v[84:87]
	v_mfma_f32_16x16x32_bf16 v[80:83], v[186:189], v[162:165], v[80:83]
	v_mfma_f32_16x16x32_bf16 v[68:71], v[178:181], v[170:173], v[68:71]
	v_mfma_f32_16x16x32_bf16 v[64:67], v[186:189], v[170:173], v[64:67]
	v_mfma_f32_16x16x32_bf16 v[122:125], v[182:185], v[150:153], v[122:125]
	v_mfma_f32_16x16x32_bf16 v[118:121], v[190:193], v[150:153], v[118:121]
	v_mfma_f32_16x16x32_bf16 v[104:107], v[182:185], v[158:161], v[104:107]
	v_mfma_f32_16x16x32_bf16 v[96:99], v[190:193], v[158:161], v[96:99]
	v_mfma_f32_16x16x32_bf16 v[84:87], v[182:185], v[166:169], v[84:87]
	v_mfma_f32_16x16x32_bf16 v[80:83], v[190:193], v[166:169], v[80:83]
	s_setprio 2
	s_barrier
	v_mfma_f32_16x16x32_bf16 v[68:71], v[182:185], v[174:177], v[68:71]
	v_mfma_f32_16x16x32_bf16 v[64:67], v[190:193], v[174:177], v[64:67]
	s_setprio 0
	s_mov_b32 m0, s78
	v_lshl_add_u64 v[220:221], s[76:77], 0, v[198:199]
	ds_read_b128 v[146:149], v228 offset:16384
	ds_read_b128 v[150:153], v228 offset:17408
	ds_read_b128 v[154:157], v228 offset:18432
	ds_read_b128 v[158:161], v228 offset:19456
	ds_read_b128 v[162:165], v228 offset:20480
	ds_read_b128 v[166:169], v228 offset:21504
	ds_read_b128 v[170:173], v228 offset:22528
	ds_read_b128 v[174:177], v228 offset:23552
	global_load_lds_dwordx4 v[220:221], off
	v_lshl_add_u64 v[232:233], s[76:77], 0, v[202:203]
	s_mov_b32 m0, s79
	s_nop 0
	global_load_lds_dwordx4 v[232:233], off
	s_barrier
	s_waitcnt lgkmcnt(0)
	s_setprio 1
	s_waitcnt lgkmcnt(0)
	v_mfma_f32_16x16x32_bf16 v[60:63], v[100:103], v[146:149], v[60:63]
	v_mfma_f32_16x16x32_bf16 v[56:59], v[138:141], v[146:149], v[56:59]
	v_mfma_f32_16x16x32_bf16 v[44:47], v[100:103], v[154:157], v[44:47]
	v_mfma_f32_16x16x32_bf16 v[40:43], v[138:141], v[154:157], v[40:43]
	v_mfma_f32_16x16x32_bf16 v[28:31], v[100:103], v[162:165], v[28:31]
	v_mfma_f32_16x16x32_bf16 v[24:27], v[138:141], v[162:165], v[24:27]
	v_mfma_f32_16x16x32_bf16 v[12:15], v[100:103], v[170:173], v[12:15]
	v_mfma_f32_16x16x32_bf16 v[8:11], v[138:141], v[170:173], v[8:11]
	v_mfma_f32_16x16x32_bf16 v[60:63], v[134:137], v[150:153], v[60:63]
	v_mfma_f32_16x16x32_bf16 v[56:59], v[142:145], v[150:153], v[56:59]
	v_mfma_f32_16x16x32_bf16 v[44:47], v[134:137], v[158:161], v[44:47]
	v_mfma_f32_16x16x32_bf16 v[40:43], v[142:145], v[158:161], v[40:43]
	v_mfma_f32_16x16x32_bf16 v[28:31], v[134:137], v[166:169], v[28:31]
	v_mfma_f32_16x16x32_bf16 v[24:27], v[142:145], v[166:169], v[24:27]
	s_setprio 2
	s_barrier
; #define PG8_STAGE(bufoff, gbase, voff) do { _Pragma("unroll") for (int _i = 0; _i < 2; ++_i) \
;         __builtin_amdgcn_global_load_lds((const unsigned*)((const char*)(gbase) + (voff)[_i]), (LAS unsigned*)(lds + (bufoff) + ldsw + _i * 8192), 16, 0, 0); } while (0)
; #define PG8_LDA(dst, b, h) do { _Pragma("unroll") for (int m = 0; m < 4; ++m) _Pragma("unroll") for (int k = 0; k < 2; ++k) dst[m][k] = *(const LAS bf16x8*)(lds + PG8_SA(b, h) + aoff + m * 2048 + k * 1024); } while (0)
; #define PG8_LDB(dst, b, h) do { _Pragma("unroll") for (int n = 0; n < 2; ++n) _Pragma("unroll") for (int k = 0; k < 2; ++k) dst[n][k] = *(const LAS bf16x8*)(lds + PG8_SB(b, h) + boff + n * 2048 + k * 1024); } while (0)
; #define PG8_MMA(ai, bj, At, Bt) do { __builtin_amdgcn_s_setprio(1); _Pragma("unroll") for (int m = 0; m < 4; ++m) _Pragma("unroll") for (int n = 0; n < 2; ++n) _Pragma("unroll") for (int k = 0; k < 2; ++k) \
;         acc[ai][bj][m][n] = __builtin_amdgcn_mfma_f32_16x16x32_bf16(Bt[n][k], At[m][k], acc[ai][bj][m][n], 0, 0, 0); __builtin_amdgcn_s_setprio(0); } while (0)
; #define PG8_WAIT_V(n) asm volatile("s_waitcnt vmcnt(" #n ")" ::: "memory")
; #define PG8_WAIT_L(n) asm volatile("s_waitcnt lgkmcnt(" #n ")" ::: "memory")
; #define PG8_BAR __builtin_amdgcn_s_barrier()
; #define PG8_SCHED __builtin_amdgcn_sched_barrier(0)
; #define PG8_STAGE(bufoff, gbase, voff) do { _Pragma("unroll") for (int _i = 0; _i < 2; ++_i) \
;         __builtin_amdgcn_global_load_lds((const unsigned*)((const char*)(gbase) + (voff)[_i]), (LAS unsigned*)(lds + (bufoff) + ldsw + _i * 8192), 16, 0, 0); } while (0)
; #define PG8_BAR __builtin_amdgcn_s_barrier()
; template <class Epi>
; DI void gemm_phase(LAS unsigned char* lds, const Gemm g, const StaticOrder S, const Epi E) {
;     ...
;             PG8_BAR; PG8_WAIT_L(0); PG8_MMA(1, 0, At, B0); PG8_BAR; PG8_SCHED;
;             PG8_STAGE(PG8_SB(0, 1), b2 + hstep, voffB);
;             PG8_WAIT_V(6); PG8_BAR; PG8_MMA(1, 1, At, B1); PG8_BAR;
;             PG8_LDB(B0, 1, 0); PG8_SCHED; PG8_LDA(At, 1, 0); PG8_STAGE(PG8_SA(0, 1), a2 + hstep, voffA);
;             PG8_WAIT_L(8); PG8_BAR; PG8_WAIT_L(0); PG8_MMA(0, 0, At, B0); PG8_BAR; PG8_SCHED;
;             PG8_LDB(B1, 1, 1); PG8_STAGE(PG8_SB(1, 0), b3, voffB);
;             PG8_BAR; PG8_WAIT_L(0); PG8_MMA(0, 1, At, B1); PG8_BAR;
;             PG8_LDA(At, 1, 1); PG8_STAGE(PG8_SA(1, 0), a3, voffA);
	v_mfma_f32_16x16x32_bf16 v[12:15], v[134:137], v[174:177], v[12:15]
	v_mfma_f32_16x16x32_bf16 v[8:11], v[142:145], v[174:177], v[8:11]
	s_setprio 0
	s_add_u32 s14, s52, 0x40000
	s_addc_u32 s15, s53, 0
	s_add_i32 s35, s90, s59
	v_lshl_add_u64 v[100:101], s[14:15], 0, v[200:201]
	s_mov_b32 m0, s35
	s_nop 0
	global_load_lds_dwordx4 v[100:101], off
	v_lshl_add_u64 v[100:101], s[14:15], 0, v[204:205]
	s_add_i32 m0, s35, 0x2000
	s_nop 0
	global_load_lds_dwordx4 v[100:101], off
	s_waitcnt vmcnt(6)
	s_barrier
	s_setprio 1
	v_mfma_f32_16x16x32_bf16 v[52:55], v[178:181], v[146:149], v[52:55]
	v_mfma_f32_16x16x32_bf16 v[48:51], v[186:189], v[146:149], v[48:51]
	v_mfma_f32_16x16x32_bf16 v[36:39], v[178:181], v[154:157], v[36:39]
	v_mfma_f32_16x16x32_bf16 v[32:35], v[186:189], v[154:157], v[32:35]
	v_mfma_f32_16x16x32_bf16 v[20:23], v[178:181], v[162:165], v[20:23]
	v_mfma_f32_16x16x32_bf16 v[16:19], v[186:189], v[162:165], v[16:19]
	v_mfma_f32_16x16x32_bf16 v[4:7], v[178:181], v[170:173], v[4:7]
	v_mfma_f32_16x16x32_bf16 v[0:3], v[186:189], v[170:173], v[0:3]
	v_mfma_f32_16x16x32_bf16 v[52:55], v[182:185], v[150:153], v[52:55]
	v_mfma_f32_16x16x32_bf16 v[48:51], v[190:193], v[150:153], v[48:51]
	v_mfma_f32_16x16x32_bf16 v[36:39], v[182:185], v[158:161], v[36:39]
	v_mfma_f32_16x16x32_bf16 v[32:35], v[190:193], v[158:161], v[32:35]
	v_mfma_f32_16x16x32_bf16 v[20:23], v[182:185], v[166:169], v[20:23]
	v_mfma_f32_16x16x32_bf16 v[16:19], v[190:193], v[166:169], v[16:19]
	s_setprio 2
	s_barrier
	v_mfma_f32_16x16x32_bf16 v[4:7], v[182:185], v[174:177], v[4:7]
	v_mfma_f32_16x16x32_bf16 v[0:3], v[190:193], v[174:177], v[0:3]
	s_setprio 0
	s_add_i32 s35, 0, 0x18000
	v_add_u32_e32 v108, s35, v225
	ds_read_b128 v[100:103], v108
	ds_read_b128 v[134:137], v108 offset:1024
	ds_read_b128 v[138:141], v108 offset:2048
	ds_read_b128 v[142:145], v108 offset:3072
	s_add_u32 s14, s76, 0x40000
	s_addc_u32 s15, s77, 0
	s_mov_b32 m0, s80
	v_lshl_add_u64 v[108:109], s[14:15], 0, v[198:199]
	ds_read_b128 v[146:149], v228 offset:32768
	ds_read_b128 v[150:153], v228 offset:33792
	ds_read_b128 v[154:157], v228 offset:34816
	ds_read_b128 v[158:161], v228 offset:35840
	ds_read_b128 v[162:165], v228 offset:36864
	ds_read_b128 v[166:169], v228 offset:37888
	ds_read_b128 v[170:173], v228 offset:38912
	ds_read_b128 v[174:177], v228 offset:39936
	global_load_lds_dwordx4 v[108:109], off
	v_lshl_add_u64 v[108:109], s[14:15], 0, v[202:203]
	s_mov_b32 m0, s81
	s_nop 0
	global_load_lds_dwordx4 v[108:109], off
	s_waitcnt lgkmcnt(8)
	s_barrier
	s_waitcnt lgkmcnt(0)
	s_setprio 1
	s_waitcnt lgkmcnt(0)
	v_mfma_f32_16x16x32_bf16 v[130:133], v[100:103], v[146:149], v[130:133]
	v_mfma_f32_16x16x32_bf16 v[126:129], v[138:141], v[146:149], v[126:129]
	v_mfma_f32_16x16x32_bf16 v[114:117], v[100:103], v[154:157], v[114:117]
	v_mfma_f32_16x16x32_bf16 v[108:111], v[138:141], v[154:157], v[110:113]
	v_mfma_f32_16x16x32_bf16 v[92:95], v[100:103], v[162:165], v[92:95]
	v_mfma_f32_16x16x32_bf16 v[88:91], v[138:141], v[162:165], v[88:91]
	v_mfma_f32_16x16x32_bf16 v[76:79], v[100:103], v[170:173], v[76:79]
	v_mfma_f32_16x16x32_bf16 v[72:75], v[138:141], v[170:173], v[72:75]
	v_mfma_f32_16x16x32_bf16 v[130:133], v[134:137], v[150:153], v[130:133]
	v_mfma_f32_16x16x32_bf16 v[126:129], v[142:145], v[150:153], v[126:129]
	v_mfma_f32_16x16x32_bf16 v[114:117], v[134:137], v[158:161], v[114:117]
	v_mfma_f32_16x16x32_bf16 v[110:113], v[142:145], v[158:161], v[108:111]
	v_mfma_f32_16x16x32_bf16 v[92:95], v[134:137], v[166:169], v[92:95]
	v_mfma_f32_16x16x32_bf16 v[88:91], v[142:145], v[166:169], v[88:91]
	s_setprio 2
	s_barrier
	v_mfma_f32_16x16x32_bf16 v[76:79], v[134:137], v[174:177], v[76:79]
	v_mfma_f32_16x16x32_bf16 v[72:75], v[142:145], v[174:177], v[72:75]
	s_setprio 0
	s_add_i32 s76, 0, 0x1c000
	v_add_u32_e32 v108, s76, v225
	s_add_i32 s14, s35, s59
	ds_read_b128 v[178:181], v108
	ds_read_b128 v[182:185], v108 offset:1024
	ds_read_b128 v[186:189], v108 offset:2048
	ds_read_b128 v[190:193], v108 offset:3072
	v_lshl_add_u64 v[108:109], v[194:195], 0, s[18:19]
	s_mov_b32 m0, s14
	s_nop 0
	global_load_lds_dwordx4 v[108:109], off
	v_lshl_add_u64 v[108:109], v[196:197], 0, s[18:19]
	s_add_i32 m0, s14, 0x2000
	s_nop 0
	global_load_lds_dwordx4 v[108:109], off
	s_barrier
	s_waitcnt lgkmcnt(0)
	s_setprio 1
	s_waitcnt lgkmcnt(0)
	v_mfma_f32_16x16x32_bf16 v[122:125], v[178:181], v[146:149], v[122:125]
	v_mfma_f32_16x16x32_bf16 v[118:121], v[186:189], v[146:149], v[118:121]
	v_mfma_f32_16x16x32_bf16 v[104:107], v[178:181], v[154:157], v[104:107]
	v_mfma_f32_16x16x32_bf16 v[96:99], v[186:189], v[154:157], v[96:99]
	v_mfma_f32_16x16x32_bf16 v[84:87], v[178:181], v[162:165], v[84:87]
	v_mfma_f32_16x16x32_bf16 v[80:83], v[186:189], v[162:165], v[80:83]
	v_mfma_f32_16x16x32_bf16 v[68:71], v[178:181], v[170:173], v[68:71]
	v_mfma_f32_16x16x32_bf16 v[64:67], v[186:189], v[170:173], v[64:67]
	v_mfma_f32_16x16x32_bf16 v[122:125], v[182:185], v[150:153], v[122:125]
	v_mfma_f32_16x16x32_bf16 v[118:121], v[190:193], v[150:153], v[118:121]
	v_mfma_f32_16x16x32_bf16 v[106:109], v[182:185], v[158:161], v[104:107]
	v_mfma_f32_16x16x32_bf16 v[96:99], v[190:193], v[158:161], v[96:99]
	v_mfma_f32_16x16x32_bf16 v[84:87], v[182:185], v[166:169], v[84:87]
	v_mfma_f32_16x16x32_bf16 v[80:83], v[190:193], v[166:169], v[80:83]
	s_setprio 2
	s_barrier
; #define PG8_STAGE(bufoff, gbase, voff) do { _Pragma("unroll") for (int _i = 0; _i < 2; ++_i) \
;         __builtin_amdgcn_global_load_lds((const unsigned*)((const char*)(gbase) + (voff)[_i]), (LAS unsigned*)(lds + (bufoff) + ldsw + _i * 8192), 16, 0, 0); } while (0)
; #define PG8_LDA(dst, b, h) do { _Pragma("unroll") for (int m = 0; m < 4; ++m) _Pragma("unroll") for (int k = 0; k < 2; ++k) dst[m][k] = *(const LAS bf16x8*)(lds + PG8_SA(b, h) + aoff + m * 2048 + k * 1024); } while (0)
; #define PG8_MMA(ai, bj, At, Bt) do { __builtin_amdgcn_s_setprio(1); _Pragma("unroll") for (int m = 0; m < 4; ++m) _Pragma("unroll") for (int n = 0; n < 2; ++n) _Pragma("unroll") for (int k = 0; k < 2; ++k) \
;         acc[ai][bj][m][n] = __builtin_amdgcn_mfma_f32_16x16x32_bf16(Bt[n][k], At[m][k], acc[ai][bj][m][n], 0, 0, 0); __builtin_amdgcn_s_setprio(0); } while (0)
; #define PG8_WAIT_V(n) asm volatile("s_waitcnt vmcnt(" #n ")" ::: "memory")
; #define PG8_WAIT_L(n) asm volatile("s_waitcnt lgkmcnt(" #n ")" ::: "memory")
; #define PG8_BAR __builtin_amdgcn_s_barrier()
; #define PG8_SCHED __builtin_amdgcn_sched_barrier(0)
; #define PG8_STAGE(bufoff, gbase, voff) do { _Pragma("unroll") for (int _i = 0; _i < 2; ++_i) \
;         __builtin_amdgcn_global_load_lds((const unsigned*)((const char*)(gbase) + (voff)[_i]), (LAS unsigned*)(lds + (bufoff) + ldsw + _i * 8192), 16, 0, 0); } while (0)
; #define PG8_LDA(dst, b, h) do { _Pragma("unroll") for (int m = 0; m < 4; ++m) _Pragma("unroll") for (int k = 0; k < 2; ++k) dst[m][k] = *(const LAS bf16x8*)(lds + PG8_SA(b, h) + aoff + m * 2048 + k * 1024); } while (0)
; #define PG8_WAIT_V(n) asm volatile("s_waitcnt vmcnt(" #n ")" ::: "memory")
; #define PG8_WAIT_L(n) asm volatile("s_waitcnt lgkmcnt(" #n ")" ::: "memory")
; #define PG8_BAR __builtin_amdgcn_s_barrier()
; #define PG8_SCHED __builtin_amdgcn_sched_barrier(0)
; template <class Epi>
; DI void gemm_phase(LAS unsigned char* lds, const Gemm g, const StaticOrder S, const Epi E) {
;     ...
;             PG8_BAR; PG8_WAIT_L(0); PG8_MMA(0, 1, At, B1); PG8_BAR;
;             PG8_LDA(At, 1, 1); PG8_STAGE(PG8_SA(1, 0), a3, voffA);
;             PG8_BAR; PG8_WAIT_L(0); PG8_MMA(1, 0, At, B0); PG8_BAR; PG8_SCHED;
;             PG8_STAGE(PG8_SB(1, 1), b3 + hstep, voffB);
;             PG8_WAIT_V(6); PG8_BAR; PG8_MMA(1, 1, At, B1); PG8_BAR;
	v_mfma_f32_16x16x32_bf16 v[68:71], v[182:185], v[174:177], v[68:71]
	v_mfma_f32_16x16x32_bf16 v[64:67], v[190:193], v[174:177], v[64:67]
	s_setprio 0
	s_mov_b32 m0, s83
	v_lshl_add_u64 v[104:105], v[220:221], 0, s[18:19]
	ds_read_b128 v[146:149], v228 offset:49152
	ds_read_b128 v[150:153], v228 offset:50176
	ds_read_b128 v[154:157], v228 offset:51200
	ds_read_b128 v[158:161], v228 offset:52224
	ds_read_b128 v[162:165], v228 offset:53248
	ds_read_b128 v[166:169], v228 offset:54272
	ds_read_b128 v[170:173], v228 offset:55296
	ds_read_b128 v[174:177], v228 offset:56320
	global_load_lds_dwordx4 v[104:105], off
	v_lshl_add_u64 v[104:105], v[232:233], 0, s[18:19]
	s_mov_b32 m0, s84
	s_nop 0
	global_load_lds_dwordx4 v[104:105], off
	s_barrier
	s_waitcnt lgkmcnt(0)
	s_setprio 1
	s_waitcnt lgkmcnt(0)
	v_mfma_f32_16x16x32_bf16 v[60:63], v[100:103], v[146:149], v[60:63]
	v_mfma_f32_16x16x32_bf16 v[56:59], v[138:141], v[146:149], v[56:59]
	v_mfma_f32_16x16x32_bf16 v[44:47], v[100:103], v[154:157], v[44:47]
	v_mfma_f32_16x16x32_bf16 v[40:43], v[138:141], v[154:157], v[40:43]
	v_mfma_f32_16x16x32_bf16 v[28:31], v[100:103], v[162:165], v[28:31]
	v_mfma_f32_16x16x32_bf16 v[24:27], v[138:141], v[162:165], v[24:27]
	v_mfma_f32_16x16x32_bf16 v[12:15], v[100:103], v[170:173], v[12:15]
	v_mfma_f32_16x16x32_bf16 v[8:11], v[138:141], v[170:173], v[8:11]
	v_mfma_f32_16x16x32_bf16 v[60:63], v[134:137], v[150:153], v[60:63]
	v_mfma_f32_16x16x32_bf16 v[56:59], v[142:145], v[150:153], v[56:59]
	v_mfma_f32_16x16x32_bf16 v[44:47], v[134:137], v[158:161], v[44:47]
	v_mfma_f32_16x16x32_bf16 v[40:43], v[142:145], v[158:161], v[40:43]
	v_mfma_f32_16x16x32_bf16 v[28:31], v[134:137], v[166:169], v[28:31]
	v_mfma_f32_16x16x32_bf16 v[24:27], v[142:145], v[166:169], v[24:27]
	s_setprio 2
	s_barrier
	v_mfma_f32_16x16x32_bf16 v[12:15], v[134:137], v[174:177], v[12:15]
	v_mfma_f32_16x16x32_bf16 v[8:11], v[142:145], v[174:177], v[8:11]
	s_setprio 0
	s_add_u32 s14, s52, 0x40080
	s_addc_u32 s15, s53, 0
	s_add_i32 s35, s76, s59
	v_lshl_add_u64 v[100:101], s[14:15], 0, v[200:201]
	s_mov_b32 m0, s35
	s_nop 0
	global_load_lds_dwordx4 v[100:101], off
	v_lshl_add_u64 v[100:101], s[14:15], 0, v[204:205]
	s_add_i32 m0, s35, 0x2000
	s_nop 0
	global_load_lds_dwordx4 v[100:101], off
	s_waitcnt vmcnt(6)
	s_barrier
	s_setprio 1
	v_mfma_f32_16x16x32_bf16 v[52:55], v[178:181], v[146:149], v[52:55]
	v_mfma_f32_16x16x32_bf16 v[48:51], v[186:189], v[146:149], v[48:51]
	v_mfma_f32_16x16x32_bf16 v[36:39], v[178:181], v[154:157], v[36:39]
	v_mfma_f32_16x16x32_bf16 v[32:35], v[186:189], v[154:157], v[32:35]
	v_mfma_f32_16x16x32_bf16 v[20:23], v[178:181], v[162:165], v[20:23]
	v_mfma_f32_16x16x32_bf16 v[16:19], v[186:189], v[162:165], v[16:19]
	v_mfma_f32_16x16x32_bf16 v[4:7], v[178:181], v[170:173], v[4:7]
	v_mfma_f32_16x16x32_bf16 v[0:3], v[186:189], v[170:173], v[0:3]
	v_mfma_f32_16x16x32_bf16 v[52:55], v[182:185], v[150:153], v[52:55]
	v_mfma_f32_16x16x32_bf16 v[48:51], v[190:193], v[150:153], v[48:51]
	v_mfma_f32_16x16x32_bf16 v[36:39], v[182:185], v[158:161], v[36:39]
	v_mfma_f32_16x16x32_bf16 v[32:35], v[190:193], v[158:161], v[32:35]
	v_mfma_f32_16x16x32_bf16 v[20:23], v[182:185], v[166:169], v[20:23]
	v_mfma_f32_16x16x32_bf16 v[16:19], v[190:193], v[166:169], v[16:19]
	s_setprio 2
	s_barrier
	v_mfma_f32_16x16x32_bf16 v[4:7], v[182:185], v[174:177], v[4:7]
	v_mfma_f32_16x16x32_bf16 v[0:3], v[190:193], v[174:177], v[0:3]
	s_setprio 0
	s_add_i32 s95, s95, 2
	s_add_u32 s8, s8, 0x100
	s_addc_u32 s9, s9, 0
	s_add_u32 s23, s23, 0x100
	s_addc_u32 s94, s94, 0
	s_cmp_gt_u32 s95, 13
	s_cbranch_scc0 .LBB0_274
; DI RowScales load_rowscales(const float* ss, int row0) {
;     RowScales t;
; #pragma unroll
;     for (int ai = 0; ai < 2; ++ai)
; #pragma unroll
;         for (int m = 0; m < 4; ++m) t.r[ai][m] = ss[row0 + ai * 128 + m * 16];
;     DI void operator()(AccRef acc, const Unit& u, int wr, int wc, int fr, int fq) const {
;         const int X = u.pn >> 2, h = u.pn & 3, isk = wc >> 1, i0 = (wc & 1) * 32 + 8 * fq;
;         bf16_t* dst = (X ? qkoB : qkoA) + h * 256 + isk * 128 + i0;
;         const float qs0 = isk ? 1.0f : 0.08838834764831845f;
;         const int row0 = u.pm * 256 + wr * 64 + fr;
;         const RowScales rsc = load_rowscales(ss, row0);
; #pragma unroll
;         for (int ai = 0; ai < 2; ++ai) {
;             f32x4 cs[4][2], sn[4][2];
;             if (X == 0) {
; #pragma unroll
;                 for (int m = 0; m < 4; ++m) {
;                     const int pos = (row0 + ai * 128 + m * 16) & (SEQ - 1);
;                     cs[m][0] = *(const f32x4*)(cosT + pos * 64 + i0); cs[m][1] = *(const f32x4*)(cosT + pos * 64 + i0 + 4);
;                     sn[m][0] = *(const f32x4*)(sinT + pos * 64 + i0); sn[m][1] = *(const f32x4*)(sinT + pos * 64 + i0 + 4);
;                 }
;             } else {
; #pragma unroll
;                 for (int m = 0; m < 4; ++m) { cs[m][0] = cs[m][1] = (f32x4){1.f, 1.f, 1.f, 1.f}; sn[m][0] = sn[m][1] = (f32x4){0.f, 0.f, 0.f, 0.f}; }
;             }
	v_lshl_add_u32 v102, s0, 8, v224
	v_ashrrev_i32_e32 v103, 31, v102
	v_lshl_add_u64 v[134:135], v[102:103], 2, s[60:61]
	global_load_dword v237, v[134:135], off
	global_load_dword v236, v[134:135], off offset:64
	global_load_dword v105, v[134:135], off offset:128
	global_load_dword v101, v[134:135], off offset:192
	global_load_dword v231, v[134:135], off offset:512
	global_load_dword v232, v[134:135], off offset:576
	global_load_dword v233, v[134:135], off offset:640
	global_load_dword v234, v[134:135], off offset:704
	s_cmp_lt_u32 s93, 4
	s_cselect_b64 s[0:1], -1, 0
	s_cmp_gt_u32 s93, 3
	v_lshlrev_b32_e32 v235, 6, v102
	v_mov_b32_e32 v100, 1.0
	v_mov_b32_e32 v104, 0
	v_mov_b32_e32 v134, 0
	v_mov_b32_e32 v135, 0
	v_mov_b32_e32 v136, 0
	v_mov_b32_e32 v137, 0
	v_mov_b32_e32 v142, 0
	v_mov_b32_e32 v143, 0
	v_mov_b32_e32 v144, 0
	v_mov_b32_e32 v145, 0
	v_mov_b32_e32 v146, 0
	v_mov_b32_e32 v147, 0
	v_mov_b32_e32 v148, 0
	v_mov_b32_e32 v149, 0
	v_mov_b32_e32 v154, 0
	v_mov_b32_e32 v155, 0
	v_mov_b32_e32 v156, 0
	v_mov_b32_e32 v157, 0
	v_mov_b32_e32 v162, 0
	v_mov_b32_e32 v163, 0
	v_mov_b32_e32 v164, 0
	v_mov_b32_e32 v165, 0
	v_mov_b32_e32 v174, 0
	v_mov_b32_e32 v175, 0
	v_mov_b32_e32 v176, 0
	v_mov_b32_e32 v177, 0
	v_mov_b32_e32 v182, 0
	v_mov_b32_e32 v183, 0
	v_mov_b32_e32 v184, 0
	v_mov_b32_e32 v185, 0
	v_mov_b32_e32 v194, 0
	v_mov_b32_e32 v195, 0
	v_mov_b32_e32 v196, 0
	v_mov_b32_e32 v197, 0
	v_mov_b32_e32 v138, 1.0
	v_mov_b32_e32 v139, 1.0
	v_mov_b32_e32 v140, 1.0
	v_mov_b32_e32 v141, 1.0
	v_mov_b32_e32 v190, 1.0
	v_mov_b32_e32 v191, 1.0
	v_mov_b32_e32 v192, 1.0
	v_mov_b32_e32 v193, 1.0
	v_mov_b32_e32 v186, 1.0
	v_mov_b32_e32 v187, 1.0
	v_mov_b32_e32 v188, 1.0
	v_mov_b32_e32 v189, 1.0
	v_mov_b32_e32 v178, 1.0
	v_mov_b32_e32 v179, 1.0
	v_mov_b32_e32 v180, 1.0
	v_mov_b32_e32 v181, 1.0
	v_mov_b32_e32 v170, 1.0
	v_mov_b32_e32 v171, 1.0
	v_mov_b32_e32 v172, 1.0
	v_mov_b32_e32 v173, 1.0
	v_mov_b32_e32 v166, 1.0
	v_mov_b32_e32 v167, 1.0
	v_mov_b32_e32 v168, 1.0
	v_mov_b32_e32 v169, 1.0
	v_mov_b32_e32 v158, 1.0
	v_mov_b32_e32 v159, 1.0
	v_mov_b32_e32 v160, 1.0
	v_mov_b32_e32 v161, 1.0
	v_mov_b32_e32 v150, 1.0
	v_mov_b32_e32 v151, 1.0
	v_mov_b32_e32 v152, 1.0
	v_mov_b32_e32 v153, 1.0
	s_cbranch_scc1 .LBB0_277
	v_lshlrev_b32_e32 v134, 2, v235
	v_and_b32_e32 v134, 0x1fcf00, v134
	v_mov_b32_e32 v135, v207
	v_lshl_add_u64 v[136:137], v[208:209], 0, v[134:135]
	global_load_dwordx4 v[190:193], v[136:137], off
	global_load_dwordx4 v[186:189], v[136:137], off offset:16
	v_lshl_add_u64 v[136:137], v[210:211], 0, v[134:135]
	global_load_dwordx4 v[182:185], v[136:137], off offset:16
	global_load_dwordx4 v[194:197], v[136:137], off
	v_or_b32_e32 v136, 0x1000, v134
	v_mov_b32_e32 v137, v207
	v_lshl_add_u64 v[138:139], v[208:209], 0, v[136:137]
	v_lshl_add_u64 v[136:137], v[210:211], 0, v[136:137]
	global_load_dwordx4 v[178:181], v[138:139], off
	global_load_dwordx4 v[170:173], v[138:139], off offset:16
	global_load_dwordx4 v[162:165], v[136:137], off offset:16
	global_load_dwordx4 v[174:177], v[136:137], off
	v_or_b32_e32 v136, 0x2000, v134
	v_mov_b32_e32 v137, v207
	v_lshl_add_u64 v[138:139], v[208:209], 0, v[136:137]
	v_lshl_add_u64 v[136:137], v[210:211], 0, v[136:137]
	v_or_b32_e32 v134, 0x3000, v134
	global_load_dwordx4 v[166:169], v[138:139], off
	global_load_dwordx4 v[158:161], v[138:139], off offset:16
	global_load_dwordx4 v[146:149], v[136:137], off offset:16
	global_load_dwordx4 v[154:157], v[136:137], off
	v_lshl_add_u64 v[136:137], v[208:209], 0, v[134:135]
	v_lshl_add_u64 v[142:143], v[210:211], 0, v[134:135]
	global_load_dwordx4 v[138:141], v[136:137], off offset:16
	global_load_dwordx4 v[150:153], v[136:137], off
	s_nop 0
	global_load_dwordx4 v[134:137], v[142:143], off offset:16
	s_nop 0
	global_load_dwordx4 v[142:145], v[142:143], off

; #define PG8_STAGE(bufoff, gbase, voff) do { _Pragma("unroll") for (int _i = 0; _i < 2; ++_i) \
;         __builtin_amdgcn_global_load_lds((const unsigned*)((const char*)(gbase) + (voff)[_i]), (LAS unsigned*)(lds + (bufoff) + ldsw + _i * 8192), 16, 0, 0); } while (0)
; #define PG8_LDA(dst, b, h) do { _Pragma("unroll") for (int m = 0; m < 4; ++m) _Pragma("unroll") for (int k = 0; k < 2; ++k) dst[m][k] = *(const LAS bf16x8*)(lds + PG8_SA(b, h) + aoff + m * 2048 + k * 1024); } while (0)
; #define PG8_LDB(dst, b, h) do { _Pragma("unroll") for (int n = 0; n < 2; ++n) _Pragma("unroll") for (int k = 0; k < 2; ++k) dst[n][k] = *(const LAS bf16x8*)(lds + PG8_SB(b, h) + boff + n * 2048 + k * 1024); } while (0)
; #define PG8_MMA(ai, bj, At, Bt) do { __builtin_amdgcn_s_setprio(1); _Pragma("unroll") for (int m = 0; m < 4; ++m) _Pragma("unroll") for (int n = 0; n < 2; ++n) _Pragma("unroll") for (int k = 0; k < 2; ++k) \
;         acc[ai][bj][m][n] = __builtin_amdgcn_mfma_f32_16x16x32_bf16(Bt[n][k], At[m][k], acc[ai][bj][m][n], 0, 0, 0); __builtin_amdgcn_s_setprio(0); } while (0)
; #define PG8_WAIT_L(n) asm volatile("s_waitcnt lgkmcnt(" #n ")" ::: "memory")
; #define PG8_BAR __builtin_amdgcn_s_barrier()
; #define PG8_SCHED __builtin_amdgcn_sched_barrier(0)
; #define PG8_WAIT_L(n) asm volatile("s_waitcnt lgkmcnt(" #n ")" ::: "memory")
; #define PG8_BAR __builtin_amdgcn_s_barrier()
; #define PG8_SCHED __builtin_amdgcn_sched_barrier(0)
; template <class Epi>
; DI void gemm_phase(LAS unsigned char* lds, const Gemm g, const StaticOrder S, const Epi E) {
;     ...
;             const bool last = (t == nt - 2);
;             const char* a1 = cA + (size_t)(t + 1) * kstep;
;             const char* a2 = last ? nA : cA + (size_t)(t + 2) * kstep; const char* b2 = last ? nB : cB + (size_t)(t + 2) * kstep;
;             const char* a3 = a2 + kstep; const char* b3 = b2 + kstep;
;             PG8_LDB(B0, 0, 0); PG8_SCHED; PG8_LDA(At, 0, 0); PG8_STAGE(PG8_SA(1, 1), a1 + hstep, voffA);
;             PG8_WAIT_L(8); PG8_BAR; PG8_WAIT_L(0); PG8_MMA(0, 0, At, B0); PG8_BAR; PG8_SCHED;
;             PG8_LDB(B1, 0, 1); PG8_STAGE(PG8_SB(0, 0), b2, voffB);
;             PG8_BAR; PG8_WAIT_L(0); PG8_MMA(0, 1, At, B1); PG8_BAR;
;             PG8_LDA(At, 0, 1); PG8_STAGE(PG8_SA(0, 0), a2, voffA);
;             PG8_BAR; PG8_WAIT_L(0); PG8_MMA(1, 0, At, B0); PG8_BAR; PG8_SCHED;
.LBB0_298:
	ds_read_b128 v[128:131], v168
	ds_read_b128 v[132:135], v168 offset:1024
	ds_read_b128 v[154:157], v168 offset:2048
	ds_read_b128 v[158:161], v168 offset:3072
	s_add_u32 s5, s8, 0xfffc0080
	s_addc_u32 s14, s9, -1
	s_cmp_eq_u32 s4, 12
	s_cselect_b32 s81, s6, s14
	s_cselect_b32 s80, s7, s5
	s_cselect_b32 s79, s21, vcc_hi
	s_cselect_b32 s78, s23, vcc_lo
	v_lshl_add_u64 v[162:163], s[8:9], 0, v[146:147]
	s_add_i32 m0, s58, 0xc000
	ds_read_b128 v[172:175], v169
	ds_read_b128 v[176:179], v169 offset:1024
	ds_read_b128 v[180:183], v169 offset:2048
	ds_read_b128 v[184:187], v169 offset:3072
	ds_read_b128 v[188:191], v169 offset:4096
	ds_read_b128 v[192:195], v169 offset:5120
	ds_read_b128 v[196:199], v169 offset:6144
	ds_read_b128 v[200:203], v169 offset:7168
	global_load_lds_dwordx4 v[162:163], off
	v_lshl_add_u64 v[162:163], s[8:9], 0, v[148:149]
	s_add_i32 m0, s58, 0xe000
	s_nop 0
	global_load_lds_dwordx4 v[162:163], off
	s_waitcnt lgkmcnt(8)
	s_barrier
	s_waitcnt lgkmcnt(0)
	s_setprio 1
	s_waitcnt lgkmcnt(0)
	v_mfma_f32_16x16x32_bf16 v[124:127], v[128:131], v[172:175], v[124:127]
	v_mfma_f32_16x16x32_bf16 v[120:123], v[154:157], v[172:175], v[120:123]
	v_mfma_f32_16x16x32_bf16 v[112:115], v[128:131], v[180:183], v[112:115]
	v_mfma_f32_16x16x32_bf16 v[104:107], v[154:157], v[180:183], v[104:107]
	v_mfma_f32_16x16x32_bf16 v[96:99], v[128:131], v[188:191], v[96:99]
	v_mfma_f32_16x16x32_bf16 v[88:91], v[154:157], v[188:191], v[88:91]
	v_mfma_f32_16x16x32_bf16 v[80:83], v[128:131], v[196:199], v[80:83]
	v_mfma_f32_16x16x32_bf16 v[72:75], v[154:157], v[196:199], v[72:75]
	v_mfma_f32_16x16x32_bf16 v[124:127], v[132:135], v[176:179], v[124:127]
	v_mfma_f32_16x16x32_bf16 v[120:123], v[158:161], v[176:179], v[120:123]
	v_mfma_f32_16x16x32_bf16 v[112:115], v[132:135], v[184:187], v[112:115]
	v_mfma_f32_16x16x32_bf16 v[104:107], v[158:161], v[184:187], v[104:107]
	v_mfma_f32_16x16x32_bf16 v[96:99], v[132:135], v[192:195], v[96:99]
	v_mfma_f32_16x16x32_bf16 v[88:91], v[158:161], v[192:195], v[88:91]
	s_setprio 2
	s_barrier
	v_mfma_f32_16x16x32_bf16 v[80:83], v[132:135], v[200:203], v[80:83]
	v_mfma_f32_16x16x32_bf16 v[72:75], v[158:161], v[200:203], v[72:75]
	s_setprio 0
	s_add_i32 s5, s94, s19
	v_lshl_add_u64 v[162:163], s[78:79], 0, v[138:139]
	s_mov_b32 m0, s5
	ds_read_b128 v[204:207], v170
	ds_read_b128 v[208:211], v170 offset:1024
	ds_read_b128 v[212:215], v170 offset:2048
	ds_read_b128 v[216:219], v170 offset:3072
	global_load_lds_dwordx4 v[162:163], off
	v_lshl_add_u64 v[220:221], s[78:79], 0, v[142:143]
	s_add_i32 m0, s5, 0x2000
	s_nop 0
	global_load_lds_dwordx4 v[220:221], off
	s_barrier
	s_waitcnt lgkmcnt(0)
	s_setprio 1
	s_waitcnt lgkmcnt(0)
	v_mfma_f32_16x16x32_bf16 v[116:119], v[204:207], v[172:175], v[116:119]
	v_mfma_f32_16x16x32_bf16 v[108:111], v[212:215], v[172:175], v[108:111]
	v_mfma_f32_16x16x32_bf16 v[100:103], v[204:207], v[180:183], v[100:103]
	v_mfma_f32_16x16x32_bf16 v[92:95], v[212:215], v[180:183], v[92:95]
	v_mfma_f32_16x16x32_bf16 v[84:87], v[204:207], v[188:191], v[84:87]
	v_mfma_f32_16x16x32_bf16 v[76:79], v[212:215], v[188:191], v[76:79]
	v_mfma_f32_16x16x32_bf16 v[68:71], v[204:207], v[196:199], v[68:71]
	v_mfma_f32_16x16x32_bf16 v[64:67], v[212:215], v[196:199], v[64:67]
	v_mfma_f32_16x16x32_bf16 v[116:119], v[208:211], v[176:179], v[116:119]
	v_mfma_f32_16x16x32_bf16 v[108:111], v[216:219], v[176:179], v[108:111]
	v_mfma_f32_16x16x32_bf16 v[100:103], v[208:211], v[184:187], v[100:103]
	v_mfma_f32_16x16x32_bf16 v[92:95], v[216:219], v[184:187], v[92:95]
	v_mfma_f32_16x16x32_bf16 v[84:87], v[208:211], v[192:195], v[84:87]
	v_mfma_f32_16x16x32_bf16 v[76:79], v[216:219], v[192:195], v[76:79]
	s_setprio 2
	s_barrier
	v_mfma_f32_16x16x32_bf16 v[68:71], v[208:211], v[200:203], v[68:71]
	v_mfma_f32_16x16x32_bf16 v[64:67], v[216:219], v[200:203], v[64:67]
	s_setprio 0
	s_mov_b32 m0, s58
	v_lshl_add_u64 v[224:225], s[80:81], 0, v[136:137]
	ds_read_b128 v[172:175], v169 offset:16384
	ds_read_b128 v[176:179], v169 offset:17408
	ds_read_b128 v[180:183], v169 offset:18432
	ds_read_b128 v[184:187], v169 offset:19456
	ds_read_b128 v[188:191], v169 offset:20480
	ds_read_b128 v[192:195], v169 offset:21504
	ds_read_b128 v[196:199], v169 offset:22528
	ds_read_b128 v[200:203], v169 offset:23552
	global_load_lds_dwordx4 v[224:225], off
	v_lshl_add_u64 v[226:227], s[80:81], 0, v[140:141]
	s_mov_b32 m0, s59
	s_nop 0
	global_load_lds_dwordx4 v[226:227], off
	s_barrier
	s_waitcnt lgkmcnt(0)
	s_setprio 1
	s_waitcnt lgkmcnt(0)
	v_mfma_f32_16x16x32_bf16 v[60:63], v[128:131], v[172:175], v[60:63]
	v_mfma_f32_16x16x32_bf16 v[56:59], v[154:157], v[172:175], v[56:59]
	v_mfma_f32_16x16x32_bf16 v[48:51], v[128:131], v[180:183], v[48:51]
	v_mfma_f32_16x16x32_bf16 v[40:43], v[154:157], v[180:183], v[40:43]
	v_mfma_f32_16x16x32_bf16 v[32:35], v[128:131], v[188:191], v[32:35]
	v_mfma_f32_16x16x32_bf16 v[24:27], v[154:157], v[188:191], v[24:27]
	v_mfma_f32_16x16x32_bf16 v[16:19], v[128:131], v[196:199], v[16:19]
	v_mfma_f32_16x16x32_bf16 v[8:11], v[154:157], v[196:199], v[8:11]
	v_mfma_f32_16x16x32_bf16 v[60:63], v[132:135], v[176:179], v[60:63]
	v_mfma_f32_16x16x32_bf16 v[56:59], v[158:161], v[176:179], v[56:59]
	v_mfma_f32_16x16x32_bf16 v[48:51], v[132:135], v[184:187], v[48:51]
	v_mfma_f32_16x16x32_bf16 v[40:43], v[158:161], v[184:187], v[40:43]
	v_mfma_f32_16x16x32_bf16 v[32:35], v[132:135], v[192:195], v[32:35]
	v_mfma_f32_16x16x32_bf16 v[24:27], v[158:161], v[192:195], v[24:27]
	s_setprio 2
	s_barrier
; #define PG8_STAGE(bufoff, gbase, voff) do { _Pragma("unroll") for (int _i = 0; _i < 2; ++_i) \
;         __builtin_amdgcn_global_load_lds((const unsigned*)((const char*)(gbase) + (voff)[_i]), (LAS unsigned*)(lds + (bufoff) + ldsw + _i * 8192), 16, 0, 0); } while (0)
; #define PG8_LDA(dst, b, h) do { _Pragma("unroll") for (int m = 0; m < 4; ++m) _Pragma("unroll") for (int k = 0; k < 2; ++k) dst[m][k] = *(const LAS bf16x8*)(lds + PG8_SA(b, h) + aoff + m * 2048 + k * 1024); } while (0)
; #define PG8_LDB(dst, b, h) do { _Pragma("unroll") for (int n = 0; n < 2; ++n) _Pragma("unroll") for (int k = 0; k < 2; ++k) dst[n][k] = *(const LAS bf16x8*)(lds + PG8_SB(b, h) + boff + n * 2048 + k * 1024); } while (0)
; #define PG8_MMA(ai, bj, At, Bt) do { __builtin_amdgcn_s_setprio(1); _Pragma("unroll") for (int m = 0; m < 4; ++m) _Pragma("unroll") for (int n = 0; n < 2; ++n) _Pragma("unroll") for (int k = 0; k < 2; ++k) \
;         acc[ai][bj][m][n] = __builtin_amdgcn_mfma_f32_16x16x32_bf16(Bt[n][k], At[m][k], acc[ai][bj][m][n], 0, 0, 0); __builtin_amdgcn_s_setprio(0); } while (0)
; #define PG8_WAIT_V(n) asm volatile("s_waitcnt vmcnt(" #n ")" ::: "memory")
; #define PG8_WAIT_L(n) asm volatile("s_waitcnt lgkmcnt(" #n ")" ::: "memory")
; #define PG8_BAR __builtin_amdgcn_s_barrier()
; #define PG8_SCHED __builtin_amdgcn_sched_barrier(0)
; #define PG8_STAGE(bufoff, gbase, voff) do { _Pragma("unroll") for (int _i = 0; _i < 2; ++_i) \
;         __builtin_amdgcn_global_load_lds((const unsigned*)((const char*)(gbase) + (voff)[_i]), (LAS unsigned*)(lds + (bufoff) + ldsw + _i * 8192), 16, 0, 0); } while (0)
; #define PG8_BAR __builtin_amdgcn_s_barrier()
; template <class Epi>
; DI void gemm_phase(LAS unsigned char* lds, const Gemm g, const StaticOrder S, const Epi E) {
;     ...
;             PG8_BAR; PG8_WAIT_L(0); PG8_MMA(1, 0, At, B0); PG8_BAR; PG8_SCHED;
;             PG8_STAGE(PG8_SB(0, 1), b2 + hstep, voffB);
;             PG8_WAIT_V(6); PG8_BAR; PG8_MMA(1, 1, At, B1); PG8_BAR;
;             PG8_LDB(B0, 1, 0); PG8_SCHED; PG8_LDA(At, 1, 0); PG8_STAGE(PG8_SA(0, 1), a2 + hstep, voffA);
;             PG8_WAIT_L(8); PG8_BAR; PG8_WAIT_L(0); PG8_MMA(0, 0, At, B0); PG8_BAR; PG8_SCHED;
;             PG8_LDB(B1, 1, 1); PG8_STAGE(PG8_SB(1, 0), b3, voffB);
;             PG8_BAR; PG8_WAIT_L(0); PG8_MMA(0, 1, At, B1); PG8_BAR;
;             PG8_LDA(At, 1, 1); PG8_STAGE(PG8_SA(1, 0), a3, voffA);
	v_mfma_f32_16x16x32_bf16 v[16:19], v[132:135], v[200:203], v[16:19]
	v_mfma_f32_16x16x32_bf16 v[8:11], v[158:161], v[200:203], v[8:11]
	s_setprio 0
	s_add_u32 s14, s78, 0x40000
	s_addc_u32 s15, s79, 0
	s_add_i32 s5, s95, s19
	v_lshl_add_u64 v[128:129], s[14:15], 0, v[138:139]
	s_mov_b32 m0, s5
	s_nop 0
	global_load_lds_dwordx4 v[128:129], off
	v_lshl_add_u64 v[128:129], s[14:15], 0, v[142:143]
	s_add_i32 m0, s5, 0x2000
	s_nop 0
	global_load_lds_dwordx4 v[128:129], off
	s_waitcnt vmcnt(6)
	s_barrier
	s_setprio 1
	v_mfma_f32_16x16x32_bf16 v[52:55], v[204:207], v[172:175], v[52:55]
	v_mfma_f32_16x16x32_bf16 v[44:47], v[212:215], v[172:175], v[44:47]
	v_mfma_f32_16x16x32_bf16 v[36:39], v[204:207], v[180:183], v[36:39]
	v_mfma_f32_16x16x32_bf16 v[28:31], v[212:215], v[180:183], v[28:31]
	v_mfma_f32_16x16x32_bf16 v[20:23], v[204:207], v[188:191], v[20:23]
	v_mfma_f32_16x16x32_bf16 v[12:15], v[212:215], v[188:191], v[12:15]
	v_mfma_f32_16x16x32_bf16 v[4:7], v[204:207], v[196:199], v[4:7]
	v_mfma_f32_16x16x32_bf16 v[0:3], v[212:215], v[196:199], v[0:3]
	v_mfma_f32_16x16x32_bf16 v[52:55], v[208:211], v[176:179], v[52:55]
	v_mfma_f32_16x16x32_bf16 v[44:47], v[216:219], v[176:179], v[44:47]
	v_mfma_f32_16x16x32_bf16 v[36:39], v[208:211], v[184:187], v[36:39]
	v_mfma_f32_16x16x32_bf16 v[28:31], v[216:219], v[184:187], v[28:31]
	v_mfma_f32_16x16x32_bf16 v[20:23], v[208:211], v[192:195], v[20:23]
	v_mfma_f32_16x16x32_bf16 v[12:15], v[216:219], v[192:195], v[12:15]
	s_setprio 2
	s_barrier
	v_mfma_f32_16x16x32_bf16 v[4:7], v[208:211], v[200:203], v[4:7]
	v_mfma_f32_16x16x32_bf16 v[0:3], v[216:219], v[200:203], v[0:3]
	s_setprio 0
	s_add_i32 s5, 0, 0x18000
	v_add_u32_e32 v158, s5, v165
	ds_read_b128 v[128:131], v158
	ds_read_b128 v[132:135], v158 offset:1024
	ds_read_b128 v[154:157], v158 offset:2048
	ds_read_b128 v[158:161], v158 offset:3072
	s_add_u32 s14, s80, 0x40000
	s_addc_u32 s15, s81, 0
	s_mov_b32 m0, s77
	v_lshl_add_u64 v[204:205], s[14:15], 0, v[136:137]
	ds_read_b128 v[172:175], v169 offset:32768
	ds_read_b128 v[176:179], v169 offset:33792
	ds_read_b128 v[180:183], v169 offset:34816
	ds_read_b128 v[184:187], v169 offset:35840
	ds_read_b128 v[188:191], v169 offset:36864
	ds_read_b128 v[192:195], v169 offset:37888
	ds_read_b128 v[196:199], v169 offset:38912
	ds_read_b128 v[200:203], v169 offset:39936
	global_load_lds_dwordx4 v[204:205], off
	v_lshl_add_u64 v[204:205], s[14:15], 0, v[140:141]
	s_mov_b32 m0, s82
	s_nop 0
	global_load_lds_dwordx4 v[204:205], off
	s_waitcnt lgkmcnt(8)
	s_barrier
	s_waitcnt lgkmcnt(0)
	s_setprio 1
	s_waitcnt lgkmcnt(0)
	v_mfma_f32_16x16x32_bf16 v[124:127], v[128:131], v[172:175], v[124:127]
	v_mfma_f32_16x16x32_bf16 v[120:123], v[154:157], v[172:175], v[120:123]
	v_mfma_f32_16x16x32_bf16 v[112:115], v[128:131], v[180:183], v[112:115]
	v_mfma_f32_16x16x32_bf16 v[104:107], v[154:157], v[180:183], v[104:107]
	v_mfma_f32_16x16x32_bf16 v[96:99], v[128:131], v[188:191], v[96:99]
	v_mfma_f32_16x16x32_bf16 v[88:91], v[154:157], v[188:191], v[88:91]
	v_mfma_f32_16x16x32_bf16 v[80:83], v[128:131], v[196:199], v[80:83]
	v_mfma_f32_16x16x32_bf16 v[72:75], v[154:157], v[196:199], v[72:75]
	v_mfma_f32_16x16x32_bf16 v[124:127], v[132:135], v[176:179], v[124:127]
	v_mfma_f32_16x16x32_bf16 v[120:123], v[158:161], v[176:179], v[120:123]
	v_mfma_f32_16x16x32_bf16 v[112:115], v[132:135], v[184:187], v[112:115]
	v_mfma_f32_16x16x32_bf16 v[104:107], v[158:161], v[184:187], v[104:107]
	v_mfma_f32_16x16x32_bf16 v[96:99], v[132:135], v[192:195], v[96:99]
	v_mfma_f32_16x16x32_bf16 v[88:91], v[158:161], v[192:195], v[88:91]
	s_setprio 2
	s_barrier
	v_mfma_f32_16x16x32_bf16 v[80:83], v[132:135], v[200:203], v[80:83]
	v_mfma_f32_16x16x32_bf16 v[72:75], v[158:161], v[200:203], v[72:75]
	s_setprio 0
	s_add_i32 s35, 0, 0x1c000
	s_add_i32 s5, s5, s19
	v_add_u32_e32 v171, s35, v165
	v_lshl_add_u64 v[162:163], v[162:163], 0, s[10:11]
	s_mov_b32 m0, s5
	ds_read_b128 v[204:207], v171
	ds_read_b128 v[208:211], v171 offset:1024
	ds_read_b128 v[212:215], v171 offset:2048
	ds_read_b128 v[216:219], v171 offset:3072
	global_load_lds_dwordx4 v[162:163], off
	v_lshl_add_u64 v[162:163], v[220:221], 0, s[10:11]
	s_add_i32 m0, s5, 0x2000
	s_nop 0
	global_load_lds_dwordx4 v[162:163], off
	s_barrier
	s_waitcnt lgkmcnt(0)
	s_setprio 1
	s_waitcnt lgkmcnt(0)
	v_mfma_f32_16x16x32_bf16 v[116:119], v[204:207], v[172:175], v[116:119]
	v_mfma_f32_16x16x32_bf16 v[108:111], v[212:215], v[172:175], v[108:111]
	v_mfma_f32_16x16x32_bf16 v[100:103], v[204:207], v[180:183], v[100:103]
	v_mfma_f32_16x16x32_bf16 v[92:95], v[212:215], v[180:183], v[92:95]
	v_mfma_f32_16x16x32_bf16 v[84:87], v[204:207], v[188:191], v[84:87]
	v_mfma_f32_16x16x32_bf16 v[76:79], v[212:215], v[188:191], v[76:79]
	v_mfma_f32_16x16x32_bf16 v[68:71], v[204:207], v[196:199], v[68:71]
	v_mfma_f32_16x16x32_bf16 v[64:67], v[212:215], v[196:199], v[64:67]
	v_mfma_f32_16x16x32_bf16 v[116:119], v[208:211], v[176:179], v[116:119]
	v_mfma_f32_16x16x32_bf16 v[108:111], v[216:219], v[176:179], v[108:111]
	v_mfma_f32_16x16x32_bf16 v[100:103], v[208:211], v[184:187], v[100:103]
	v_mfma_f32_16x16x32_bf16 v[92:95], v[216:219], v[184:187], v[92:95]
	v_mfma_f32_16x16x32_bf16 v[84:87], v[208:211], v[192:195], v[84:87]
	v_mfma_f32_16x16x32_bf16 v[76:79], v[216:219], v[192:195], v[76:79]
	s_setprio 2
	s_barrier
; #define PG8_STAGE(bufoff, gbase, voff) do { _Pragma("unroll") for (int _i = 0; _i < 2; ++_i) \
;         __builtin_amdgcn_global_load_lds((const unsigned*)((const char*)(gbase) + (voff)[_i]), (LAS unsigned*)(lds + (bufoff) + ldsw + _i * 8192), 16, 0, 0); } while (0)
; #define PG8_LDA(dst, b, h) do { _Pragma("unroll") for (int m = 0; m < 4; ++m) _Pragma("unroll") for (int k = 0; k < 2; ++k) dst[m][k] = *(const LAS bf16x8*)(lds + PG8_SA(b, h) + aoff + m * 2048 + k * 1024); } while (0)
; #define PG8_MMA(ai, bj, At, Bt) do { __builtin_amdgcn_s_setprio(1); _Pragma("unroll") for (int m = 0; m < 4; ++m) _Pragma("unroll") for (int n = 0; n < 2; ++n) _Pragma("unroll") for (int k = 0; k < 2; ++k) \
;         acc[ai][bj][m][n] = __builtin_amdgcn_mfma_f32_16x16x32_bf16(Bt[n][k], At[m][k], acc[ai][bj][m][n], 0, 0, 0); __builtin_amdgcn_s_setprio(0); } while (0)
; #define PG8_WAIT_V(n) asm volatile("s_waitcnt vmcnt(" #n ")" ::: "memory")
; #define PG8_WAIT_L(n) asm volatile("s_waitcnt lgkmcnt(" #n ")" ::: "memory")
; #define PG8_BAR __builtin_amdgcn_s_barrier()
; #define PG8_SCHED __builtin_amdgcn_sched_barrier(0)
; #define PG8_STAGE(bufoff, gbase, voff) do { _Pragma("unroll") for (int _i = 0; _i < 2; ++_i) \
;         __builtin_amdgcn_global_load_lds((const unsigned*)((const char*)(gbase) + (voff)[_i]), (LAS unsigned*)(lds + (bufoff) + ldsw + _i * 8192), 16, 0, 0); } while (0)
; #define PG8_LDA(dst, b, h) do { _Pragma("unroll") for (int m = 0; m < 4; ++m) _Pragma("unroll") for (int k = 0; k < 2; ++k) dst[m][k] = *(const LAS bf16x8*)(lds + PG8_SA(b, h) + aoff + m * 2048 + k * 1024); } while (0)
; template <class Epi>
; DI void gemm_phase(LAS unsigned char* lds, const Gemm g, const StaticOrder S, const Epi E) {
;     ...
;             PG8_BAR; PG8_WAIT_L(0); PG8_MMA(0, 1, At, B1); PG8_BAR;
;             PG8_LDA(At, 1, 1); PG8_STAGE(PG8_SA(1, 0), a3, voffA);
;             PG8_BAR; PG8_WAIT_L(0); PG8_MMA(1, 0, At, B0); PG8_BAR; PG8_SCHED;
;             PG8_STAGE(PG8_SB(1, 1), b3 + hstep, voffB);
;             PG8_WAIT_V(6); PG8_BAR; PG8_MMA(1, 1, At, B1); PG8_BAR;
;     DI void operator()(AccRef acc, const Unit& u, int wr, int wc, int fr, int fq) const {
;         f32x4 ts[2][2];
; #pragma unroll
;         for (int bj = 0; bj < 2; ++bj) { const int tok = u.pn * 256 + bj * 128 + wc * 32 + 8 * fq; ts[bj][0] = *(const f32x4*)(ss + tok); ts[bj][1] = *(const f32x4*)(ss + tok + 4); }
	v_mfma_f32_16x16x32_bf16 v[68:71], v[208:211], v[200:203], v[68:71]
	v_mfma_f32_16x16x32_bf16 v[64:67], v[216:219], v[200:203], v[64:67]
	s_setprio 0
	s_mov_b32 m0, s86
	v_lshl_add_u64 v[162:163], v[224:225], 0, s[10:11]
	ds_read_b128 v[172:175], v169 offset:49152
	ds_read_b128 v[176:179], v169 offset:50176
	ds_read_b128 v[180:183], v169 offset:51200
	ds_read_b128 v[184:187], v169 offset:52224
	ds_read_b128 v[188:191], v169 offset:53248
	ds_read_b128 v[192:195], v169 offset:54272
	ds_read_b128 v[196:199], v169 offset:55296
	ds_read_b128 v[200:203], v169 offset:56320
	global_load_lds_dwordx4 v[162:163], off
	v_lshl_add_u64 v[162:163], v[226:227], 0, s[10:11]
	s_mov_b32 m0, s87
	s_nop 0
	global_load_lds_dwordx4 v[162:163], off
	s_barrier
	s_waitcnt lgkmcnt(0)
	s_setprio 1
	s_waitcnt lgkmcnt(0)
	v_mfma_f32_16x16x32_bf16 v[60:63], v[128:131], v[172:175], v[60:63]
	v_mfma_f32_16x16x32_bf16 v[56:59], v[154:157], v[172:175], v[56:59]
	v_mfma_f32_16x16x32_bf16 v[48:51], v[128:131], v[180:183], v[48:51]
	v_mfma_f32_16x16x32_bf16 v[40:43], v[154:157], v[180:183], v[40:43]
	v_mfma_f32_16x16x32_bf16 v[32:35], v[128:131], v[188:191], v[32:35]
	v_mfma_f32_16x16x32_bf16 v[24:27], v[154:157], v[188:191], v[24:27]
	v_mfma_f32_16x16x32_bf16 v[16:19], v[128:131], v[196:199], v[16:19]
	v_mfma_f32_16x16x32_bf16 v[8:11], v[154:157], v[196:199], v[8:11]
	v_mfma_f32_16x16x32_bf16 v[60:63], v[132:135], v[176:179], v[60:63]
	v_mfma_f32_16x16x32_bf16 v[56:59], v[158:161], v[176:179], v[56:59]
	v_mfma_f32_16x16x32_bf16 v[48:51], v[132:135], v[184:187], v[48:51]
	v_mfma_f32_16x16x32_bf16 v[40:43], v[158:161], v[184:187], v[40:43]
	v_mfma_f32_16x16x32_bf16 v[32:35], v[132:135], v[192:195], v[32:35]
	v_mfma_f32_16x16x32_bf16 v[24:27], v[158:161], v[192:195], v[24:27]
	s_setprio 2
	s_barrier
	v_mfma_f32_16x16x32_bf16 v[16:19], v[132:135], v[200:203], v[16:19]
	v_mfma_f32_16x16x32_bf16 v[8:11], v[158:161], v[200:203], v[8:11]
	s_setprio 0
	s_add_u32 s14, s78, 0x40080
	s_addc_u32 s15, s79, 0
	s_add_i32 s5, s35, s19
	v_lshl_add_u64 v[128:129], s[14:15], 0, v[138:139]
	s_mov_b32 m0, s5
	s_nop 0
	global_load_lds_dwordx4 v[128:129], off
	v_lshl_add_u64 v[128:129], s[14:15], 0, v[142:143]
	s_add_i32 m0, s5, 0x2000
	s_nop 0
	global_load_lds_dwordx4 v[128:129], off
	s_waitcnt vmcnt(6)
	s_barrier
	s_setprio 1
	v_mfma_f32_16x16x32_bf16 v[52:55], v[204:207], v[172:175], v[52:55]
	v_mfma_f32_16x16x32_bf16 v[44:47], v[212:215], v[172:175], v[44:47]
	v_mfma_f32_16x16x32_bf16 v[36:39], v[204:207], v[180:183], v[36:39]
	v_mfma_f32_16x16x32_bf16 v[28:31], v[212:215], v[180:183], v[28:31]
	v_mfma_f32_16x16x32_bf16 v[20:23], v[204:207], v[188:191], v[20:23]
	v_mfma_f32_16x16x32_bf16 v[12:15], v[212:215], v[188:191], v[12:15]
	v_mfma_f32_16x16x32_bf16 v[4:7], v[204:207], v[196:199], v[4:7]
	v_mfma_f32_16x16x32_bf16 v[0:3], v[212:215], v[196:199], v[0:3]
	v_mfma_f32_16x16x32_bf16 v[52:55], v[208:211], v[176:179], v[52:55]
	v_mfma_f32_16x16x32_bf16 v[44:47], v[216:219], v[176:179], v[44:47]
	v_mfma_f32_16x16x32_bf16 v[36:39], v[208:211], v[184:187], v[36:39]
	v_mfma_f32_16x16x32_bf16 v[28:31], v[216:219], v[184:187], v[28:31]
	v_mfma_f32_16x16x32_bf16 v[20:23], v[208:211], v[192:195], v[20:23]
	v_mfma_f32_16x16x32_bf16 v[12:15], v[216:219], v[192:195], v[12:15]
	s_setprio 2
	s_barrier
	v_mfma_f32_16x16x32_bf16 v[4:7], v[208:211], v[200:203], v[4:7]
	v_mfma_f32_16x16x32_bf16 v[0:3], v[216:219], v[200:203], v[0:3]
	s_setprio 0
	s_add_i32 s4, s4, 2
	s_add_u32 s8, s8, 0x100
	s_addc_u32 s9, s9, 0
	s_add_u32 vcc_lo, vcc_lo, 0x100
	s_addc_u32 vcc_hi, vcc_hi, 0
	s_cmp_gt_u32 s4, 13
	s_cbranch_scc0 .LBB0_298
	s_lshl_b32 s4, s97, 8
	v_or_b32_e32 v128, s4, v166
	v_ashrrev_i32_e32 v129, 31, v128
	v_lshl_add_u64 v[132:133], v[128:129], 2, s[60:61]
	global_load_dwordx4 v[158:161], v[132:133], off offset:16
	global_load_dwordx4 v[154:157], v[132:133], off
	global_load_dwordx4 v[128:131], v[132:133], off offset:528
	s_nop 0
	global_load_dwordx4 v[132:135], v[132:133], off offset:512
	s_mov_b32 s6, 0x358637bd
	v_mov_b64_e32 v[162:163], s[6:7]
	s_lshl_b32 s6, s76, 8
	s_add_i32 s6, s6, s84
	s_lshr_b32 s5, s97, 3
	s_and_b32 s7, s5, 0x1fffc
	s_bfe_u32 s5, s6, 0x20008
	s_or_b32 s4, s4, s85
	s_or_b32 s5, s5, s7
	s_cmpk_lt_u32 s6, 0x400
	s_mov_b32 s97, s20
	s_mov_b32 s76, s22
	s_mov_b64 s[78:79], s[28:29]
	s_waitcnt vmcnt(0)
; DI unsigned pk_bf16(float lo, float hi) { f32x2 v = {lo, hi}; return __builtin_bit_cast(unsigned, __builtin_convertvector(v, bf16v2)); }
;     DI void operator()(AccRef acc, const Unit& u, int wr, int wc, int fr, int fq) const {
;         f32x4 ts[2][2];
; #pragma unroll
;         for (int bj = 0; bj < 2; ++bj) { const int tok = u.pn * 256 + bj * 128 + wc * 32 + 8 * fq; ts[bj][0] = *(const f32x4*)(ss + tok); ts[bj][1] = *(const f32x4*)(ss + tok + 4); }
; #pragma unroll
;         for (int bj = 0; bj < 2; ++bj)
; #pragma unroll
;             for (int n = 0; n < 2; ++n)
; #pragma unroll
;                 for (int e = 0; e < 4; ++e) ts[bj][n][e] = rsqrtf(ts[bj][n][e] * (1.0f / 1024.0f) + 1e-6f);
; #pragma unroll
;         for (int ai = 0; ai < 2; ++ai)
; #pragma unroll
;             for (int m = 0; m < 4; ++m) {
;                 const int R = u.pm * 256 + ai * 128 + wr * 64 + m * 16 + fr, X = R >> 10, hv = R & 1023;
; #pragma unroll
;                 for (int bj = 0; bj < 2; ++bj) {
;                     const int tok = u.pn * 256 + bj * 128 + wc * 32 + 8 * fq, b = tok >> 13, s = tok & (SEQ - 1);
;                     bf16_t* dst = (X ? vtB : vtA) + ((size_t)(((b * 4 + (hv >> 8)) * 128 + (s >> 6)) * 256 + (hv & 255))) * 64 + (s & 63);
;                     const f32x4 v0 = acc[ai][bj][m][0] * ts[bj][0], v1 = acc[ai][bj][m][1] * ts[bj][1];
;                     u32x4 w; w.x = pk_bf16(v0[0], v0[1]); w.y = pk_bf16(v0[2], v0[3]); w.z = pk_bf16(v1[0], v1[1]); w.w = pk_bf16(v1[2], v1[3]);
;                     *(u32x4*)dst = w;
	v_pk_fma_f32 v[158:159], v[158:159], s[16:17], v[162:163] op_sel_hi:[1,0,0]
	v_pk_fma_f32 v[154:155], v[154:155], s[16:17], v[162:163] op_sel_hi:[1,0,0]
	v_pk_fma_f32 v[156:157], v[156:157], s[16:17], v[162:163] op_sel_hi:[1,0,0]
	v_mul_f32_e32 v171, 0x4b800000, v154
	v_cmp_gt_f32_e64 s[8:9], s96, v154
	v_cmp_gt_f32_e32 vcc, s96, v155
	v_pk_fma_f32 v[160:161], v[160:161], s[16:17], v[162:163] op_sel_hi:[1,0,0]
	v_cndmask_b32_e64 v154, v154, v171, s[8:9]
	v_mul_f32_e32 v171, 0x4b800000, v155
	v_cndmask_b32_e32 v155, v155, v171, vcc
	v_rsq_f32_e32 v154, v154
	v_rsq_f32_e32 v155, v155
	v_mul_f32_e32 v171, 0x4b800000, v156
	v_pk_fma_f32 v[132:133], v[132:133], s[16:17], v[162:163] op_sel_hi:[1,0,0]
	v_pk_fma_f32 v[134:135], v[134:135], s[16:17], v[162:163] op_sel_hi:[1,0,0]
	v_pk_mul_f32 v[172:173], v[154:155], s[18:19] op_sel_hi:[1,0]
	v_pk_fma_f32 v[128:129], v[128:129], s[16:17], v[162:163] op_sel_hi:[1,0,0]
	v_cndmask_b32_e64 v154, v154, v172, s[8:9]
	v_cmp_gt_f32_e64 s[8:9], s96, v156
	v_cndmask_b32_e32 v155, v155, v173, vcc
	v_cmp_gt_f32_e32 vcc, s96, v157
	v_cndmask_b32_e64 v156, v156, v171, s[8:9]
	v_mul_f32_e32 v171, 0x4b800000, v157
	v_cndmask_b32_e32 v157, v157, v171, vcc
	v_rsq_f32_e32 v156, v156
	v_rsq_f32_e32 v157, v157
	v_mul_f32_e32 v171, 0x4b800000, v158
	v_pk_fma_f32 v[130:131], v[130:131], s[16:17], v[162:163] op_sel_hi:[1,0,0]
	v_pk_mul_f32 v[124:125], v[124:125], v[154:155]
	v_pk_mul_f32 v[172:173], v[156:157], s[18:19] op_sel_hi:[1,0]
	v_mul_f32_e32 v162, 0x4b800000, v130
	v_cndmask_b32_e64 v156, v156, v172, s[8:9]
	v_cmp_gt_f32_e64 s[8:9], s96, v158
	v_cndmask_b32_e32 v157, v157, v173, vcc
	v_cmp_gt_f32_e32 vcc, s96, v159
	v_cndmask_b32_e64 v158, v158, v171, s[8:9]
	v_mul_f32_e32 v171, 0x4b800000, v159
	v_cndmask_b32_e32 v159, v159, v171, vcc
	v_rsq_f32_e32 v158, v158
	v_rsq_f32_e32 v159, v159
	v_mul_f32_e32 v171, 0x4b800000, v160
	v_pk_mul_f32 v[126:127], v[126:127], v[156:157]
	v_pk_mul_f32 v[112:113], v[112:113], v[154:155]
	v_pk_mul_f32 v[172:173], v[158:159], s[18:19] op_sel_hi:[1,0]
	v_pk_mul_f32 v[96:97], v[96:97], v[154:155]
	v_cndmask_b32_e64 v158, v158, v172, s[8:9]
	v_cmp_gt_f32_e64 s[8:9], s96, v160
	v_cndmask_b32_e32 v159, v159, v173, vcc
	v_cmp_gt_f32_e32 vcc, s96, v161
	v_cndmask_b32_e64 v160, v160, v171, s[8:9]
	v_mul_f32_e32 v171, 0x4b800000, v161
	v_cndmask_b32_e32 v161, v161, v171, vcc
	v_rsq_f32_e32 v160, v160
	v_rsq_f32_e32 v161, v161
	v_mul_f32_e32 v171, 0x4b800000, v132
	v_pk_mul_f32 v[80:81], v[80:81], v[154:155]
	v_pk_mul_f32 v[62:63], v[62:63], v[156:157]
	v_pk_mul_f32 v[172:173], v[160:161], s[18:19] op_sel_hi:[1,0]
	v_pk_mul_f32 v[60:61], v[60:61], v[154:155]
	v_cndmask_b32_e64 v160, v160, v172, s[8:9]
	v_cmp_gt_f32_e64 s[8:9], s96, v132
	v_cndmask_b32_e32 v161, v161, v173, vcc
	v_cmp_gt_f32_e32 vcc, s96, v133
	v_cndmask_b32_e64 v132, v132, v171, s[8:9]
	v_mul_f32_e32 v171, 0x4b800000, v133
	v_cndmask_b32_e32 v133, v133, v171, vcc
	v_rsq_f32_e32 v132, v132
	v_rsq_f32_e32 v133, v133
	v_mul_f32_e32 v171, 0x4b800000, v134
	v_pk_mul_f32 v[48:49], v[48:49], v[154:155]
	v_pk_mul_f32 v[32:33], v[32:33], v[154:155]
	v_pk_mul_f32 v[172:173], v[132:133], s[18:19] op_sel_hi:[1,0]
	v_pk_mul_f32 v[16:17], v[16:17], v[154:155]
	v_cndmask_b32_e64 v132, v132, v172, s[8:9]
	v_cmp_gt_f32_e64 s[8:9], s96, v134
	v_cndmask_b32_e32 v133, v133, v173, vcc
	v_cmp_gt_f32_e32 vcc, s96, v135
	v_cndmask_b32_e64 v134, v134, v171, s[8:9]
	v_mul_f32_e32 v171, 0x4b800000, v135
	v_cndmask_b32_e32 v135, v135, v171, vcc
	v_rsq_f32_e32 v134, v134
	v_rsq_f32_e32 v135, v135
	v_mul_f32_e32 v171, 0x4b800000, v128
	v_pk_mul_f32 v[116:117], v[116:117], v[132:133]
	v_pk_mul_f32 v[100:101], v[100:101], v[132:133]
	v_pk_mul_f32 v[172:173], v[134:135], s[18:19] op_sel_hi:[1,0]
	v_pk_mul_f32 v[84:85], v[84:85], v[132:133]
	v_cndmask_b32_e64 v134, v134, v172, s[8:9]
	v_cmp_gt_f32_e64 s[8:9], s96, v128
	v_cndmask_b32_e32 v135, v135, v173, vcc
	v_cmp_gt_f32_e32 vcc, s96, v129
	v_cndmask_b32_e64 v128, v128, v171, s[8:9]
	v_mul_f32_e32 v171, 0x4b800000, v129
	v_cndmask_b32_e32 v129, v129, v171, vcc
	v_rsq_f32_e32 v128, v128
	v_rsq_f32_e32 v129, v129
	v_lshl_or_b32 v171, s5, 15, v167
	v_pk_mul_f32 v[118:119], v[118:119], v[134:135]
	v_pk_mul_f32 v[102:103], v[102:103], v[134:135]
	v_pk_mul_f32 v[172:173], v[128:129], s[18:19] op_sel_hi:[1,0]
	v_pk_mul_f32 v[86:87], v[86:87], v[134:135]
	v_cndmask_b32_e64 v128, v128, v172, s[8:9]
	v_cmp_gt_f32_e64 s[8:9], s96, v130
	v_cndmask_b32_e32 v129, v129, v173, vcc
	v_cmp_gt_f32_e32 vcc, s96, v131
	v_cndmask_b32_e64 v130, v130, v162, s[8:9]
	v_mul_f32_e32 v162, 0x4b800000, v131
	v_cndmask_b32_e32 v131, v131, v162, vcc
	v_rsq_f32_e32 v130, v130
	v_rsq_f32_e32 v131, v131
	v_pk_mul_f32 v[172:173], v[122:123], v[160:161]
	v_pk_mul_f32 v[122:123], v[120:121], v[158:159]
	v_cvt_pk_bf16_f32 v120, v124, v125
	v_pk_mul_f32 v[162:163], v[130:131], s[18:19] op_sel_hi:[1,0]
	v_cvt_pk_bf16_f32 v121, v126, v127
	v_cndmask_b32_e64 v130, v130, v162, s[8:9]
	s_cselect_b32 s9, s53, s91
	s_cselect_b32 s8, s52, s90
	s_lshl_b32 s4, s4, 2
	s_and_b32 s4, s4, 0x7d00
	v_or_b32_e32 v162, s4, v171
	v_cndmask_b32_e32 v131, v131, v163, vcc
	v_ashrrev_i32_e32 v163, 31, v162
	v_lshlrev_b64 v[162:163], 7, v[162:163]
	v_lshl_add_u64 v[162:163], s[8:9], 0, v[162:163]
	v_lshl_add_u64 v[162:163], v[162:163], 0, v[144:145]
	v_cvt_pk_bf16_f32 v122, v122, v123
	v_cvt_pk_bf16_f32 v123, v172, v173
	s_or_b32 s5, s4, 0x200
	global_store_dwordx4 v[162:163], v[120:123], off
	s_addk_i32 s6, 0x80
	v_pk_mul_f32 v[70:71], v[70:71], v[134:135]
	v_or_b32_e32 v120, s5, v171
	v_ashrrev_i32_e32 v121, 31, v120
	v_lshlrev_b64 v[120:121], 7, v[120:121]
; DI unsigned pk_bf16(float lo, float hi) { f32x2 v = {lo, hi}; return __builtin_bit_cast(unsigned, __builtin_convertvector(v, bf16v2)); }
;     DI void operator()(AccRef acc, const Unit& u, int wr, int wc, int fr, int fq) const {
;     ...
;             for (int m = 0; m < 4; ++m) {
;                 const int R = u.pm * 256 + ai * 128 + wr * 64 + m * 16 + fr, X = R >> 10, hv = R & 1023;
; #pragma unroll
;                 for (int bj = 0; bj < 2; ++bj) {
;                     const int tok = u.pn * 256 + bj * 128 + wc * 32 + 8 * fq, b = tok >> 13, s = tok & (SEQ - 1);
;                     bf16_t* dst = (X ? vtB : vtA) + ((size_t)(((b * 4 + (hv >> 8)) * 128 + (s >> 6)) * 256 + (hv & 255))) * 64 + (s & 63);
;                     const f32x4 v0 = acc[ai][bj][m][0] * ts[bj][0], v1 = acc[ai][bj][m][1] * ts[bj][1];
;                     u32x4 w; w.x = pk_bf16(v0[0], v0[1]); w.y = pk_bf16(v0[2], v0[3]); w.z = pk_bf16(v1[0], v1[1]); w.w = pk_bf16(v1[2], v1[3]);
;                     *(u32x4*)dst = w;
	v_lshl_add_u64 v[120:121], s[8:9], 0, v[120:121]
	v_pk_mul_f32 v[122:123], v[110:111], v[130:131]
	v_pk_mul_f32 v[110:111], v[108:109], v[128:129]
	v_lshl_add_u64 v[120:121], v[120:121], 0, v[144:145]
	v_cvt_pk_bf16_f32 v108, v116, v117
	v_cvt_pk_bf16_f32 v109, v118, v119
	v_cvt_pk_bf16_f32 v110, v110, v111
	v_cvt_pk_bf16_f32 v111, v122, v123
	v_or_b32_e32 v116, 16, v171
	global_store_dwordx4 v[120:121], v[108:111], off
	v_pk_mul_f32 v[68:69], v[68:69], v[132:133]
	v_pk_mul_f32 v[54:55], v[54:55], v[134:135]
	v_or_b32_e32 v108, s4, v116
	v_ashrrev_i32_e32 v109, 31, v108
	v_lshlrev_b64 v[108:109], 7, v[108:109]
	v_lshl_add_u64 v[108:109], s[8:9], 0, v[108:109]
	v_pk_mul_f32 v[110:111], v[114:115], v[156:157]
	v_pk_mul_f32 v[114:115], v[106:107], v[160:161]
	v_pk_mul_f32 v[106:107], v[104:105], v[158:159]
	v_lshl_add_u64 v[108:109], v[108:109], 0, v[144:145]
	v_cvt_pk_bf16_f32 v104, v112, v113
	v_cvt_pk_bf16_f32 v105, v110, v111
	v_cvt_pk_bf16_f32 v106, v106, v107
	v_cvt_pk_bf16_f32 v107, v114, v115
	global_store_dwordx4 v[108:109], v[104:107], off
	v_pk_mul_f32 v[52:53], v[52:53], v[132:133]
	v_pk_mul_f32 v[38:39], v[38:39], v[134:135]
	v_or_b32_e32 v104, s5, v116
	v_ashrrev_i32_e32 v105, 31, v104
	v_lshlrev_b64 v[104:105], 7, v[104:105]
	v_lshl_add_u64 v[104:105], s[8:9], 0, v[104:105]
	v_pk_mul_f32 v[106:107], v[94:95], v[130:131]
	v_pk_mul_f32 v[94:95], v[92:93], v[128:129]
	v_lshl_add_u64 v[104:105], v[104:105], 0, v[144:145]
	v_cvt_pk_bf16_f32 v92, v100, v101
	v_cvt_pk_bf16_f32 v93, v102, v103
	v_cvt_pk_bf16_f32 v94, v94, v95
	v_cvt_pk_bf16_f32 v95, v106, v107
	v_or_b32_e32 v100, 32, v171
	global_store_dwordx4 v[104:105], v[92:95], off
	v_pk_mul_f32 v[36:37], v[36:37], v[132:133]
	v_pk_mul_f32 v[22:23], v[22:23], v[134:135]
	v_or_b32_e32 v92, s4, v100
	v_ashrrev_i32_e32 v93, 31, v92
	v_lshlrev_b64 v[92:93], 7, v[92:93]
	v_lshl_add_u64 v[92:93], s[8:9], 0, v[92:93]
	v_pk_mul_f32 v[94:95], v[98:99], v[156:157]
	v_pk_mul_f32 v[98:99], v[90:91], v[160:161]
	v_pk_mul_f32 v[90:91], v[88:89], v[158:159]
	v_lshl_add_u64 v[92:93], v[92:93], 0, v[144:145]
	v_cvt_pk_bf16_f32 v88, v96, v97
	v_cvt_pk_bf16_f32 v89, v94, v95
	v_cvt_pk_bf16_f32 v90, v90, v91
	v_cvt_pk_bf16_f32 v91, v98, v99
	global_store_dwordx4 v[92:93], v[88:91], off
	v_pk_mul_f32 v[20:21], v[20:21], v[132:133]
	v_pk_mul_f32 v[6:7], v[6:7], v[134:135]
	v_or_b32_e32 v88, s5, v100
	v_ashrrev_i32_e32 v89, 31, v88
	v_lshlrev_b64 v[88:89], 7, v[88:89]
	v_lshl_add_u64 v[88:89], s[8:9], 0, v[88:89]
	v_pk_mul_f32 v[90:91], v[78:79], v[130:131]
	v_pk_mul_f32 v[78:79], v[76:77], v[128:129]
	v_lshl_add_u64 v[88:89], v[88:89], 0, v[144:145]
	v_cvt_pk_bf16_f32 v76, v84, v85
	v_cvt_pk_bf16_f32 v77, v86, v87
	v_cvt_pk_bf16_f32 v78, v78, v79
	v_cvt_pk_bf16_f32 v79, v90, v91
	v_or_b32_e32 v84, 48, v171
	global_store_dwordx4 v[88:89], v[76:79], off
	v_pk_mul_f32 v[4:5], v[4:5], v[132:133]
	s_nop 0
	v_or_b32_e32 v76, s4, v84
	v_ashrrev_i32_e32 v77, 31, v76
	v_lshlrev_b64 v[76:77], 7, v[76:77]
	v_lshl_add_u64 v[76:77], s[8:9], 0, v[76:77]
	v_pk_mul_f32 v[78:79], v[82:83], v[156:157]
	v_pk_mul_f32 v[82:83], v[74:75], v[160:161]
	v_pk_mul_f32 v[74:75], v[72:73], v[158:159]
	v_lshl_add_u64 v[76:77], v[76:77], 0, v[144:145]
	v_cvt_pk_bf16_f32 v72, v80, v81
	v_cvt_pk_bf16_f32 v73, v78, v79
	v_cvt_pk_bf16_f32 v74, v74, v75
	v_cvt_pk_bf16_f32 v75, v82, v83
	global_store_dwordx4 v[76:77], v[72:75], off
	s_nop 1
	v_or_b32_e32 v72, s5, v84
	v_ashrrev_i32_e32 v73, 31, v72
	v_lshlrev_b64 v[72:73], 7, v[72:73]
	v_lshl_add_u64 v[72:73], s[8:9], 0, v[72:73]
	s_bfe_u32 s8, s6, 0x20008
	s_or_b32 s7, s8, s7
	s_lshl_b32 s7, s7, 15
	s_and_b32 s8, s6, 0xc0
	v_pk_mul_f32 v[74:75], v[66:67], v[130:131]
	v_pk_mul_f32 v[66:67], v[64:65], v[128:129]
	s_or_b32 s7, s7, s8
	v_lshl_add_u64 v[72:73], v[72:73], 0, v[144:145]
	v_cvt_pk_bf16_f32 v64, v68, v69
	v_cvt_pk_bf16_f32 v65, v70, v71
	v_cvt_pk_bf16_f32 v66, v66, v67
	v_cvt_pk_bf16_f32 v67, v74, v75
	v_or_b32_e32 v68, s7, v164
	global_store_dwordx4 v[72:73], v[64:67], off
	s_cmpk_lt_u32 s6, 0x400
	s_cselect_b32 s9, s53, s91
	v_or_b32_e32 v64, s4, v68
; DI unsigned pk_bf16(float lo, float hi) { f32x2 v = {lo, hi}; return __builtin_bit_cast(unsigned, __builtin_convertvector(v, bf16v2)); }
; #define PG8_WAIT_V(n) asm volatile("s_waitcnt vmcnt(" #n ")" ::: "memory")
; #define PG8_BAR __builtin_amdgcn_s_barrier()
; #define PG8_WAIT_V(n) asm volatile("s_waitcnt vmcnt(" #n ")" ::: "memory")
; #define PG8_BAR __builtin_amdgcn_s_barrier()
; template <class Epi>
; DI void gemm_phase(LAS unsigned char* lds, const Gemm g, const StaticOrder S, const Epi E) {
;     ...
;     PG8_WAIT_V(0);
;     if (wr == 0) PG8_BAR;
;     PG8_BAR;
;     DI void operator()(AccRef acc, const Unit& u, int wr, int wc, int fr, int fq) const {
;     ...
; #pragma unroll
;         for (int ai = 0; ai < 2; ++ai)
; #pragma unroll
;             for (int m = 0; m < 4; ++m) {
;                 const int R = u.pm * 256 + ai * 128 + wr * 64 + m * 16 + fr, X = R >> 10, hv = R & 1023;
; #pragma unroll
;                 for (int bj = 0; bj < 2; ++bj) {
;                     const int tok = u.pn * 256 + bj * 128 + wc * 32 + 8 * fq, b = tok >> 13, s = tok & (SEQ - 1);
;                     bf16_t* dst = (X ? vtB : vtA) + ((size_t)(((b * 4 + (hv >> 8)) * 128 + (s >> 6)) * 256 + (hv & 255))) * 64 + (s & 63);
;                     const f32x4 v0 = acc[ai][bj][m][0] * ts[bj][0], v1 = acc[ai][bj][m][1] * ts[bj][1];
;                     u32x4 w; w.x = pk_bf16(v0[0], v0[1]); w.y = pk_bf16(v0[2], v0[3]); w.z = pk_bf16(v1[0], v1[1]); w.w = pk_bf16(v1[2], v1[3]);
;                     *(u32x4*)dst = w;
;                 }
;             }
	v_ashrrev_i32_e32 v65, 31, v64
	s_cselect_b32 s8, s52, s90
	v_lshlrev_b64 v[64:65], 7, v[64:65]
	v_lshl_add_u64 v[64:65], s[8:9], 0, v[64:65]
	v_pk_mul_f32 v[66:67], v[58:59], v[160:161]
	v_pk_mul_f32 v[58:59], v[56:57], v[158:159]
	v_lshl_add_u64 v[64:65], v[64:65], 0, v[144:145]
	v_cvt_pk_bf16_f32 v56, v60, v61
	v_cvt_pk_bf16_f32 v57, v62, v63
	v_cvt_pk_bf16_f32 v58, v58, v59
	v_cvt_pk_bf16_f32 v59, v66, v67
	global_store_dwordx4 v[64:65], v[56:59], off
	s_and_b64 vcc, exec, s[0:1]
	s_nop 0
	v_or_b32_e32 v56, s5, v68
	v_ashrrev_i32_e32 v57, 31, v56
	v_lshlrev_b64 v[56:57], 7, v[56:57]
	v_lshl_add_u64 v[56:57], s[8:9], 0, v[56:57]
	v_pk_mul_f32 v[58:59], v[46:47], v[130:131]
	v_pk_mul_f32 v[46:47], v[44:45], v[128:129]
	v_lshl_add_u64 v[56:57], v[56:57], 0, v[144:145]
	v_cvt_pk_bf16_f32 v44, v52, v53
	v_cvt_pk_bf16_f32 v45, v54, v55
	v_cvt_pk_bf16_f32 v46, v46, v47
	v_cvt_pk_bf16_f32 v47, v58, v59
	v_or_b32_e32 v52, 16, v68
	global_store_dwordx4 v[56:57], v[44:47], off
	s_nop 1
	v_or_b32_e32 v44, s4, v52
	v_ashrrev_i32_e32 v45, 31, v44
	v_lshlrev_b64 v[44:45], 7, v[44:45]
	v_lshl_add_u64 v[44:45], s[8:9], 0, v[44:45]
	v_pk_mul_f32 v[46:47], v[50:51], v[156:157]
	v_pk_mul_f32 v[50:51], v[42:43], v[160:161]
	v_pk_mul_f32 v[42:43], v[40:41], v[158:159]
	v_lshl_add_u64 v[44:45], v[44:45], 0, v[144:145]
	v_cvt_pk_bf16_f32 v40, v48, v49
	v_cvt_pk_bf16_f32 v41, v46, v47
	v_cvt_pk_bf16_f32 v42, v42, v43
	v_cvt_pk_bf16_f32 v43, v50, v51
	global_store_dwordx4 v[44:45], v[40:43], off
	s_nop 1
	v_or_b32_e32 v40, s5, v52
	v_ashrrev_i32_e32 v41, 31, v40
	v_lshlrev_b64 v[40:41], 7, v[40:41]
	v_lshl_add_u64 v[40:41], s[8:9], 0, v[40:41]
	v_pk_mul_f32 v[42:43], v[30:31], v[130:131]
	v_pk_mul_f32 v[30:31], v[28:29], v[128:129]
	v_lshl_add_u64 v[40:41], v[40:41], 0, v[144:145]
	v_cvt_pk_bf16_f32 v28, v36, v37
	v_cvt_pk_bf16_f32 v29, v38, v39
	v_cvt_pk_bf16_f32 v30, v30, v31
	v_cvt_pk_bf16_f32 v31, v42, v43
	v_or_b32_e32 v36, 32, v68
	global_store_dwordx4 v[40:41], v[28:31], off
	s_nop 1
	v_or_b32_e32 v28, s4, v36
	v_ashrrev_i32_e32 v29, 31, v28
	v_lshlrev_b64 v[28:29], 7, v[28:29]
	v_lshl_add_u64 v[28:29], s[8:9], 0, v[28:29]
	v_pk_mul_f32 v[30:31], v[34:35], v[156:157]
	v_pk_mul_f32 v[34:35], v[26:27], v[160:161]
	v_pk_mul_f32 v[26:27], v[24:25], v[158:159]
	v_lshl_add_u64 v[28:29], v[28:29], 0, v[144:145]
	v_cvt_pk_bf16_f32 v24, v32, v33
	v_cvt_pk_bf16_f32 v25, v30, v31
	v_cvt_pk_bf16_f32 v26, v26, v27
	v_cvt_pk_bf16_f32 v27, v34, v35
	global_store_dwordx4 v[28:29], v[24:27], off
	s_nop 1
	v_or_b32_e32 v24, s5, v36
	v_ashrrev_i32_e32 v25, 31, v24
	v_lshlrev_b64 v[24:25], 7, v[24:25]
	v_lshl_add_u64 v[24:25], s[8:9], 0, v[24:25]
	v_pk_mul_f32 v[26:27], v[14:15], v[130:131]
	v_pk_mul_f32 v[14:15], v[12:13], v[128:129]
	v_lshl_add_u64 v[24:25], v[24:25], 0, v[144:145]
	v_cvt_pk_bf16_f32 v12, v20, v21
	v_cvt_pk_bf16_f32 v13, v22, v23
	v_cvt_pk_bf16_f32 v14, v14, v15
	v_cvt_pk_bf16_f32 v15, v26, v27
	v_or_b32_e32 v20, 48, v68
	global_store_dwordx4 v[24:25], v[12:15], off
	s_nop 1
	v_or_b32_e32 v12, s4, v20
	v_ashrrev_i32_e32 v13, 31, v12
	v_lshlrev_b64 v[12:13], 7, v[12:13]
	v_lshl_add_u64 v[12:13], s[8:9], 0, v[12:13]
	v_pk_mul_f32 v[14:15], v[18:19], v[156:157]
	v_pk_mul_f32 v[18:19], v[10:11], v[160:161]
	v_pk_mul_f32 v[10:11], v[8:9], v[158:159]
	v_lshl_add_u64 v[12:13], v[12:13], 0, v[144:145]
	v_cvt_pk_bf16_f32 v8, v16, v17
	v_cvt_pk_bf16_f32 v9, v14, v15
	v_cvt_pk_bf16_f32 v10, v10, v11
	v_cvt_pk_bf16_f32 v11, v18, v19
	global_store_dwordx4 v[12:13], v[8:11], off
	s_nop 1
	v_or_b32_e32 v8, s5, v20
	v_ashrrev_i32_e32 v9, 31, v8
	v_lshlrev_b64 v[8:9], 7, v[8:9]
	v_lshl_add_u64 v[8:9], s[8:9], 0, v[8:9]
	v_pk_mul_f32 v[10:11], v[2:3], v[130:131]
	v_pk_mul_f32 v[2:3], v[0:1], v[128:129]
	v_lshl_add_u64 v[8:9], v[8:9], 0, v[144:145]
	v_cvt_pk_bf16_f32 v0, v4, v5
	v_cvt_pk_bf16_f32 v1, v6, v7
	v_cvt_pk_bf16_f32 v2, v2, v3
	v_cvt_pk_bf16_f32 v3, v10, v11
	s_mov_b64 s[8:9], s[24:25]
	global_store_dwordx4 v[8:9], v[0:3], off
	s_cbranch_vccz .LBB0_291
	s_waitcnt vmcnt(0)
	s_cmpk_gt_u32 s17, 0xff
	s_cbranch_scc1 .LBB0_302
	s_barrier

; #define PG8_STAGE(bufoff, gbase, voff) do { _Pragma("unroll") for (int _i = 0; _i < 2; ++_i) \
;         __builtin_amdgcn_global_load_lds((const unsigned*)((const char*)(gbase) + (voff)[_i]), (LAS unsigned*)(lds + (bufoff) + ldsw + _i * 8192), 16, 0, 0); } while (0)
; #define PG8_LDA(dst, b, h) do { _Pragma("unroll") for (int m = 0; m < 4; ++m) _Pragma("unroll") for (int k = 0; k < 2; ++k) dst[m][k] = *(const LAS bf16x8*)(lds + PG8_SA(b, h) + aoff + m * 2048 + k * 1024); } while (0)
; #define PG8_LDB(dst, b, h) do { _Pragma("unroll") for (int n = 0; n < 2; ++n) _Pragma("unroll") for (int k = 0; k < 2; ++k) dst[n][k] = *(const LAS bf16x8*)(lds + PG8_SB(b, h) + boff + n * 2048 + k * 1024); } while (0)
; #define PG8_MMA(ai, bj, At, Bt) do { __builtin_amdgcn_s_setprio(1); _Pragma("unroll") for (int m = 0; m < 4; ++m) _Pragma("unroll") for (int n = 0; n < 2; ++n) _Pragma("unroll") for (int k = 0; k < 2; ++k) \
;         acc[ai][bj][m][n] = __builtin_amdgcn_mfma_f32_16x16x32_bf16(Bt[n][k], At[m][k], acc[ai][bj][m][n], 0, 0, 0); __builtin_amdgcn_s_setprio(0); } while (0)
; #define PG8_WAIT_L(n) asm volatile("s_waitcnt lgkmcnt(" #n ")" ::: "memory")
; #define PG8_BAR __builtin_amdgcn_s_barrier()
; #define PG8_SCHED __builtin_amdgcn_sched_barrier(0)
; #define PG8_STAGE(bufoff, gbase, voff) do { _Pragma("unroll") for (int _i = 0; _i < 2; ++_i) \
;         __builtin_amdgcn_global_load_lds((const unsigned*)((const char*)(gbase) + (voff)[_i]), (LAS unsigned*)(lds + (bufoff) + ldsw + _i * 8192), 16, 0, 0); } while (0)
; #define PG8_WAIT_L(n) asm volatile("s_waitcnt lgkmcnt(" #n ")" ::: "memory")
; #define PG8_BAR __builtin_amdgcn_s_barrier()
; #define PG8_SCHED __builtin_amdgcn_sched_barrier(0)
; template <class Epi0, class Epi1>
; DI void gemm_phase_dual(LAS unsigned char* lds, const Gemm g, const Gemm g1, const StaticOrder S, const Epi0 E0, const Epi1 E1) {
;     ...
;             PG8_LDB(B0, 0, 0); PG8_SCHED; PG8_LDA(At, 0, 0); PG8_STAGE(PG8_SA(1, 1), a1 + hstep, voffA);
;             PG8_WAIT_L(8); PG8_BAR; PG8_WAIT_L(0); PG8_MMA(0, 0, At, B0); PG8_BAR; PG8_SCHED;
;             PG8_LDB(B1, 0, 1); PG8_STAGE(PG8_SB(0, 0), b2, voffB);
;             PG8_BAR; PG8_WAIT_L(0); PG8_MMA(0, 1, At, B1); PG8_BAR;
;             PG8_LDA(At, 0, 1); PG8_STAGE(PG8_SA(0, 0), a2, voffA);
;             PG8_BAR; PG8_WAIT_L(0); PG8_MMA(1, 0, At, B0); PG8_BAR; PG8_SCHED;
.LBB0_632:
	ds_read_b128 v[128:131], v181
	ds_read_b128 v[132:135], v181 offset:1024
	ds_read_b128 v[136:139], v181 offset:2048
	ds_read_b128 v[140:143], v181 offset:3072
	s_add_u32 s12, s10, 0xfffc0080
	s_addc_u32 s13, s11, -1
	s_cmp_eq_u32 s19, 12
	s_cselect_b32 s15, s1, s13
	s_cselect_b32 s14, s6, s12
	s_cselect_b32 s13, s7, s18
	s_cselect_b32 s12, s16, s17
	v_lshl_add_u64 v[190:191], s[10:11], 0, v[168:169]
	s_add_i32 m0, s49, 0xc000
	ds_read_b128 v[144:147], v183
	ds_read_b128 v[148:151], v183 offset:1024
	ds_read_b128 v[152:155], v183 offset:2048
	ds_read_b128 v[184:187], v183 offset:3072
	ds_read_b128 v[194:197], v183 offset:4096
	ds_read_b128 v[198:201], v183 offset:5120
	ds_read_b128 v[202:205], v183 offset:6144
	ds_read_b128 v[206:209], v183 offset:7168
	global_load_lds_dwordx4 v[190:191], off
	v_lshl_add_u64 v[190:191], s[10:11], 0, v[170:171]
	s_add_i32 m0, s49, 0xe000
	s_nop 0
	global_load_lds_dwordx4 v[190:191], off
	s_waitcnt lgkmcnt(8)
	s_barrier
	s_waitcnt lgkmcnt(0)
	s_setprio 1
	s_waitcnt lgkmcnt(0)
	v_mfma_f32_16x16x32_bf16 v[124:127], v[128:131], v[144:147], v[124:127]
	v_mfma_f32_16x16x32_bf16 v[120:123], v[136:139], v[144:147], v[120:123]
	v_mfma_f32_16x16x32_bf16 v[108:111], v[128:131], v[152:155], v[108:111]
	v_mfma_f32_16x16x32_bf16 v[104:107], v[136:139], v[152:155], v[104:107]
	v_mfma_f32_16x16x32_bf16 v[92:95], v[128:131], v[194:197], v[92:95]
	v_mfma_f32_16x16x32_bf16 v[88:91], v[136:139], v[194:197], v[88:91]
	v_mfma_f32_16x16x32_bf16 v[76:79], v[128:131], v[202:205], v[76:79]
	v_mfma_f32_16x16x32_bf16 v[72:75], v[136:139], v[202:205], v[72:75]
	v_mfma_f32_16x16x32_bf16 v[124:127], v[132:135], v[148:151], v[124:127]
	v_mfma_f32_16x16x32_bf16 v[120:123], v[140:143], v[148:151], v[120:123]
	v_mfma_f32_16x16x32_bf16 v[108:111], v[132:135], v[184:187], v[108:111]
	v_mfma_f32_16x16x32_bf16 v[104:107], v[140:143], v[184:187], v[104:107]
	v_mfma_f32_16x16x32_bf16 v[92:95], v[132:135], v[198:201], v[92:95]
	v_mfma_f32_16x16x32_bf16 v[88:91], v[140:143], v[198:201], v[88:91]
	s_setprio 2
	s_barrier
	v_mfma_f32_16x16x32_bf16 v[76:79], v[132:135], v[206:209], v[76:79]
	v_mfma_f32_16x16x32_bf16 v[72:75], v[140:143], v[206:209], v[72:75]
	s_setprio 0
	s_add_i32 s41, s78, s48
	v_lshl_add_u64 v[190:191], s[12:13], 0, v[158:159]
	s_mov_b32 m0, s41
	ds_read_b128 v[210:213], v189
	ds_read_b128 v[214:217], v189 offset:1024
	ds_read_b128 v[218:221], v189 offset:2048
	ds_read_b128 v[224:227], v189 offset:3072
	global_load_lds_dwordx4 v[190:191], off
	v_lshl_add_u64 v[228:229], s[12:13], 0, v[162:163]
	s_add_i32 m0, s41, 0x2000
	s_nop 0
	global_load_lds_dwordx4 v[228:229], off
	s_barrier
	s_waitcnt lgkmcnt(0)
	s_setprio 1
	s_waitcnt lgkmcnt(0)
	v_mfma_f32_16x16x32_bf16 v[116:119], v[210:213], v[144:147], v[116:119]
	v_mfma_f32_16x16x32_bf16 v[112:115], v[218:221], v[144:147], v[112:115]
	v_mfma_f32_16x16x32_bf16 v[100:103], v[210:213], v[152:155], v[100:103]
	v_mfma_f32_16x16x32_bf16 v[96:99], v[218:221], v[152:155], v[96:99]
	v_mfma_f32_16x16x32_bf16 v[84:87], v[210:213], v[194:197], v[84:87]
	v_mfma_f32_16x16x32_bf16 v[80:83], v[218:221], v[194:197], v[80:83]
	v_mfma_f32_16x16x32_bf16 v[68:71], v[210:213], v[202:205], v[68:71]
	v_mfma_f32_16x16x32_bf16 v[64:67], v[218:221], v[202:205], v[64:67]
	v_mfma_f32_16x16x32_bf16 v[116:119], v[214:217], v[148:151], v[116:119]
	v_mfma_f32_16x16x32_bf16 v[112:115], v[224:227], v[148:151], v[112:115]
	v_mfma_f32_16x16x32_bf16 v[100:103], v[214:217], v[184:187], v[100:103]
	v_mfma_f32_16x16x32_bf16 v[96:99], v[224:227], v[184:187], v[96:99]
	v_mfma_f32_16x16x32_bf16 v[84:87], v[214:217], v[198:201], v[84:87]
	v_mfma_f32_16x16x32_bf16 v[80:83], v[224:227], v[198:201], v[80:83]
	s_setprio 2
	s_barrier
	v_mfma_f32_16x16x32_bf16 v[68:71], v[214:217], v[206:209], v[68:71]
	v_mfma_f32_16x16x32_bf16 v[64:67], v[224:227], v[206:209], v[64:67]
	s_setprio 0
	s_mov_b32 m0, s49
	v_lshl_add_u64 v[230:231], s[14:15], 0, v[156:157]
	ds_read_b128 v[144:147], v183 offset:16384
	ds_read_b128 v[148:151], v183 offset:17408
	ds_read_b128 v[152:155], v183 offset:18432
	ds_read_b128 v[184:187], v183 offset:19456
	ds_read_b128 v[194:197], v183 offset:20480
	ds_read_b128 v[198:201], v183 offset:21504
	ds_read_b128 v[202:205], v183 offset:22528
	ds_read_b128 v[206:209], v183 offset:23552
	global_load_lds_dwordx4 v[230:231], off
	v_lshl_add_u64 v[232:233], s[14:15], 0, v[160:161]
	s_mov_b32 m0, s50
	s_nop 0
	global_load_lds_dwordx4 v[232:233], off
	s_barrier
	s_waitcnt lgkmcnt(0)
	s_setprio 1
	s_waitcnt lgkmcnt(0)
	v_mfma_f32_16x16x32_bf16 v[60:63], v[128:131], v[144:147], v[60:63]
	v_mfma_f32_16x16x32_bf16 v[56:59], v[136:139], v[144:147], v[56:59]
	v_mfma_f32_16x16x32_bf16 v[44:47], v[128:131], v[152:155], v[44:47]
	v_mfma_f32_16x16x32_bf16 v[40:43], v[136:139], v[152:155], v[40:43]
	v_mfma_f32_16x16x32_bf16 v[28:31], v[128:131], v[194:197], v[28:31]
	v_mfma_f32_16x16x32_bf16 v[24:27], v[136:139], v[194:197], v[24:27]
	v_mfma_f32_16x16x32_bf16 v[12:15], v[128:131], v[202:205], v[12:15]
	v_mfma_f32_16x16x32_bf16 v[8:11], v[136:139], v[202:205], v[8:11]
	v_mfma_f32_16x16x32_bf16 v[60:63], v[132:135], v[148:151], v[60:63]
	v_mfma_f32_16x16x32_bf16 v[56:59], v[140:143], v[148:151], v[56:59]
	v_mfma_f32_16x16x32_bf16 v[44:47], v[132:135], v[184:187], v[44:47]
	v_mfma_f32_16x16x32_bf16 v[40:43], v[140:143], v[184:187], v[40:43]
	v_mfma_f32_16x16x32_bf16 v[28:31], v[132:135], v[198:201], v[28:31]
	v_mfma_f32_16x16x32_bf16 v[24:27], v[140:143], v[198:201], v[24:27]
	s_setprio 2
	s_barrier
; #define PG8_STAGE(bufoff, gbase, voff) do { _Pragma("unroll") for (int _i = 0; _i < 2; ++_i) \
;         __builtin_amdgcn_global_load_lds((const unsigned*)((const char*)(gbase) + (voff)[_i]), (LAS unsigned*)(lds + (bufoff) + ldsw + _i * 8192), 16, 0, 0); } while (0)
; #define PG8_LDA(dst, b, h) do { _Pragma("unroll") for (int m = 0; m < 4; ++m) _Pragma("unroll") for (int k = 0; k < 2; ++k) dst[m][k] = *(const LAS bf16x8*)(lds + PG8_SA(b, h) + aoff + m * 2048 + k * 1024); } while (0)
; #define PG8_LDB(dst, b, h) do { _Pragma("unroll") for (int n = 0; n < 2; ++n) _Pragma("unroll") for (int k = 0; k < 2; ++k) dst[n][k] = *(const LAS bf16x8*)(lds + PG8_SB(b, h) + boff + n * 2048 + k * 1024); } while (0)
; #define PG8_MMA(ai, bj, At, Bt) do { __builtin_amdgcn_s_setprio(1); _Pragma("unroll") for (int m = 0; m < 4; ++m) _Pragma("unroll") for (int n = 0; n < 2; ++n) _Pragma("unroll") for (int k = 0; k < 2; ++k) \
;         acc[ai][bj][m][n] = __builtin_amdgcn_mfma_f32_16x16x32_bf16(Bt[n][k], At[m][k], acc[ai][bj][m][n], 0, 0, 0); __builtin_amdgcn_s_setprio(0); } while (0)
; #define PG8_WAIT_V(n) asm volatile("s_waitcnt vmcnt(" #n ")" ::: "memory")
; #define PG8_WAIT_L(n) asm volatile("s_waitcnt lgkmcnt(" #n ")" ::: "memory")
; #define PG8_BAR __builtin_amdgcn_s_barrier()
; #define PG8_SCHED __builtin_amdgcn_sched_barrier(0)
; #define PG8_STAGE(bufoff, gbase, voff) do { _Pragma("unroll") for (int _i = 0; _i < 2; ++_i) \
;         __builtin_amdgcn_global_load_lds((const unsigned*)((const char*)(gbase) + (voff)[_i]), (LAS unsigned*)(lds + (bufoff) + ldsw + _i * 8192), 16, 0, 0); } while (0)
; #define PG8_BAR __builtin_amdgcn_s_barrier()
; template <class Epi0, class Epi1>
; DI void gemm_phase_dual(LAS unsigned char* lds, const Gemm g, const Gemm g1, const StaticOrder S, const Epi0 E0, const Epi1 E1) {
;     ...
;             PG8_BAR; PG8_WAIT_L(0); PG8_MMA(1, 0, At, B0); PG8_BAR; PG8_SCHED;
;             PG8_STAGE(PG8_SB(0, 1), b2 + hstep, voffB);
;             PG8_WAIT_V(6); PG8_BAR; PG8_MMA(1, 1, At, B1); PG8_BAR;
;             PG8_LDB(B0, 1, 0); PG8_SCHED; PG8_LDA(At, 1, 0); PG8_STAGE(PG8_SA(0, 1), a2 + hstep, voffA);
;             PG8_WAIT_L(8); PG8_BAR; PG8_WAIT_L(0); PG8_MMA(0, 0, At, B0); PG8_BAR; PG8_SCHED;
;             PG8_LDB(B1, 1, 1); PG8_STAGE(PG8_SB(1, 0), b3, voffB);
;             PG8_BAR; PG8_WAIT_L(0); PG8_MMA(0, 1, At, B1); PG8_BAR;
	v_mfma_f32_16x16x32_bf16 v[12:15], v[132:135], v[206:209], v[12:15]
	v_mfma_f32_16x16x32_bf16 v[8:11], v[140:143], v[206:209], v[8:11]
	s_setprio 0
	s_add_u32 s90, s12, 0x40000
	s_addc_u32 s91, s13, 0
	s_add_i32 s41, s79, s48
	v_lshl_add_u64 v[128:129], s[90:91], 0, v[158:159]
	s_mov_b32 m0, s41
	s_nop 0
	global_load_lds_dwordx4 v[128:129], off
	v_lshl_add_u64 v[128:129], s[90:91], 0, v[162:163]
	s_add_i32 m0, s41, 0x2000
	s_nop 0
	global_load_lds_dwordx4 v[128:129], off
	s_waitcnt vmcnt(6)
	s_barrier
	s_setprio 1
	v_mfma_f32_16x16x32_bf16 v[52:55], v[210:213], v[144:147], v[52:55]
	v_mfma_f32_16x16x32_bf16 v[48:51], v[218:221], v[144:147], v[48:51]
	v_mfma_f32_16x16x32_bf16 v[36:39], v[210:213], v[152:155], v[36:39]
	v_mfma_f32_16x16x32_bf16 v[32:35], v[218:221], v[152:155], v[32:35]
	v_mfma_f32_16x16x32_bf16 v[20:23], v[210:213], v[194:197], v[20:23]
	v_mfma_f32_16x16x32_bf16 v[16:19], v[218:221], v[194:197], v[16:19]
	v_mfma_f32_16x16x32_bf16 v[4:7], v[210:213], v[202:205], v[4:7]
	v_mfma_f32_16x16x32_bf16 v[0:3], v[218:221], v[202:205], v[0:3]
	v_mfma_f32_16x16x32_bf16 v[52:55], v[214:217], v[148:151], v[52:55]
	v_mfma_f32_16x16x32_bf16 v[48:51], v[224:227], v[148:151], v[48:51]
	v_mfma_f32_16x16x32_bf16 v[36:39], v[214:217], v[184:187], v[36:39]
	v_mfma_f32_16x16x32_bf16 v[32:35], v[224:227], v[184:187], v[32:35]
	v_mfma_f32_16x16x32_bf16 v[20:23], v[214:217], v[198:201], v[20:23]
	v_mfma_f32_16x16x32_bf16 v[16:19], v[224:227], v[198:201], v[16:19]
	s_setprio 2
	s_barrier
	v_mfma_f32_16x16x32_bf16 v[4:7], v[214:217], v[206:209], v[4:7]
	v_mfma_f32_16x16x32_bf16 v[0:3], v[224:227], v[206:209], v[0:3]
	s_setprio 0
	s_add_i32 s41, 0, 0x18000
	v_add_u32_e32 v140, s41, v179
	ds_read_b128 v[128:131], v140
	ds_read_b128 v[132:135], v140 offset:1024
	ds_read_b128 v[136:139], v140 offset:2048
	ds_read_b128 v[140:143], v140 offset:3072
	s_add_u32 s14, s14, 0x40000
	s_addc_u32 s15, s15, 0
	s_mov_b32 m0, s51
	v_lshl_add_u64 v[210:211], s[14:15], 0, v[156:157]
	ds_read_b128 v[144:147], v183 offset:32768
	ds_read_b128 v[148:151], v183 offset:33792
	ds_read_b128 v[152:155], v183 offset:34816
	ds_read_b128 v[184:187], v183 offset:35840
	ds_read_b128 v[194:197], v183 offset:36864
	ds_read_b128 v[198:201], v183 offset:37888
	ds_read_b128 v[202:205], v183 offset:38912
	ds_read_b128 v[206:209], v183 offset:39936
	global_load_lds_dwordx4 v[210:211], off
	v_lshl_add_u64 v[210:211], s[14:15], 0, v[160:161]
	s_mov_b32 m0, s58
	s_nop 0
	global_load_lds_dwordx4 v[210:211], off
	s_waitcnt lgkmcnt(8)
	s_barrier
	s_waitcnt lgkmcnt(0)
	s_setprio 1
	s_waitcnt lgkmcnt(0)
	v_mfma_f32_16x16x32_bf16 v[124:127], v[128:131], v[144:147], v[124:127]
	v_mfma_f32_16x16x32_bf16 v[120:123], v[136:139], v[144:147], v[120:123]
	v_mfma_f32_16x16x32_bf16 v[108:111], v[128:131], v[152:155], v[108:111]
	v_mfma_f32_16x16x32_bf16 v[104:107], v[136:139], v[152:155], v[104:107]
	v_mfma_f32_16x16x32_bf16 v[92:95], v[128:131], v[194:197], v[92:95]
	v_mfma_f32_16x16x32_bf16 v[88:91], v[136:139], v[194:197], v[88:91]
	v_mfma_f32_16x16x32_bf16 v[76:79], v[128:131], v[202:205], v[76:79]
	v_mfma_f32_16x16x32_bf16 v[72:75], v[136:139], v[202:205], v[72:75]
	v_mfma_f32_16x16x32_bf16 v[124:127], v[132:135], v[148:151], v[124:127]
	v_mfma_f32_16x16x32_bf16 v[120:123], v[140:143], v[148:151], v[120:123]
	v_mfma_f32_16x16x32_bf16 v[108:111], v[132:135], v[184:187], v[108:111]
	v_mfma_f32_16x16x32_bf16 v[104:107], v[140:143], v[184:187], v[104:107]
	v_mfma_f32_16x16x32_bf16 v[92:95], v[132:135], v[198:201], v[92:95]
	v_mfma_f32_16x16x32_bf16 v[88:91], v[140:143], v[198:201], v[88:91]
	s_setprio 2
	s_barrier
	v_mfma_f32_16x16x32_bf16 v[76:79], v[132:135], v[206:209], v[76:79]
	v_mfma_f32_16x16x32_bf16 v[72:75], v[140:143], v[206:209], v[72:75]
	s_setprio 0
	s_add_i32 s14, 0, 0x1c000
	s_add_i32 s15, s41, s48
	v_add_u32_e32 v176, s14, v179
	v_lshl_add_u64 v[190:191], v[190:191], 0, s[22:23]
	s_mov_b32 m0, s15
	ds_read_b128 v[210:213], v176
	ds_read_b128 v[214:217], v176 offset:1024
	ds_read_b128 v[218:221], v176 offset:2048
	ds_read_b128 v[224:227], v176 offset:3072
	global_load_lds_dwordx4 v[190:191], off
	v_lshl_add_u64 v[190:191], v[228:229], 0, s[22:23]
	s_add_i32 m0, s15, 0x2000
	s_nop 0
	global_load_lds_dwordx4 v[190:191], off
	s_barrier
	s_waitcnt lgkmcnt(0)
	s_setprio 1
	s_waitcnt lgkmcnt(0)
	v_mfma_f32_16x16x32_bf16 v[116:119], v[210:213], v[144:147], v[116:119]
	v_mfma_f32_16x16x32_bf16 v[112:115], v[218:221], v[144:147], v[112:115]
	v_mfma_f32_16x16x32_bf16 v[100:103], v[210:213], v[152:155], v[100:103]
	v_mfma_f32_16x16x32_bf16 v[96:99], v[218:221], v[152:155], v[96:99]
	v_mfma_f32_16x16x32_bf16 v[84:87], v[210:213], v[194:197], v[84:87]
	v_mfma_f32_16x16x32_bf16 v[80:83], v[218:221], v[194:197], v[80:83]
	v_mfma_f32_16x16x32_bf16 v[68:71], v[210:213], v[202:205], v[68:71]
	v_mfma_f32_16x16x32_bf16 v[64:67], v[218:221], v[202:205], v[64:67]
	v_mfma_f32_16x16x32_bf16 v[116:119], v[214:217], v[148:151], v[116:119]
	v_mfma_f32_16x16x32_bf16 v[112:115], v[224:227], v[148:151], v[112:115]
	v_mfma_f32_16x16x32_bf16 v[100:103], v[214:217], v[184:187], v[100:103]
	v_mfma_f32_16x16x32_bf16 v[96:99], v[224:227], v[184:187], v[96:99]
	v_mfma_f32_16x16x32_bf16 v[84:87], v[214:217], v[198:201], v[84:87]
	v_mfma_f32_16x16x32_bf16 v[80:83], v[224:227], v[198:201], v[80:83]
	s_setprio 2
	s_barrier
; #define PG8_STAGE(bufoff, gbase, voff) do { _Pragma("unroll") for (int _i = 0; _i < 2; ++_i) \
;         __builtin_amdgcn_global_load_lds((const unsigned*)((const char*)(gbase) + (voff)[_i]), (LAS unsigned*)(lds + (bufoff) + ldsw + _i * 8192), 16, 0, 0); } while (0)
; #define PG8_LDA(dst, b, h) do { _Pragma("unroll") for (int m = 0; m < 4; ++m) _Pragma("unroll") for (int k = 0; k < 2; ++k) dst[m][k] = *(const LAS bf16x8*)(lds + PG8_SA(b, h) + aoff + m * 2048 + k * 1024); } while (0)
; #define PG8_MMA(ai, bj, At, Bt) do { __builtin_amdgcn_s_setprio(1); _Pragma("unroll") for (int m = 0; m < 4; ++m) _Pragma("unroll") for (int n = 0; n < 2; ++n) _Pragma("unroll") for (int k = 0; k < 2; ++k) \
;         acc[ai][bj][m][n] = __builtin_amdgcn_mfma_f32_16x16x32_bf16(Bt[n][k], At[m][k], acc[ai][bj][m][n], 0, 0, 0); __builtin_amdgcn_s_setprio(0); } while (0)
; #define PG8_WAIT_V(n) asm volatile("s_waitcnt vmcnt(" #n ")" ::: "memory")
; #define PG8_WAIT_L(n) asm volatile("s_waitcnt lgkmcnt(" #n ")" ::: "memory")
; #define PG8_BAR __builtin_amdgcn_s_barrier()
; #define PG8_SCHED __builtin_amdgcn_sched_barrier(0)
; #define PG8_STAGE(bufoff, gbase, voff) do { _Pragma("unroll") for (int _i = 0; _i < 2; ++_i) \
;         __builtin_amdgcn_global_load_lds((const unsigned*)((const char*)(gbase) + (voff)[_i]), (LAS unsigned*)(lds + (bufoff) + ldsw + _i * 8192), 16, 0, 0); } while (0)
; #define PG8_WAIT_V(n) asm volatile("s_waitcnt vmcnt(" #n ")" ::: "memory")
; template <class Epi0, class Epi1>
; DI void gemm_phase_dual(LAS unsigned char* lds, const Gemm g, const Gemm g1, const StaticOrder S, const Epi0 E0, const Epi1 E1) {
;     ...
;             PG8_BAR; PG8_WAIT_L(0); PG8_MMA(0, 1, At, B1); PG8_BAR;
;             PG8_LDA(At, 1, 1); PG8_STAGE(PG8_SA(1, 0), a3, voffA);
;             PG8_BAR; PG8_WAIT_L(0); PG8_MMA(1, 0, At, B0); PG8_BAR; PG8_SCHED;
;             PG8_STAGE(PG8_SB(1, 1), b3 + hstep, voffB);
;             PG8_WAIT_V(6); PG8_BAR; PG8_MMA(1, 1, At, B1); PG8_BAR;
;         }
;         if (ui & 1) E1(acc, cur, wr, wc, fr, fq); else E0(acc, cur, wr, wc, fr, fq);
;     DI void operator()(AccRef acc, const Unit& u, int wr, int wc, int fr, int fq) const {
;         const int row0 = u.pm * 256 + wr * 64 + fr;
;         bf16_t* Gp = gab + (size_t)(u.pm * 8 + u.pn) * 65536 + (wr * 64 + fr) * 256 + wc * 32 + 8 * fq;
;         const RowScales rsc = load_rowscales(ss, row0);
	v_mfma_f32_16x16x32_bf16 v[68:71], v[214:217], v[206:209], v[68:71]
	v_mfma_f32_16x16x32_bf16 v[64:67], v[224:227], v[206:209], v[64:67]
	s_setprio 0
	s_mov_b32 m0, s76
	v_lshl_add_u64 v[190:191], v[230:231], 0, s[22:23]
	ds_read_b128 v[144:147], v183 offset:49152
	ds_read_b128 v[148:151], v183 offset:50176
	ds_read_b128 v[152:155], v183 offset:51200
	ds_read_b128 v[184:187], v183 offset:52224
	ds_read_b128 v[194:197], v183 offset:53248
	ds_read_b128 v[198:201], v183 offset:54272
	ds_read_b128 v[202:205], v183 offset:55296
	ds_read_b128 v[206:209], v183 offset:56320
	global_load_lds_dwordx4 v[190:191], off
	v_lshl_add_u64 v[190:191], v[232:233], 0, s[22:23]
	s_mov_b32 m0, s77
	s_nop 0
	global_load_lds_dwordx4 v[190:191], off
	s_barrier
	s_waitcnt lgkmcnt(0)
	s_setprio 1
	s_waitcnt lgkmcnt(0)
	v_mfma_f32_16x16x32_bf16 v[60:63], v[128:131], v[144:147], v[60:63]
	v_mfma_f32_16x16x32_bf16 v[56:59], v[136:139], v[144:147], v[56:59]
	v_mfma_f32_16x16x32_bf16 v[44:47], v[128:131], v[152:155], v[44:47]
	v_mfma_f32_16x16x32_bf16 v[40:43], v[136:139], v[152:155], v[40:43]
	v_mfma_f32_16x16x32_bf16 v[28:31], v[128:131], v[194:197], v[28:31]
	v_mfma_f32_16x16x32_bf16 v[24:27], v[136:139], v[194:197], v[24:27]
	v_mfma_f32_16x16x32_bf16 v[12:15], v[128:131], v[202:205], v[12:15]
	v_mfma_f32_16x16x32_bf16 v[8:11], v[136:139], v[202:205], v[8:11]
	v_mfma_f32_16x16x32_bf16 v[60:63], v[132:135], v[148:151], v[60:63]
	v_mfma_f32_16x16x32_bf16 v[56:59], v[140:143], v[148:151], v[56:59]
	v_mfma_f32_16x16x32_bf16 v[44:47], v[132:135], v[184:187], v[44:47]
	v_mfma_f32_16x16x32_bf16 v[40:43], v[140:143], v[184:187], v[40:43]
	v_mfma_f32_16x16x32_bf16 v[28:31], v[132:135], v[198:201], v[28:31]
	v_mfma_f32_16x16x32_bf16 v[24:27], v[140:143], v[198:201], v[24:27]
	s_setprio 2
	s_barrier
	v_mfma_f32_16x16x32_bf16 v[12:15], v[132:135], v[206:209], v[12:15]
	v_mfma_f32_16x16x32_bf16 v[8:11], v[140:143], v[206:209], v[8:11]
	s_setprio 0
	s_add_u32 s12, s12, 0x40080
	s_addc_u32 s13, s13, 0
	s_add_i32 s14, s14, s48
	v_lshl_add_u64 v[128:129], s[12:13], 0, v[158:159]
	s_mov_b32 m0, s14
	s_nop 0
	global_load_lds_dwordx4 v[128:129], off
	v_lshl_add_u64 v[128:129], s[12:13], 0, v[162:163]
	s_add_i32 m0, s14, 0x2000
	s_nop 0
	global_load_lds_dwordx4 v[128:129], off
	s_waitcnt vmcnt(6)
	s_barrier
	s_setprio 1
	v_mfma_f32_16x16x32_bf16 v[52:55], v[210:213], v[144:147], v[52:55]
	v_mfma_f32_16x16x32_bf16 v[48:51], v[218:221], v[144:147], v[48:51]
	v_mfma_f32_16x16x32_bf16 v[36:39], v[210:213], v[152:155], v[36:39]
	v_mfma_f32_16x16x32_bf16 v[32:35], v[218:221], v[152:155], v[32:35]
	v_mfma_f32_16x16x32_bf16 v[20:23], v[210:213], v[194:197], v[20:23]
	v_mfma_f32_16x16x32_bf16 v[16:19], v[218:221], v[194:197], v[16:19]
	v_mfma_f32_16x16x32_bf16 v[4:7], v[210:213], v[202:205], v[4:7]
	v_mfma_f32_16x16x32_bf16 v[0:3], v[218:221], v[202:205], v[0:3]
	v_mfma_f32_16x16x32_bf16 v[52:55], v[214:217], v[148:151], v[52:55]
	v_mfma_f32_16x16x32_bf16 v[48:51], v[224:227], v[148:151], v[48:51]
	v_mfma_f32_16x16x32_bf16 v[36:39], v[214:217], v[184:187], v[36:39]
	v_mfma_f32_16x16x32_bf16 v[32:35], v[224:227], v[184:187], v[32:35]
	v_mfma_f32_16x16x32_bf16 v[20:23], v[214:217], v[198:201], v[20:23]
	v_mfma_f32_16x16x32_bf16 v[16:19], v[224:227], v[198:201], v[16:19]
	s_setprio 2
	s_barrier
	v_mfma_f32_16x16x32_bf16 v[4:7], v[214:217], v[206:209], v[4:7]
	v_mfma_f32_16x16x32_bf16 v[0:3], v[224:227], v[206:209], v[0:3]
	s_setprio 0
	s_add_i32 s19, s19, 2
	s_add_u32 s10, s10, 0x100
	s_addc_u32 s11, s11, 0
	s_add_u32 s17, s17, 0x100
	s_addc_u32 s18, s18, 0
	s_cmp_gt_u32 s19, 13
	s_cbranch_scc0 .LBB0_632
	v_lshl_add_u32 v128, s0, 8, v177
	s_mov_b64 s[6:7], -1
	s_and_b64 vcc, exec, s[8:9]
	v_ashrrev_i32_e32 v129, 31, v128
	s_cbranch_vccz .LBB0_635
	v_lshl_add_u64 v[130:131], v[128:129], 2, s[60:61]
	global_load_dword v132, v[130:131], off
	global_load_dword v133, v[130:131], off offset:64
	global_load_dword v134, v[130:131], off offset:128
	global_load_dword v135, v[130:131], off offset:192
	global_load_dword v136, v[130:131], off offset:512
	global_load_dword v137, v[130:131], off offset:576
	global_load_dword v138, v[130:131], off offset:640
	global_load_dword v139, v[130:131], off offset:704
	s_lshl_b32 s0, s0, 3
	s_add_i32 s0, s0, s87
	s_ashr_i32 s1, s0, 31
	s_lshl_b64 s[0:1], s[0:1], 17
	v_lshl_add_u64 v[130:131], v[166:167], 0, s[0:1]
	s_mov_b64 s[6:7], 0
	s_waitcnt vmcnt(0)
; DI unsigned pk_bf16(float lo, float hi) { f32x2 v = {lo, hi}; return __builtin_bit_cast(unsigned, __builtin_convertvector(v, bf16v2)); }
; DI float fast_sigmoid(float x) { return __builtin_amdgcn_rcpf(1.0f + __expf(-x)); }
; DI RowScales load_rowscales(const float* ss, int row0) {
;     ...
;         for (int m = 0; m < 4; ++m) t.r[ai][m] = ss[row0 + ai * 128 + m * 16];
; #pragma unroll
;     for (int ai = 0; ai < 2; ++ai)
; #pragma unroll
;         for (int m = 0; m < 4; ++m) t.r[ai][m] = rsqrtf(t.r[ai][m] * (1.0f / 1024.0f) + 1e-6f);
;     DI void operator()(AccRef acc, const Unit& u, int wr, int wc, int fr, int fq) const {
;     ...
;         const RowScales rsc = load_rowscales(ss, row0);
; #pragma unroll
;         for (int ai = 0; ai < 2; ++ai)
; #pragma unroll
;             for (int m = 0; m < 4; ++m)
; #pragma unroll
;                 for (int bj = 0; bj < 2; ++bj) {
;                     const float rs = rsc.r[ai][m];
;                     const f32x4 r0 = acc[ai][bj][m][0] * rs, r1 = acc[ai][bj][m][1] * rs;
;                     u32x4 w;
;                     w.x = pk_bf16(fast_sigmoid(r0[0]), fast_sigmoid(r0[1])); w.y = pk_bf16(fast_sigmoid(r0[2]), fast_sigmoid(r0[3]));
;                     w.z = pk_bf16(fast_sigmoid(r1[0]), fast_sigmoid(r1[1])); w.w = pk_bf16(fast_sigmoid(r1[2]), fast_sigmoid(r1[3]));
;                     *(u32x4*)(Gp + (ai * 128 + m * 16) * 256 + bj * 128) = w;
	v_fmamk_f32 v132, v132, 0x3a800000, v193
	v_mul_f32_e32 v140, 0x4b800000, v132
	v_cmp_gt_f32_e32 vcc, s80, v132
	v_fmamk_f32 v134, v134, 0x3a800000, v193
	v_fmamk_f32 v136, v136, 0x3a800000, v193
	v_fmamk_f32 v137, v137, 0x3a800000, v193
	v_fmamk_f32 v138, v138, 0x3a800000, v193
	v_fmamk_f32 v139, v139, 0x3a800000, v193
	v_mul_f32_e32 v144, 0x4b800000, v136
	v_mul_f32_e32 v145, 0x4b800000, v137
	v_cndmask_b32_e32 v132, v132, v140, vcc
	v_cmp_gt_f32_e64 s[12:13], s80, v136
	v_cmp_gt_f32_e64 s[14:15], s80, v137
	v_fmamk_f32 v133, v133, 0x3a800000, v193
	v_fmamk_f32 v135, v135, 0x3a800000, v193
	v_mul_f32_e32 v142, 0x4b800000, v134
	v_mul_f32_e32 v146, 0x4b800000, v138
	v_mul_f32_e32 v147, 0x4b800000, v139
	v_cmp_gt_f32_e64 s[8:9], s80, v134
	v_cndmask_b32_e64 v136, v136, v144, s[12:13]
	v_cndmask_b32_e64 v137, v137, v145, s[14:15]
	v_cmp_gt_f32_e64 s[16:17], s80, v138
	v_cmp_gt_f32_e64 s[18:19], s80, v139
	v_rsq_f32_e32 v132, v132
	v_mul_f32_e32 v141, 0x4b800000, v133
	v_mul_f32_e32 v143, 0x4b800000, v135
	v_cmp_gt_f32_e64 s[0:1], s80, v133
	v_cndmask_b32_e64 v134, v134, v142, s[8:9]
	v_cmp_gt_f32_e64 s[10:11], s80, v135
	v_cndmask_b32_e64 v138, v138, v146, s[16:17]
	v_cndmask_b32_e64 v139, v139, v147, s[18:19]
	v_rsq_f32_e32 v136, v136
	v_rsq_f32_e32 v137, v137
	v_cndmask_b32_e64 v133, v133, v141, s[0:1]
	v_cndmask_b32_e64 v135, v135, v143, s[10:11]
	v_rsq_f32_e32 v134, v134
	v_rsq_f32_e32 v141, v138
	v_rsq_f32_e32 v139, v139
	v_rsq_f32_e32 v133, v133
	v_rsq_f32_e32 v135, v135
	v_mul_f32_e32 v138, 0x45800000, v132
	v_mul_f32_e32 v144, 0x45800000, v136
	v_mul_f32_e32 v145, 0x45800000, v137
	v_cndmask_b32_e32 v148, v132, v138, vcc
	v_mul_f32_e32 v142, 0x45800000, v134
	v_mul_f32_e32 v146, 0x45800000, v141
	v_mul_f32_e32 v147, 0x45800000, v139
	v_cndmask_b32_e64 v138, v136, v144, s[12:13]
	v_cndmask_b32_e64 v136, v137, v145, s[14:15]
	v_pk_mul_f32 v[144:145], v[126:127], v[148:149] op_sel_hi:[1,0]
	v_pk_mul_f32 v[152:153], v[122:123], v[148:149] op_sel_hi:[1,0]
	v_mul_f32_e32 v140, 0x45800000, v133
	v_mul_f32_e32 v143, 0x45800000, v135
	v_cndmask_b32_e64 v142, v134, v142, s[8:9]
	v_cndmask_b32_e64 v134, v141, v146, s[16:17]
	v_cndmask_b32_e64 v132, v139, v147, s[18:19]
	v_pk_mul_f32 v[146:147], v[124:125], v[148:149] op_sel_hi:[1,0]
	v_pk_mul_f32 v[154:155], v[120:121], v[148:149] op_sel_hi:[1,0]
	v_mul_f32_e32 v137, 0xbfb8aa3b, v144
	v_mul_f32_e32 v144, 0xbfb8aa3b, v152
	v_cndmask_b32_e64 v150, v133, v140, s[0:1]
	v_cndmask_b32_e64 v140, v135, v143, s[10:11]
	v_mul_f32_e32 v133, 0xbfb8aa3b, v146
	v_mul_f32_e32 v135, 0xbfb8aa3b, v147
	v_mul_f32_e32 v139, 0xbfb8aa3b, v145
	v_mul_f32_e32 v141, 0xbfb8aa3b, v154
	v_mul_f32_e32 v143, 0xbfb8aa3b, v155
	v_exp_f32_e32 v144, v144
	v_mul_f32_e32 v145, 0xbfb8aa3b, v153
	v_exp_f32_e32 v133, v133
	v_exp_f32_e32 v135, v135
	v_exp_f32_e32 v137, v137
	v_exp_f32_e32 v139, v139
	v_exp_f32_e32 v141, v141
	v_exp_f32_e32 v143, v143
	v_exp_f32_e32 v145, v145
	v_add_f32_e32 v144, 1.0, v144
	v_add_f32_e32 v133, 1.0, v133
	v_add_f32_e32 v135, 1.0, v135
	v_add_f32_e32 v137, 1.0, v137
	v_add_f32_e32 v139, 1.0, v139
	v_add_f32_e32 v141, 1.0, v141
	v_add_f32_e32 v143, 1.0, v143
	v_rcp_f32_e32 v147, v144
	v_add_f32_e32 v144, 1.0, v145
	v_rcp_f32_e32 v133, v133
	v_rcp_f32_e32 v135, v135
	v_rcp_f32_e32 v137, v137
	v_rcp_f32_e32 v139, v139
	v_rcp_f32_e32 v141, v141
	v_rcp_f32_e32 v143, v143
	v_rcp_f32_e32 v149, v144
	v_cvt_pk_bf16_f32 v144, v133, v135
	v_cvt_pk_bf16_f32 v145, v137, v139
	v_cvt_pk_bf16_f32 v146, v141, v143
	v_cvt_pk_bf16_f32 v147, v147, v149
	global_store_dwordx4 v[130:131], v[144:147], off
	v_pk_mul_f32 v[152:153], v[114:115], v[148:149] op_sel_hi:[1,0]
	s_nop 0
	v_pk_mul_f32 v[144:145], v[118:119], v[148:149] op_sel_hi:[1,0]
	v_pk_mul_f32 v[146:147], v[116:117], v[148:149] op_sel_hi:[1,0]
	v_mul_f32_e32 v137, 0xbfb8aa3b, v144
	v_mul_f32_e32 v133, 0xbfb8aa3b, v146
	v_mul_f32_e32 v135, 0xbfb8aa3b, v147
	v_pk_mul_f32 v[146:147], v[112:113], v[148:149] op_sel_hi:[1,0]
	v_mul_f32_e32 v144, 0xbfb8aa3b, v152
	v_mul_f32_e32 v139, 0xbfb8aa3b, v145
	v_mul_f32_e32 v141, 0xbfb8aa3b, v146
	v_mul_f32_e32 v143, 0xbfb8aa3b, v147
	v_exp_f32_e32 v144, v144
	v_mul_f32_e32 v145, 0xbfb8aa3b, v153
	v_exp_f32_e32 v133, v133
	v_exp_f32_e32 v135, v135
	v_exp_f32_e32 v137, v137
	v_exp_f32_e32 v139, v139
	v_exp_f32_e32 v141, v141
	v_exp_f32_e32 v143, v143
	v_exp_f32_e32 v145, v145
	v_add_f32_e32 v144, 1.0, v144
	v_add_f32_e32 v133, 1.0, v133
	v_add_f32_e32 v135, 1.0, v135
	v_add_f32_e32 v137, 1.0, v137
	v_add_f32_e32 v139, 1.0, v139
	v_add_f32_e32 v141, 1.0, v141
	v_add_f32_e32 v143, 1.0, v143
	v_rcp_f32_e32 v147, v144
	v_add_f32_e32 v144, 1.0, v145
	v_rcp_f32_e32 v133, v133
	v_rcp_f32_e32 v135, v135
	v_rcp_f32_e32 v137, v137
	v_rcp_f32_e32 v139, v139
	v_rcp_f32_e32 v141, v141
	v_rcp_f32_e32 v143, v143
	v_rcp_f32_e32 v148, v144
	v_cvt_pk_bf16_f32 v144, v133, v135
	v_cvt_pk_bf16_f32 v145, v137, v139
	v_cvt_pk_bf16_f32 v146, v141, v143
	v_cvt_pk_bf16_f32 v147, v147, v148
	global_store_dwordx4 v[130:131], v[144:147], off offset:256
	v_pk_mul_f32 v[148:149], v[106:107], v[150:151] op_sel_hi:[1,0]
	v_pk_mul_f32 v[152:153], v[98:99], v[150:151] op_sel_hi:[1,0]
	v_pk_mul_f32 v[144:145], v[110:111], v[150:151] op_sel_hi:[1,0]
	v_pk_mul_f32 v[146:147], v[108:109], v[150:151] op_sel_hi:[1,0]
	v_mul_f32_e32 v137, 0xbfb8aa3b, v144
	v_mul_f32_e32 v144, 0xbfb8aa3b, v148
	v_mul_f32_e32 v133, 0xbfb8aa3b, v146
	v_mul_f32_e32 v135, 0xbfb8aa3b, v147
	v_pk_mul_f32 v[146:147], v[104:105], v[150:151] op_sel_hi:[1,0]
	v_mul_f32_e32 v139, 0xbfb8aa3b, v145
	v_exp_f32_e32 v144, v144
	v_mul_f32_e32 v145, 0xbfb8aa3b, v149
	v_mul_f32_e32 v141, 0xbfb8aa3b, v146
; DI unsigned pk_bf16(float lo, float hi) { f32x2 v = {lo, hi}; return __builtin_bit_cast(unsigned, __builtin_convertvector(v, bf16v2)); }
; DI float fast_sigmoid(float x) { return __builtin_amdgcn_rcpf(1.0f + __expf(-x)); }
;     DI void operator()(AccRef acc, const Unit& u, int wr, int wc, int fr, int fq) const {
;     ...
;         for (int ai = 0; ai < 2; ++ai)
; #pragma unroll
;             for (int m = 0; m < 4; ++m)
; #pragma unroll
;                 for (int bj = 0; bj < 2; ++bj) {
;                     const float rs = rsc.r[ai][m];
;                     const f32x4 r0 = acc[ai][bj][m][0] * rs, r1 = acc[ai][bj][m][1] * rs;
;                     u32x4 w;
;                     w.x = pk_bf16(fast_sigmoid(r0[0]), fast_sigmoid(r0[1])); w.y = pk_bf16(fast_sigmoid(r0[2]), fast_sigmoid(r0[3]));
;                     w.z = pk_bf16(fast_sigmoid(r1[0]), fast_sigmoid(r1[1])); w.w = pk_bf16(fast_sigmoid(r1[2]), fast_sigmoid(r1[3]));
;                     *(u32x4*)(Gp + (ai * 128 + m * 16) * 256 + bj * 128) = w;
	v_mul_f32_e32 v143, 0xbfb8aa3b, v147
	v_exp_f32_e32 v145, v145
	v_exp_f32_e32 v133, v133
	v_exp_f32_e32 v135, v135
	v_exp_f32_e32 v137, v137
	v_exp_f32_e32 v139, v139
	v_exp_f32_e32 v141, v141
	v_exp_f32_e32 v143, v143
	v_add_f32_e32 v144, 1.0, v144
	v_rcp_f32_e32 v147, v144
	v_add_f32_e32 v144, 1.0, v145
	v_add_f32_e32 v133, 1.0, v133
	v_add_f32_e32 v135, 1.0, v135
	v_add_f32_e32 v137, 1.0, v137
	v_add_f32_e32 v139, 1.0, v139
	v_add_f32_e32 v141, 1.0, v141
	v_add_f32_e32 v143, 1.0, v143
	v_rcp_f32_e32 v148, v144
	v_rcp_f32_e32 v133, v133
	v_rcp_f32_e32 v135, v135
	v_rcp_f32_e32 v137, v137
	v_rcp_f32_e32 v139, v139
	v_rcp_f32_e32 v141, v141
	v_rcp_f32_e32 v143, v143
	v_cvt_pk_bf16_f32 v147, v147, v148
	v_add_co_u32_e32 v148, vcc, s59, v130
	v_cvt_pk_bf16_f32 v144, v133, v135
	v_cvt_pk_bf16_f32 v145, v137, v139
	v_cvt_pk_bf16_f32 v146, v141, v143
	v_addc_co_u32_e32 v149, vcc, 0, v131, vcc
	global_store_dwordx4 v[148:149], v[144:147], off
	s_nop 1
	v_pk_mul_f32 v[144:145], v[102:103], v[150:151] op_sel_hi:[1,0]
	v_pk_mul_f32 v[146:147], v[100:101], v[150:151] op_sel_hi:[1,0]
	v_mul_f32_e32 v137, 0xbfb8aa3b, v144
	v_mul_f32_e32 v133, 0xbfb8aa3b, v146
	v_mul_f32_e32 v135, 0xbfb8aa3b, v147
	v_pk_mul_f32 v[146:147], v[96:97], v[150:151] op_sel_hi:[1,0]
	v_mul_f32_e32 v144, 0xbfb8aa3b, v152
	v_mul_f32_e32 v139, 0xbfb8aa3b, v145
	v_mul_f32_e32 v141, 0xbfb8aa3b, v146
	v_mul_f32_e32 v143, 0xbfb8aa3b, v147
	v_exp_f32_e32 v144, v144
	v_mul_f32_e32 v145, 0xbfb8aa3b, v153
	v_exp_f32_e32 v133, v133
	v_exp_f32_e32 v135, v135
	v_exp_f32_e32 v137, v137
	v_exp_f32_e32 v139, v139
	v_exp_f32_e32 v141, v141
	v_exp_f32_e32 v143, v143
	v_exp_f32_e32 v145, v145
	v_add_f32_e32 v144, 1.0, v144
	v_add_f32_e32 v133, 1.0, v133
	v_add_f32_e32 v135, 1.0, v135
	v_add_f32_e32 v137, 1.0, v137
	v_add_f32_e32 v139, 1.0, v139
	v_add_f32_e32 v141, 1.0, v141
	v_add_f32_e32 v143, 1.0, v143
	v_rcp_f32_e32 v147, v144
	v_add_f32_e32 v144, 1.0, v145
	v_rcp_f32_e32 v133, v133
	v_rcp_f32_e32 v135, v135
	v_rcp_f32_e32 v137, v137
	v_rcp_f32_e32 v139, v139
	v_rcp_f32_e32 v141, v141
	v_rcp_f32_e32 v143, v143
	v_rcp_f32_e32 v150, v144
	v_cvt_pk_bf16_f32 v144, v133, v135
	v_cvt_pk_bf16_f32 v145, v137, v139
	v_cvt_pk_bf16_f32 v146, v141, v143
	v_cvt_pk_bf16_f32 v147, v147, v150
	global_store_dwordx4 v[148:149], v[144:147], off offset:256
	v_pk_mul_f32 v[148:149], v[90:91], v[142:143] op_sel_hi:[1,0]
	s_nop 0
	v_pk_mul_f32 v[144:145], v[94:95], v[142:143] op_sel_hi:[1,0]
	v_pk_mul_f32 v[146:147], v[92:93], v[142:143] op_sel_hi:[1,0]
	v_mul_f32_e32 v137, 0xbfb8aa3b, v144
	v_mul_f32_e32 v144, 0xbfb8aa3b, v148
	v_mul_f32_e32 v133, 0xbfb8aa3b, v146
	v_mul_f32_e32 v135, 0xbfb8aa3b, v147
	v_pk_mul_f32 v[146:147], v[88:89], v[142:143] op_sel_hi:[1,0]
	v_mul_f32_e32 v139, 0xbfb8aa3b, v145
	v_exp_f32_e32 v144, v144
	v_mul_f32_e32 v145, 0xbfb8aa3b, v149
	v_mul_f32_e32 v141, 0xbfb8aa3b, v146
	v_mul_f32_e32 v143, 0xbfb8aa3b, v147
	v_exp_f32_e32 v145, v145
	v_exp_f32_e32 v133, v133
	v_exp_f32_e32 v135, v135
	v_exp_f32_e32 v137, v137
	v_exp_f32_e32 v139, v139
	v_exp_f32_e32 v141, v141
	v_exp_f32_e32 v143, v143
	v_add_f32_e32 v144, 1.0, v144
	v_rcp_f32_e32 v147, v144
	v_add_f32_e32 v144, 1.0, v145
	v_add_f32_e32 v133, 1.0, v133
	v_add_f32_e32 v135, 1.0, v135
	v_add_f32_e32 v137, 1.0, v137
	v_add_f32_e32 v139, 1.0, v139
	v_add_f32_e32 v141, 1.0, v141
	v_add_f32_e32 v143, 1.0, v143
	v_rcp_f32_e32 v148, v144
	v_rcp_f32_e32 v133, v133
	v_rcp_f32_e32 v135, v135
	v_rcp_f32_e32 v137, v137
	v_rcp_f32_e32 v139, v139
	v_rcp_f32_e32 v141, v141
	v_rcp_f32_e32 v143, v143
	v_cvt_pk_bf16_f32 v147, v147, v148
	v_add_co_u32_e32 v148, vcc, s66, v130
	v_cvt_pk_bf16_f32 v144, v133, v135
	v_cvt_pk_bf16_f32 v145, v137, v139
	v_cvt_pk_bf16_f32 v146, v141, v143
	v_addc_co_u32_e32 v149, vcc, 0, v131, vcc
	global_store_dwordx4 v[148:149], v[144:147], off
	v_pk_mul_f32 v[150:151], v[82:83], v[142:143] op_sel_hi:[1,0]
	s_nop 0
	v_pk_mul_f32 v[144:145], v[86:87], v[142:143] op_sel_hi:[1,0]
	v_pk_mul_f32 v[146:147], v[84:85], v[142:143] op_sel_hi:[1,0]
	v_pk_mul_f32 v[142:143], v[80:81], v[142:143] op_sel_hi:[1,0]
	v_mul_f32_e32 v133, 0xbfb8aa3b, v146
	v_mul_f32_e32 v141, 0xbfb8aa3b, v142
	v_mul_f32_e32 v142, 0xbfb8aa3b, v143
	v_exp_f32_e32 v142, v142
	v_mul_f32_e32 v143, 0xbfb8aa3b, v150
	v_mul_f32_e32 v135, 0xbfb8aa3b, v147
	v_mul_f32_e32 v137, 0xbfb8aa3b, v144
	v_mul_f32_e32 v139, 0xbfb8aa3b, v145
	v_exp_f32_e32 v143, v143
	v_mul_f32_e32 v144, 0xbfb8aa3b, v151
	v_exp_f32_e32 v133, v133
	v_exp_f32_e32 v135, v135
	v_exp_f32_e32 v137, v137
	v_exp_f32_e32 v139, v139
	v_exp_f32_e32 v141, v141
	v_exp_f32_e32 v144, v144
	v_add_f32_e32 v142, 1.0, v142
	v_rcp_f32_e32 v145, v142
	v_add_f32_e32 v142, 1.0, v143
	v_add_f32_e32 v133, 1.0, v133
	v_add_f32_e32 v135, 1.0, v135
	v_add_f32_e32 v137, 1.0, v137
	v_add_f32_e32 v139, 1.0, v139
	v_add_f32_e32 v141, 1.0, v141
	v_rcp_f32_e32 v146, v142
	v_add_f32_e32 v142, 1.0, v144
	v_rcp_f32_e32 v133, v133
	v_rcp_f32_e32 v135, v135
	v_rcp_f32_e32 v137, v137
	v_rcp_f32_e32 v139, v139
	v_rcp_f32_e32 v141, v141
	v_rcp_f32_e32 v147, v142
	v_cvt_pk_bf16_f32 v142, v133, v135
	v_cvt_pk_bf16_f32 v143, v137, v139
	v_cvt_pk_bf16_f32 v144, v141, v145
	v_cvt_pk_bf16_f32 v145, v146, v147
	global_store_dwordx4 v[148:149], v[142:145], off offset:256
	v_pk_mul_f32 v[146:147], v[74:75], v[140:141] op_sel_hi:[1,0]
	s_nop 0
	v_pk_mul_f32 v[144:145], v[76:77], v[140:141] op_sel_hi:[1,0]
	v_pk_mul_f32 v[142:143], v[78:79], v[140:141] op_sel_hi:[1,0]
	v_mul_f32_e32 v133, 0xbfb8aa3b, v144
	v_mul_f32_e32 v135, 0xbfb8aa3b, v145
	v_pk_mul_f32 v[144:145], v[72:73], v[140:141] op_sel_hi:[1,0]
	v_mul_f32_e32 v137, 0xbfb8aa3b, v142
; DI unsigned pk_bf16(float lo, float hi) { f32x2 v = {lo, hi}; return __builtin_bit_cast(unsigned, __builtin_convertvector(v, bf16v2)); }
; DI float fast_sigmoid(float x) { return __builtin_amdgcn_rcpf(1.0f + __expf(-x)); }
;     DI void operator()(AccRef acc, const Unit& u, int wr, int wc, int fr, int fq) const {
;     ...
;         for (int ai = 0; ai < 2; ++ai)
; #pragma unroll
;             for (int m = 0; m < 4; ++m)
; #pragma unroll
;                 for (int bj = 0; bj < 2; ++bj) {
;                     const float rs = rsc.r[ai][m];
;                     const f32x4 r0 = acc[ai][bj][m][0] * rs, r1 = acc[ai][bj][m][1] * rs;
;                     u32x4 w;
;                     w.x = pk_bf16(fast_sigmoid(r0[0]), fast_sigmoid(r0[1])); w.y = pk_bf16(fast_sigmoid(r0[2]), fast_sigmoid(r0[3]));
;                     w.z = pk_bf16(fast_sigmoid(r1[0]), fast_sigmoid(r1[1])); w.w = pk_bf16(fast_sigmoid(r1[2]), fast_sigmoid(r1[3]));
;                     *(u32x4*)(Gp + (ai * 128 + m * 16) * 256 + bj * 128) = w;
	v_mul_f32_e32 v142, 0xbfb8aa3b, v145
	v_mul_f32_e32 v139, 0xbfb8aa3b, v143
	v_exp_f32_e32 v142, v142
	v_mul_f32_e32 v143, 0xbfb8aa3b, v146
	v_mul_f32_e32 v141, 0xbfb8aa3b, v144
	v_exp_f32_e32 v143, v143
	v_mul_f32_e32 v144, 0xbfb8aa3b, v147
	v_exp_f32_e32 v141, v141
	v_exp_f32_e32 v144, v144
	v_exp_f32_e32 v133, v133
	v_exp_f32_e32 v135, v135
	v_exp_f32_e32 v137, v137
	v_exp_f32_e32 v139, v139
	v_add_f32_e32 v142, 1.0, v142
	v_rcp_f32_e32 v145, v142
	v_add_f32_e32 v142, 1.0, v143
	v_add_f32_e32 v141, 1.0, v141
	v_rcp_f32_e32 v146, v142
	v_add_f32_e32 v142, 1.0, v144
	v_add_f32_e32 v133, 1.0, v133
	v_add_f32_e32 v135, 1.0, v135
	v_add_f32_e32 v137, 1.0, v137
	v_add_f32_e32 v139, 1.0, v139
	v_rcp_f32_e32 v141, v141
	v_rcp_f32_e32 v147, v142
	v_rcp_f32_e32 v133, v133
	v_rcp_f32_e32 v135, v135
	v_rcp_f32_e32 v137, v137
	v_rcp_f32_e32 v139, v139
	v_cvt_pk_bf16_f32 v144, v141, v145
	v_cvt_pk_bf16_f32 v145, v146, v147
	v_add_co_u32_e32 v146, vcc, s67, v130
	v_cvt_pk_bf16_f32 v142, v133, v135
	v_cvt_pk_bf16_f32 v143, v137, v139
	v_addc_co_u32_e32 v147, vcc, 0, v131, vcc
	global_store_dwordx4 v[146:147], v[142:145], off
	v_pk_mul_f32 v[148:149], v[66:67], v[140:141] op_sel_hi:[1,0]
	s_nop 0
	v_pk_mul_f32 v[142:143], v[70:71], v[140:141] op_sel_hi:[1,0]
	v_pk_mul_f32 v[144:145], v[68:69], v[140:141] op_sel_hi:[1,0]
	v_pk_mul_f32 v[140:141], v[64:65], v[140:141] op_sel_hi:[1,0]
	v_mul_f32_e32 v137, 0xbfb8aa3b, v142
	v_mul_f32_e32 v140, 0xbfb8aa3b, v140
	v_exp_f32_e32 v140, v140
	v_mul_f32_e32 v141, 0xbfb8aa3b, v141
	v_exp_f32_e32 v141, v141
	v_mul_f32_e32 v133, 0xbfb8aa3b, v144
	v_add_f32_e32 v140, 1.0, v140
	v_rcp_f32_e32 v142, v140
	v_add_f32_e32 v140, 1.0, v141
	v_mul_f32_e32 v141, 0xbfb8aa3b, v148
	v_mul_f32_e32 v135, 0xbfb8aa3b, v145
	v_mul_f32_e32 v139, 0xbfb8aa3b, v143
	v_exp_f32_e32 v141, v141
	v_mul_f32_e32 v143, 0xbfb8aa3b, v149
	v_exp_f32_e32 v133, v133
	v_exp_f32_e32 v135, v135
	v_exp_f32_e32 v137, v137
	v_exp_f32_e32 v139, v139
	v_exp_f32_e32 v143, v143
	v_rcp_f32_e32 v144, v140
	v_add_f32_e32 v140, 1.0, v141
	v_add_f32_e32 v133, 1.0, v133
	v_add_f32_e32 v135, 1.0, v135
	v_add_f32_e32 v137, 1.0, v137
	v_add_f32_e32 v139, 1.0, v139
	v_rcp_f32_e32 v145, v140
	v_add_f32_e32 v140, 1.0, v143
	v_rcp_f32_e32 v133, v133
	v_rcp_f32_e32 v135, v135
	v_rcp_f32_e32 v137, v137
	v_rcp_f32_e32 v139, v139
	v_rcp_f32_e32 v143, v140
	v_cvt_pk_bf16_f32 v140, v133, v135
	v_cvt_pk_bf16_f32 v142, v142, v144
	v_cvt_pk_bf16_f32 v141, v137, v139
	v_cvt_pk_bf16_f32 v143, v145, v143
	global_store_dwordx4 v[146:147], v[140:143], off offset:256
	v_pk_mul_f32 v[144:145], v[58:59], v[138:139] op_sel_hi:[1,0]
	s_nop 0
	v_pk_mul_f32 v[142:143], v[60:61], v[138:139] op_sel_hi:[1,0]
	v_pk_mul_f32 v[140:141], v[62:63], v[138:139] op_sel_hi:[1,0]
	v_mul_f32_e32 v133, 0xbfb8aa3b, v142
	v_mul_f32_e32 v135, 0xbfb8aa3b, v143
	v_pk_mul_f32 v[142:143], v[56:57], v[138:139] op_sel_hi:[1,0]
	v_mul_f32_e32 v137, 0xbfb8aa3b, v140
	v_mul_f32_e32 v140, 0xbfb8aa3b, v142
	v_mul_f32_e32 v139, 0xbfb8aa3b, v141
	v_exp_f32_e32 v140, v140
	v_mul_f32_e32 v141, 0xbfb8aa3b, v143
	v_exp_f32_e32 v141, v141
	v_mul_f32_e32 v143, 0xbfb8aa3b, v145
	v_add_f32_e32 v140, 1.0, v140
	v_rcp_f32_e32 v142, v140
	v_add_f32_e32 v140, 1.0, v141
	v_mul_f32_e32 v141, 0xbfb8aa3b, v144
	v_exp_f32_e32 v141, v141
	v_exp_f32_e32 v133, v133
	v_exp_f32_e32 v135, v135
	v_exp_f32_e32 v137, v137
	v_exp_f32_e32 v139, v139
	v_exp_f32_e32 v143, v143
	v_rcp_f32_e32 v144, v140
	v_add_f32_e32 v140, 1.0, v141
	v_add_f32_e32 v133, 1.0, v133
	v_add_f32_e32 v135, 1.0, v135
	v_add_f32_e32 v137, 1.0, v137
	v_add_f32_e32 v139, 1.0, v139
	v_rcp_f32_e32 v145, v140
	v_add_f32_e32 v140, 1.0, v143
	v_rcp_f32_e32 v133, v133
	v_rcp_f32_e32 v135, v135
	v_rcp_f32_e32 v137, v137
	v_rcp_f32_e32 v139, v139
	v_rcp_f32_e32 v143, v140
	v_cvt_pk_bf16_f32 v142, v142, v144
	v_add_co_u32_e32 v144, vcc, s62, v130
	v_cvt_pk_bf16_f32 v140, v133, v135
	v_cvt_pk_bf16_f32 v141, v137, v139
	v_cvt_pk_bf16_f32 v143, v145, v143
	v_addc_co_u32_e32 v145, vcc, 0, v131, vcc
	global_store_dwordx4 v[144:145], v[140:143], off
	v_pk_mul_f32 v[146:147], v[50:51], v[138:139] op_sel_hi:[1,0]
	s_nop 0
	v_pk_mul_f32 v[140:141], v[54:55], v[138:139] op_sel_hi:[1,0]
	v_pk_mul_f32 v[142:143], v[52:53], v[138:139] op_sel_hi:[1,0]
	v_pk_mul_f32 v[138:139], v[48:49], v[138:139] op_sel_hi:[1,0]
	v_mul_f32_e32 v137, 0xbfb8aa3b, v140
	v_mul_f32_e32 v138, 0xbfb8aa3b, v138
	v_exp_f32_e32 v138, v138
	v_mul_f32_e32 v139, 0xbfb8aa3b, v139
	v_exp_f32_e32 v139, v139
	v_mul_f32_e32 v140, 0xbfb8aa3b, v141
	v_add_f32_e32 v138, 1.0, v138
	v_rcp_f32_e32 v141, v138
	v_add_f32_e32 v138, 1.0, v139
	v_mul_f32_e32 v139, 0xbfb8aa3b, v146
	v_mul_f32_e32 v133, 0xbfb8aa3b, v142
	v_mul_f32_e32 v135, 0xbfb8aa3b, v143
	v_exp_f32_e32 v139, v139
	v_mul_f32_e32 v142, 0xbfb8aa3b, v147
	v_exp_f32_e32 v133, v133
	v_exp_f32_e32 v135, v135
	v_exp_f32_e32 v137, v137
	v_exp_f32_e32 v140, v140
	v_exp_f32_e32 v142, v142
	v_rcp_f32_e32 v143, v138
	v_add_f32_e32 v138, 1.0, v139
	v_add_f32_e32 v133, 1.0, v133
	v_add_f32_e32 v135, 1.0, v135
	v_add_f32_e32 v137, 1.0, v137
	v_add_f32_e32 v140, 1.0, v140
	v_rcp_f32_e32 v146, v138
	v_add_f32_e32 v138, 1.0, v142
	v_rcp_f32_e32 v133, v133
	v_rcp_f32_e32 v135, v135
	v_rcp_f32_e32 v137, v137
	v_rcp_f32_e32 v140, v140
	v_rcp_f32_e32 v142, v138
	v_cvt_pk_bf16_f32 v138, v133, v135
	v_cvt_pk_bf16_f32 v139, v137, v140
	v_cvt_pk_bf16_f32 v140, v141, v143
	v_cvt_pk_bf16_f32 v141, v146, v142
	global_store_dwordx4 v[144:145], v[138:141], off offset:256
	v_pk_mul_f32 v[142:143], v[42:43], v[136:137] op_sel_hi:[1,0]
	s_nop 0
	v_pk_mul_f32 v[138:139], v[46:47], v[136:137] op_sel_hi:[1,0]
; DI unsigned pk_bf16(float lo, float hi) { f32x2 v = {lo, hi}; return __builtin_bit_cast(unsigned, __builtin_convertvector(v, bf16v2)); }
; DI float fast_sigmoid(float x) { return __builtin_amdgcn_rcpf(1.0f + __expf(-x)); }
;     DI void operator()(AccRef acc, const Unit& u, int wr, int wc, int fr, int fq) const {
;     ...
;         for (int ai = 0; ai < 2; ++ai)
; #pragma unroll
;             for (int m = 0; m < 4; ++m)
; #pragma unroll
;                 for (int bj = 0; bj < 2; ++bj) {
;                     const float rs = rsc.r[ai][m];
;                     const f32x4 r0 = acc[ai][bj][m][0] * rs, r1 = acc[ai][bj][m][1] * rs;
;                     u32x4 w;
;                     w.x = pk_bf16(fast_sigmoid(r0[0]), fast_sigmoid(r0[1])); w.y = pk_bf16(fast_sigmoid(r0[2]), fast_sigmoid(r0[3]));
;                     w.z = pk_bf16(fast_sigmoid(r1[0]), fast_sigmoid(r1[1])); w.w = pk_bf16(fast_sigmoid(r1[2]), fast_sigmoid(r1[3]));
;                     *(u32x4*)(Gp + (ai * 128 + m * 16) * 256 + bj * 128) = w;
	v_pk_mul_f32 v[140:141], v[44:45], v[136:137] op_sel_hi:[1,0]
	s_nop 0
	v_mul_f32_e32 v133, 0xbfb8aa3b, v140
	v_mul_f32_e32 v135, 0xbfb8aa3b, v141
	v_pk_mul_f32 v[140:141], v[40:41], v[136:137] op_sel_hi:[1,0]
	v_mul_f32_e32 v137, 0xbfb8aa3b, v138
	v_mul_f32_e32 v138, 0xbfb8aa3b, v139
	v_exp_f32_e32 v138, v138
	v_mul_f32_e32 v139, 0xbfb8aa3b, v140
	v_exp_f32_e32 v139, v139
	v_mul_f32_e32 v140, 0xbfb8aa3b, v141
	v_exp_f32_e32 v140, v140
	v_add_f32_e32 v138, 1.0, v138
	v_rcp_f32_e32 v141, v138
	v_add_f32_e32 v138, 1.0, v139
	v_mul_f32_e32 v139, 0xbfb8aa3b, v142
	v_rcp_f32_e32 v144, v138
	v_add_f32_e32 v138, 1.0, v140
	v_exp_f32_e32 v139, v139
	v_mul_f32_e32 v140, 0xbfb8aa3b, v143
	v_exp_f32_e32 v133, v133
	v_exp_f32_e32 v135, v135
	v_exp_f32_e32 v137, v137
	v_exp_f32_e32 v140, v140
	v_rcp_f32_e32 v142, v138
	v_add_f32_e32 v138, 1.0, v139
	v_add_f32_e32 v133, 1.0, v133
	v_add_f32_e32 v135, 1.0, v135
	v_add_f32_e32 v137, 1.0, v137
	v_rcp_f32_e32 v143, v138
	v_add_f32_e32 v138, 1.0, v140
	v_rcp_f32_e32 v133, v133
	v_rcp_f32_e32 v135, v135
	v_rcp_f32_e32 v137, v137
	v_rcp_f32_e32 v145, v138
	v_cvt_pk_bf16_f32 v140, v144, v142
	v_add_co_u32_e32 v142, vcc, s63, v130
	v_cvt_pk_bf16_f32 v138, v133, v135
	v_cvt_pk_bf16_f32 v139, v137, v141
	v_cvt_pk_bf16_f32 v141, v143, v145
	v_addc_co_u32_e32 v143, vcc, 0, v131, vcc
	global_store_dwordx4 v[142:143], v[138:141], off
	v_pk_mul_f32 v[144:145], v[34:35], v[136:137] op_sel_hi:[1,0]
	s_nop 0
	v_pk_mul_f32 v[138:139], v[38:39], v[136:137] op_sel_hi:[1,0]
	v_pk_mul_f32 v[140:141], v[36:37], v[136:137] op_sel_hi:[1,0]
	v_pk_mul_f32 v[136:137], v[32:33], v[136:137] op_sel_hi:[1,0]
	v_mul_f32_e32 v133, 0xbfb8aa3b, v140
	v_mul_f32_e32 v136, 0xbfb8aa3b, v136
	v_exp_f32_e32 v136, v136
	v_mul_f32_e32 v137, 0xbfb8aa3b, v137
	v_exp_f32_e32 v137, v137
	v_mul_f32_e32 v135, 0xbfb8aa3b, v141
	v_add_f32_e32 v136, 1.0, v136
	v_rcp_f32_e32 v140, v136
	v_add_f32_e32 v136, 1.0, v137
	v_mul_f32_e32 v137, 0xbfb8aa3b, v144
	v_mul_f32_e32 v138, 0xbfb8aa3b, v138
	v_mul_f32_e32 v139, 0xbfb8aa3b, v139
	v_exp_f32_e32 v137, v137
	v_mul_f32_e32 v141, 0xbfb8aa3b, v145
	v_exp_f32_e32 v133, v133
	v_exp_f32_e32 v135, v135
	v_exp_f32_e32 v138, v138
	v_exp_f32_e32 v139, v139
	v_exp_f32_e32 v141, v141
	v_rcp_f32_e32 v144, v136
	v_add_f32_e32 v136, 1.0, v137
	v_add_f32_e32 v133, 1.0, v133
	v_add_f32_e32 v135, 1.0, v135
	v_add_f32_e32 v138, 1.0, v138
	v_add_f32_e32 v139, 1.0, v139
	v_rcp_f32_e32 v145, v136
	v_add_f32_e32 v136, 1.0, v141
	v_rcp_f32_e32 v133, v133
	v_rcp_f32_e32 v135, v135
	v_rcp_f32_e32 v138, v138
	v_rcp_f32_e32 v139, v139
	v_rcp_f32_e32 v141, v136
	v_cvt_pk_bf16_f32 v136, v133, v135
	v_cvt_pk_bf16_f32 v137, v138, v139
	v_cvt_pk_bf16_f32 v138, v140, v144
	v_cvt_pk_bf16_f32 v139, v145, v141
	global_store_dwordx4 v[142:143], v[136:139], off offset:256
	v_pk_mul_f32 v[140:141], v[26:27], v[134:135] op_sel_hi:[1,0]
	s_nop 0
	v_pk_mul_f32 v[136:137], v[30:31], v[134:135] op_sel_hi:[1,0]
	v_pk_mul_f32 v[138:139], v[28:29], v[134:135] op_sel_hi:[1,0]
	v_mul_f32_e32 v136, 0xbfb8aa3b, v136
	v_mul_f32_e32 v135, 0xbfb8aa3b, v139
	v_exp_f32_e32 v135, v135
	v_exp_f32_e32 v136, v136
	v_mul_f32_e32 v137, 0xbfb8aa3b, v137
	v_exp_f32_e32 v137, v137
	v_mul_f32_e32 v133, 0xbfb8aa3b, v138
	v_pk_mul_f32 v[138:139], v[24:25], v[134:135] op_sel_hi:[1,0]
	v_add_f32_e32 v136, 1.0, v136
	v_rcp_f32_e32 v142, v136
	v_add_f32_e32 v136, 1.0, v137
	v_mul_f32_e32 v137, 0xbfb8aa3b, v138
	v_exp_f32_e32 v137, v137
	v_mul_f32_e32 v138, 0xbfb8aa3b, v139
	v_exp_f32_e32 v138, v138
	v_rcp_f32_e32 v139, v136
	v_add_f32_e32 v136, 1.0, v137
	v_mul_f32_e32 v137, 0xbfb8aa3b, v140
	v_rcp_f32_e32 v143, v136
	v_add_f32_e32 v136, 1.0, v138
	v_exp_f32_e32 v137, v137
	v_mul_f32_e32 v138, 0xbfb8aa3b, v141
	v_exp_f32_e32 v133, v133
	v_exp_f32_e32 v138, v138
	v_rcp_f32_e32 v140, v136
	v_add_f32_e32 v136, 1.0, v137
	v_add_f32_e32 v133, 1.0, v133
	v_add_f32_e32 v135, 1.0, v135
	v_rcp_f32_e32 v141, v136
	v_add_f32_e32 v136, 1.0, v138
	v_rcp_f32_e32 v133, v133
	v_rcp_f32_e32 v135, v135
	v_rcp_f32_e32 v144, v136
	v_cvt_pk_bf16_f32 v138, v143, v140
	v_add_co_u32_e32 v140, vcc, s64, v130
	v_cvt_pk_bf16_f32 v136, v133, v135
	v_cvt_pk_bf16_f32 v137, v142, v139
	v_cvt_pk_bf16_f32 v139, v141, v144
	v_addc_co_u32_e32 v141, vcc, 0, v131, vcc
	global_store_dwordx4 v[140:141], v[136:139], off
; DI unsigned pk_bf16(float lo, float hi) { f32x2 v = {lo, hi}; return __builtin_bit_cast(unsigned, __builtin_convertvector(v, bf16v2)); }
; DI float fast_sigmoid(float x) { return __builtin_amdgcn_rcpf(1.0f + __expf(-x)); }
;     DI void operator()(AccRef acc, const Unit& u, int wr, int wc, int fr, int fq) const {
;     ...
;         for (int ai = 0; ai < 2; ++ai)
; #pragma unroll
;             for (int m = 0; m < 4; ++m)
; #pragma unroll
;                 for (int bj = 0; bj < 2; ++bj) {
;                     const float rs = rsc.r[ai][m];
;                     const f32x4 r0 = acc[ai][bj][m][0] * rs, r1 = acc[ai][bj][m][1] * rs;
;                     u32x4 w;
;                     w.x = pk_bf16(fast_sigmoid(r0[0]), fast_sigmoid(r0[1])); w.y = pk_bf16(fast_sigmoid(r0[2]), fast_sigmoid(r0[3]));
;                     w.z = pk_bf16(fast_sigmoid(r1[0]), fast_sigmoid(r1[1])); w.w = pk_bf16(fast_sigmoid(r1[2]), fast_sigmoid(r1[3]));
;                     *(u32x4*)(Gp + (ai * 128 + m * 16) * 256 + bj * 128) = w;
	v_pk_mul_f32 v[142:143], v[18:19], v[134:135] op_sel_hi:[1,0]
	s_nop 0
	v_pk_mul_f32 v[138:139], v[20:21], v[134:135] op_sel_hi:[1,0]
	v_pk_mul_f32 v[136:137], v[22:23], v[134:135] op_sel_hi:[1,0]
	v_mul_f32_e32 v135, 0xbfb8aa3b, v139
	v_mul_f32_e32 v133, 0xbfb8aa3b, v138
	v_exp_f32_e32 v138, v135
	v_pk_mul_f32 v[134:135], v[16:17], v[134:135] op_sel_hi:[1,0]
	v_mul_f32_e32 v136, 0xbfb8aa3b, v136
	v_mul_f32_e32 v134, 0xbfb8aa3b, v134
	v_exp_f32_e32 v134, v134
	v_mul_f32_e32 v135, 0xbfb8aa3b, v135
	v_exp_f32_e32 v135, v135
	v_mul_f32_e32 v137, 0xbfb8aa3b, v137
	v_add_f32_e32 v134, 1.0, v134
	v_rcp_f32_e32 v139, v134
	v_add_f32_e32 v134, 1.0, v135
	v_mul_f32_e32 v135, 0xbfb8aa3b, v142
	v_exp_f32_e32 v135, v135
	v_mul_f32_e32 v142, 0xbfb8aa3b, v143
	v_exp_f32_e32 v133, v133
	v_exp_f32_e32 v136, v136
	v_exp_f32_e32 v137, v137
	v_exp_f32_e32 v142, v142
	v_rcp_f32_e32 v143, v134
	v_add_f32_e32 v134, 1.0, v135
	v_add_f32_e32 v133, 1.0, v133
	v_add_f32_e32 v138, 1.0, v138
	v_add_f32_e32 v136, 1.0, v136
	v_add_f32_e32 v137, 1.0, v137
	v_rcp_f32_e32 v144, v134
	v_add_f32_e32 v134, 1.0, v142
	v_rcp_f32_e32 v133, v133
	v_rcp_f32_e32 v138, v138
	v_rcp_f32_e32 v136, v136
	v_rcp_f32_e32 v137, v137
	v_rcp_f32_e32 v142, v134
	v_cvt_pk_bf16_f32 v134, v133, v138
	v_cvt_pk_bf16_f32 v135, v136, v137
	v_cvt_pk_bf16_f32 v136, v139, v143
	v_cvt_pk_bf16_f32 v137, v144, v142
	global_store_dwordx4 v[140:141], v[134:137], off offset:256
	v_pk_mul_f32 v[138:139], v[10:11], v[132:133] op_sel_hi:[1,0]
	s_nop 0
	v_pk_mul_f32 v[134:135], v[14:15], v[132:133] op_sel_hi:[1,0]
	v_pk_mul_f32 v[136:137], v[12:13], v[132:133] op_sel_hi:[1,0]
	v_mul_f32_e32 v134, 0xbfb8aa3b, v134
	v_mul_f32_e32 v133, 0xbfb8aa3b, v136
	v_exp_f32_e32 v133, v133
	v_exp_f32_e32 v134, v134
	v_mul_f32_e32 v135, 0xbfb8aa3b, v135
	v_exp_f32_e32 v135, v135
	v_mul_f32_e32 v136, 0xbfb8aa3b, v137
	v_exp_f32_e32 v140, v136
	v_pk_mul_f32 v[136:137], v[8:9], v[132:133] op_sel_hi:[1,0]
	v_add_f32_e32 v134, 1.0, v134
	v_rcp_f32_e32 v141, v134
	v_add_f32_e32 v134, 1.0, v135
	v_mul_f32_e32 v135, 0xbfb8aa3b, v136
	v_exp_f32_e32 v135, v135
	v_mul_f32_e32 v136, 0xbfb8aa3b, v137
	v_exp_f32_e32 v136, v136
	v_rcp_f32_e32 v137, v134
	v_add_f32_e32 v134, 1.0, v135
	v_mul_f32_e32 v135, 0xbfb8aa3b, v138
	v_rcp_f32_e32 v142, v134
	v_add_f32_e32 v134, 1.0, v136
	v_exp_f32_e32 v135, v135
	v_mul_f32_e32 v136, 0xbfb8aa3b, v139
	v_exp_f32_e32 v136, v136
	v_rcp_f32_e32 v138, v134
	v_add_f32_e32 v134, 1.0, v135
	v_add_f32_e32 v133, 1.0, v133
	v_rcp_f32_e32 v139, v134
	v_add_f32_e32 v134, 1.0, v136
	v_rcp_f32_e32 v133, v133
	v_rcp_f32_e32 v143, v134
	v_add_f32_e32 v140, 1.0, v140
	v_rcp_f32_e32 v140, v140
	v_cvt_pk_bf16_f32 v136, v142, v138
	v_add_co_u32_e32 v138, vcc, s65, v130
	v_cvt_pk_bf16_f32 v135, v141, v137
	v_cvt_pk_bf16_f32 v137, v139, v143
	v_addc_co_u32_e32 v139, vcc, 0, v131, vcc
	v_pk_mul_f32 v[130:131], v[6:7], v[132:133] op_sel_hi:[1,0]
	v_cvt_pk_bf16_f32 v134, v133, v140
	v_mul_f32_e32 v130, 0xbfb8aa3b, v130
	v_exp_f32_e32 v130, v130
	v_mul_f32_e32 v131, 0xbfb8aa3b, v131
	global_store_dwordx4 v[138:139], v[134:137], off
	v_exp_f32_e32 v131, v131
	v_add_f32_e32 v130, 1.0, v130
	v_pk_mul_f32 v[134:135], v[4:5], v[132:133] op_sel_hi:[1,0]
	v_pk_mul_f32 v[136:137], v[2:3], v[132:133] op_sel_hi:[1,0]
	v_mul_f32_e32 v133, 0xbfb8aa3b, v134
	v_exp_f32_e32 v134, v133
	v_mul_f32_e32 v133, 0xbfb8aa3b, v135
	v_exp_f32_e32 v135, v133
	v_pk_mul_f32 v[132:133], v[0:1], v[132:133] op_sel_hi:[1,0]
	v_rcp_f32_e32 v140, v130
	v_add_f32_e32 v130, 1.0, v131
	v_mul_f32_e32 v131, 0xbfb8aa3b, v132
	v_exp_f32_e32 v131, v131
	v_mul_f32_e32 v132, 0xbfb8aa3b, v133
	v_exp_f32_e32 v132, v132
	v_rcp_f32_e32 v133, v130
	v_add_f32_e32 v130, 1.0, v131
	v_mul_f32_e32 v131, 0xbfb8aa3b, v136
	v_rcp_f32_e32 v141, v130
	v_add_f32_e32 v130, 1.0, v132
	v_exp_f32_e32 v131, v131
	v_mul_f32_e32 v132, 0xbfb8aa3b, v137
	v_exp_f32_e32 v132, v132
	v_rcp_f32_e32 v136, v130
	v_add_f32_e32 v130, 1.0, v131
	v_add_f32_e32 v134, 1.0, v134
	v_add_f32_e32 v135, 1.0, v135
	v_rcp_f32_e32 v137, v130
	v_add_f32_e32 v130, 1.0, v132
	v_rcp_f32_e32 v134, v134
	v_rcp_f32_e32 v135, v135
	v_rcp_f32_e32 v142, v130
	v_cvt_pk_bf16_f32 v131, v140, v133
	v_cvt_pk_bf16_f32 v132, v141, v136
	v_cvt_pk_bf16_f32 v130, v134, v135
	v_cvt_pk_bf16_f32 v133, v137, v142
	global_store_dwordx4 v[138:139], v[130:133], off offset:256

; #define PG8_STAGE(bufoff, gbase, voff) do { _Pragma("unroll") for (int _i = 0; _i < 2; ++_i) \
;         __builtin_amdgcn_global_load_lds((const unsigned*)((const char*)(gbase) + (voff)[_i]), (LAS unsigned*)(lds + (bufoff) + ldsw + _i * 8192), 16, 0, 0); } while (0)
; #define PG8_LDA(dst, b, h) do { _Pragma("unroll") for (int m = 0; m < 4; ++m) _Pragma("unroll") for (int k = 0; k < 2; ++k) dst[m][k] = *(const LAS bf16x8*)(lds + PG8_SA(b, h) + aoff + m * 2048 + k * 1024); } while (0)
; #define PG8_LDB(dst, b, h) do { _Pragma("unroll") for (int n = 0; n < 2; ++n) _Pragma("unroll") for (int k = 0; k < 2; ++k) dst[n][k] = *(const LAS bf16x8*)(lds + PG8_SB(b, h) + boff + n * 2048 + k * 1024); } while (0)
; #define PG8_MMA(ai, bj, At, Bt) do { __builtin_amdgcn_s_setprio(1); _Pragma("unroll") for (int m = 0; m < 4; ++m) _Pragma("unroll") for (int n = 0; n < 2; ++n) _Pragma("unroll") for (int k = 0; k < 2; ++k) \
;         acc[ai][bj][m][n] = __builtin_amdgcn_mfma_f32_16x16x32_bf16(Bt[n][k], At[m][k], acc[ai][bj][m][n], 0, 0, 0); __builtin_amdgcn_s_setprio(0); } while (0)
; #define PG8_WAIT_L(n) asm volatile("s_waitcnt lgkmcnt(" #n ")" ::: "memory")
; #define PG8_BAR __builtin_amdgcn_s_barrier()
; #define PG8_SCHED __builtin_amdgcn_sched_barrier(0)
; #define PG8_STAGE(bufoff, gbase, voff) do { _Pragma("unroll") for (int _i = 0; _i < 2; ++_i) \
;         __builtin_amdgcn_global_load_lds((const unsigned*)((const char*)(gbase) + (voff)[_i]), (LAS unsigned*)(lds + (bufoff) + ldsw + _i * 8192), 16, 0, 0); } while (0)
; #define PG8_WAIT_L(n) asm volatile("s_waitcnt lgkmcnt(" #n ")" ::: "memory")
; #define PG8_BAR __builtin_amdgcn_s_barrier()
; #define PG8_SCHED __builtin_amdgcn_sched_barrier(0)
; template <class Epi0, class Epi1>
; DI void gemm_phase_dual(LAS unsigned char* lds, const Gemm g, const Gemm g1, const StaticOrder S, const Epi0 E0, const Epi1 E1) {
;     ...
;             PG8_LDB(B0, 0, 0); PG8_SCHED; PG8_LDA(At, 0, 0); PG8_STAGE(PG8_SA(1, 1), a1 + hstep, voffA);
;             PG8_WAIT_L(8); PG8_BAR; PG8_WAIT_L(0); PG8_MMA(0, 0, At, B0); PG8_BAR; PG8_SCHED;
;             PG8_LDB(B1, 0, 1); PG8_STAGE(PG8_SB(0, 0), b2, voffB);
;             PG8_BAR; PG8_WAIT_L(0); PG8_MMA(0, 1, At, B1); PG8_BAR;
;             PG8_LDA(At, 0, 1); PG8_STAGE(PG8_SA(0, 0), a2, voffA);
;             PG8_BAR; PG8_WAIT_L(0); PG8_MMA(1, 0, At, B0); PG8_BAR; PG8_SCHED;
.LBB0_708:
	ds_read_b128 v[156:159], v179
	ds_read_b128 v[160:163], v179 offset:1024
	ds_read_b128 v[164:167], v179 offset:2048
	ds_read_b128 v[168:171], v179 offset:3072
	s_add_u32 s40, s38, 0xfffc0080
	s_addc_u32 s41, s39, -1
	s_cmp_eq_u32 s69, 12
	s_cselect_b32 s43, s6, s41
	s_cselect_b32 s42, s7, s40
	s_cselect_b32 s41, s17, s68
	s_cselect_b32 s40, s19, s67
	v_lshl_add_u64 v[210:211], s[38:39], 0, v[148:149]
	s_add_i32 m0, s25, 0xc000
	ds_read_b128 v[172:175], v180
	ds_read_b128 v[182:185], v180 offset:1024
	ds_read_b128 v[186:189], v180 offset:2048
	ds_read_b128 v[190:193], v180 offset:3072
	ds_read_b128 v[194:197], v180 offset:4096
	ds_read_b128 v[198:201], v180 offset:5120
	ds_read_b128 v[202:205], v180 offset:6144
	ds_read_b128 v[206:209], v180 offset:7168
	global_load_lds_dwordx4 v[210:211], off
	v_lshl_add_u64 v[210:211], s[38:39], 0, v[150:151]
	s_add_i32 m0, s25, 0xe000
	s_nop 0
	global_load_lds_dwordx4 v[210:211], off
	s_waitcnt lgkmcnt(8)
	s_barrier
	s_waitcnt lgkmcnt(0)
	s_setprio 1
	s_waitcnt lgkmcnt(0)
	v_mfma_f32_16x16x32_bf16 v[124:127], v[156:159], v[172:175], v[124:127]
	v_mfma_f32_16x16x32_bf16 v[120:123], v[164:167], v[172:175], v[120:123]
	v_mfma_f32_16x16x32_bf16 v[108:111], v[156:159], v[186:189], v[108:111]
	v_mfma_f32_16x16x32_bf16 v[104:107], v[164:167], v[186:189], v[104:107]
	v_mfma_f32_16x16x32_bf16 v[92:95], v[156:159], v[194:197], v[92:95]
	v_mfma_f32_16x16x32_bf16 v[88:91], v[164:167], v[194:197], v[88:91]
	v_mfma_f32_16x16x32_bf16 v[84:87], v[156:159], v[202:205], v[84:87]
	v_mfma_f32_16x16x32_bf16 v[80:83], v[164:167], v[202:205], v[80:83]
	v_mfma_f32_16x16x32_bf16 v[124:127], v[160:163], v[182:185], v[124:127]
	v_mfma_f32_16x16x32_bf16 v[120:123], v[168:171], v[182:185], v[120:123]
	v_mfma_f32_16x16x32_bf16 v[108:111], v[160:163], v[190:193], v[108:111]
	v_mfma_f32_16x16x32_bf16 v[104:107], v[168:171], v[190:193], v[104:107]
	v_mfma_f32_16x16x32_bf16 v[92:95], v[160:163], v[198:201], v[92:95]
	v_mfma_f32_16x16x32_bf16 v[88:91], v[168:171], v[198:201], v[88:91]
	s_setprio 2
	s_barrier
	v_mfma_f32_16x16x32_bf16 v[84:87], v[160:163], v[206:209], v[84:87]
	v_mfma_f32_16x16x32_bf16 v[80:83], v[168:171], v[206:209], v[80:83]
	s_setprio 0
	s_add_i32 s76, s52, s44
	v_lshl_add_u64 v[228:229], s[40:41], 0, v[130:131]
	s_mov_b32 m0, s76
	ds_read_b128 v[210:213], v181
	ds_read_b128 v[214:217], v181 offset:1024
	ds_read_b128 v[218:221], v181 offset:2048
	ds_read_b128 v[224:227], v181 offset:3072
	global_load_lds_dwordx4 v[228:229], off
	v_lshl_add_u64 v[230:231], s[40:41], 0, v[134:135]
	s_add_i32 m0, s76, 0x2000
	s_nop 0
	global_load_lds_dwordx4 v[230:231], off
	s_barrier
	s_waitcnt lgkmcnt(0)
	s_setprio 1
	s_waitcnt lgkmcnt(0)
	v_mfma_f32_16x16x32_bf16 v[116:119], v[210:213], v[172:175], v[116:119]
	v_mfma_f32_16x16x32_bf16 v[112:115], v[218:221], v[172:175], v[112:115]
	v_mfma_f32_16x16x32_bf16 v[100:103], v[210:213], v[186:189], v[100:103]
	v_mfma_f32_16x16x32_bf16 v[96:99], v[218:221], v[186:189], v[96:99]
	v_mfma_f32_16x16x32_bf16 v[76:79], v[210:213], v[194:197], v[76:79]
	v_mfma_f32_16x16x32_bf16 v[72:75], v[218:221], v[194:197], v[72:75]
	v_mfma_f32_16x16x32_bf16 v[68:71], v[210:213], v[202:205], v[68:71]
	v_mfma_f32_16x16x32_bf16 v[64:67], v[218:221], v[202:205], v[64:67]
	v_mfma_f32_16x16x32_bf16 v[116:119], v[214:217], v[182:185], v[116:119]
	v_mfma_f32_16x16x32_bf16 v[112:115], v[224:227], v[182:185], v[112:115]
	v_mfma_f32_16x16x32_bf16 v[100:103], v[214:217], v[190:193], v[100:103]
	v_mfma_f32_16x16x32_bf16 v[96:99], v[224:227], v[190:193], v[96:99]
	v_mfma_f32_16x16x32_bf16 v[76:79], v[214:217], v[198:201], v[76:79]
	v_mfma_f32_16x16x32_bf16 v[72:75], v[224:227], v[198:201], v[72:75]
	s_setprio 2
	s_barrier
	v_mfma_f32_16x16x32_bf16 v[68:71], v[214:217], v[206:209], v[68:71]
	v_mfma_f32_16x16x32_bf16 v[64:67], v[224:227], v[206:209], v[64:67]
	s_setprio 0
	s_mov_b32 m0, s25
	v_lshl_add_u64 v[232:233], s[42:43], 0, v[128:129]
	ds_read_b128 v[172:175], v180 offset:16384
	ds_read_b128 v[182:185], v180 offset:17408
	ds_read_b128 v[186:189], v180 offset:18432
	ds_read_b128 v[190:193], v180 offset:19456
	ds_read_b128 v[194:197], v180 offset:20480
	ds_read_b128 v[198:201], v180 offset:21504
	ds_read_b128 v[202:205], v180 offset:22528
	ds_read_b128 v[206:209], v180 offset:23552
	global_load_lds_dwordx4 v[232:233], off
	v_lshl_add_u64 v[234:235], s[42:43], 0, v[132:133]
	s_mov_b32 m0, s45
	s_nop 0
	global_load_lds_dwordx4 v[234:235], off
	s_barrier
	s_waitcnt lgkmcnt(0)
	s_setprio 1
	s_waitcnt lgkmcnt(0)
	v_mfma_f32_16x16x32_bf16 v[60:63], v[156:159], v[172:175], v[60:63]
	v_mfma_f32_16x16x32_bf16 v[56:59], v[164:167], v[172:175], v[56:59]
	v_mfma_f32_16x16x32_bf16 v[52:55], v[156:159], v[186:189], v[52:55]
	v_mfma_f32_16x16x32_bf16 v[48:51], v[164:167], v[186:189], v[48:51]
	v_mfma_f32_16x16x32_bf16 v[28:31], v[156:159], v[194:197], v[28:31]
	v_mfma_f32_16x16x32_bf16 v[24:27], v[164:167], v[194:197], v[24:27]
	v_mfma_f32_16x16x32_bf16 v[20:23], v[156:159], v[202:205], v[20:23]
	v_mfma_f32_16x16x32_bf16 v[16:19], v[164:167], v[202:205], v[16:19]
	v_mfma_f32_16x16x32_bf16 v[60:63], v[160:163], v[182:185], v[60:63]
	v_mfma_f32_16x16x32_bf16 v[56:59], v[168:171], v[182:185], v[56:59]
	v_mfma_f32_16x16x32_bf16 v[52:55], v[160:163], v[190:193], v[52:55]
	v_mfma_f32_16x16x32_bf16 v[48:51], v[168:171], v[190:193], v[48:51]
	v_mfma_f32_16x16x32_bf16 v[28:31], v[160:163], v[198:201], v[28:31]
	v_mfma_f32_16x16x32_bf16 v[24:27], v[168:171], v[198:201], v[24:27]
	s_setprio 2
	s_barrier
; #define PG8_STAGE(bufoff, gbase, voff) do { _Pragma("unroll") for (int _i = 0; _i < 2; ++_i) \
;         __builtin_amdgcn_global_load_lds((const unsigned*)((const char*)(gbase) + (voff)[_i]), (LAS unsigned*)(lds + (bufoff) + ldsw + _i * 8192), 16, 0, 0); } while (0)
; #define PG8_LDA(dst, b, h) do { _Pragma("unroll") for (int m = 0; m < 4; ++m) _Pragma("unroll") for (int k = 0; k < 2; ++k) dst[m][k] = *(const LAS bf16x8*)(lds + PG8_SA(b, h) + aoff + m * 2048 + k * 1024); } while (0)
; #define PG8_LDB(dst, b, h) do { _Pragma("unroll") for (int n = 0; n < 2; ++n) _Pragma("unroll") for (int k = 0; k < 2; ++k) dst[n][k] = *(const LAS bf16x8*)(lds + PG8_SB(b, h) + boff + n * 2048 + k * 1024); } while (0)
; #define PG8_MMA(ai, bj, At, Bt) do { __builtin_amdgcn_s_setprio(1); _Pragma("unroll") for (int m = 0; m < 4; ++m) _Pragma("unroll") for (int n = 0; n < 2; ++n) _Pragma("unroll") for (int k = 0; k < 2; ++k) \
;         acc[ai][bj][m][n] = __builtin_amdgcn_mfma_f32_16x16x32_bf16(Bt[n][k], At[m][k], acc[ai][bj][m][n], 0, 0, 0); __builtin_amdgcn_s_setprio(0); } while (0)
; #define PG8_WAIT_V(n) asm volatile("s_waitcnt vmcnt(" #n ")" ::: "memory")
; #define PG8_WAIT_L(n) asm volatile("s_waitcnt lgkmcnt(" #n ")" ::: "memory")
; #define PG8_BAR __builtin_amdgcn_s_barrier()
; #define PG8_SCHED __builtin_amdgcn_sched_barrier(0)
; #define PG8_STAGE(bufoff, gbase, voff) do { _Pragma("unroll") for (int _i = 0; _i < 2; ++_i) \
;         __builtin_amdgcn_global_load_lds((const unsigned*)((const char*)(gbase) + (voff)[_i]), (LAS unsigned*)(lds + (bufoff) + ldsw + _i * 8192), 16, 0, 0); } while (0)
; #define PG8_BAR __builtin_amdgcn_s_barrier()
; template <class Epi0, class Epi1>
; DI void gemm_phase_dual(LAS unsigned char* lds, const Gemm g, const Gemm g1, const StaticOrder S, const Epi0 E0, const Epi1 E1) {
;     ...
;             PG8_BAR; PG8_WAIT_L(0); PG8_MMA(1, 0, At, B0); PG8_BAR; PG8_SCHED;
;             PG8_STAGE(PG8_SB(0, 1), b2 + hstep, voffB);
;             PG8_WAIT_V(6); PG8_BAR; PG8_MMA(1, 1, At, B1); PG8_BAR;
;             PG8_LDB(B0, 1, 0); PG8_SCHED; PG8_LDA(At, 1, 0); PG8_STAGE(PG8_SA(0, 1), a2 + hstep, voffA);
;             PG8_WAIT_L(8); PG8_BAR; PG8_WAIT_L(0); PG8_MMA(0, 0, At, B0); PG8_BAR; PG8_SCHED;
;             PG8_LDB(B1, 1, 1); PG8_STAGE(PG8_SB(1, 0), b3, voffB);
;             PG8_BAR; PG8_WAIT_L(0); PG8_MMA(0, 1, At, B1); PG8_BAR;
	v_mfma_f32_16x16x32_bf16 v[20:23], v[160:163], v[206:209], v[20:23]
	v_mfma_f32_16x16x32_bf16 v[16:19], v[168:171], v[206:209], v[16:19]
	s_setprio 0
	s_add_u32 s76, s40, 0x40000
	s_addc_u32 s77, s41, 0
	s_add_i32 s78, s53, s44
	v_lshl_add_u64 v[156:157], s[76:77], 0, v[130:131]
	s_mov_b32 m0, s78
	s_nop 0
	global_load_lds_dwordx4 v[156:157], off
	v_lshl_add_u64 v[156:157], s[76:77], 0, v[134:135]
	s_add_i32 m0, s78, 0x2000
	s_nop 0
	global_load_lds_dwordx4 v[156:157], off
	s_waitcnt vmcnt(6)
	s_barrier
	s_setprio 1
	v_mfma_f32_16x16x32_bf16 v[44:47], v[210:213], v[172:175], v[44:47]
	v_mfma_f32_16x16x32_bf16 v[40:43], v[218:221], v[172:175], v[40:43]
	v_mfma_f32_16x16x32_bf16 v[36:39], v[210:213], v[186:189], v[36:39]
	v_mfma_f32_16x16x32_bf16 v[32:35], v[218:221], v[186:189], v[32:35]
	v_mfma_f32_16x16x32_bf16 v[12:15], v[210:213], v[194:197], v[12:15]
	v_mfma_f32_16x16x32_bf16 v[8:11], v[218:221], v[194:197], v[8:11]
	v_mfma_f32_16x16x32_bf16 v[4:7], v[210:213], v[202:205], v[4:7]
	v_mfma_f32_16x16x32_bf16 v[0:3], v[218:221], v[202:205], v[0:3]
	v_mfma_f32_16x16x32_bf16 v[44:47], v[214:217], v[182:185], v[44:47]
	v_mfma_f32_16x16x32_bf16 v[40:43], v[224:227], v[182:185], v[40:43]
	v_mfma_f32_16x16x32_bf16 v[36:39], v[214:217], v[190:193], v[36:39]
	v_mfma_f32_16x16x32_bf16 v[32:35], v[224:227], v[190:193], v[32:35]
	v_mfma_f32_16x16x32_bf16 v[12:15], v[214:217], v[198:201], v[12:15]
	v_mfma_f32_16x16x32_bf16 v[8:11], v[224:227], v[198:201], v[8:11]
	s_setprio 2
	s_barrier
	v_mfma_f32_16x16x32_bf16 v[4:7], v[214:217], v[206:209], v[4:7]
	v_mfma_f32_16x16x32_bf16 v[0:3], v[224:227], v[206:209], v[0:3]
	s_setprio 0
	s_add_i32 s76, 0, 0x18000
	v_add_u32_e32 v168, s76, v177
	ds_read_b128 v[156:159], v168
	ds_read_b128 v[160:163], v168 offset:1024
	ds_read_b128 v[164:167], v168 offset:2048
	ds_read_b128 v[168:171], v168 offset:3072
	s_add_u32 s42, s42, 0x40000
	s_addc_u32 s43, s43, 0
	s_mov_b32 m0, s46
	v_lshl_add_u64 v[210:211], s[42:43], 0, v[128:129]
	ds_read_b128 v[172:175], v180 offset:32768
	ds_read_b128 v[182:185], v180 offset:33792
	ds_read_b128 v[186:189], v180 offset:34816
	ds_read_b128 v[190:193], v180 offset:35840
	ds_read_b128 v[194:197], v180 offset:36864
	ds_read_b128 v[198:201], v180 offset:37888
	ds_read_b128 v[202:205], v180 offset:38912
	ds_read_b128 v[206:209], v180 offset:39936
	global_load_lds_dwordx4 v[210:211], off
	v_lshl_add_u64 v[210:211], s[42:43], 0, v[132:133]
	s_mov_b32 m0, s47
	s_nop 0
	global_load_lds_dwordx4 v[210:211], off
	s_waitcnt lgkmcnt(8)
	s_barrier
	s_waitcnt lgkmcnt(0)
	s_setprio 1
	s_waitcnt lgkmcnt(0)
	v_mfma_f32_16x16x32_bf16 v[124:127], v[156:159], v[172:175], v[124:127]
	v_mfma_f32_16x16x32_bf16 v[120:123], v[164:167], v[172:175], v[120:123]
	v_mfma_f32_16x16x32_bf16 v[108:111], v[156:159], v[186:189], v[108:111]
	v_mfma_f32_16x16x32_bf16 v[104:107], v[164:167], v[186:189], v[104:107]
	v_mfma_f32_16x16x32_bf16 v[92:95], v[156:159], v[194:197], v[92:95]
	v_mfma_f32_16x16x32_bf16 v[88:91], v[164:167], v[194:197], v[88:91]
	v_mfma_f32_16x16x32_bf16 v[84:87], v[156:159], v[202:205], v[84:87]
	v_mfma_f32_16x16x32_bf16 v[80:83], v[164:167], v[202:205], v[80:83]
	v_mfma_f32_16x16x32_bf16 v[124:127], v[160:163], v[182:185], v[124:127]
	v_mfma_f32_16x16x32_bf16 v[120:123], v[168:171], v[182:185], v[120:123]
	v_mfma_f32_16x16x32_bf16 v[108:111], v[160:163], v[190:193], v[108:111]
	v_mfma_f32_16x16x32_bf16 v[104:107], v[168:171], v[190:193], v[104:107]
	v_mfma_f32_16x16x32_bf16 v[92:95], v[160:163], v[198:201], v[92:95]
	v_mfma_f32_16x16x32_bf16 v[88:91], v[168:171], v[198:201], v[88:91]
	s_setprio 2
	s_barrier
	v_mfma_f32_16x16x32_bf16 v[84:87], v[160:163], v[206:209], v[84:87]
	v_mfma_f32_16x16x32_bf16 v[80:83], v[168:171], v[206:209], v[80:83]
	s_setprio 0
	s_add_i32 s42, 0, 0x1c000
	s_add_i32 s43, s76, s44
	v_add_u32_e32 v224, s42, v177
	v_lshl_add_u64 v[228:229], v[228:229], 0, s[8:9]
	s_mov_b32 m0, s43
	ds_read_b128 v[210:213], v224
	ds_read_b128 v[214:217], v224 offset:1024
	ds_read_b128 v[218:221], v224 offset:2048
	ds_read_b128 v[224:227], v224 offset:3072
	global_load_lds_dwordx4 v[228:229], off
	v_lshl_add_u64 v[228:229], v[230:231], 0, s[8:9]
	s_add_i32 m0, s43, 0x2000
	s_nop 0
	global_load_lds_dwordx4 v[228:229], off
	s_barrier
	s_waitcnt lgkmcnt(0)
	s_setprio 1
	s_waitcnt lgkmcnt(0)
	v_mfma_f32_16x16x32_bf16 v[116:119], v[210:213], v[172:175], v[116:119]
	v_mfma_f32_16x16x32_bf16 v[112:115], v[218:221], v[172:175], v[112:115]
	v_mfma_f32_16x16x32_bf16 v[100:103], v[210:213], v[186:189], v[100:103]
	v_mfma_f32_16x16x32_bf16 v[96:99], v[218:221], v[186:189], v[96:99]
	v_mfma_f32_16x16x32_bf16 v[76:79], v[210:213], v[194:197], v[76:79]
	v_mfma_f32_16x16x32_bf16 v[72:75], v[218:221], v[194:197], v[72:75]
	v_mfma_f32_16x16x32_bf16 v[68:71], v[210:213], v[202:205], v[68:71]
	v_mfma_f32_16x16x32_bf16 v[64:67], v[218:221], v[202:205], v[64:67]
	v_mfma_f32_16x16x32_bf16 v[116:119], v[214:217], v[182:185], v[116:119]
	v_mfma_f32_16x16x32_bf16 v[112:115], v[224:227], v[182:185], v[112:115]
	v_mfma_f32_16x16x32_bf16 v[100:103], v[214:217], v[190:193], v[100:103]
	v_mfma_f32_16x16x32_bf16 v[96:99], v[224:227], v[190:193], v[96:99]
	v_mfma_f32_16x16x32_bf16 v[76:79], v[214:217], v[198:201], v[76:79]
	v_mfma_f32_16x16x32_bf16 v[72:75], v[224:227], v[198:201], v[72:75]
	s_setprio 2
	s_barrier
; #define PG8_STAGE(bufoff, gbase, voff) do { _Pragma("unroll") for (int _i = 0; _i < 2; ++_i) \
;         __builtin_amdgcn_global_load_lds((const unsigned*)((const char*)(gbase) + (voff)[_i]), (LAS unsigned*)(lds + (bufoff) + ldsw + _i * 8192), 16, 0, 0); } while (0)
; #define PG8_LDA(dst, b, h) do { _Pragma("unroll") for (int m = 0; m < 4; ++m) _Pragma("unroll") for (int k = 0; k < 2; ++k) dst[m][k] = *(const LAS bf16x8*)(lds + PG8_SA(b, h) + aoff + m * 2048 + k * 1024); } while (0)
; #define PG8_MMA(ai, bj, At, Bt) do { __builtin_amdgcn_s_setprio(1); _Pragma("unroll") for (int m = 0; m < 4; ++m) _Pragma("unroll") for (int n = 0; n < 2; ++n) _Pragma("unroll") for (int k = 0; k < 2; ++k) \
;         acc[ai][bj][m][n] = __builtin_amdgcn_mfma_f32_16x16x32_bf16(Bt[n][k], At[m][k], acc[ai][bj][m][n], 0, 0, 0); __builtin_amdgcn_s_setprio(0); } while (0)
; #define PG8_WAIT_V(n) asm volatile("s_waitcnt vmcnt(" #n ")" ::: "memory")
; #define PG8_WAIT_L(n) asm volatile("s_waitcnt lgkmcnt(" #n ")" ::: "memory")
; #define PG8_BAR __builtin_amdgcn_s_barrier()
; template <class Epi0, class Epi1>
; DI void gemm_phase_dual(LAS unsigned char* lds, const Gemm g, const Gemm g1, const StaticOrder S, const Epi0 E0, const Epi1 E1) {
;     ...
;             PG8_BAR; PG8_WAIT_L(0); PG8_MMA(0, 1, At, B1); PG8_BAR;
;             PG8_LDA(At, 1, 1); PG8_STAGE(PG8_SA(1, 0), a3, voffA);
;             PG8_BAR; PG8_WAIT_L(0); PG8_MMA(1, 0, At, B0); PG8_BAR; PG8_SCHED;
;             PG8_STAGE(PG8_SB(1, 1), b3 + hstep, voffB);
;             PG8_WAIT_V(6); PG8_BAR; PG8_MMA(1, 1, At, B1); PG8_BAR;
;         }
;         if (ui & 1) E1(acc, cur, wr, wc, fr, fq); else E0(acc, cur, wr, wc, fr, fq);
;     DI void operator()(AccRef acc, const Unit& u, int wr, int wc, int fr, int fq) const {
;     ...
;                 u32x4 gv[2][2], mv[2][2];
; #pragma unroll
;                 for (int mm = 0; mm < 2; ++mm)
; #pragma unroll
;                     for (int bj = 0; bj < 2; ++bj) {
;                         const size_t row = (size_t)(row0 + ai * 128 + (mh * 2 + mm) * 16); const int col = col0 + bj * 128;
;                         gv[mm][bj] = *(const u32x4*)(gab + (size_t)(u.pm * 8 + SECOND * 4 + u.pn) * 65536 + (wr * 64 + fr + ai * 128 + (mh * 2 + mm) * 16) * 256 + wc * 32 + 8 * fq + bj * 128);
;                         if (SECOND) mv[mm][bj] = *(const u32x4*)(mrg + row * 1024 + col);
;                     }
	v_mfma_f32_16x16x32_bf16 v[68:71], v[214:217], v[206:209], v[68:71]
	v_mfma_f32_16x16x32_bf16 v[64:67], v[224:227], v[206:209], v[64:67]
	s_setprio 0
	s_mov_b32 m0, s59
	v_lshl_add_u64 v[228:229], v[232:233], 0, s[8:9]
	ds_read_b128 v[172:175], v180 offset:49152
	ds_read_b128 v[182:185], v180 offset:50176
	ds_read_b128 v[186:189], v180 offset:51200
	ds_read_b128 v[190:193], v180 offset:52224
	ds_read_b128 v[194:197], v180 offset:53248
	ds_read_b128 v[198:201], v180 offset:54272
	ds_read_b128 v[202:205], v180 offset:55296
	ds_read_b128 v[206:209], v180 offset:56320
	global_load_lds_dwordx4 v[228:229], off
	v_lshl_add_u64 v[228:229], v[234:235], 0, s[8:9]
	s_mov_b32 m0, s60
	s_nop 0
	global_load_lds_dwordx4 v[228:229], off
	s_barrier
	s_waitcnt lgkmcnt(0)
	s_setprio 1
	s_waitcnt lgkmcnt(0)
	v_mfma_f32_16x16x32_bf16 v[60:63], v[156:159], v[172:175], v[60:63]
	v_mfma_f32_16x16x32_bf16 v[56:59], v[164:167], v[172:175], v[56:59]
	v_mfma_f32_16x16x32_bf16 v[52:55], v[156:159], v[186:189], v[52:55]
	v_mfma_f32_16x16x32_bf16 v[48:51], v[164:167], v[186:189], v[48:51]
	v_mfma_f32_16x16x32_bf16 v[28:31], v[156:159], v[194:197], v[28:31]
	v_mfma_f32_16x16x32_bf16 v[24:27], v[164:167], v[194:197], v[24:27]
	v_mfma_f32_16x16x32_bf16 v[20:23], v[156:159], v[202:205], v[20:23]
	v_mfma_f32_16x16x32_bf16 v[16:19], v[164:167], v[202:205], v[16:19]
	v_mfma_f32_16x16x32_bf16 v[60:63], v[160:163], v[182:185], v[60:63]
	v_mfma_f32_16x16x32_bf16 v[56:59], v[168:171], v[182:185], v[56:59]
	v_mfma_f32_16x16x32_bf16 v[52:55], v[160:163], v[190:193], v[52:55]
	v_mfma_f32_16x16x32_bf16 v[48:51], v[168:171], v[190:193], v[48:51]
	v_mfma_f32_16x16x32_bf16 v[28:31], v[160:163], v[198:201], v[28:31]
	v_mfma_f32_16x16x32_bf16 v[24:27], v[168:171], v[198:201], v[24:27]
	s_setprio 2
	s_barrier
	v_mfma_f32_16x16x32_bf16 v[20:23], v[160:163], v[206:209], v[20:23]
	v_mfma_f32_16x16x32_bf16 v[16:19], v[168:171], v[206:209], v[16:19]
	s_setprio 0
	s_add_u32 s40, s40, 0x40080
	s_addc_u32 s41, s41, 0
	s_add_i32 s42, s42, s44
	v_lshl_add_u64 v[156:157], s[40:41], 0, v[130:131]
	s_mov_b32 m0, s42
	s_nop 0
	global_load_lds_dwordx4 v[156:157], off
	v_lshl_add_u64 v[156:157], s[40:41], 0, v[134:135]
	s_add_i32 m0, s42, 0x2000
	s_nop 0
	global_load_lds_dwordx4 v[156:157], off
	s_waitcnt vmcnt(6)
	s_barrier
	s_setprio 1
	v_mfma_f32_16x16x32_bf16 v[44:47], v[210:213], v[172:175], v[44:47]
	v_mfma_f32_16x16x32_bf16 v[40:43], v[218:221], v[172:175], v[40:43]
	v_mfma_f32_16x16x32_bf16 v[36:39], v[210:213], v[186:189], v[36:39]
	v_mfma_f32_16x16x32_bf16 v[32:35], v[218:221], v[186:189], v[32:35]
	v_mfma_f32_16x16x32_bf16 v[12:15], v[210:213], v[194:197], v[12:15]
	v_mfma_f32_16x16x32_bf16 v[8:11], v[218:221], v[194:197], v[8:11]
	v_mfma_f32_16x16x32_bf16 v[4:7], v[210:213], v[202:205], v[4:7]
	v_mfma_f32_16x16x32_bf16 v[0:3], v[218:221], v[202:205], v[0:3]
	v_mfma_f32_16x16x32_bf16 v[44:47], v[214:217], v[182:185], v[44:47]
	v_mfma_f32_16x16x32_bf16 v[40:43], v[224:227], v[182:185], v[40:43]
	v_mfma_f32_16x16x32_bf16 v[36:39], v[214:217], v[190:193], v[36:39]
	v_mfma_f32_16x16x32_bf16 v[32:35], v[224:227], v[190:193], v[32:35]
	v_mfma_f32_16x16x32_bf16 v[12:15], v[214:217], v[198:201], v[12:15]
	v_mfma_f32_16x16x32_bf16 v[8:11], v[224:227], v[198:201], v[8:11]
	s_setprio 2
	s_barrier
	v_mfma_f32_16x16x32_bf16 v[4:7], v[214:217], v[206:209], v[4:7]
	v_mfma_f32_16x16x32_bf16 v[0:3], v[224:227], v[206:209], v[0:3]
	s_setprio 0
	s_add_i32 s69, s69, 2
	s_add_u32 s38, s38, 0x100
	s_addc_u32 s39, s39, 0
	s_add_u32 s67, s67, 0x100
	s_addc_u32 s68, s68, 0
	s_cmp_gt_u32 s69, 13
	s_cbranch_scc0 .LBB0_708
	v_lshl_add_u32 v164, s24, 8, v176
	s_lshl_b32 s17, s66, 8
	v_or_b32_e32 v162, s17, v178
	v_or_b32_e32 v160, 16, v164
	s_mov_b64 s[6:7], -1
	s_and_b64 vcc, exec, s[28:29]
	v_ashrrev_i32_e32 v165, 31, v164
	v_ashrrev_i32_e32 v163, 31, v162
	v_ashrrev_i32_e32 v161, 31, v160
	v_or_b32_e32 v158, 32, v164
	v_or_b32_e32 v156, 48, v164
	s_cbranch_vccz .LBB0_711
	s_lshl_b32 s6, s24, 3
	s_add_i32 s6, s66, s6
	s_add_i32 s6, s6, 4
	v_lshlrev_b64 v[168:169], 11, v[160:161]
	s_ashr_i32 s7, s6, 31
	v_lshlrev_b64 v[166:167], 11, v[164:165]
	v_lshlrev_b64 v[170:171], 1, v[162:163]
	v_lshl_add_u64 v[168:169], s[36:37], 0, v[168:169]
	s_lshl_b64 s[6:7], s[6:7], 17
	v_lshl_add_u64 v[166:167], s[36:37], 0, v[166:167]
	v_lshl_add_u64 v[174:175], v[168:169], 0, v[170:171]
	v_lshl_add_u64 v[168:169], v[136:137], 0, s[6:7]
	v_lshl_add_u64 v[166:167], v[166:167], 0, v[170:171]
	v_lshl_add_u64 v[172:173], v[138:139], 1, v[168:169]
	global_load_dwordx4 v[182:185], v[166:167], off
	global_load_dwordx4 v[186:189], v[166:167], off offset:256
	global_load_dwordx4 v[190:193], v[174:175], off
	global_load_dwordx4 v[194:197], v[172:173], off
	global_load_dwordx4 v[198:201], v[172:173], off offset:256
	v_add_co_u32_e32 v206, vcc, s48, v172
	v_ashrrev_i32_e32 v159, 31, v158
	s_nop 0
	v_addc_co_u32_e32 v207, vcc, 0, v173, vcc
	global_load_dwordx4 v[202:205], v[206:207], off
	s_nop 0
	global_load_dwordx4 v[206:209], v[206:207], off offset:256
	s_nop 0
	global_load_dwordx4 v[210:213], v[174:175], off offset:256
	v_ashrrev_i32_e32 v157, 31, v156
	s_mov_b64 s[6:7], 0
	s_waitcnt vmcnt(0)
; DI unsigned pk_bf16(float lo, float hi) { f32x2 v = {lo, hi}; return __builtin_bit_cast(unsigned, __builtin_convertvector(v, bf16v2)); }
; DI float bf_lo(unsigned w) { return __uint_as_float(w << 16); }
; DI float bf_hi(unsigned w) { return __uint_as_float(w & 0xffff0000u); }
;     DI void operator()(AccRef acc, const Unit& u, int wr, int wc, int fr, int fq) const {
;     ...
;                 for (int mm = 0; mm < 2; ++mm)
; #pragma unroll
;                     for (int bj = 0; bj < 2; ++bj) {
;                         const int m = mh * 2 + mm;
;                         const size_t row = (size_t)(row0 + ai * 128 + m * 16); const int col = col0 + bj * 128;
;                         const u32x4 gt = gv[mm][bj];
;                         const f32x4 r0 = acc[ai][bj][m][0], r1 = acc[ai][bj][m][1];
;                         float v[8] = {bf_lo(gt.x) * r0[0], bf_hi(gt.x) * r0[1], bf_lo(gt.y) * r0[2], bf_hi(gt.y) * r0[3], bf_lo(gt.z) * r1[0], bf_hi(gt.z) * r1[1], bf_lo(gt.w) * r1[2], bf_hi(gt.w) * r1[3]};
;                         if (SECOND) { const u32x4 o = mv[mm][bj]; v[0] += bf_lo(o.x); v[1] += bf_hi(o.x); v[2] += bf_lo(o.y); v[3] += bf_hi(o.y); v[4] += bf_lo(o.z); v[5] += bf_hi(o.z); v[6] += bf_lo(o.w); v[7] += bf_hi(o.w); }
;                         u32x4 w; w.x = pk_bf16(v[0], v[1]); w.y = pk_bf16(v[2], v[3]); w.z = pk_bf16(v[4], v[5]); w.w = pk_bf16(v[6], v[7]);
;                         *(u32x4*)(mrg + row * 1024 + col) = w;
	v_lshlrev_b32_e32 v214, 16, v182
	v_and_b32_e32 v215, 0xffff0000, v182
	v_lshlrev_b32_e32 v182, 16, v183
	v_and_b32_e32 v183, 0xffff0000, v183
	v_lshlrev_b32_e32 v216, 16, v184
	v_and_b32_e32 v217, 0xffff0000, v184
	v_lshlrev_b32_e32 v184, 16, v185
	v_and_b32_e32 v185, 0xffff0000, v185
	v_lshlrev_b32_e32 v228, 16, v194
	v_and_b32_e32 v229, 0xffff0000, v194
	v_lshlrev_b32_e32 v194, 16, v195
	v_and_b32_e32 v195, 0xffff0000, v195
	v_lshlrev_b32_e32 v230, 16, v196
	v_and_b32_e32 v231, 0xffff0000, v196
	v_lshlrev_b32_e32 v196, 16, v197
	v_and_b32_e32 v197, 0xffff0000, v197
	v_lshlrev_b32_e32 v218, 16, v186
	v_and_b32_e32 v219, 0xffff0000, v186
	v_lshlrev_b32_e32 v186, 16, v187
	v_and_b32_e32 v187, 0xffff0000, v187
	v_lshlrev_b32_e32 v220, 16, v188
	v_and_b32_e32 v221, 0xffff0000, v188
	v_lshlrev_b32_e32 v188, 16, v189
	v_and_b32_e32 v189, 0xffff0000, v189
	v_lshlrev_b32_e32 v232, 16, v198
	v_and_b32_e32 v233, 0xffff0000, v198
	v_lshlrev_b32_e32 v198, 16, v199
	v_and_b32_e32 v199, 0xffff0000, v199
	v_lshlrev_b32_e32 v234, 16, v200
	v_and_b32_e32 v235, 0xffff0000, v200
	v_lshlrev_b32_e32 v200, 16, v201
	v_and_b32_e32 v201, 0xffff0000, v201
	v_pk_fma_f32 v[214:215], v[124:125], v[228:229], v[214:215]
	v_pk_fma_f32 v[194:195], v[126:127], v[194:195], v[182:183]
	v_pk_fma_f32 v[216:217], v[120:121], v[230:231], v[216:217]
	v_pk_fma_f32 v[196:197], v[122:123], v[196:197], v[184:185]
	v_pk_fma_f32 v[218:219], v[116:117], v[232:233], v[218:219]
	v_pk_fma_f32 v[198:199], v[118:119], v[198:199], v[186:187]
	v_pk_fma_f32 v[220:221], v[112:113], v[234:235], v[220:221]
	v_pk_fma_f32 v[200:201], v[114:115], v[200:201], v[188:189]
	v_cvt_pk_bf16_f32 v182, v214, v215
	v_cvt_pk_bf16_f32 v183, v194, v195
	v_cvt_pk_bf16_f32 v184, v216, v217
	v_cvt_pk_bf16_f32 v185, v196, v197
	v_lshlrev_b32_e32 v224, 16, v190
	v_and_b32_e32 v225, 0xffff0000, v190
	v_lshlrev_b32_e32 v190, 16, v191
	v_and_b32_e32 v191, 0xffff0000, v191
	v_lshlrev_b32_e32 v226, 16, v192
	v_and_b32_e32 v227, 0xffff0000, v192
	v_lshlrev_b32_e32 v228, 16, v202
	v_and_b32_e32 v229, 0xffff0000, v202
	v_lshlrev_b32_e32 v202, 16, v203
	v_and_b32_e32 v203, 0xffff0000, v203
	v_lshlrev_b32_e32 v230, 16, v204
	v_and_b32_e32 v231, 0xffff0000, v204
	v_cvt_pk_bf16_f32 v186, v218, v219
	v_cvt_pk_bf16_f32 v187, v198, v199
	v_cvt_pk_bf16_f32 v188, v220, v221
	v_cvt_pk_bf16_f32 v189, v200, v201
	global_store_dwordx4 v[166:167], v[182:185], off
	global_store_dwordx4 v[166:167], v[186:189], off offset:256
	v_pk_fma_f32 v[194:195], v[108:109], v[228:229], v[224:225]
	v_lshlrev_b32_e32 v182, 16, v205
	v_and_b32_e32 v183, 0xffff0000, v205
	v_lshlrev_b32_e32 v184, 16, v193
	v_and_b32_e32 v185, 0xffff0000, v193
	v_pk_fma_f32 v[190:191], v[110:111], v[202:203], v[190:191]
	v_pk_fma_f32 v[196:197], v[104:105], v[230:231], v[226:227]
	v_pk_fma_f32 v[186:187], v[106:107], v[182:183], v[184:185]
	v_cvt_pk_bf16_f32 v182, v194, v195
	v_cvt_pk_bf16_f32 v183, v190, v191
	v_cvt_pk_bf16_f32 v184, v196, v197
	v_cvt_pk_bf16_f32 v185, v186, v187
	global_store_dwordx4 v[174:175], v[182:185], off
	v_lshlrev_b32_e32 v186, 16, v211
	v_and_b32_e32 v187, 0xffff0000, v211
	v_lshlrev_b32_e32 v182, 16, v206
	v_and_b32_e32 v183, 0xffff0000, v206
	v_lshlrev_b32_e32 v184, 16, v210
	v_and_b32_e32 v185, 0xffff0000, v210
	v_pk_fma_f32 v[182:183], v[100:101], v[182:183], v[184:185]
	v_lshlrev_b32_e32 v184, 16, v207
	v_and_b32_e32 v185, 0xffff0000, v207
	v_pk_fma_f32 v[184:185], v[102:103], v[184:185], v[186:187]
	v_lshlrev_b32_e32 v186, 16, v208
	v_and_b32_e32 v187, 0xffff0000, v208
	v_lshlrev_b32_e32 v188, 16, v212
	v_and_b32_e32 v189, 0xffff0000, v212
	v_pk_fma_f32 v[190:191], v[96:97], v[186:187], v[188:189]
	v_lshlrev_b32_e32 v186, 16, v209
	v_and_b32_e32 v187, 0xffff0000, v209
	v_lshlrev_b32_e32 v188, 16, v213
	v_and_b32_e32 v189, 0xffff0000, v213
	v_cvt_pk_bf16_f32 v182, v182, v183
	v_cvt_pk_bf16_f32 v183, v184, v185
	v_lshlrev_b64 v[184:185], 11, v[158:159]
	v_pk_fma_f32 v[192:193], v[98:99], v[186:187], v[188:189]
	v_lshl_add_u64 v[184:185], s[36:37], 0, v[184:185]
	v_lshl_add_u64 v[210:211], v[184:185], 0, v[170:171]
	v_cvt_pk_bf16_f32 v184, v190, v191
	v_cvt_pk_bf16_f32 v185, v192, v193
	global_load_dwordx4 v[186:189], v[210:211], off
	s_waitcnt vmcnt(0)
	v_lshlrev_b32_e32 v214, 16, v188
	global_store_dwordx4 v[174:175], v[182:185], off offset:256
	v_add_co_u32_e32 v174, vcc, s49, v172
	v_and_b32_e32 v215, 0xffff0000, v188
	s_nop 0
	v_addc_co_u32_e32 v175, vcc, 0, v173, vcc
	global_load_dwordx4 v[182:185], v[174:175], off
	global_load_dwordx4 v[190:193], v[174:175], off offset:256
	global_load_dwordx4 v[194:197], v[210:211], off offset:256
	v_add_co_u32_e32 v202, vcc, s50, v172
	v_lshlrev_b64 v[174:175], 11, v[156:157]
	s_nop 0
	v_addc_co_u32_e32 v203, vcc, 0, v173, vcc
	v_lshl_add_u64 v[198:199], s[36:37], 0, v[174:175]
	global_load_dwordx4 v[172:175], v[202:203], off
	v_lshl_add_u64 v[212:213], v[198:199], 0, v[170:171]
	global_load_dwordx4 v[198:201], v[212:213], off
	s_nop 0
	global_load_dwordx4 v[202:205], v[202:203], off offset:256
	s_nop 0
	global_load_dwordx4 v[206:209], v[212:213], off offset:256
	v_lshlrev_b32_e32 v170, 16, v186
	v_and_b32_e32 v171, 0xffff0000, v186
	v_lshlrev_b32_e32 v186, 16, v187
	v_and_b32_e32 v187, 0xffff0000, v187
	v_lshlrev_b32_e32 v188, 16, v189
	v_and_b32_e32 v189, 0xffff0000, v189
	s_waitcnt vmcnt(0)
; DI unsigned pk_bf16(float lo, float hi) { f32x2 v = {lo, hi}; return __builtin_bit_cast(unsigned, __builtin_convertvector(v, bf16v2)); }
; DI float bf_lo(unsigned w) { return __uint_as_float(w << 16); }
; DI float bf_hi(unsigned w) { return __uint_as_float(w & 0xffff0000u); }
;     DI void operator()(AccRef acc, const Unit& u, int wr, int wc, int fr, int fq) const {
;     ...
;                 for (int mm = 0; mm < 2; ++mm)
; #pragma unroll
;                     for (int bj = 0; bj < 2; ++bj) {
;                         const int m = mh * 2 + mm;
;                         const size_t row = (size_t)(row0 + ai * 128 + m * 16); const int col = col0 + bj * 128;
;                         const u32x4 gt = gv[mm][bj];
;                         const f32x4 r0 = acc[ai][bj][m][0], r1 = acc[ai][bj][m][1];
;                         float v[8] = {bf_lo(gt.x) * r0[0], bf_hi(gt.x) * r0[1], bf_lo(gt.y) * r0[2], bf_hi(gt.y) * r0[3], bf_lo(gt.z) * r1[0], bf_hi(gt.z) * r1[1], bf_lo(gt.w) * r1[2], bf_hi(gt.w) * r1[3]};
;                         if (SECOND) { const u32x4 o = mv[mm][bj]; v[0] += bf_lo(o.x); v[1] += bf_hi(o.x); v[2] += bf_lo(o.y); v[3] += bf_hi(o.y); v[4] += bf_lo(o.z); v[5] += bf_hi(o.z); v[6] += bf_lo(o.w); v[7] += bf_hi(o.w); }
;                         u32x4 w; w.x = pk_bf16(v[0], v[1]); w.y = pk_bf16(v[2], v[3]); w.z = pk_bf16(v[4], v[5]); w.w = pk_bf16(v[6], v[7]);
;                         *(u32x4*)(mrg + row * 1024 + col) = w;
	v_lshlrev_b32_e32 v216, 16, v182
	v_and_b32_e32 v217, 0xffff0000, v182
	v_lshlrev_b32_e32 v182, 16, v183
	v_and_b32_e32 v183, 0xffff0000, v183
	v_lshlrev_b32_e32 v218, 16, v184
	v_and_b32_e32 v219, 0xffff0000, v184
	v_lshlrev_b32_e32 v184, 16, v185
	v_and_b32_e32 v185, 0xffff0000, v185
	v_pk_fma_f32 v[170:171], v[92:93], v[216:217], v[170:171]
	v_pk_fma_f32 v[186:187], v[94:95], v[182:183], v[186:187]
	v_pk_fma_f32 v[214:215], v[88:89], v[218:219], v[214:215]
	v_pk_fma_f32 v[188:189], v[90:91], v[184:185], v[188:189]
	v_cvt_pk_bf16_f32 v182, v170, v171
	v_cvt_pk_bf16_f32 v183, v186, v187
	v_cvt_pk_bf16_f32 v184, v214, v215
	v_cvt_pk_bf16_f32 v185, v188, v189
	global_store_dwordx4 v[210:211], v[182:185], off
	v_lshlrev_b32_e32 v186, 16, v196
	v_and_b32_e32 v187, 0xffff0000, v196
	v_lshlrev_b32_e32 v182, 16, v191
	v_and_b32_e32 v183, 0xffff0000, v191
	v_lshlrev_b32_e32 v184, 16, v195
	v_and_b32_e32 v185, 0xffff0000, v195
	v_pk_fma_f32 v[184:185], v[78:79], v[182:183], v[184:185]
	v_lshlrev_b32_e32 v182, 16, v192
	v_and_b32_e32 v183, 0xffff0000, v192
	v_lshlrev_b32_e32 v220, 16, v190
	v_and_b32_e32 v221, 0xffff0000, v190
	v_lshlrev_b32_e32 v170, 16, v194
	v_and_b32_e32 v171, 0xffff0000, v194
	v_pk_fma_f32 v[186:187], v[72:73], v[182:183], v[186:187]
	v_lshlrev_b32_e32 v182, 16, v193
	v_and_b32_e32 v183, 0xffff0000, v193
	v_lshlrev_b32_e32 v188, 16, v197
	v_and_b32_e32 v189, 0xffff0000, v197
	v_pk_fma_f32 v[170:171], v[76:77], v[220:221], v[170:171]
	v_pk_fma_f32 v[188:189], v[74:75], v[182:183], v[188:189]
	v_cvt_pk_bf16_f32 v182, v170, v171
	v_cvt_pk_bf16_f32 v183, v184, v185
	v_cvt_pk_bf16_f32 v184, v186, v187
	v_cvt_pk_bf16_f32 v185, v188, v189
	global_store_dwordx4 v[210:211], v[182:185], off offset:256
	v_lshlrev_b32_e32 v170, 16, v172
	v_and_b32_e32 v171, 0xffff0000, v172
	v_lshlrev_b32_e32 v182, 16, v198
	v_and_b32_e32 v183, 0xffff0000, v198
	v_pk_fma_f32 v[170:171], v[84:85], v[170:171], v[182:183]
	v_lshlrev_b32_e32 v172, 16, v173
	v_and_b32_e32 v173, 0xffff0000, v173
	v_lshlrev_b32_e32 v182, 16, v199
	v_and_b32_e32 v183, 0xffff0000, v199
	v_pk_fma_f32 v[172:173], v[86:87], v[172:173], v[182:183]
	v_lshlrev_b32_e32 v182, 16, v174
	v_and_b32_e32 v183, 0xffff0000, v174
	v_lshlrev_b32_e32 v184, 16, v200
	v_and_b32_e32 v185, 0xffff0000, v200
	v_pk_fma_f32 v[182:183], v[80:81], v[182:183], v[184:185]
	v_lshlrev_b32_e32 v174, 16, v175
	v_and_b32_e32 v175, 0xffff0000, v175
	v_lshlrev_b32_e32 v184, 16, v201
	v_and_b32_e32 v185, 0xffff0000, v201
	v_pk_fma_f32 v[174:175], v[82:83], v[174:175], v[184:185]
	v_cvt_pk_bf16_f32 v170, v170, v171
	v_cvt_pk_bf16_f32 v171, v172, v173
	v_cvt_pk_bf16_f32 v172, v182, v183
	v_cvt_pk_bf16_f32 v173, v174, v175
	global_store_dwordx4 v[212:213], v[170:173], off
	v_lshlrev_b32_e32 v174, 16, v207
	v_and_b32_e32 v175, 0xffff0000, v207
	v_lshlrev_b32_e32 v170, 16, v202
	v_and_b32_e32 v171, 0xffff0000, v202
	v_lshlrev_b32_e32 v172, 16, v206
	v_and_b32_e32 v173, 0xffff0000, v206
	v_pk_fma_f32 v[170:171], v[68:69], v[170:171], v[172:173]
	v_lshlrev_b32_e32 v172, 16, v203
	v_and_b32_e32 v173, 0xffff0000, v203
	v_pk_fma_f32 v[172:173], v[70:71], v[172:173], v[174:175]
	v_lshlrev_b32_e32 v174, 16, v204
	v_and_b32_e32 v175, 0xffff0000, v204
	v_lshlrev_b32_e32 v182, 16, v208
	v_and_b32_e32 v183, 0xffff0000, v208
	v_pk_fma_f32 v[174:175], v[64:65], v[174:175], v[182:183]
	v_lshlrev_b32_e32 v182, 16, v205
	v_and_b32_e32 v183, 0xffff0000, v205
	v_lshlrev_b32_e32 v184, 16, v209
	v_and_b32_e32 v185, 0xffff0000, v209
	v_pk_fma_f32 v[182:183], v[66:67], v[182:183], v[184:185]
	v_cvt_pk_bf16_f32 v170, v170, v171
	v_cvt_pk_bf16_f32 v171, v172, v173
	v_cvt_pk_bf16_f32 v172, v174, v175
	v_cvt_pk_bf16_f32 v173, v182, v183
	global_store_dwordx4 v[212:213], v[170:173], off offset:256
	v_lshl_add_u64 v[174:175], v[140:141], 1, v[168:169]
	v_add_co_u32_e32 v210, vcc, s61, v166
	global_load_dwordx4 v[170:173], v[174:175], off
	s_nop 0
	v_addc_co_u32_e32 v211, vcc, 0, v167, vcc
	global_load_dwordx4 v[182:185], v[210:211], off
	global_load_dwordx4 v[186:189], v[174:175], off offset:256
	v_lshl_add_u64 v[174:175], v[166:167], 0, s[0:1]
	global_load_dwordx4 v[190:193], v[174:175], off offset:256
	v_lshl_add_u64 v[202:203], v[142:143], 1, v[168:169]
	v_add_co_u32_e32 v212, vcc, s62, v166
	global_load_dwordx4 v[194:197], v[202:203], off
	s_nop 0
	v_addc_co_u32_e32 v213, vcc, 0, v167, vcc
	global_load_dwordx4 v[198:201], v[212:213], off
	s_nop 0
	global_load_dwordx4 v[202:205], v[202:203], off offset:256
	v_lshl_add_u64 v[214:215], v[166:167], 0, s[10:11]
	global_load_dwordx4 v[206:209], v[214:215], off offset:256
	s_waitcnt vmcnt(0)
; DI unsigned pk_bf16(float lo, float hi) { f32x2 v = {lo, hi}; return __builtin_bit_cast(unsigned, __builtin_convertvector(v, bf16v2)); }
; DI float bf_lo(unsigned w) { return __uint_as_float(w << 16); }
; DI float bf_hi(unsigned w) { return __uint_as_float(w & 0xffff0000u); }
;     DI void operator()(AccRef acc, const Unit& u, int wr, int wc, int fr, int fq) const {
;     ...
;                 for (int mm = 0; mm < 2; ++mm)
; #pragma unroll
;                     for (int bj = 0; bj < 2; ++bj) {
;                         const int m = mh * 2 + mm;
;                         const size_t row = (size_t)(row0 + ai * 128 + m * 16); const int col = col0 + bj * 128;
;                         const u32x4 gt = gv[mm][bj];
;                         const f32x4 r0 = acc[ai][bj][m][0], r1 = acc[ai][bj][m][1];
;                         float v[8] = {bf_lo(gt.x) * r0[0], bf_hi(gt.x) * r0[1], bf_lo(gt.y) * r0[2], bf_hi(gt.y) * r0[3], bf_lo(gt.z) * r1[0], bf_hi(gt.z) * r1[1], bf_lo(gt.w) * r1[2], bf_hi(gt.w) * r1[3]};
;                         if (SECOND) { const u32x4 o = mv[mm][bj]; v[0] += bf_lo(o.x); v[1] += bf_hi(o.x); v[2] += bf_lo(o.y); v[3] += bf_hi(o.y); v[4] += bf_lo(o.z); v[5] += bf_hi(o.z); v[6] += bf_lo(o.w); v[7] += bf_hi(o.w); }
;                         u32x4 w; w.x = pk_bf16(v[0], v[1]); w.y = pk_bf16(v[2], v[3]); w.z = pk_bf16(v[4], v[5]); w.w = pk_bf16(v[6], v[7]);
;                         *(u32x4*)(mrg + row * 1024 + col) = w;
	v_lshlrev_b32_e32 v216, 16, v170
	v_and_b32_e32 v217, 0xffff0000, v170
	v_lshlrev_b32_e32 v218, 16, v182
	v_and_b32_e32 v219, 0xffff0000, v182
	v_lshlrev_b32_e32 v170, 16, v171
	v_and_b32_e32 v171, 0xffff0000, v171
	v_lshlrev_b32_e32 v182, 16, v183
	v_and_b32_e32 v183, 0xffff0000, v183
	v_pk_fma_f32 v[216:217], v[60:61], v[216:217], v[218:219]
	v_pk_fma_f32 v[182:183], v[62:63], v[170:171], v[182:183]
	v_lshlrev_b32_e32 v170, 16, v172
	v_and_b32_e32 v171, 0xffff0000, v172
	v_lshlrev_b32_e32 v218, 16, v184
	v_and_b32_e32 v219, 0xffff0000, v184
	v_pk_fma_f32 v[218:219], v[56:57], v[170:171], v[218:219]
	v_lshlrev_b32_e32 v170, 16, v173
	v_and_b32_e32 v171, 0xffff0000, v173
	v_lshlrev_b32_e32 v172, 16, v185
	v_and_b32_e32 v173, 0xffff0000, v185
	v_pk_fma_f32 v[184:185], v[58:59], v[170:171], v[172:173]
	v_cvt_pk_bf16_f32 v170, v216, v217
	v_cvt_pk_bf16_f32 v171, v182, v183
	v_cvt_pk_bf16_f32 v172, v218, v219
	v_cvt_pk_bf16_f32 v173, v184, v185
	global_store_dwordx4 v[210:211], v[170:173], off
	v_lshlrev_b32_e32 v182, 16, v191
	v_and_b32_e32 v183, 0xffff0000, v191
	v_lshlrev_b32_e32 v170, 16, v186
	v_and_b32_e32 v171, 0xffff0000, v186
	v_lshlrev_b32_e32 v172, 16, v190
	v_and_b32_e32 v173, 0xffff0000, v190
	v_pk_fma_f32 v[170:171], v[44:45], v[170:171], v[172:173]
	v_lshlrev_b32_e32 v172, 16, v187
	v_and_b32_e32 v173, 0xffff0000, v187
	v_pk_fma_f32 v[172:173], v[46:47], v[172:173], v[182:183]
	v_lshlrev_b32_e32 v182, 16, v188
	v_and_b32_e32 v183, 0xffff0000, v188
	v_lshlrev_b32_e32 v184, 16, v192
	v_and_b32_e32 v185, 0xffff0000, v192
	v_pk_fma_f32 v[182:183], v[40:41], v[182:183], v[184:185]
	v_lshlrev_b32_e32 v184, 16, v189
	v_and_b32_e32 v185, 0xffff0000, v189
	v_lshlrev_b32_e32 v186, 16, v193
	v_and_b32_e32 v187, 0xffff0000, v193
	v_pk_fma_f32 v[184:185], v[42:43], v[184:185], v[186:187]
	v_cvt_pk_bf16_f32 v170, v170, v171
	v_cvt_pk_bf16_f32 v171, v172, v173
	v_cvt_pk_bf16_f32 v172, v182, v183
	v_cvt_pk_bf16_f32 v173, v184, v185
	global_store_dwordx4 v[174:175], v[170:173], off offset:256
	v_lshlrev_b32_e32 v174, 16, v199
	v_and_b32_e32 v175, 0xffff0000, v199
	v_lshlrev_b32_e32 v170, 16, v194
	v_and_b32_e32 v171, 0xffff0000, v194
	v_lshlrev_b32_e32 v172, 16, v198
	v_and_b32_e32 v173, 0xffff0000, v198
	v_pk_fma_f32 v[170:171], v[52:53], v[170:171], v[172:173]
	v_lshlrev_b32_e32 v172, 16, v195
	v_and_b32_e32 v173, 0xffff0000, v195
	v_pk_fma_f32 v[172:173], v[54:55], v[172:173], v[174:175]
	v_lshlrev_b32_e32 v174, 16, v196
	v_and_b32_e32 v175, 0xffff0000, v196
	v_lshlrev_b32_e32 v182, 16, v200
	v_and_b32_e32 v183, 0xffff0000, v200
	v_pk_fma_f32 v[174:175], v[48:49], v[174:175], v[182:183]
	v_lshlrev_b32_e32 v182, 16, v197
	v_and_b32_e32 v183, 0xffff0000, v197
	v_lshlrev_b32_e32 v184, 16, v201
	v_and_b32_e32 v185, 0xffff0000, v201
	v_pk_fma_f32 v[182:183], v[50:51], v[182:183], v[184:185]
	v_cvt_pk_bf16_f32 v170, v170, v171
	v_cvt_pk_bf16_f32 v171, v172, v173
	v_cvt_pk_bf16_f32 v172, v174, v175
	v_cvt_pk_bf16_f32 v173, v182, v183
	global_store_dwordx4 v[212:213], v[170:173], off
	v_lshlrev_b32_e32 v174, 16, v207
	v_and_b32_e32 v175, 0xffff0000, v207
	v_lshlrev_b32_e32 v170, 16, v202
	v_and_b32_e32 v171, 0xffff0000, v202
	v_lshlrev_b32_e32 v172, 16, v206
	v_and_b32_e32 v173, 0xffff0000, v206
	v_pk_fma_f32 v[170:171], v[36:37], v[170:171], v[172:173]
	v_lshlrev_b32_e32 v172, 16, v203
	v_and_b32_e32 v173, 0xffff0000, v203
	v_pk_fma_f32 v[172:173], v[38:39], v[172:173], v[174:175]
	v_lshlrev_b32_e32 v174, 16, v204
	v_and_b32_e32 v175, 0xffff0000, v204
	v_lshlrev_b32_e32 v182, 16, v208
	v_and_b32_e32 v183, 0xffff0000, v208
	v_pk_fma_f32 v[174:175], v[32:33], v[174:175], v[182:183]
	v_lshlrev_b32_e32 v182, 16, v205
	v_and_b32_e32 v183, 0xffff0000, v205
	v_lshlrev_b32_e32 v184, 16, v209
	v_and_b32_e32 v185, 0xffff0000, v209
	v_pk_fma_f32 v[182:183], v[34:35], v[182:183], v[184:185]
	v_cvt_pk_bf16_f32 v170, v170, v171
	v_cvt_pk_bf16_f32 v171, v172, v173
	v_cvt_pk_bf16_f32 v172, v174, v175
	v_cvt_pk_bf16_f32 v173, v182, v183
	global_store_dwordx4 v[214:215], v[170:173], off offset:256
	v_lshl_add_u64 v[174:175], v[144:145], 1, v[168:169]
	v_add_co_u32_e32 v206, vcc, s63, v166
	global_load_dwordx4 v[170:173], v[174:175], off
	s_nop 0
	v_addc_co_u32_e32 v207, vcc, 0, v167, vcc
	global_load_dwordx4 v[182:185], v[206:207], off
	global_load_dwordx4 v[186:189], v[174:175], off offset:256
	v_lshl_add_u64 v[174:175], v[166:167], 0, s[12:13]
	global_load_dwordx4 v[190:193], v[174:175], off offset:256
	v_lshl_add_u64 v[168:169], v[146:147], 1, v[168:169]
	v_add_co_u32_e32 v208, vcc, s64, v166
	global_load_dwordx4 v[194:197], v[168:169], off
	s_nop 0
	v_addc_co_u32_e32 v209, vcc, 0, v167, vcc
	global_load_dwordx4 v[198:201], v[208:209], off
	global_load_dwordx4 v[202:205], v[168:169], off offset:256
	v_lshl_add_u64 v[210:211], v[166:167], 0, s[14:15]
	global_load_dwordx4 v[166:169], v[210:211], off offset:256
	s_waitcnt vmcnt(0)
; DI unsigned pk_bf16(float lo, float hi) { f32x2 v = {lo, hi}; return __builtin_bit_cast(unsigned, __builtin_convertvector(v, bf16v2)); }
; DI float bf_lo(unsigned w) { return __uint_as_float(w << 16); }
; DI float bf_hi(unsigned w) { return __uint_as_float(w & 0xffff0000u); }
;     DI void operator()(AccRef acc, const Unit& u, int wr, int wc, int fr, int fq) const {
;     ...
;                 for (int mm = 0; mm < 2; ++mm)
; #pragma unroll
;                     for (int bj = 0; bj < 2; ++bj) {
;                         const int m = mh * 2 + mm;
;                         const size_t row = (size_t)(row0 + ai * 128 + m * 16); const int col = col0 + bj * 128;
;                         const u32x4 gt = gv[mm][bj];
;                         const f32x4 r0 = acc[ai][bj][m][0], r1 = acc[ai][bj][m][1];
;                         float v[8] = {bf_lo(gt.x) * r0[0], bf_hi(gt.x) * r0[1], bf_lo(gt.y) * r0[2], bf_hi(gt.y) * r0[3], bf_lo(gt.z) * r1[0], bf_hi(gt.z) * r1[1], bf_lo(gt.w) * r1[2], bf_hi(gt.w) * r1[3]};
;                         if (SECOND) { const u32x4 o = mv[mm][bj]; v[0] += bf_lo(o.x); v[1] += bf_hi(o.x); v[2] += bf_lo(o.y); v[3] += bf_hi(o.y); v[4] += bf_lo(o.z); v[5] += bf_hi(o.z); v[6] += bf_lo(o.w); v[7] += bf_hi(o.w); }
;                         u32x4 w; w.x = pk_bf16(v[0], v[1]); w.y = pk_bf16(v[2], v[3]); w.z = pk_bf16(v[4], v[5]); w.w = pk_bf16(v[6], v[7]);
;                         *(u32x4*)(mrg + row * 1024 + col) = w;
	v_lshlrev_b32_e32 v212, 16, v170
	v_and_b32_e32 v213, 0xffff0000, v170
	v_lshlrev_b32_e32 v214, 16, v182
	v_and_b32_e32 v215, 0xffff0000, v182
	v_lshlrev_b32_e32 v170, 16, v171
	v_and_b32_e32 v171, 0xffff0000, v171
	v_lshlrev_b32_e32 v182, 16, v183
	v_and_b32_e32 v183, 0xffff0000, v183
	v_pk_fma_f32 v[212:213], v[28:29], v[212:213], v[214:215]
	v_pk_fma_f32 v[182:183], v[30:31], v[170:171], v[182:183]
	v_lshlrev_b32_e32 v170, 16, v172
	v_and_b32_e32 v171, 0xffff0000, v172
	v_lshlrev_b32_e32 v214, 16, v184
	v_and_b32_e32 v215, 0xffff0000, v184
	v_pk_fma_f32 v[214:215], v[24:25], v[170:171], v[214:215]
	v_lshlrev_b32_e32 v170, 16, v173
	v_and_b32_e32 v171, 0xffff0000, v173
	v_lshlrev_b32_e32 v172, 16, v185
	v_and_b32_e32 v173, 0xffff0000, v185
	v_pk_fma_f32 v[184:185], v[26:27], v[170:171], v[172:173]
	v_cvt_pk_bf16_f32 v170, v212, v213
	v_cvt_pk_bf16_f32 v171, v182, v183
	v_cvt_pk_bf16_f32 v172, v214, v215
	v_cvt_pk_bf16_f32 v173, v184, v185
	global_store_dwordx4 v[206:207], v[170:173], off
	v_lshlrev_b32_e32 v182, 16, v191
	v_and_b32_e32 v183, 0xffff0000, v191
	v_lshlrev_b32_e32 v170, 16, v186
	v_and_b32_e32 v171, 0xffff0000, v186
	v_lshlrev_b32_e32 v172, 16, v190
	v_and_b32_e32 v173, 0xffff0000, v190
	v_pk_fma_f32 v[170:171], v[12:13], v[170:171], v[172:173]
	v_lshlrev_b32_e32 v172, 16, v187
	v_and_b32_e32 v173, 0xffff0000, v187
	v_pk_fma_f32 v[172:173], v[14:15], v[172:173], v[182:183]
	v_lshlrev_b32_e32 v182, 16, v188
	v_and_b32_e32 v183, 0xffff0000, v188
	v_lshlrev_b32_e32 v184, 16, v192
	v_and_b32_e32 v185, 0xffff0000, v192
	v_pk_fma_f32 v[182:183], v[8:9], v[182:183], v[184:185]
	v_lshlrev_b32_e32 v184, 16, v189
	v_and_b32_e32 v185, 0xffff0000, v189
	v_lshlrev_b32_e32 v186, 16, v193
	v_and_b32_e32 v187, 0xffff0000, v193
	v_pk_fma_f32 v[184:185], v[10:11], v[184:185], v[186:187]
	v_cvt_pk_bf16_f32 v170, v170, v171
	v_cvt_pk_bf16_f32 v171, v172, v173
	v_cvt_pk_bf16_f32 v172, v182, v183
	v_cvt_pk_bf16_f32 v173, v184, v185
	global_store_dwordx4 v[174:175], v[170:173], off offset:256
	v_lshlrev_b32_e32 v174, 16, v199
	v_and_b32_e32 v175, 0xffff0000, v199
	v_lshlrev_b32_e32 v170, 16, v194
	v_and_b32_e32 v171, 0xffff0000, v194
	v_lshlrev_b32_e32 v172, 16, v198
	v_and_b32_e32 v173, 0xffff0000, v198
	v_pk_fma_f32 v[170:171], v[20:21], v[170:171], v[172:173]
	v_lshlrev_b32_e32 v172, 16, v195
	v_and_b32_e32 v173, 0xffff0000, v195
	v_pk_fma_f32 v[172:173], v[22:23], v[172:173], v[174:175]
	v_lshlrev_b32_e32 v174, 16, v196
	v_and_b32_e32 v175, 0xffff0000, v196
	v_lshlrev_b32_e32 v182, 16, v200
	v_and_b32_e32 v183, 0xffff0000, v200
	v_pk_fma_f32 v[174:175], v[16:17], v[174:175], v[182:183]
	v_lshlrev_b32_e32 v182, 16, v197
	v_and_b32_e32 v183, 0xffff0000, v197
	v_lshlrev_b32_e32 v184, 16, v201
	v_and_b32_e32 v185, 0xffff0000, v201
	v_pk_fma_f32 v[182:183], v[18:19], v[182:183], v[184:185]
	v_cvt_pk_bf16_f32 v170, v170, v171
	v_cvt_pk_bf16_f32 v171, v172, v173
	v_cvt_pk_bf16_f32 v172, v174, v175
	v_cvt_pk_bf16_f32 v173, v182, v183
	global_store_dwordx4 v[208:209], v[170:173], off
	v_lshlrev_b32_e32 v174, 16, v168
	v_and_b32_e32 v175, 0xffff0000, v168
	v_lshlrev_b32_e32 v170, 16, v202
	v_and_b32_e32 v171, 0xffff0000, v202
	v_lshlrev_b32_e32 v172, 16, v166
	v_and_b32_e32 v173, 0xffff0000, v166
	v_pk_fma_f32 v[170:171], v[4:5], v[170:171], v[172:173]
	v_lshlrev_b32_e32 v172, 16, v203
	v_and_b32_e32 v173, 0xffff0000, v203
	v_lshlrev_b32_e32 v166, 16, v167
	v_and_b32_e32 v167, 0xffff0000, v167
	v_pk_fma_f32 v[172:173], v[6:7], v[172:173], v[166:167]
	v_lshlrev_b32_e32 v166, 16, v204
	v_and_b32_e32 v167, 0xffff0000, v204
	v_pk_fma_f32 v[174:175], v[0:1], v[166:167], v[174:175]
	v_lshlrev_b32_e32 v166, 16, v205
	v_and_b32_e32 v167, 0xffff0000, v205
	v_lshlrev_b32_e32 v168, 16, v169
	v_and_b32_e32 v169, 0xffff0000, v169
	v_pk_fma_f32 v[182:183], v[2:3], v[166:167], v[168:169]
	v_cvt_pk_bf16_f32 v166, v170, v171
	v_cvt_pk_bf16_f32 v167, v172, v173
	v_cvt_pk_bf16_f32 v168, v174, v175
	v_cvt_pk_bf16_f32 v169, v182, v183
	global_store_dwordx4 v[210:211], v[166:169], off offset:256

; #define PG8_STAGE(bufoff, gbase, voff) do { _Pragma("unroll") for (int _i = 0; _i < 2; ++_i) \
;         __builtin_amdgcn_global_load_lds((const unsigned*)((const char*)(gbase) + (voff)[_i]), (LAS unsigned*)(lds + (bufoff) + ldsw + _i * 8192), 16, 0, 0); } while (0)
; #define PG8_LDA(dst, b, h) do { _Pragma("unroll") for (int m = 0; m < 4; ++m) _Pragma("unroll") for (int k = 0; k < 2; ++k) dst[m][k] = *(const LAS bf16x8*)(lds + PG8_SA(b, h) + aoff + m * 2048 + k * 1024); } while (0)
; #define PG8_LDB(dst, b, h) do { _Pragma("unroll") for (int n = 0; n < 2; ++n) _Pragma("unroll") for (int k = 0; k < 2; ++k) dst[n][k] = *(const LAS bf16x8*)(lds + PG8_SB(b, h) + boff + n * 2048 + k * 1024); } while (0)
; #define PG8_MMA(ai, bj, At, Bt) do { __builtin_amdgcn_s_setprio(1); _Pragma("unroll") for (int m = 0; m < 4; ++m) _Pragma("unroll") for (int n = 0; n < 2; ++n) _Pragma("unroll") for (int k = 0; k < 2; ++k) \
;         acc[ai][bj][m][n] = __builtin_amdgcn_mfma_f32_16x16x32_bf16(Bt[n][k], At[m][k], acc[ai][bj][m][n], 0, 0, 0); __builtin_amdgcn_s_setprio(0); } while (0)
; #define PG8_WAIT_L(n) asm volatile("s_waitcnt lgkmcnt(" #n ")" ::: "memory")
; #define PG8_BAR __builtin_amdgcn_s_barrier()
; #define PG8_SCHED __builtin_amdgcn_sched_barrier(0)
; #define PG8_STAGE(bufoff, gbase, voff) do { _Pragma("unroll") for (int _i = 0; _i < 2; ++_i) \
;         __builtin_amdgcn_global_load_lds((const unsigned*)((const char*)(gbase) + (voff)[_i]), (LAS unsigned*)(lds + (bufoff) + ldsw + _i * 8192), 16, 0, 0); } while (0)
; #define PG8_LDA(dst, b, h) do { _Pragma("unroll") for (int m = 0; m < 4; ++m) _Pragma("unroll") for (int k = 0; k < 2; ++k) dst[m][k] = *(const LAS bf16x8*)(lds + PG8_SA(b, h) + aoff + m * 2048 + k * 1024); } while (0)
; template <class Epi>
; DI void gemm_phase(LAS unsigned char* lds, const Gemm g, const StaticOrder S, const Epi E) {
;     ...
;             PG8_LDB(B0, 0, 0); PG8_SCHED; PG8_LDA(At, 0, 0); PG8_STAGE(PG8_SA(1, 1), a1 + hstep, voffA);
;             PG8_WAIT_L(8); PG8_BAR; PG8_WAIT_L(0); PG8_MMA(0, 0, At, B0); PG8_BAR; PG8_SCHED;
;             PG8_LDB(B1, 0, 1); PG8_STAGE(PG8_SB(0, 0), b2, voffB);
;             PG8_BAR; PG8_WAIT_L(0); PG8_MMA(0, 1, At, B1); PG8_BAR;
;             PG8_LDA(At, 0, 1); PG8_STAGE(PG8_SA(0, 0), a2, voffA);
;             PG8_BAR; PG8_WAIT_L(0); PG8_MMA(1, 0, At, B0); PG8_BAR; PG8_SCHED;
.LBB0_786:
	ds_read_b128 v[128:131], v187
	ds_read_b128 v[132:135], v187 offset:1024
	ds_read_b128 v[136:139], v187 offset:2048
	ds_read_b128 v[140:143], v187 offset:3072
	s_add_u32 s28, s24, 0xfffc0080
	s_addc_u32 s29, s25, -1
	s_cmp_eq_u32 s52, 12
	s_cselect_b32 s39, s6, s29
	s_cselect_b32 s38, s7, s28
	s_cselect_b32 s29, s11, s51
	s_cselect_b32 s28, s13, s50
	v_lshl_add_u64 v[200:201], s[24:25], 0, v[160:161]
	s_add_i32 m0, s19, 0xc000
	ds_read_b128 v[144:147], v188
	ds_read_b128 v[148:151], v188 offset:1024
	ds_read_b128 v[168:171], v188 offset:2048
	ds_read_b128 v[172:175], v188 offset:3072
	ds_read_b128 v[176:179], v188 offset:4096
	ds_read_b128 v[180:183], v188 offset:5120
	ds_read_b128 v[192:195], v188 offset:6144
	ds_read_b128 v[196:199], v188 offset:7168
	global_load_lds_dwordx4 v[200:201], off
	v_lshl_add_u64 v[200:201], s[24:25], 0, v[162:163]
	s_add_i32 m0, s19, 0xe000
	s_nop 0
	global_load_lds_dwordx4 v[200:201], off
	s_waitcnt lgkmcnt(8)
	s_barrier
	s_waitcnt lgkmcnt(0)
	s_setprio 1
	s_waitcnt lgkmcnt(0)
	v_mfma_f32_16x16x32_bf16 v[124:127], v[128:131], v[144:147], v[124:127]
	v_mfma_f32_16x16x32_bf16 v[120:123], v[136:139], v[144:147], v[120:123]
	v_mfma_f32_16x16x32_bf16 v[108:111], v[128:131], v[168:171], v[108:111]
	v_mfma_f32_16x16x32_bf16 v[104:107], v[136:139], v[168:171], v[104:107]
	v_mfma_f32_16x16x32_bf16 v[92:95], v[128:131], v[176:179], v[92:95]
	v_mfma_f32_16x16x32_bf16 v[88:91], v[136:139], v[176:179], v[88:91]
	v_mfma_f32_16x16x32_bf16 v[76:79], v[128:131], v[192:195], v[76:79]
	v_mfma_f32_16x16x32_bf16 v[72:75], v[136:139], v[192:195], v[72:75]
	v_mfma_f32_16x16x32_bf16 v[124:127], v[132:135], v[148:151], v[124:127]
	v_mfma_f32_16x16x32_bf16 v[120:123], v[140:143], v[148:151], v[120:123]
	v_mfma_f32_16x16x32_bf16 v[108:111], v[132:135], v[172:175], v[108:111]
	v_mfma_f32_16x16x32_bf16 v[104:107], v[140:143], v[172:175], v[104:107]
	v_mfma_f32_16x16x32_bf16 v[92:95], v[132:135], v[180:183], v[92:95]
	v_mfma_f32_16x16x32_bf16 v[88:91], v[140:143], v[180:183], v[88:91]
	s_setprio 2
	s_barrier
	v_mfma_f32_16x16x32_bf16 v[76:79], v[132:135], v[196:199], v[76:79]
	v_mfma_f32_16x16x32_bf16 v[72:75], v[140:143], v[196:199], v[72:75]
	s_setprio 0
	s_add_i32 s53, s48, s40
	v_lshl_add_u64 v[216:217], s[28:29], 0, v[154:155]
	s_mov_b32 m0, s53
	ds_read_b128 v[200:203], v189
	ds_read_b128 v[204:207], v189 offset:1024
	ds_read_b128 v[208:211], v189 offset:2048
	ds_read_b128 v[212:215], v189 offset:3072
	global_load_lds_dwordx4 v[216:217], off
	v_lshl_add_u64 v[218:219], s[28:29], 0, v[158:159]
	s_add_i32 m0, s53, 0x2000
	s_nop 0
	global_load_lds_dwordx4 v[218:219], off
	s_barrier
	s_waitcnt lgkmcnt(0)
	s_setprio 1
	s_waitcnt lgkmcnt(0)
	v_mfma_f32_16x16x32_bf16 v[116:119], v[200:203], v[144:147], v[116:119]
	v_mfma_f32_16x16x32_bf16 v[112:115], v[208:211], v[144:147], v[112:115]
	v_mfma_f32_16x16x32_bf16 v[100:103], v[200:203], v[168:171], v[100:103]
	v_mfma_f32_16x16x32_bf16 v[96:99], v[208:211], v[168:171], v[96:99]
	v_mfma_f32_16x16x32_bf16 v[84:87], v[200:203], v[176:179], v[84:87]
	v_mfma_f32_16x16x32_bf16 v[80:83], v[208:211], v[176:179], v[80:83]
	v_mfma_f32_16x16x32_bf16 v[68:71], v[200:203], v[192:195], v[68:71]
	v_mfma_f32_16x16x32_bf16 v[64:67], v[208:211], v[192:195], v[64:67]
	v_mfma_f32_16x16x32_bf16 v[116:119], v[204:207], v[148:151], v[116:119]
	v_mfma_f32_16x16x32_bf16 v[112:115], v[212:215], v[148:151], v[112:115]
	v_mfma_f32_16x16x32_bf16 v[100:103], v[204:207], v[172:175], v[100:103]
	v_mfma_f32_16x16x32_bf16 v[96:99], v[212:215], v[172:175], v[96:99]
	v_mfma_f32_16x16x32_bf16 v[84:87], v[204:207], v[180:183], v[84:87]
	v_mfma_f32_16x16x32_bf16 v[80:83], v[212:215], v[180:183], v[80:83]
	s_setprio 2
	s_barrier
	v_mfma_f32_16x16x32_bf16 v[68:71], v[204:207], v[196:199], v[68:71]
	v_mfma_f32_16x16x32_bf16 v[64:67], v[212:215], v[196:199], v[64:67]
	s_setprio 0
	s_mov_b32 m0, s19
	v_lshl_add_u64 v[220:221], s[38:39], 0, v[152:153]
	ds_read_b128 v[144:147], v188 offset:16384
	ds_read_b128 v[148:151], v188 offset:17408
	ds_read_b128 v[168:171], v188 offset:18432
	ds_read_b128 v[172:175], v188 offset:19456
	ds_read_b128 v[176:179], v188 offset:20480
	ds_read_b128 v[180:183], v188 offset:21504
	ds_read_b128 v[192:195], v188 offset:22528
	ds_read_b128 v[196:199], v188 offset:23552
	global_load_lds_dwordx4 v[220:221], off
	v_lshl_add_u64 v[224:225], s[38:39], 0, v[156:157]
	s_mov_b32 m0, s23
	s_nop 0
	global_load_lds_dwordx4 v[224:225], off
	s_barrier
	s_waitcnt lgkmcnt(0)
	s_setprio 1
	s_waitcnt lgkmcnt(0)
	v_mfma_f32_16x16x32_bf16 v[60:63], v[128:131], v[144:147], v[60:63]
	v_mfma_f32_16x16x32_bf16 v[56:59], v[136:139], v[144:147], v[56:59]
	v_mfma_f32_16x16x32_bf16 v[44:47], v[128:131], v[168:171], v[44:47]
	v_mfma_f32_16x16x32_bf16 v[40:43], v[136:139], v[168:171], v[40:43]
	v_mfma_f32_16x16x32_bf16 v[28:31], v[128:131], v[176:179], v[28:31]
	v_mfma_f32_16x16x32_bf16 v[24:27], v[136:139], v[176:179], v[24:27]
	v_mfma_f32_16x16x32_bf16 v[12:15], v[128:131], v[192:195], v[12:15]
	v_mfma_f32_16x16x32_bf16 v[8:11], v[136:139], v[192:195], v[8:11]
	v_mfma_f32_16x16x32_bf16 v[60:63], v[132:135], v[148:151], v[60:63]
	v_mfma_f32_16x16x32_bf16 v[56:59], v[140:143], v[148:151], v[56:59]
	v_mfma_f32_16x16x32_bf16 v[44:47], v[132:135], v[172:175], v[44:47]
	v_mfma_f32_16x16x32_bf16 v[40:43], v[140:143], v[172:175], v[40:43]
	v_mfma_f32_16x16x32_bf16 v[28:31], v[132:135], v[180:183], v[28:31]
	v_mfma_f32_16x16x32_bf16 v[24:27], v[140:143], v[180:183], v[24:27]
	s_setprio 2
	s_barrier
; #define PG8_STAGE(bufoff, gbase, voff) do { _Pragma("unroll") for (int _i = 0; _i < 2; ++_i) \
;         __builtin_amdgcn_global_load_lds((const unsigned*)((const char*)(gbase) + (voff)[_i]), (LAS unsigned*)(lds + (bufoff) + ldsw + _i * 8192), 16, 0, 0); } while (0)
; #define PG8_LDA(dst, b, h) do { _Pragma("unroll") for (int m = 0; m < 4; ++m) _Pragma("unroll") for (int k = 0; k < 2; ++k) dst[m][k] = *(const LAS bf16x8*)(lds + PG8_SA(b, h) + aoff + m * 2048 + k * 1024); } while (0)
; #define PG8_LDB(dst, b, h) do { _Pragma("unroll") for (int n = 0; n < 2; ++n) _Pragma("unroll") for (int k = 0; k < 2; ++k) dst[n][k] = *(const LAS bf16x8*)(lds + PG8_SB(b, h) + boff + n * 2048 + k * 1024); } while (0)
; #define PG8_MMA(ai, bj, At, Bt) do { __builtin_amdgcn_s_setprio(1); _Pragma("unroll") for (int m = 0; m < 4; ++m) _Pragma("unroll") for (int n = 0; n < 2; ++n) _Pragma("unroll") for (int k = 0; k < 2; ++k) \
;         acc[ai][bj][m][n] = __builtin_amdgcn_mfma_f32_16x16x32_bf16(Bt[n][k], At[m][k], acc[ai][bj][m][n], 0, 0, 0); __builtin_amdgcn_s_setprio(0); } while (0)
; #define PG8_WAIT_V(n) asm volatile("s_waitcnt vmcnt(" #n ")" ::: "memory")
; #define PG8_WAIT_L(n) asm volatile("s_waitcnt lgkmcnt(" #n ")" ::: "memory")
; #define PG8_BAR __builtin_amdgcn_s_barrier()
; #define PG8_SCHED __builtin_amdgcn_sched_barrier(0)
; #define PG8_STAGE(bufoff, gbase, voff) do { _Pragma("unroll") for (int _i = 0; _i < 2; ++_i) \
;         __builtin_amdgcn_global_load_lds((const unsigned*)((const char*)(gbase) + (voff)[_i]), (LAS unsigned*)(lds + (bufoff) + ldsw + _i * 8192), 16, 0, 0); } while (0)
; #define PG8_WAIT_V(n) asm volatile("s_waitcnt vmcnt(" #n ")" ::: "memory")
; template <class Epi>
; DI void gemm_phase(LAS unsigned char* lds, const Gemm g, const StaticOrder S, const Epi E) {
;     ...
;             PG8_BAR; PG8_WAIT_L(0); PG8_MMA(1, 0, At, B0); PG8_BAR; PG8_SCHED;
;             PG8_STAGE(PG8_SB(0, 1), b2 + hstep, voffB);
;             PG8_WAIT_V(6); PG8_BAR; PG8_MMA(1, 1, At, B1); PG8_BAR;
;             PG8_LDB(B0, 1, 0); PG8_SCHED; PG8_LDA(At, 1, 0); PG8_STAGE(PG8_SA(0, 1), a2 + hstep, voffA);
;             PG8_WAIT_L(8); PG8_BAR; PG8_WAIT_L(0); PG8_MMA(0, 0, At, B0); PG8_BAR; PG8_SCHED;
;             PG8_LDB(B1, 1, 1); PG8_STAGE(PG8_SB(1, 0), b3, voffB);
;             PG8_BAR; PG8_WAIT_L(0); PG8_MMA(0, 1, At, B1); PG8_BAR;
	v_mfma_f32_16x16x32_bf16 v[12:15], v[132:135], v[196:199], v[12:15]
	v_mfma_f32_16x16x32_bf16 v[8:11], v[140:143], v[196:199], v[8:11]
	s_setprio 0
	s_add_u32 s58, s28, 0x40000
	s_addc_u32 s59, s29, 0
	s_add_i32 s53, s49, s40
	v_lshl_add_u64 v[128:129], s[58:59], 0, v[154:155]
	s_mov_b32 m0, s53
	s_nop 0
	global_load_lds_dwordx4 v[128:129], off
	v_lshl_add_u64 v[128:129], s[58:59], 0, v[158:159]
	s_add_i32 m0, s53, 0x2000
	s_nop 0
	global_load_lds_dwordx4 v[128:129], off
	s_waitcnt vmcnt(6)
	s_barrier
	s_setprio 1
	v_mfma_f32_16x16x32_bf16 v[52:55], v[200:203], v[144:147], v[52:55]
	v_mfma_f32_16x16x32_bf16 v[48:51], v[208:211], v[144:147], v[48:51]
	v_mfma_f32_16x16x32_bf16 v[36:39], v[200:203], v[168:171], v[36:39]
	v_mfma_f32_16x16x32_bf16 v[32:35], v[208:211], v[168:171], v[32:35]
	v_mfma_f32_16x16x32_bf16 v[20:23], v[200:203], v[176:179], v[20:23]
	v_mfma_f32_16x16x32_bf16 v[16:19], v[208:211], v[176:179], v[16:19]
	v_mfma_f32_16x16x32_bf16 v[4:7], v[200:203], v[192:195], v[4:7]
	v_mfma_f32_16x16x32_bf16 v[0:3], v[208:211], v[192:195], v[0:3]
	v_mfma_f32_16x16x32_bf16 v[52:55], v[204:207], v[148:151], v[52:55]
	v_mfma_f32_16x16x32_bf16 v[48:51], v[212:215], v[148:151], v[48:51]
	v_mfma_f32_16x16x32_bf16 v[36:39], v[204:207], v[172:175], v[36:39]
	v_mfma_f32_16x16x32_bf16 v[32:35], v[212:215], v[172:175], v[32:35]
	v_mfma_f32_16x16x32_bf16 v[20:23], v[204:207], v[180:183], v[20:23]
	v_mfma_f32_16x16x32_bf16 v[16:19], v[212:215], v[180:183], v[16:19]
	s_setprio 2
	s_barrier
	v_mfma_f32_16x16x32_bf16 v[4:7], v[204:207], v[196:199], v[4:7]
	v_mfma_f32_16x16x32_bf16 v[0:3], v[212:215], v[196:199], v[0:3]
	s_setprio 0
	s_add_i32 s53, 0, 0x18000
	v_add_u32_e32 v140, s53, v185
	ds_read_b128 v[128:131], v140
	ds_read_b128 v[132:135], v140 offset:1024
	ds_read_b128 v[136:139], v140 offset:2048
	ds_read_b128 v[140:143], v140 offset:3072
	s_add_u32 s38, s38, 0x40000
	s_addc_u32 s39, s39, 0
	s_mov_b32 m0, s41
	v_lshl_add_u64 v[200:201], s[38:39], 0, v[152:153]
	ds_read_b128 v[144:147], v188 offset:32768
	ds_read_b128 v[148:151], v188 offset:33792
	ds_read_b128 v[168:171], v188 offset:34816
	ds_read_b128 v[172:175], v188 offset:35840
	ds_read_b128 v[176:179], v188 offset:36864
	ds_read_b128 v[180:183], v188 offset:37888
	ds_read_b128 v[192:195], v188 offset:38912
	ds_read_b128 v[196:199], v188 offset:39936
	global_load_lds_dwordx4 v[200:201], off
	v_lshl_add_u64 v[200:201], s[38:39], 0, v[156:157]
	s_mov_b32 m0, s42
	s_nop 0
	global_load_lds_dwordx4 v[200:201], off
	s_waitcnt lgkmcnt(8)
	s_barrier
	s_waitcnt lgkmcnt(0)
	s_setprio 1
	s_waitcnt lgkmcnt(0)
	v_mfma_f32_16x16x32_bf16 v[124:127], v[128:131], v[144:147], v[124:127]
	v_mfma_f32_16x16x32_bf16 v[120:123], v[136:139], v[144:147], v[120:123]
	v_mfma_f32_16x16x32_bf16 v[108:111], v[128:131], v[168:171], v[108:111]
	v_mfma_f32_16x16x32_bf16 v[104:107], v[136:139], v[168:171], v[104:107]
	v_mfma_f32_16x16x32_bf16 v[92:95], v[128:131], v[176:179], v[92:95]
	v_mfma_f32_16x16x32_bf16 v[88:91], v[136:139], v[176:179], v[88:91]
	v_mfma_f32_16x16x32_bf16 v[76:79], v[128:131], v[192:195], v[76:79]
	v_mfma_f32_16x16x32_bf16 v[72:75], v[136:139], v[192:195], v[72:75]
	v_mfma_f32_16x16x32_bf16 v[124:127], v[132:135], v[148:151], v[124:127]
	v_mfma_f32_16x16x32_bf16 v[120:123], v[140:143], v[148:151], v[120:123]
	v_mfma_f32_16x16x32_bf16 v[108:111], v[132:135], v[172:175], v[108:111]
	v_mfma_f32_16x16x32_bf16 v[104:107], v[140:143], v[172:175], v[104:107]
	v_mfma_f32_16x16x32_bf16 v[92:95], v[132:135], v[180:183], v[92:95]
	v_mfma_f32_16x16x32_bf16 v[88:91], v[140:143], v[180:183], v[88:91]
	s_setprio 2
	s_barrier
	v_mfma_f32_16x16x32_bf16 v[76:79], v[132:135], v[196:199], v[76:79]
	v_mfma_f32_16x16x32_bf16 v[72:75], v[140:143], v[196:199], v[72:75]
	s_setprio 0
	s_add_i32 s38, 0, 0x1c000
	s_add_i32 s39, s53, s40
	v_add_u32_e32 v191, s38, v185
	v_lshl_add_u64 v[216:217], v[216:217], 0, s[8:9]
	s_mov_b32 m0, s39
	ds_read_b128 v[200:203], v191
	ds_read_b128 v[204:207], v191 offset:1024
	ds_read_b128 v[208:211], v191 offset:2048
	ds_read_b128 v[212:215], v191 offset:3072
	global_load_lds_dwordx4 v[216:217], off
	v_lshl_add_u64 v[216:217], v[218:219], 0, s[8:9]
	s_add_i32 m0, s39, 0x2000
	s_nop 0
	global_load_lds_dwordx4 v[216:217], off
	s_barrier
	s_waitcnt lgkmcnt(0)
	s_setprio 1
	s_waitcnt lgkmcnt(0)
	v_mfma_f32_16x16x32_bf16 v[116:119], v[200:203], v[144:147], v[116:119]
	v_mfma_f32_16x16x32_bf16 v[112:115], v[208:211], v[144:147], v[112:115]
	v_mfma_f32_16x16x32_bf16 v[100:103], v[200:203], v[168:171], v[100:103]
	v_mfma_f32_16x16x32_bf16 v[96:99], v[208:211], v[168:171], v[96:99]
	v_mfma_f32_16x16x32_bf16 v[84:87], v[200:203], v[176:179], v[84:87]
	v_mfma_f32_16x16x32_bf16 v[80:83], v[208:211], v[176:179], v[80:83]
	v_mfma_f32_16x16x32_bf16 v[68:71], v[200:203], v[192:195], v[68:71]
	v_mfma_f32_16x16x32_bf16 v[64:67], v[208:211], v[192:195], v[64:67]
	v_mfma_f32_16x16x32_bf16 v[116:119], v[204:207], v[148:151], v[116:119]
	v_mfma_f32_16x16x32_bf16 v[112:115], v[212:215], v[148:151], v[112:115]
	v_mfma_f32_16x16x32_bf16 v[100:103], v[204:207], v[172:175], v[100:103]
	v_mfma_f32_16x16x32_bf16 v[96:99], v[212:215], v[172:175], v[96:99]
	v_mfma_f32_16x16x32_bf16 v[84:87], v[204:207], v[180:183], v[84:87]
	v_mfma_f32_16x16x32_bf16 v[80:83], v[212:215], v[180:183], v[80:83]
	s_setprio 2
	s_barrier
; #define PG8_STAGE(bufoff, gbase, voff) do { _Pragma("unroll") for (int _i = 0; _i < 2; ++_i) \
;         __builtin_amdgcn_global_load_lds((const unsigned*)((const char*)(gbase) + (voff)[_i]), (LAS unsigned*)(lds + (bufoff) + ldsw + _i * 8192), 16, 0, 0); } while (0)
; #define PG8_LDA(dst, b, h) do { _Pragma("unroll") for (int m = 0; m < 4; ++m) _Pragma("unroll") for (int k = 0; k < 2; ++k) dst[m][k] = *(const LAS bf16x8*)(lds + PG8_SA(b, h) + aoff + m * 2048 + k * 1024); } while (0)
; #define PG8_MMA(ai, bj, At, Bt) do { __builtin_amdgcn_s_setprio(1); _Pragma("unroll") for (int m = 0; m < 4; ++m) _Pragma("unroll") for (int n = 0; n < 2; ++n) _Pragma("unroll") for (int k = 0; k < 2; ++k) \
;         acc[ai][bj][m][n] = __builtin_amdgcn_mfma_f32_16x16x32_bf16(Bt[n][k], At[m][k], acc[ai][bj][m][n], 0, 0, 0); __builtin_amdgcn_s_setprio(0); } while (0)
; #define PG8_WAIT_V(n) asm volatile("s_waitcnt vmcnt(" #n ")" ::: "memory")
; #define PG8_WAIT_L(n) asm volatile("s_waitcnt lgkmcnt(" #n ")" ::: "memory")
; #define PG8_BAR __builtin_amdgcn_s_barrier()
; #define PG8_SCHED __builtin_amdgcn_sched_barrier(0)
; #define PG8_STAGE(bufoff, gbase, voff) do { _Pragma("unroll") for (int _i = 0; _i < 2; ++_i) \
;         __builtin_amdgcn_global_load_lds((const unsigned*)((const char*)(gbase) + (voff)[_i]), (LAS unsigned*)(lds + (bufoff) + ldsw + _i * 8192), 16, 0, 0); } while (0)
; #define PG8_LDA(dst, b, h) do { _Pragma("unroll") for (int m = 0; m < 4; ++m) _Pragma("unroll") for (int k = 0; k < 2; ++k) dst[m][k] = *(const LAS bf16x8*)(lds + PG8_SA(b, h) + aoff + m * 2048 + k * 1024); } while (0)
; #define PG8_WAIT_V(n) asm volatile("s_waitcnt vmcnt(" #n ")" ::: "memory")
; #define PG8_WAIT_L(n) asm volatile("s_waitcnt lgkmcnt(" #n ")" ::: "memory")
; #define PG8_BAR __builtin_amdgcn_s_barrier()
; #define PG8_SCHED __builtin_amdgcn_sched_barrier(0)
; template <class Epi>
; DI void gemm_phase(LAS unsigned char* lds, const Gemm g, const StaticOrder S, const Epi E) {
;     ...
;             PG8_BAR; PG8_WAIT_L(0); PG8_MMA(0, 1, At, B1); PG8_BAR;
;             PG8_LDA(At, 1, 1); PG8_STAGE(PG8_SA(1, 0), a3, voffA);
;             PG8_BAR; PG8_WAIT_L(0); PG8_MMA(1, 0, At, B0); PG8_BAR; PG8_SCHED;
;             PG8_STAGE(PG8_SB(1, 1), b3 + hstep, voffB);
;             PG8_WAIT_V(6); PG8_BAR; PG8_MMA(1, 1, At, B1); PG8_BAR;
	v_mfma_f32_16x16x32_bf16 v[68:71], v[204:207], v[196:199], v[68:71]
	v_mfma_f32_16x16x32_bf16 v[64:67], v[212:215], v[196:199], v[64:67]
	s_setprio 0
	s_mov_b32 m0, s44
	v_lshl_add_u64 v[216:217], v[220:221], 0, s[8:9]
	ds_read_b128 v[144:147], v188 offset:49152
	ds_read_b128 v[148:151], v188 offset:50176
	ds_read_b128 v[168:171], v188 offset:51200
	ds_read_b128 v[172:175], v188 offset:52224
	ds_read_b128 v[176:179], v188 offset:53248
	ds_read_b128 v[180:183], v188 offset:54272
	ds_read_b128 v[192:195], v188 offset:55296
	ds_read_b128 v[196:199], v188 offset:56320
	global_load_lds_dwordx4 v[216:217], off
	v_lshl_add_u64 v[216:217], v[224:225], 0, s[8:9]
	s_mov_b32 m0, s45
	s_nop 0
	global_load_lds_dwordx4 v[216:217], off
	s_barrier
	s_waitcnt lgkmcnt(0)
	s_setprio 1
	s_waitcnt lgkmcnt(0)
	v_mfma_f32_16x16x32_bf16 v[60:63], v[128:131], v[144:147], v[60:63]
	v_mfma_f32_16x16x32_bf16 v[56:59], v[136:139], v[144:147], v[56:59]
	v_mfma_f32_16x16x32_bf16 v[44:47], v[128:131], v[168:171], v[44:47]
	v_mfma_f32_16x16x32_bf16 v[40:43], v[136:139], v[168:171], v[40:43]
	v_mfma_f32_16x16x32_bf16 v[28:31], v[128:131], v[176:179], v[28:31]
	v_mfma_f32_16x16x32_bf16 v[24:27], v[136:139], v[176:179], v[24:27]
	v_mfma_f32_16x16x32_bf16 v[12:15], v[128:131], v[192:195], v[12:15]
	v_mfma_f32_16x16x32_bf16 v[8:11], v[136:139], v[192:195], v[8:11]
	v_mfma_f32_16x16x32_bf16 v[60:63], v[132:135], v[148:151], v[60:63]
	v_mfma_f32_16x16x32_bf16 v[56:59], v[140:143], v[148:151], v[56:59]
	v_mfma_f32_16x16x32_bf16 v[44:47], v[132:135], v[172:175], v[44:47]
	v_mfma_f32_16x16x32_bf16 v[40:43], v[140:143], v[172:175], v[40:43]
	v_mfma_f32_16x16x32_bf16 v[28:31], v[132:135], v[180:183], v[28:31]
	v_mfma_f32_16x16x32_bf16 v[24:27], v[140:143], v[180:183], v[24:27]
	s_setprio 2
	s_barrier
	v_mfma_f32_16x16x32_bf16 v[12:15], v[132:135], v[196:199], v[12:15]
	v_mfma_f32_16x16x32_bf16 v[8:11], v[140:143], v[196:199], v[8:11]
	s_setprio 0
	s_add_u32 s28, s28, 0x40080
	s_addc_u32 s29, s29, 0
	s_add_i32 s38, s38, s40
	v_lshl_add_u64 v[128:129], s[28:29], 0, v[154:155]
	s_mov_b32 m0, s38
	s_nop 0
	global_load_lds_dwordx4 v[128:129], off
	v_lshl_add_u64 v[128:129], s[28:29], 0, v[158:159]
	s_add_i32 m0, s38, 0x2000
	s_nop 0
	global_load_lds_dwordx4 v[128:129], off
	s_waitcnt vmcnt(6)
	s_barrier
	s_setprio 1
	v_mfma_f32_16x16x32_bf16 v[52:55], v[200:203], v[144:147], v[52:55]
	v_mfma_f32_16x16x32_bf16 v[48:51], v[208:211], v[144:147], v[48:51]
	v_mfma_f32_16x16x32_bf16 v[36:39], v[200:203], v[168:171], v[36:39]
	v_mfma_f32_16x16x32_bf16 v[32:35], v[208:211], v[168:171], v[32:35]
	v_mfma_f32_16x16x32_bf16 v[20:23], v[200:203], v[176:179], v[20:23]
	v_mfma_f32_16x16x32_bf16 v[16:19], v[208:211], v[176:179], v[16:19]
	v_mfma_f32_16x16x32_bf16 v[4:7], v[200:203], v[192:195], v[4:7]
	v_mfma_f32_16x16x32_bf16 v[0:3], v[208:211], v[192:195], v[0:3]
	v_mfma_f32_16x16x32_bf16 v[52:55], v[204:207], v[148:151], v[52:55]
	v_mfma_f32_16x16x32_bf16 v[48:51], v[212:215], v[148:151], v[48:51]
	v_mfma_f32_16x16x32_bf16 v[36:39], v[204:207], v[172:175], v[36:39]
	v_mfma_f32_16x16x32_bf16 v[32:35], v[212:215], v[172:175], v[32:35]
	v_mfma_f32_16x16x32_bf16 v[20:23], v[204:207], v[180:183], v[20:23]
	v_mfma_f32_16x16x32_bf16 v[16:19], v[212:215], v[180:183], v[16:19]
	s_setprio 2
	s_barrier
	v_mfma_f32_16x16x32_bf16 v[4:7], v[204:207], v[196:199], v[4:7]
	v_mfma_f32_16x16x32_bf16 v[0:3], v[212:215], v[196:199], v[0:3]
	s_setprio 0
	s_add_i32 s52, s52, 2
	s_add_u32 s24, s24, 0x100
	s_addc_u32 s25, s25, 0
	s_add_u32 s50, s50, 0x100
	s_addc_u32 s51, s51, 0
	s_cmp_gt_u32 s52, 13
	s_cbranch_scc0 .LBB0_786
; DI unsigned pk_bf16(float lo, float hi) { f32x2 v = {lo, hi}; return __builtin_bit_cast(unsigned, __builtin_convertvector(v, bf16v2)); }
; DI f32x4 bf_lo4(u32x4 w) { f32x4 r; r[0] = bf_lo(w.x); r[1] = bf_hi(w.x); r[2] = bf_lo(w.y); r[3] = bf_hi(w.y); return r; }
; DI f32x4 bf_hi4(u32x4 w) { f32x4 r; r[0] = bf_lo(w.z); r[1] = bf_hi(w.z); r[2] = bf_lo(w.w); r[3] = bf_hi(w.w); return r; }
;     DI void operator()(AccRef acc, const Unit& u, int wr, int wc, int fr, int fq) const {
;     ...
;             for (int m = 0; m < 4; ++m)
; #pragma unroll
;                 for (int bj = 0; bj < 2; ++bj) {
;                     const size_t o = (size_t)(row0 + ai * 128 + m * 16) * DM + col0 + bj * 128;
;                     if (BASEF32) { bv[m][bj][0] = *(const f32x4*)(basef + o); bv[m][bj][1] = *(const f32x4*)(basef + o + 4); }
;                     else { const u32x4 h = *(const u32x4*)(xnb + o); bv[m][bj][0] = bf_lo4(h); bv[m][bj][1] = bf_hi4(h); }
;                 }
; #pragma unroll
;             for (int m = 0; m < 4; ++m) {
;                 const int row = row0 + ai * 128 + m * 16;
;                 float q = 0.f;
; #pragma unroll
;                 for (int bj = 0; bj < 2; ++bj) {
;                     const size_t o = (size_t)row * DM + col0 + bj * 128;
;                     const f32x4 r0 = bv[m][bj][0] + scale * acc[ai][bj][m][0], r1 = bv[m][bj][1] + scale * acc[ai][bj][m][1];
;                     u32x4 w; w.x = pk_bf16(r0[0], r0[1]); w.y = pk_bf16(r0[2], r0[3]); w.z = pk_bf16(r1[0], r1[1]); w.w = pk_bf16(r1[2], r1[3]);
;                     *(u32x4*)(xnb + o) = w;
;                     if (STATS) q += r0[0] * r0[0] + r0[1] * r0[1] + r0[2] * r0[2] + r0[3] * r0[3] + r1[0] * r1[0] + r1[1] * r1[1] + r1[2] * r1[2] + r1[3] * r1[3];
;                 }
;                 if (STATS) { q += __shfl_xor(q, 16); q += __shfl_xor(q, 32); if (fq == 0) atomicAdd(ss + row, q); }
	v_lshl_add_u32 v170, s18, 8, v184
	v_lshl_or_b32 v128, s22, 8, v186
	v_ashrrev_i32_e32 v129, 31, v128
	v_ashrrev_i32_e32 v171, 31, v170
	v_lshl_add_u64 v[168:169], v[128:129], 1, s[56:57]
	v_lshlrev_b64 v[128:129], 11, v[170:171]
	v_lshl_add_u64 v[202:203], v[168:169], 0, v[128:129]
	global_load_dwordx4 v[194:197], v[202:203], off
	global_load_dwordx4 v[198:201], v[202:203], off offset:256
	v_or_b32_e32 v180, 16, v170
	v_or_b32_e32 v176, 32, v170
	v_or_b32_e32 v172, 48, v170
	v_ashrrev_i32_e32 v181, 31, v180
	v_ashrrev_i32_e32 v177, 31, v176
	v_ashrrev_i32_e32 v173, 31, v172
	v_lshlrev_b64 v[128:129], 11, v[180:181]
	v_lshlrev_b64 v[130:131], 11, v[176:177]
	v_lshlrev_b64 v[132:133], 11, v[172:173]
	v_lshl_add_u64 v[182:183], v[168:169], 0, v[128:129]
	v_lshl_add_u64 v[178:179], v[168:169], 0, v[130:131]
	v_lshl_add_u64 v[174:175], v[168:169], 0, v[132:133]
	global_load_dwordx4 v[148:151], v[182:183], off
	global_load_dwordx4 v[144:147], v[182:183], off offset:256
	global_load_dwordx4 v[140:143], v[178:179], off
	global_load_dwordx4 v[136:139], v[178:179], off offset:256
	global_load_dwordx4 v[132:135], v[174:175], off
	global_load_dwordx4 v[128:131], v[174:175], off offset:256
	v_and_b32_e32 v192, 64, v190
	v_xor_b32_e32 v191, 16, v190
	v_add_u32_e32 v192, 64, v192
	v_cmp_lt_i32_e32 vcc, v191, v192
	v_xor_b32_e32 v193, 32, v190
	s_waitcnt vmcnt(0)
	v_lshlrev_b32_e32 v204, 16, v194
	v_and_b32_e32 v205, 0xffff0000, v194
	v_lshlrev_b32_e32 v208, 16, v198
	v_and_b32_e32 v209, 0xffff0000, v198
	v_lshlrev_b32_e32 v194, 16, v195
	v_and_b32_e32 v195, 0xffff0000, v195
	v_lshlrev_b32_e32 v210, 16, v200
	v_and_b32_e32 v211, 0xffff0000, v200
	v_lshlrev_b32_e32 v200, 16, v201
	v_and_b32_e32 v201, 0xffff0000, v201
	v_pk_add_f32 v[124:125], v[124:125], v[204:205]
	v_pk_add_f32 v[116:117], v[116:117], v[208:209]
	v_lshlrev_b32_e32 v198, 16, v199
	v_and_b32_e32 v199, 0xffff0000, v199
	v_pk_add_f32 v[126:127], v[126:127], v[194:195]
	v_pk_add_f32 v[194:195], v[114:115], v[200:201]
	v_mul_f32_e32 v114, v125, v125
	v_mul_f32_e32 v115, v117, v117
	v_pk_add_f32 v[118:119], v[118:119], v[198:199]
	v_fmac_f32_e32 v114, v124, v124
	v_fmac_f32_e32 v115, v116, v116
	v_lshlrev_b32_e32 v206, 16, v196
	v_and_b32_e32 v207, 0xffff0000, v196
	v_lshlrev_b32_e32 v196, 16, v197
	v_and_b32_e32 v197, 0xffff0000, v197
	v_fmac_f32_e32 v114, v126, v126
	v_fmac_f32_e32 v115, v118, v118
	v_pk_add_f32 v[122:123], v[122:123], v[196:197]
	v_pk_add_f32 v[120:121], v[120:121], v[206:207]
	v_pk_add_f32 v[196:197], v[112:113], v[210:211]
	v_fmac_f32_e32 v114, v127, v127
	v_fmac_f32_e32 v115, v119, v119
	v_fmac_f32_e32 v114, v120, v120
	v_fmac_f32_e32 v115, v196, v196
	v_fmac_f32_e32 v114, v121, v121
	v_fmac_f32_e32 v115, v197, v197
	v_fmac_f32_e32 v114, v122, v122
	v_fmac_f32_e32 v115, v194, v194
	v_cndmask_b32_e32 v191, v190, v191, vcc
	v_fmac_f32_e32 v114, v123, v123
	v_fmac_f32_e32 v115, v195, v195
	v_cmp_lt_i32_e32 vcc, v193, v192
	v_lshlrev_b32_e32 v192, 2, v191
	v_cvt_pk_bf16_f32 v112, v124, v125
	v_add_f32_e32 v124, v114, v115
	ds_bpermute_b32 v125, v192, v124
	v_cndmask_b32_e32 v193, v190, v193, vcc
	v_cvt_pk_bf16_f32 v113, v126, v127
	v_cvt_pk_bf16_f32 v114, v120, v121
	v_cvt_pk_bf16_f32 v115, v122, v123
	v_lshlrev_b32_e32 v191, 2, v193
	global_store_dwordx4 v[202:203], v[112:115], off
	s_waitcnt lgkmcnt(0)
	s_nop 0
	v_add_f32_e32 v112, v124, v125
	ds_bpermute_b32 v113, v191, v112
	v_cvt_pk_bf16_f32 v114, v116, v117
	v_cvt_pk_bf16_f32 v115, v118, v119
	v_cvt_pk_bf16_f32 v116, v196, v197
	v_cvt_pk_bf16_f32 v117, v194, v195
	global_store_dwordx4 v[202:203], v[114:117], off offset:256
	s_and_saveexec_b64 s[6:7], s[0:1]
	s_cbranch_execz .LBB0_789
	s_waitcnt lgkmcnt(0)
	v_add_f32_e32 v114, v112, v113
	v_lshl_add_u64 v[112:113], v[170:171], 2, s[20:21]
	global_atomic_add_f32 v[112:113], v114, off

; #define PG8_STAGE(bufoff, gbase, voff) do { _Pragma("unroll") for (int _i = 0; _i < 2; ++_i) \
;         __builtin_amdgcn_global_load_lds((const unsigned*)((const char*)(gbase) + (voff)[_i]), (LAS unsigned*)(lds + (bufoff) + ldsw + _i * 8192), 16, 0, 0); } while (0)
; #define PG8_LDA(dst, b, h) do { _Pragma("unroll") for (int m = 0; m < 4; ++m) _Pragma("unroll") for (int k = 0; k < 2; ++k) dst[m][k] = *(const LAS bf16x8*)(lds + PG8_SA(b, h) + aoff + m * 2048 + k * 1024); } while (0)
; #define PG8_LDB(dst, b, h) do { _Pragma("unroll") for (int n = 0; n < 2; ++n) _Pragma("unroll") for (int k = 0; k < 2; ++k) dst[n][k] = *(const LAS bf16x8*)(lds + PG8_SB(b, h) + boff + n * 2048 + k * 1024); } while (0)
; #define PG8_MMA(ai, bj, At, Bt) do { __builtin_amdgcn_s_setprio(1); _Pragma("unroll") for (int m = 0; m < 4; ++m) _Pragma("unroll") for (int n = 0; n < 2; ++n) _Pragma("unroll") for (int k = 0; k < 2; ++k) \
;         acc[ai][bj][m][n] = __builtin_amdgcn_mfma_f32_16x16x32_bf16(Bt[n][k], At[m][k], acc[ai][bj][m][n], 0, 0, 0); __builtin_amdgcn_s_setprio(0); } while (0)
; #define PG8_WAIT_L(n) asm volatile("s_waitcnt lgkmcnt(" #n ")" ::: "memory")
; #define PG8_BAR __builtin_amdgcn_s_barrier()
; #define PG8_SCHED __builtin_amdgcn_sched_barrier(0)
; #define PG8_STAGE(bufoff, gbase, voff) do { _Pragma("unroll") for (int _i = 0; _i < 2; ++_i) \
;         __builtin_amdgcn_global_load_lds((const unsigned*)((const char*)(gbase) + (voff)[_i]), (LAS unsigned*)(lds + (bufoff) + ldsw + _i * 8192), 16, 0, 0); } while (0)
; #define PG8_LDA(dst, b, h) do { _Pragma("unroll") for (int m = 0; m < 4; ++m) _Pragma("unroll") for (int k = 0; k < 2; ++k) dst[m][k] = *(const LAS bf16x8*)(lds + PG8_SA(b, h) + aoff + m * 2048 + k * 1024); } while (0)
; template <class Epi>
; DI void gemm_phase(LAS unsigned char* lds, const Gemm g, const StaticOrder S, const Epi E) {
;     ...
;             PG8_LDB(B0, 0, 0); PG8_SCHED; PG8_LDA(At, 0, 0); PG8_STAGE(PG8_SA(1, 1), a1 + hstep, voffA);
;             PG8_WAIT_L(8); PG8_BAR; PG8_WAIT_L(0); PG8_MMA(0, 0, At, B0); PG8_BAR; PG8_SCHED;
;             PG8_LDB(B1, 0, 1); PG8_STAGE(PG8_SB(0, 0), b2, voffB);
;             PG8_BAR; PG8_WAIT_L(0); PG8_MMA(0, 1, At, B1); PG8_BAR;
;             PG8_LDA(At, 0, 1); PG8_STAGE(PG8_SA(0, 0), a2, voffA);
;             PG8_BAR; PG8_WAIT_L(0); PG8_MMA(1, 0, At, B0); PG8_BAR; PG8_SCHED;
.LBB0_865:
	ds_read_b128 v[144:147], v155
	ds_read_b128 v[160:163], v155 offset:1024
	ds_read_b128 v[164:167], v155 offset:2048
	ds_read_b128 v[168:171], v155 offset:3072
	s_add_u32 s10, s8, 0xfffc0080
	s_addc_u32 s11, s9, -1
	s_cmp_eq_u32 s25, 12
	s_cselect_b32 s13, s14, s11
	s_cselect_b32 s12, s15, s10
	s_cselect_b32 s11, s16, s19
	s_cselect_b32 s10, s17, s18
	v_lshl_add_u64 v[204:205], s[8:9], 0, v[136:137]
	s_add_i32 m0, s40, 0xc000
	ds_read_b128 v[172:175], v157
	ds_read_b128 v[176:179], v157 offset:1024
	ds_read_b128 v[180:183], v157 offset:2048
	ds_read_b128 v[184:187], v157 offset:3072
	ds_read_b128 v[188:191], v157 offset:4096
	ds_read_b128 v[192:195], v157 offset:5120
	ds_read_b128 v[196:199], v157 offset:6144
	ds_read_b128 v[200:203], v157 offset:7168
	global_load_lds_dwordx4 v[204:205], off
	v_lshl_add_u64 v[204:205], s[8:9], 0, v[138:139]
	s_add_i32 m0, s40, 0xe000
	s_nop 0
	global_load_lds_dwordx4 v[204:205], off
	s_waitcnt lgkmcnt(8)
	s_barrier
	s_waitcnt lgkmcnt(0)
	s_setprio 1
	s_waitcnt lgkmcnt(0)
	v_mfma_f32_16x16x32_bf16 v[124:127], v[144:147], v[172:175], v[124:127]
	v_mfma_f32_16x16x32_bf16 v[120:123], v[164:167], v[172:175], v[120:123]
	v_mfma_f32_16x16x32_bf16 v[108:111], v[144:147], v[180:183], v[108:111]
	v_mfma_f32_16x16x32_bf16 v[104:107], v[164:167], v[180:183], v[104:107]
	v_mfma_f32_16x16x32_bf16 v[92:95], v[144:147], v[188:191], v[92:95]
	v_mfma_f32_16x16x32_bf16 v[88:91], v[164:167], v[188:191], v[88:91]
	v_mfma_f32_16x16x32_bf16 v[76:79], v[144:147], v[196:199], v[76:79]
	v_mfma_f32_16x16x32_bf16 v[72:75], v[164:167], v[196:199], v[72:75]
	v_mfma_f32_16x16x32_bf16 v[124:127], v[160:163], v[176:179], v[124:127]
	v_mfma_f32_16x16x32_bf16 v[120:123], v[168:171], v[176:179], v[120:123]
	v_mfma_f32_16x16x32_bf16 v[108:111], v[160:163], v[184:187], v[108:111]
	v_mfma_f32_16x16x32_bf16 v[104:107], v[168:171], v[184:187], v[104:107]
	v_mfma_f32_16x16x32_bf16 v[92:95], v[160:163], v[192:195], v[92:95]
	v_mfma_f32_16x16x32_bf16 v[88:91], v[168:171], v[192:195], v[88:91]
	s_setprio 2
	s_barrier
	v_mfma_f32_16x16x32_bf16 v[76:79], v[160:163], v[200:203], v[76:79]
	v_mfma_f32_16x16x32_bf16 v[72:75], v[168:171], v[200:203], v[72:75]
	s_setprio 0
	s_add_i32 s29, s49, s34
	v_lshl_add_u64 v[220:221], s[10:11], 0, v[132:133]
	s_mov_b32 m0, s29
	ds_read_b128 v[204:207], v158
	ds_read_b128 v[208:211], v158 offset:1024
	ds_read_b128 v[212:215], v158 offset:2048
	ds_read_b128 v[216:219], v158 offset:3072
	global_load_lds_dwordx4 v[220:221], off
	v_lshl_add_u64 v[224:225], s[10:11], 0, v[128:129]
	s_add_i32 m0, s29, 0x2000
	s_nop 0
	global_load_lds_dwordx4 v[224:225], off
	s_barrier
	s_waitcnt lgkmcnt(0)
	s_setprio 1
	s_waitcnt lgkmcnt(0)
	v_mfma_f32_16x16x32_bf16 v[116:119], v[204:207], v[172:175], v[116:119]
	v_mfma_f32_16x16x32_bf16 v[112:115], v[212:215], v[172:175], v[112:115]
	v_mfma_f32_16x16x32_bf16 v[100:103], v[204:207], v[180:183], v[100:103]
	v_mfma_f32_16x16x32_bf16 v[96:99], v[212:215], v[180:183], v[96:99]
	v_mfma_f32_16x16x32_bf16 v[84:87], v[204:207], v[188:191], v[84:87]
	v_mfma_f32_16x16x32_bf16 v[80:83], v[212:215], v[188:191], v[80:83]
	v_mfma_f32_16x16x32_bf16 v[68:71], v[204:207], v[196:199], v[68:71]
	v_mfma_f32_16x16x32_bf16 v[64:67], v[212:215], v[196:199], v[64:67]
	v_mfma_f32_16x16x32_bf16 v[116:119], v[208:211], v[176:179], v[116:119]
	v_mfma_f32_16x16x32_bf16 v[112:115], v[216:219], v[176:179], v[112:115]
	v_mfma_f32_16x16x32_bf16 v[100:103], v[208:211], v[184:187], v[100:103]
	v_mfma_f32_16x16x32_bf16 v[96:99], v[216:219], v[184:187], v[96:99]
	v_mfma_f32_16x16x32_bf16 v[84:87], v[208:211], v[192:195], v[84:87]
	v_mfma_f32_16x16x32_bf16 v[80:83], v[216:219], v[192:195], v[80:83]
	s_setprio 2
	s_barrier
	v_mfma_f32_16x16x32_bf16 v[68:71], v[208:211], v[200:203], v[68:71]
	v_mfma_f32_16x16x32_bf16 v[64:67], v[216:219], v[200:203], v[64:67]
	s_setprio 0
	s_mov_b32 m0, s40
	v_lshl_add_u64 v[226:227], s[12:13], 0, v[134:135]
	ds_read_b128 v[172:175], v157 offset:16384
	ds_read_b128 v[176:179], v157 offset:17408
	ds_read_b128 v[180:183], v157 offset:18432
	ds_read_b128 v[184:187], v157 offset:19456
	ds_read_b128 v[188:191], v157 offset:20480
	ds_read_b128 v[192:195], v157 offset:21504
	ds_read_b128 v[196:199], v157 offset:22528
	ds_read_b128 v[200:203], v157 offset:23552
	global_load_lds_dwordx4 v[226:227], off
	v_lshl_add_u64 v[228:229], s[12:13], 0, v[130:131]
	s_mov_b32 m0, s41
	s_nop 0
	global_load_lds_dwordx4 v[228:229], off
	s_barrier
	s_waitcnt lgkmcnt(0)
	s_setprio 1
	s_waitcnt lgkmcnt(0)
	v_mfma_f32_16x16x32_bf16 v[60:63], v[144:147], v[172:175], v[60:63]
	v_mfma_f32_16x16x32_bf16 v[56:59], v[164:167], v[172:175], v[56:59]
	v_mfma_f32_16x16x32_bf16 v[44:47], v[144:147], v[180:183], v[44:47]
	v_mfma_f32_16x16x32_bf16 v[40:43], v[164:167], v[180:183], v[40:43]
	v_mfma_f32_16x16x32_bf16 v[28:31], v[144:147], v[188:191], v[28:31]
	v_mfma_f32_16x16x32_bf16 v[24:27], v[164:167], v[188:191], v[24:27]
	v_mfma_f32_16x16x32_bf16 v[12:15], v[144:147], v[196:199], v[12:15]
	v_mfma_f32_16x16x32_bf16 v[8:11], v[164:167], v[196:199], v[8:11]
	v_mfma_f32_16x16x32_bf16 v[60:63], v[160:163], v[176:179], v[60:63]
	v_mfma_f32_16x16x32_bf16 v[56:59], v[168:171], v[176:179], v[56:59]
	v_mfma_f32_16x16x32_bf16 v[44:47], v[160:163], v[184:187], v[44:47]
	v_mfma_f32_16x16x32_bf16 v[40:43], v[168:171], v[184:187], v[40:43]
	v_mfma_f32_16x16x32_bf16 v[28:31], v[160:163], v[192:195], v[28:31]
	v_mfma_f32_16x16x32_bf16 v[24:27], v[168:171], v[192:195], v[24:27]
	s_setprio 2
	s_barrier
; #define PG8_STAGE(bufoff, gbase, voff) do { _Pragma("unroll") for (int _i = 0; _i < 2; ++_i) \
;         __builtin_amdgcn_global_load_lds((const unsigned*)((const char*)(gbase) + (voff)[_i]), (LAS unsigned*)(lds + (bufoff) + ldsw + _i * 8192), 16, 0, 0); } while (0)
; #define PG8_LDA(dst, b, h) do { _Pragma("unroll") for (int m = 0; m < 4; ++m) _Pragma("unroll") for (int k = 0; k < 2; ++k) dst[m][k] = *(const LAS bf16x8*)(lds + PG8_SA(b, h) + aoff + m * 2048 + k * 1024); } while (0)
; #define PG8_LDB(dst, b, h) do { _Pragma("unroll") for (int n = 0; n < 2; ++n) _Pragma("unroll") for (int k = 0; k < 2; ++k) dst[n][k] = *(const LAS bf16x8*)(lds + PG8_SB(b, h) + boff + n * 2048 + k * 1024); } while (0)
; #define PG8_MMA(ai, bj, At, Bt) do { __builtin_amdgcn_s_setprio(1); _Pragma("unroll") for (int m = 0; m < 4; ++m) _Pragma("unroll") for (int n = 0; n < 2; ++n) _Pragma("unroll") for (int k = 0; k < 2; ++k) \
;         acc[ai][bj][m][n] = __builtin_amdgcn_mfma_f32_16x16x32_bf16(Bt[n][k], At[m][k], acc[ai][bj][m][n], 0, 0, 0); __builtin_amdgcn_s_setprio(0); } while (0)
; #define PG8_WAIT_V(n) asm volatile("s_waitcnt vmcnt(" #n ")" ::: "memory")
; #define PG8_WAIT_L(n) asm volatile("s_waitcnt lgkmcnt(" #n ")" ::: "memory")
; #define PG8_BAR __builtin_amdgcn_s_barrier()
; #define PG8_SCHED __builtin_amdgcn_sched_barrier(0)
; #define PG8_STAGE(bufoff, gbase, voff) do { _Pragma("unroll") for (int _i = 0; _i < 2; ++_i) \
;         __builtin_amdgcn_global_load_lds((const unsigned*)((const char*)(gbase) + (voff)[_i]), (LAS unsigned*)(lds + (bufoff) + ldsw + _i * 8192), 16, 0, 0); } while (0)
; #define PG8_WAIT_V(n) asm volatile("s_waitcnt vmcnt(" #n ")" ::: "memory")
; template <class Epi>
; DI void gemm_phase(LAS unsigned char* lds, const Gemm g, const StaticOrder S, const Epi E) {
;     ...
;             PG8_BAR; PG8_WAIT_L(0); PG8_MMA(1, 0, At, B0); PG8_BAR; PG8_SCHED;
;             PG8_STAGE(PG8_SB(0, 1), b2 + hstep, voffB);
;             PG8_WAIT_V(6); PG8_BAR; PG8_MMA(1, 1, At, B1); PG8_BAR;
;             PG8_LDB(B0, 1, 0); PG8_SCHED; PG8_LDA(At, 1, 0); PG8_STAGE(PG8_SA(0, 1), a2 + hstep, voffA);
;             PG8_WAIT_L(8); PG8_BAR; PG8_WAIT_L(0); PG8_MMA(0, 0, At, B0); PG8_BAR; PG8_SCHED;
;             PG8_LDB(B1, 1, 1); PG8_STAGE(PG8_SB(1, 0), b3, voffB);
;             PG8_BAR; PG8_WAIT_L(0); PG8_MMA(0, 1, At, B1); PG8_BAR;
	v_mfma_f32_16x16x32_bf16 v[12:15], v[160:163], v[200:203], v[12:15]
	v_mfma_f32_16x16x32_bf16 v[8:11], v[168:171], v[200:203], v[8:11]
	s_setprio 0
	s_add_u32 s58, s10, 0x40000
	s_addc_u32 s59, s11, 0
	s_add_i32 s29, s50, s34
	v_lshl_add_u64 v[144:145], s[58:59], 0, v[132:133]
	s_mov_b32 m0, s29
	s_nop 0
	global_load_lds_dwordx4 v[144:145], off
	v_lshl_add_u64 v[144:145], s[58:59], 0, v[128:129]
	s_add_i32 m0, s29, 0x2000
	s_nop 0
	global_load_lds_dwordx4 v[144:145], off
	s_waitcnt vmcnt(6)
	s_barrier
	s_setprio 1
	v_mfma_f32_16x16x32_bf16 v[52:55], v[204:207], v[172:175], v[52:55]
	v_mfma_f32_16x16x32_bf16 v[48:51], v[212:215], v[172:175], v[48:51]
	v_mfma_f32_16x16x32_bf16 v[36:39], v[204:207], v[180:183], v[36:39]
	v_mfma_f32_16x16x32_bf16 v[32:35], v[212:215], v[180:183], v[32:35]
	v_mfma_f32_16x16x32_bf16 v[20:23], v[204:207], v[188:191], v[20:23]
	v_mfma_f32_16x16x32_bf16 v[16:19], v[212:215], v[188:191], v[16:19]
	v_mfma_f32_16x16x32_bf16 v[4:7], v[204:207], v[196:199], v[4:7]
	v_mfma_f32_16x16x32_bf16 v[0:3], v[212:215], v[196:199], v[0:3]
	v_mfma_f32_16x16x32_bf16 v[52:55], v[208:211], v[176:179], v[52:55]
	v_mfma_f32_16x16x32_bf16 v[48:51], v[216:219], v[176:179], v[48:51]
	v_mfma_f32_16x16x32_bf16 v[36:39], v[208:211], v[184:187], v[36:39]
	v_mfma_f32_16x16x32_bf16 v[32:35], v[216:219], v[184:187], v[32:35]
	v_mfma_f32_16x16x32_bf16 v[20:23], v[208:211], v[192:195], v[20:23]
	v_mfma_f32_16x16x32_bf16 v[16:19], v[216:219], v[192:195], v[16:19]
	s_setprio 2
	s_barrier
	v_mfma_f32_16x16x32_bf16 v[4:7], v[208:211], v[200:203], v[4:7]
	v_mfma_f32_16x16x32_bf16 v[0:3], v[216:219], v[200:203], v[0:3]
	s_setprio 0
	s_add_i32 s29, 0, 0x18000
	v_add_u32_e32 v148, s29, v151
	ds_read_b128 v[144:147], v148
	ds_read_b128 v[160:163], v148 offset:1024
	ds_read_b128 v[164:167], v148 offset:2048
	ds_read_b128 v[168:171], v148 offset:3072
	s_add_u32 s12, s12, 0x40000
	s_addc_u32 s13, s13, 0
	s_mov_b32 m0, s42
	v_lshl_add_u64 v[204:205], s[12:13], 0, v[134:135]
	ds_read_b128 v[172:175], v157 offset:32768
	ds_read_b128 v[176:179], v157 offset:33792
	ds_read_b128 v[180:183], v157 offset:34816
	ds_read_b128 v[184:187], v157 offset:35840
	ds_read_b128 v[188:191], v157 offset:36864
	ds_read_b128 v[192:195], v157 offset:37888
	ds_read_b128 v[196:199], v157 offset:38912
	ds_read_b128 v[200:203], v157 offset:39936
	global_load_lds_dwordx4 v[204:205], off
	v_lshl_add_u64 v[204:205], s[12:13], 0, v[130:131]
	s_mov_b32 m0, s43
	s_nop 0
	global_load_lds_dwordx4 v[204:205], off
	s_waitcnt lgkmcnt(8)
	s_barrier
	s_waitcnt lgkmcnt(0)
	s_setprio 1
	s_waitcnt lgkmcnt(0)
	v_mfma_f32_16x16x32_bf16 v[124:127], v[144:147], v[172:175], v[124:127]
	v_mfma_f32_16x16x32_bf16 v[120:123], v[164:167], v[172:175], v[120:123]
	v_mfma_f32_16x16x32_bf16 v[108:111], v[144:147], v[180:183], v[108:111]
	v_mfma_f32_16x16x32_bf16 v[104:107], v[164:167], v[180:183], v[104:107]
	v_mfma_f32_16x16x32_bf16 v[92:95], v[144:147], v[188:191], v[92:95]
	v_mfma_f32_16x16x32_bf16 v[88:91], v[164:167], v[188:191], v[88:91]
	v_mfma_f32_16x16x32_bf16 v[76:79], v[144:147], v[196:199], v[76:79]
	v_mfma_f32_16x16x32_bf16 v[72:75], v[164:167], v[196:199], v[72:75]
	v_mfma_f32_16x16x32_bf16 v[124:127], v[160:163], v[176:179], v[124:127]
	v_mfma_f32_16x16x32_bf16 v[120:123], v[168:171], v[176:179], v[120:123]
	v_mfma_f32_16x16x32_bf16 v[108:111], v[160:163], v[184:187], v[108:111]
	v_mfma_f32_16x16x32_bf16 v[104:107], v[168:171], v[184:187], v[104:107]
	v_mfma_f32_16x16x32_bf16 v[92:95], v[160:163], v[192:195], v[92:95]
	v_mfma_f32_16x16x32_bf16 v[88:91], v[168:171], v[192:195], v[88:91]
	s_setprio 2
	s_barrier
	v_mfma_f32_16x16x32_bf16 v[76:79], v[160:163], v[200:203], v[76:79]
	v_mfma_f32_16x16x32_bf16 v[72:75], v[168:171], v[200:203], v[72:75]
	s_setprio 0
	s_add_i32 s12, 0, 0x1c000
	s_add_i32 s13, s29, s34
	v_add_u32_e32 v148, s12, v151
	v_lshl_add_u64 v[220:221], v[220:221], 0, s[22:23]
	s_mov_b32 m0, s13
	ds_read_b128 v[204:207], v148
	ds_read_b128 v[208:211], v148 offset:1024
	ds_read_b128 v[212:215], v148 offset:2048
	ds_read_b128 v[216:219], v148 offset:3072
	global_load_lds_dwordx4 v[220:221], off
	v_lshl_add_u64 v[220:221], v[224:225], 0, s[22:23]
	s_add_i32 m0, s13, 0x2000
	s_nop 0
	global_load_lds_dwordx4 v[220:221], off
	s_barrier
	s_waitcnt lgkmcnt(0)
	s_setprio 1
	s_waitcnt lgkmcnt(0)
	v_mfma_f32_16x16x32_bf16 v[116:119], v[204:207], v[172:175], v[116:119]
	v_mfma_f32_16x16x32_bf16 v[112:115], v[212:215], v[172:175], v[112:115]
	v_mfma_f32_16x16x32_bf16 v[100:103], v[204:207], v[180:183], v[100:103]
	v_mfma_f32_16x16x32_bf16 v[96:99], v[212:215], v[180:183], v[96:99]
	v_mfma_f32_16x16x32_bf16 v[84:87], v[204:207], v[188:191], v[84:87]
	v_mfma_f32_16x16x32_bf16 v[80:83], v[212:215], v[188:191], v[80:83]
	v_mfma_f32_16x16x32_bf16 v[68:71], v[204:207], v[196:199], v[68:71]
	v_mfma_f32_16x16x32_bf16 v[64:67], v[212:215], v[196:199], v[64:67]
	v_mfma_f32_16x16x32_bf16 v[116:119], v[208:211], v[176:179], v[116:119]
	v_mfma_f32_16x16x32_bf16 v[112:115], v[216:219], v[176:179], v[112:115]
	v_mfma_f32_16x16x32_bf16 v[100:103], v[208:211], v[184:187], v[100:103]
	v_mfma_f32_16x16x32_bf16 v[96:99], v[216:219], v[184:187], v[96:99]
	v_mfma_f32_16x16x32_bf16 v[84:87], v[208:211], v[192:195], v[84:87]
	v_mfma_f32_16x16x32_bf16 v[80:83], v[216:219], v[192:195], v[80:83]
	s_setprio 2
	s_barrier
; #define PG8_STAGE(bufoff, gbase, voff) do { _Pragma("unroll") for (int _i = 0; _i < 2; ++_i) \
;         __builtin_amdgcn_global_load_lds((const unsigned*)((const char*)(gbase) + (voff)[_i]), (LAS unsigned*)(lds + (bufoff) + ldsw + _i * 8192), 16, 0, 0); } while (0)
; #define PG8_LDA(dst, b, h) do { _Pragma("unroll") for (int m = 0; m < 4; ++m) _Pragma("unroll") for (int k = 0; k < 2; ++k) dst[m][k] = *(const LAS bf16x8*)(lds + PG8_SA(b, h) + aoff + m * 2048 + k * 1024); } while (0)
; #define PG8_MMA(ai, bj, At, Bt) do { __builtin_amdgcn_s_setprio(1); _Pragma("unroll") for (int m = 0; m < 4; ++m) _Pragma("unroll") for (int n = 0; n < 2; ++n) _Pragma("unroll") for (int k = 0; k < 2; ++k) \
;         acc[ai][bj][m][n] = __builtin_amdgcn_mfma_f32_16x16x32_bf16(Bt[n][k], At[m][k], acc[ai][bj][m][n], 0, 0, 0); __builtin_amdgcn_s_setprio(0); } while (0)
; #define PG8_WAIT_V(n) asm volatile("s_waitcnt vmcnt(" #n ")" ::: "memory")
; #define PG8_WAIT_L(n) asm volatile("s_waitcnt lgkmcnt(" #n ")" ::: "memory")
; #define PG8_BAR __builtin_amdgcn_s_barrier()
; #define PG8_SCHED __builtin_amdgcn_sched_barrier(0)
; #define PG8_STAGE(bufoff, gbase, voff) do { _Pragma("unroll") for (int _i = 0; _i < 2; ++_i) \
;         __builtin_amdgcn_global_load_lds((const unsigned*)((const char*)(gbase) + (voff)[_i]), (LAS unsigned*)(lds + (bufoff) + ldsw + _i * 8192), 16, 0, 0); } while (0)
; #define PG8_LDA(dst, b, h) do { _Pragma("unroll") for (int m = 0; m < 4; ++m) _Pragma("unroll") for (int k = 0; k < 2; ++k) dst[m][k] = *(const LAS bf16x8*)(lds + PG8_SA(b, h) + aoff + m * 2048 + k * 1024); } while (0)
; #define PG8_WAIT_V(n) asm volatile("s_waitcnt vmcnt(" #n ")" ::: "memory")
; template <class Epi>
; DI void gemm_phase(LAS unsigned char* lds, const Gemm g, const StaticOrder S, const Epi E) {
;     ...
;             PG8_BAR; PG8_WAIT_L(0); PG8_MMA(0, 1, At, B1); PG8_BAR;
;             PG8_LDA(At, 1, 1); PG8_STAGE(PG8_SA(1, 0), a3, voffA);
;             PG8_BAR; PG8_WAIT_L(0); PG8_MMA(1, 0, At, B0); PG8_BAR; PG8_SCHED;
;             PG8_STAGE(PG8_SB(1, 1), b3 + hstep, voffB);
;             PG8_WAIT_V(6); PG8_BAR; PG8_MMA(1, 1, At, B1); PG8_BAR;
;     DI void operator()(AccRef acc, const Unit& u, int wr, int wc, int fr, int fq) const {
;         const int row0 = u.pm * 256 + wr * 64 + fr, col = u.pn * 128 + wc * 32 + 8 * fq;
;         RowScales rsc; if (RS) rsc = load_rowscales(ss, row0);
	v_mfma_f32_16x16x32_bf16 v[68:71], v[208:211], v[200:203], v[68:71]
	v_mfma_f32_16x16x32_bf16 v[64:67], v[216:219], v[200:203], v[64:67]
	s_setprio 0
	s_mov_b32 m0, s45
	v_lshl_add_u64 v[220:221], v[226:227], 0, s[22:23]
	ds_read_b128 v[172:175], v157 offset:49152
	ds_read_b128 v[176:179], v157 offset:50176
	ds_read_b128 v[180:183], v157 offset:51200
	ds_read_b128 v[184:187], v157 offset:52224
	ds_read_b128 v[188:191], v157 offset:53248
	ds_read_b128 v[192:195], v157 offset:54272
	ds_read_b128 v[196:199], v157 offset:55296
	ds_read_b128 v[200:203], v157 offset:56320
	global_load_lds_dwordx4 v[220:221], off
	v_lshl_add_u64 v[220:221], v[228:229], 0, s[22:23]
	s_mov_b32 m0, s46
	s_nop 0
	global_load_lds_dwordx4 v[220:221], off
	s_barrier
	s_waitcnt lgkmcnt(0)
	s_setprio 1
	s_waitcnt lgkmcnt(0)
	v_mfma_f32_16x16x32_bf16 v[60:63], v[144:147], v[172:175], v[60:63]
	v_mfma_f32_16x16x32_bf16 v[56:59], v[164:167], v[172:175], v[56:59]
	v_mfma_f32_16x16x32_bf16 v[44:47], v[144:147], v[180:183], v[44:47]
	v_mfma_f32_16x16x32_bf16 v[40:43], v[164:167], v[180:183], v[40:43]
	v_mfma_f32_16x16x32_bf16 v[28:31], v[144:147], v[188:191], v[28:31]
	v_mfma_f32_16x16x32_bf16 v[24:27], v[164:167], v[188:191], v[24:27]
	v_mfma_f32_16x16x32_bf16 v[12:15], v[144:147], v[196:199], v[12:15]
	v_mfma_f32_16x16x32_bf16 v[8:11], v[164:167], v[196:199], v[8:11]
	v_mfma_f32_16x16x32_bf16 v[60:63], v[160:163], v[176:179], v[60:63]
	v_mfma_f32_16x16x32_bf16 v[56:59], v[168:171], v[176:179], v[56:59]
	v_mfma_f32_16x16x32_bf16 v[44:47], v[160:163], v[184:187], v[44:47]
	v_mfma_f32_16x16x32_bf16 v[40:43], v[168:171], v[184:187], v[40:43]
	v_mfma_f32_16x16x32_bf16 v[28:31], v[160:163], v[192:195], v[28:31]
	v_mfma_f32_16x16x32_bf16 v[24:27], v[168:171], v[192:195], v[24:27]
	s_setprio 2
	s_barrier
	v_mfma_f32_16x16x32_bf16 v[12:15], v[160:163], v[200:203], v[12:15]
	v_mfma_f32_16x16x32_bf16 v[8:11], v[168:171], v[200:203], v[8:11]
	s_setprio 0
	s_add_u32 s10, s10, 0x40080
	s_addc_u32 s11, s11, 0
	s_add_i32 s12, s12, s34
	v_lshl_add_u64 v[144:145], s[10:11], 0, v[132:133]
	s_mov_b32 m0, s12
	s_nop 0
	global_load_lds_dwordx4 v[144:145], off
	v_lshl_add_u64 v[144:145], s[10:11], 0, v[128:129]
	s_add_i32 m0, s12, 0x2000
	s_nop 0
	global_load_lds_dwordx4 v[144:145], off
	s_waitcnt vmcnt(6)
	s_barrier
	s_setprio 1
	v_mfma_f32_16x16x32_bf16 v[52:55], v[204:207], v[172:175], v[52:55]
	v_mfma_f32_16x16x32_bf16 v[48:51], v[212:215], v[172:175], v[48:51]
	v_mfma_f32_16x16x32_bf16 v[36:39], v[204:207], v[180:183], v[36:39]
	v_mfma_f32_16x16x32_bf16 v[32:35], v[212:215], v[180:183], v[32:35]
	v_mfma_f32_16x16x32_bf16 v[20:23], v[204:207], v[188:191], v[20:23]
	v_mfma_f32_16x16x32_bf16 v[16:19], v[212:215], v[188:191], v[16:19]
	v_mfma_f32_16x16x32_bf16 v[4:7], v[204:207], v[196:199], v[4:7]
	v_mfma_f32_16x16x32_bf16 v[0:3], v[212:215], v[196:199], v[0:3]
	v_mfma_f32_16x16x32_bf16 v[52:55], v[208:211], v[176:179], v[52:55]
	v_mfma_f32_16x16x32_bf16 v[48:51], v[216:219], v[176:179], v[48:51]
	v_mfma_f32_16x16x32_bf16 v[36:39], v[208:211], v[184:187], v[36:39]
	v_mfma_f32_16x16x32_bf16 v[32:35], v[216:219], v[184:187], v[32:35]
	v_mfma_f32_16x16x32_bf16 v[20:23], v[208:211], v[192:195], v[20:23]
	v_mfma_f32_16x16x32_bf16 v[16:19], v[216:219], v[192:195], v[16:19]
	s_setprio 2
	s_barrier
	v_mfma_f32_16x16x32_bf16 v[4:7], v[208:211], v[200:203], v[4:7]
	v_mfma_f32_16x16x32_bf16 v[0:3], v[216:219], v[200:203], v[0:3]
	s_setprio 0
	s_add_i32 s25, s25, 2
	s_add_u32 s8, s8, 0x100
	s_addc_u32 s9, s9, 0
	s_add_u32 s18, s18, 0x100
	s_addc_u32 s19, s19, 0
	s_cmp_gt_u32 s25, 13
	s_cbranch_scc0 .LBB0_865
	v_lshl_add_u32 v146, s4, 8, v149
	v_ashrrev_i32_e32 v147, 31, v146
	v_lshl_add_u64 v[144:145], v[146:147], 2, s[20:21]
	global_load_dword v147, v[144:145], off
	global_load_dword v148, v[144:145], off offset:64
	global_load_dword v150, v[144:145], off offset:128
	global_load_dword v152, v[144:145], off offset:192
	global_load_dword v154, v[144:145], off offset:512
	global_load_dword v156, v[144:145], off offset:576
	global_load_dword v160, v[144:145], off offset:640
	global_load_dword v161, v[144:145], off offset:704
	v_lshl_or_b32 v144, s5, 7, v153
	v_ashrrev_i32_e32 v145, 31, v144
	v_lshl_add_u64 v[144:145], v[144:145], 1, s[54:55]
	s_waitcnt vmcnt(0)
; DI unsigned pk_bf16(float lo, float hi) { f32x2 v = {lo, hi}; return __builtin_bit_cast(unsigned, __builtin_convertvector(v, bf16v2)); }
; DI float fast_silu(float x) { return x * fast_sigmoid(x); }
; DI RowScales load_rowscales(const float* ss, int row0) {
;     ...
;         for (int m = 0; m < 4; ++m) t.r[ai][m] = ss[row0 + ai * 128 + m * 16];
; #pragma unroll
;     for (int ai = 0; ai < 2; ++ai)
; #pragma unroll
;         for (int m = 0; m < 4; ++m) t.r[ai][m] = rsqrtf(t.r[ai][m] * (1.0f / 1024.0f) + 1e-6f);
;     DI void operator()(AccRef acc, const Unit& u, int wr, int wc, int fr, int fq) const {
;         const int row0 = u.pm * 256 + wr * 64 + fr, col = u.pn * 128 + wc * 32 + 8 * fq;
;         RowScales rsc; if (RS) rsc = load_rowscales(ss, row0);
; #pragma unroll
;         for (int ai = 0; ai < 2; ++ai)
; #pragma unroll
;             for (int m = 0; m < 4; ++m) {
;                 const int row = row0 + ai * 128 + m * 16;
;                 const float r = RS ? rsc.r[ai][m] : 1.0f;
;                 const f32x4 a0 = acc[ai][0][m][0] * r, a1 = acc[ai][0][m][1] * r, b0 = acc[ai][1][m][0] * r, b1 = acc[ai][1][m][1] * r;
;                 u32x4 w;
;                 w.x = pk_bf16(fast_silu(a0[0]) * b0[0], fast_silu(a0[1]) * b0[1]); w.y = pk_bf16(fast_silu(a0[2]) * b0[2], fast_silu(a0[3]) * b0[3]);
;                 w.z = pk_bf16(fast_silu(a1[0]) * b1[0], fast_silu(a1[1]) * b1[1]); w.w = pk_bf16(fast_silu(a1[2]) * b1[2], fast_silu(a1[3]) * b1[3]);
;                 *(u32x4*)(G + (size_t)row * DFF + col) = w;
	v_fmamk_f32 v147, v147, 0x3a800000, v159
	v_mul_f32_e32 v162, 0x4b800000, v147
	v_cmp_gt_f32_e32 vcc, s51, v147
	v_fmamk_f32 v152, v152, 0x3a800000, v159
	v_fmamk_f32 v154, v154, 0x3a800000, v159
	v_cndmask_b32_e32 v147, v147, v162, vcc
	v_mul_f32_e32 v165, 0x4b800000, v152
	v_fmamk_f32 v161, v161, 0x3a800000, v159
	v_mul_f32_e32 v166, 0x4b800000, v154
	v_mul_f32_e32 v169, 0x4b800000, v161
	v_cmp_gt_f32_e64 s[10:11], s51, v152
	v_cmp_gt_f32_e64 s[12:13], s51, v154
	v_cmp_gt_f32_e64 s[18:19], s51, v161
	v_rsq_f32_e32 v147, v147
	v_fmamk_f32 v156, v156, 0x3a800000, v159
	v_cndmask_b32_e64 v152, v152, v165, s[10:11]
	v_cndmask_b32_e64 v154, v154, v166, s[12:13]
	v_cndmask_b32_e64 v161, v161, v169, s[18:19]
	v_fmamk_f32 v148, v148, 0x3a800000, v159
	v_fmamk_f32 v160, v160, 0x3a800000, v159
	v_mul_f32_e32 v167, 0x4b800000, v156
	v_cmp_gt_f32_e64 s[14:15], s51, v156
	v_rsq_f32_e32 v152, v152
	v_rsq_f32_e32 v154, v154
	v_rsq_f32_e32 v161, v161
	v_mul_f32_e32 v163, 0x4b800000, v148
	v_mul_f32_e32 v168, 0x4b800000, v160
	v_cmp_gt_f32_e64 s[4:5], s51, v148
	v_cndmask_b32_e64 v156, v156, v167, s[14:15]
	v_cmp_gt_f32_e64 s[16:17], s51, v160
	v_fmamk_f32 v150, v150, 0x3a800000, v159
	v_cndmask_b32_e64 v148, v148, v163, s[4:5]
	v_cndmask_b32_e64 v160, v160, v168, s[16:17]
	v_rsq_f32_e32 v163, v156
	v_mul_f32_e32 v156, 0x45800000, v147
	v_mul_f32_e32 v164, 0x4b800000, v150
	v_cmp_gt_f32_e64 s[8:9], s51, v150
	v_rsq_f32_e32 v165, v160
	v_cndmask_b32_e32 v160, v147, v156, vcc
	v_cndmask_b32_e64 v150, v150, v164, s[8:9]
	v_rsq_f32_e32 v148, v148
	v_mul_f32_e32 v166, 0x45800000, v152
	v_mul_f32_e32 v167, 0x45800000, v154
	v_pk_mul_f32 v[126:127], v[126:127], v[160:161] op_sel_hi:[1,0]
	v_pk_mul_f32 v[124:125], v[124:125], v[160:161] op_sel_hi:[1,0]
	v_rsq_f32_e32 v150, v150
	v_cndmask_b32_e64 v156, v152, v166, s[10:11]
	v_cndmask_b32_e64 v154, v154, v167, s[12:13]
	v_pk_mul_f32 v[122:123], v[122:123], v[160:161] op_sel_hi:[1,0]
	v_pk_mul_f32 v[120:121], v[120:121], v[160:161] op_sel_hi:[1,0]
	v_pk_mul_f32 v[118:119], v[118:119], v[160:161] op_sel_hi:[1,0]
	v_pk_mul_f32 v[116:117], v[116:117], v[160:161] op_sel_hi:[1,0]
	v_pk_mul_f32 v[166:167], v[114:115], v[160:161] op_sel_hi:[1,0]
	v_pk_mul_f32 v[114:115], v[112:113], v[160:161] op_sel_hi:[1,0]
	v_mul_f32_e32 v112, 0xbfb8aa3b, v124
	v_mul_f32_e32 v113, 0xbfb8aa3b, v125
	v_mul_f32_e32 v147, 0xbfb8aa3b, v126
	v_mul_f32_e32 v160, 0xbfb8aa3b, v127
	v_exp_f32_e32 v112, v112
	v_exp_f32_e32 v113, v113
	v_exp_f32_e32 v147, v147
	v_exp_f32_e32 v160, v160
	v_mul_f32_e32 v162, 0x45800000, v148
	v_mul_f32_e32 v170, 0x45800000, v161
	v_mul_f32_e32 v164, 0x45800000, v150
	v_mul_f32_e32 v169, 0x45800000, v165
	v_cndmask_b32_e64 v162, v148, v162, s[4:5]
	v_cndmask_b32_e64 v148, v161, v170, s[18:19]
	v_mul_f32_e32 v161, 0xbfb8aa3b, v120
	v_cndmask_b32_e64 v164, v150, v164, s[8:9]
	v_cndmask_b32_e64 v150, v165, v169, s[16:17]
	v_exp_f32_e32 v165, v161
	v_add_f32_e32 v112, 1.0, v112
	v_add_f32_e32 v113, 1.0, v113
	v_add_f32_e32 v147, 1.0, v147
	v_add_f32_e32 v161, 1.0, v160
	v_rcp_f32_e32 v112, v112
	v_rcp_f32_e32 v113, v113
	v_rcp_f32_e32 v160, v147
	v_rcp_f32_e32 v161, v161
	v_mul_f32_e32 v168, 0x45800000, v163
	v_pk_mul_f32 v[112:113], v[124:125], v[112:113]
	v_cndmask_b32_e64 v152, v163, v168, s[14:15]
	v_pk_mul_f32 v[124:125], v[126:127], v[160:161]
	v_mul_f32_e32 v163, 0xbfb8aa3b, v121
	v_pk_mul_f32 v[112:113], v[116:117], v[112:113]
	v_pk_mul_f32 v[116:117], v[118:119], v[124:125]
	v_exp_f32_e32 v163, v163
	v_cvt_pk_bf16_f32 v112, v112, v113
	v_cvt_pk_bf16_f32 v113, v116, v117
	v_mul_f32_e32 v117, 0xbfb8aa3b, v122
	v_mul_f32_e32 v118, 0xbfb8aa3b, v123
	v_exp_f32_e32 v117, v117
	v_exp_f32_e32 v118, v118
	v_add_f32_e32 v116, 1.0, v163
	v_add_f32_e32 v147, 1.0, v165
	v_rcp_f32_e32 v169, v116
	v_add_f32_e32 v116, 1.0, v117
	v_add_f32_e32 v117, 1.0, v118
	v_rcp_f32_e32 v168, v147
	v_rcp_f32_e32 v116, v116
	v_rcp_f32_e32 v117, v117
	v_pk_mul_f32 v[108:109], v[108:109], v[162:163] op_sel_hi:[1,0]
	v_pk_mul_f32 v[118:119], v[120:121], v[168:169]
	v_pk_mul_f32 v[110:111], v[110:111], v[162:163] op_sel_hi:[1,0]
	v_pk_mul_f32 v[116:117], v[122:123], v[116:117]
	v_pk_mul_f32 v[114:115], v[114:115], v[118:119]
	v_pk_mul_f32 v[116:117], v[166:167], v[116:117]
	v_cvt_pk_bf16_f32 v114, v114, v115
	v_cvt_pk_bf16_f32 v115, v116, v117
	v_mad_i64_i32 v[116:117], s[4:5], v146, s52, v[144:145]
	global_store_dwordx4 v[116:117], v[112:115], off
	v_pk_mul_f32 v[100:101], v[100:101], v[162:163] op_sel_hi:[1,0]
	v_pk_mul_f32 v[104:105], v[104:105], v[162:163] op_sel_hi:[1,0]
	v_pk_mul_f32 v[112:113], v[98:99], v[162:163] op_sel_hi:[1,0]
	v_mul_f32_e32 v98, 0xbfb8aa3b, v108
	v_exp_f32_e32 v114, v98
	v_mul_f32_e32 v98, 0xbfb8aa3b, v109
	v_exp_f32_e32 v115, v98
	v_pk_mul_f32 v[98:99], v[96:97], v[162:163] op_sel_hi:[1,0]
	v_add_f32_e32 v96, 1.0, v114
	v_mul_f32_e32 v114, 0xbfb8aa3b, v110
	v_add_f32_e32 v97, 1.0, v115
	v_mul_f32_e32 v115, 0xbfb8aa3b, v111
	v_exp_f32_e32 v114, v114
	v_exp_f32_e32 v115, v115
	v_rcp_f32_e32 v96, v96
	v_rcp_f32_e32 v97, v97
	v_add_f32_e32 v114, 1.0, v114
	v_add_f32_e32 v115, 1.0, v115
	v_rcp_f32_e32 v114, v114
	v_rcp_f32_e32 v115, v115
	v_pk_mul_f32 v[96:97], v[108:109], v[96:97]
	v_pk_mul_f32 v[102:103], v[102:103], v[162:163] op_sel_hi:[1,0]
	v_pk_mul_f32 v[96:97], v[100:101], v[96:97]
	v_pk_mul_f32 v[100:101], v[110:111], v[114:115]
	v_cvt_pk_bf16_f32 v96, v96, v97
	v_mul_f32_e32 v97, 0xbfb8aa3b, v104
	v_pk_mul_f32 v[100:101], v[102:103], v[100:101]
	v_exp_f32_e32 v102, v97
	v_mul_f32_e32 v97, 0xbfb8aa3b, v105
	v_exp_f32_e32 v103, v97
	v_pk_mul_f32 v[106:107], v[106:107], v[162:163] op_sel_hi:[1,0]
; DI unsigned pk_bf16(float lo, float hi) { f32x2 v = {lo, hi}; return __builtin_bit_cast(unsigned, __builtin_convertvector(v, bf16v2)); }
; DI float fast_silu(float x) { return x * fast_sigmoid(x); }
;     DI void operator()(AccRef acc, const Unit& u, int wr, int wc, int fr, int fq) const {
;     ...
;             for (int m = 0; m < 4; ++m) {
;                 const int row = row0 + ai * 128 + m * 16;
;                 const float r = RS ? rsc.r[ai][m] : 1.0f;
;                 const f32x4 a0 = acc[ai][0][m][0] * r, a1 = acc[ai][0][m][1] * r, b0 = acc[ai][1][m][0] * r, b1 = acc[ai][1][m][1] * r;
;                 u32x4 w;
;                 w.x = pk_bf16(fast_silu(a0[0]) * b0[0], fast_silu(a0[1]) * b0[1]); w.y = pk_bf16(fast_silu(a0[2]) * b0[2], fast_silu(a0[3]) * b0[3]);
;                 w.z = pk_bf16(fast_silu(a1[0]) * b1[0], fast_silu(a1[1]) * b1[1]); w.w = pk_bf16(fast_silu(a1[2]) * b1[2], fast_silu(a1[3]) * b1[3]);
;                 *(u32x4*)(G + (size_t)row * DFF + col) = w;
	v_cvt_pk_bf16_f32 v97, v100, v101
	v_add_f32_e32 v100, 1.0, v102
	v_add_f32_e32 v101, 1.0, v103
	v_mul_f32_e32 v102, 0xbfb8aa3b, v106
	v_mul_f32_e32 v103, 0xbfb8aa3b, v107
	v_exp_f32_e32 v102, v102
	v_exp_f32_e32 v103, v103
	v_rcp_f32_e32 v100, v100
	v_rcp_f32_e32 v101, v101
	v_add_f32_e32 v102, 1.0, v102
	v_add_f32_e32 v103, 1.0, v103
	v_rcp_f32_e32 v102, v102
	v_rcp_f32_e32 v103, v103
	v_pk_mul_f32 v[100:101], v[104:105], v[100:101]
	v_or_b32_e32 v116, 16, v146
	v_pk_mul_f32 v[98:99], v[98:99], v[100:101]
	v_pk_mul_f32 v[100:101], v[106:107], v[102:103]
	v_cvt_pk_bf16_f32 v98, v98, v99
	v_pk_mul_f32 v[100:101], v[112:113], v[100:101]
	v_pk_mul_f32 v[92:93], v[92:93], v[164:165] op_sel_hi:[1,0]
	v_cvt_pk_bf16_f32 v99, v100, v101
	v_mad_i64_i32 v[100:101], s[4:5], v116, s52, v[144:145]
	global_store_dwordx4 v[100:101], v[96:99], off
	v_pk_mul_f32 v[94:95], v[94:95], v[164:165] op_sel_hi:[1,0]
	v_pk_mul_f32 v[84:85], v[84:85], v[164:165] op_sel_hi:[1,0]
	v_pk_mul_f32 v[96:97], v[82:83], v[164:165] op_sel_hi:[1,0]
	v_mul_f32_e32 v82, 0xbfb8aa3b, v92
	v_exp_f32_e32 v98, v82
	v_mul_f32_e32 v82, 0xbfb8aa3b, v93
	v_exp_f32_e32 v99, v82
	v_pk_mul_f32 v[82:83], v[80:81], v[164:165] op_sel_hi:[1,0]
	v_add_f32_e32 v80, 1.0, v98
	v_mul_f32_e32 v98, 0xbfb8aa3b, v94
	v_add_f32_e32 v81, 1.0, v99
	v_mul_f32_e32 v99, 0xbfb8aa3b, v95
	v_exp_f32_e32 v98, v98
	v_exp_f32_e32 v99, v99
	v_rcp_f32_e32 v80, v80
	v_rcp_f32_e32 v81, v81
	v_add_f32_e32 v98, 1.0, v98
	v_add_f32_e32 v99, 1.0, v99
	v_rcp_f32_e32 v98, v98
	v_rcp_f32_e32 v99, v99
	v_pk_mul_f32 v[80:81], v[92:93], v[80:81]
	v_pk_mul_f32 v[88:89], v[88:89], v[164:165] op_sel_hi:[1,0]
	v_pk_mul_f32 v[80:81], v[84:85], v[80:81]
	v_pk_mul_f32 v[86:87], v[86:87], v[164:165] op_sel_hi:[1,0]
	v_cvt_pk_bf16_f32 v80, v80, v81
	v_pk_mul_f32 v[84:85], v[94:95], v[98:99]
	v_mul_f32_e32 v81, 0xbfb8aa3b, v88
	v_pk_mul_f32 v[84:85], v[86:87], v[84:85]
	v_exp_f32_e32 v86, v81
	v_mul_f32_e32 v81, 0xbfb8aa3b, v89
	v_exp_f32_e32 v87, v81
	v_pk_mul_f32 v[90:91], v[90:91], v[164:165] op_sel_hi:[1,0]
	v_cvt_pk_bf16_f32 v81, v84, v85
	v_add_f32_e32 v84, 1.0, v86
	v_add_f32_e32 v85, 1.0, v87
	v_mul_f32_e32 v86, 0xbfb8aa3b, v90
	v_mul_f32_e32 v87, 0xbfb8aa3b, v91
	v_exp_f32_e32 v86, v86
	v_exp_f32_e32 v87, v87
	v_rcp_f32_e32 v84, v84
	v_rcp_f32_e32 v85, v85
	v_add_f32_e32 v86, 1.0, v86
	v_add_f32_e32 v87, 1.0, v87
	v_rcp_f32_e32 v86, v86
	v_rcp_f32_e32 v87, v87
	v_pk_mul_f32 v[84:85], v[88:89], v[84:85]
	v_or_b32_e32 v100, 32, v146
	v_pk_mul_f32 v[82:83], v[82:83], v[84:85]
	v_pk_mul_f32 v[84:85], v[90:91], v[86:87]
	v_cvt_pk_bf16_f32 v82, v82, v83
	v_pk_mul_f32 v[84:85], v[96:97], v[84:85]
	v_pk_mul_f32 v[76:77], v[76:77], v[156:157] op_sel_hi:[1,0]
	v_cvt_pk_bf16_f32 v83, v84, v85
	v_mad_i64_i32 v[84:85], s[4:5], v100, s52, v[144:145]
	global_store_dwordx4 v[84:85], v[80:83], off
	v_pk_mul_f32 v[78:79], v[78:79], v[156:157] op_sel_hi:[1,0]
	v_pk_mul_f32 v[68:69], v[68:69], v[156:157] op_sel_hi:[1,0]
	v_pk_mul_f32 v[80:81], v[66:67], v[156:157] op_sel_hi:[1,0]
	v_mul_f32_e32 v66, 0xbfb8aa3b, v76
	v_exp_f32_e32 v82, v66
	v_mul_f32_e32 v66, 0xbfb8aa3b, v77
	v_exp_f32_e32 v83, v66
	v_pk_mul_f32 v[66:67], v[64:65], v[156:157] op_sel_hi:[1,0]
	v_add_f32_e32 v64, 1.0, v82
	v_mul_f32_e32 v82, 0xbfb8aa3b, v78
	v_add_f32_e32 v65, 1.0, v83
	v_mul_f32_e32 v83, 0xbfb8aa3b, v79
	v_exp_f32_e32 v82, v82
	v_exp_f32_e32 v83, v83
	v_rcp_f32_e32 v64, v64
	v_rcp_f32_e32 v65, v65
	v_add_f32_e32 v82, 1.0, v82
	v_add_f32_e32 v83, 1.0, v83
	v_rcp_f32_e32 v82, v82
	v_rcp_f32_e32 v83, v83
	v_pk_mul_f32 v[64:65], v[76:77], v[64:65]
	v_pk_mul_f32 v[72:73], v[72:73], v[156:157] op_sel_hi:[1,0]
	v_pk_mul_f32 v[64:65], v[68:69], v[64:65]
	v_pk_mul_f32 v[70:71], v[70:71], v[156:157] op_sel_hi:[1,0]
	v_cvt_pk_bf16_f32 v64, v64, v65
	v_pk_mul_f32 v[68:69], v[78:79], v[82:83]
	v_mul_f32_e32 v65, 0xbfb8aa3b, v72
	v_pk_mul_f32 v[68:69], v[70:71], v[68:69]
	v_exp_f32_e32 v70, v65
	v_mul_f32_e32 v65, 0xbfb8aa3b, v73
	v_exp_f32_e32 v71, v65
	v_pk_mul_f32 v[74:75], v[74:75], v[156:157] op_sel_hi:[1,0]
	v_cvt_pk_bf16_f32 v65, v68, v69
	v_add_f32_e32 v68, 1.0, v70
	v_add_f32_e32 v69, 1.0, v71
	v_mul_f32_e32 v70, 0xbfb8aa3b, v74
	v_mul_f32_e32 v71, 0xbfb8aa3b, v75
	v_exp_f32_e32 v70, v70
	v_exp_f32_e32 v71, v71
	v_rcp_f32_e32 v68, v68
	v_rcp_f32_e32 v69, v69
	v_add_f32_e32 v70, 1.0, v70
	v_add_f32_e32 v71, 1.0, v71
	v_rcp_f32_e32 v70, v70
	v_rcp_f32_e32 v71, v71
	v_pk_mul_f32 v[68:69], v[72:73], v[68:69]
	v_or_b32_e32 v84, 48, v146
	v_pk_mul_f32 v[66:67], v[66:67], v[68:69]
	v_pk_mul_f32 v[68:69], v[74:75], v[70:71]
	v_cvt_pk_bf16_f32 v66, v66, v67
	v_pk_mul_f32 v[68:69], v[80:81], v[68:69]
	v_pk_mul_f32 v[60:61], v[60:61], v[154:155] op_sel_hi:[1,0]
	v_cvt_pk_bf16_f32 v67, v68, v69
	v_mad_i64_i32 v[68:69], s[4:5], v84, s52, v[144:145]
	global_store_dwordx4 v[68:69], v[64:67], off
	v_pk_mul_f32 v[62:63], v[62:63], v[154:155] op_sel_hi:[1,0]
	v_pk_mul_f32 v[52:53], v[52:53], v[154:155] op_sel_hi:[1,0]
	v_pk_mul_f32 v[64:65], v[50:51], v[154:155] op_sel_hi:[1,0]
	v_mul_f32_e32 v50, 0xbfb8aa3b, v60
	v_exp_f32_e32 v66, v50
	v_mul_f32_e32 v50, 0xbfb8aa3b, v61
	v_exp_f32_e32 v67, v50
	v_pk_mul_f32 v[50:51], v[48:49], v[154:155] op_sel_hi:[1,0]
	v_add_f32_e32 v48, 1.0, v66
	v_mul_f32_e32 v66, 0xbfb8aa3b, v62
	v_add_f32_e32 v49, 1.0, v67
	v_mul_f32_e32 v67, 0xbfb8aa3b, v63
	v_exp_f32_e32 v66, v66
	v_exp_f32_e32 v67, v67
	v_rcp_f32_e32 v48, v48
	v_rcp_f32_e32 v49, v49
	v_add_f32_e32 v66, 1.0, v66
	v_add_f32_e32 v67, 1.0, v67
	v_rcp_f32_e32 v66, v66
	v_rcp_f32_e32 v67, v67
	v_pk_mul_f32 v[48:49], v[60:61], v[48:49]
	v_pk_mul_f32 v[56:57], v[56:57], v[154:155] op_sel_hi:[1,0]
; DI unsigned pk_bf16(float lo, float hi) { f32x2 v = {lo, hi}; return __builtin_bit_cast(unsigned, __builtin_convertvector(v, bf16v2)); }
; DI float fast_silu(float x) { return x * fast_sigmoid(x); }
;     DI void operator()(AccRef acc, const Unit& u, int wr, int wc, int fr, int fq) const {
;     ...
;             for (int m = 0; m < 4; ++m) {
;                 const int row = row0 + ai * 128 + m * 16;
;                 const float r = RS ? rsc.r[ai][m] : 1.0f;
;                 const f32x4 a0 = acc[ai][0][m][0] * r, a1 = acc[ai][0][m][1] * r, b0 = acc[ai][1][m][0] * r, b1 = acc[ai][1][m][1] * r;
;                 u32x4 w;
;                 w.x = pk_bf16(fast_silu(a0[0]) * b0[0], fast_silu(a0[1]) * b0[1]); w.y = pk_bf16(fast_silu(a0[2]) * b0[2], fast_silu(a0[3]) * b0[3]);
;                 w.z = pk_bf16(fast_silu(a1[0]) * b1[0], fast_silu(a1[1]) * b1[1]); w.w = pk_bf16(fast_silu(a1[2]) * b1[2], fast_silu(a1[3]) * b1[3]);
;                 *(u32x4*)(G + (size_t)row * DFF + col) = w;
	v_pk_mul_f32 v[48:49], v[52:53], v[48:49]
	v_pk_mul_f32 v[54:55], v[54:55], v[154:155] op_sel_hi:[1,0]
	v_cvt_pk_bf16_f32 v48, v48, v49
	v_pk_mul_f32 v[52:53], v[62:63], v[66:67]
	v_mul_f32_e32 v49, 0xbfb8aa3b, v56
	v_pk_mul_f32 v[52:53], v[54:55], v[52:53]
	v_exp_f32_e32 v54, v49
	v_mul_f32_e32 v49, 0xbfb8aa3b, v57
	v_exp_f32_e32 v55, v49
	v_pk_mul_f32 v[58:59], v[58:59], v[154:155] op_sel_hi:[1,0]
	v_cvt_pk_bf16_f32 v49, v52, v53
	v_add_f32_e32 v52, 1.0, v54
	v_add_f32_e32 v53, 1.0, v55
	v_mul_f32_e32 v54, 0xbfb8aa3b, v58
	v_mul_f32_e32 v55, 0xbfb8aa3b, v59
	v_exp_f32_e32 v54, v54
	v_exp_f32_e32 v55, v55
	v_rcp_f32_e32 v52, v52
	v_rcp_f32_e32 v53, v53
	v_add_f32_e32 v54, 1.0, v54
	v_add_f32_e32 v55, 1.0, v55
	v_rcp_f32_e32 v54, v54
	v_rcp_f32_e32 v55, v55
	v_pk_mul_f32 v[52:53], v[56:57], v[52:53]
	v_add_u32_e32 v68, 0x80, v146
	v_pk_mul_f32 v[50:51], v[50:51], v[52:53]
	v_pk_mul_f32 v[52:53], v[58:59], v[54:55]
	v_cvt_pk_bf16_f32 v50, v50, v51
	v_pk_mul_f32 v[52:53], v[64:65], v[52:53]
	v_pk_mul_f32 v[44:45], v[44:45], v[152:153] op_sel_hi:[1,0]
	v_cvt_pk_bf16_f32 v51, v52, v53
	v_mad_i64_i32 v[52:53], s[4:5], v68, s52, v[144:145]
	global_store_dwordx4 v[52:53], v[48:51], off
	v_pk_mul_f32 v[46:47], v[46:47], v[152:153] op_sel_hi:[1,0]
	v_pk_mul_f32 v[36:37], v[36:37], v[152:153] op_sel_hi:[1,0]
	v_pk_mul_f32 v[48:49], v[34:35], v[152:153] op_sel_hi:[1,0]
	v_mul_f32_e32 v34, 0xbfb8aa3b, v44
	v_exp_f32_e32 v50, v34
	v_mul_f32_e32 v34, 0xbfb8aa3b, v45
	v_exp_f32_e32 v51, v34
	v_pk_mul_f32 v[34:35], v[32:33], v[152:153] op_sel_hi:[1,0]
	v_add_f32_e32 v32, 1.0, v50
	v_mul_f32_e32 v50, 0xbfb8aa3b, v46
	v_add_f32_e32 v33, 1.0, v51
	v_mul_f32_e32 v51, 0xbfb8aa3b, v47
	v_exp_f32_e32 v50, v50
	v_exp_f32_e32 v51, v51
	v_rcp_f32_e32 v32, v32
	v_rcp_f32_e32 v33, v33
	v_add_f32_e32 v50, 1.0, v50
	v_add_f32_e32 v51, 1.0, v51
	v_rcp_f32_e32 v50, v50
	v_rcp_f32_e32 v51, v51
	v_pk_mul_f32 v[32:33], v[44:45], v[32:33]
	v_pk_mul_f32 v[40:41], v[40:41], v[152:153] op_sel_hi:[1,0]
	v_pk_mul_f32 v[32:33], v[36:37], v[32:33]
	v_pk_mul_f32 v[38:39], v[38:39], v[152:153] op_sel_hi:[1,0]
	v_cvt_pk_bf16_f32 v32, v32, v33
	v_pk_mul_f32 v[36:37], v[46:47], v[50:51]
	v_mul_f32_e32 v33, 0xbfb8aa3b, v40
	v_pk_mul_f32 v[36:37], v[38:39], v[36:37]
	v_exp_f32_e32 v38, v33
	v_mul_f32_e32 v33, 0xbfb8aa3b, v41
	v_exp_f32_e32 v39, v33
	v_pk_mul_f32 v[42:43], v[42:43], v[152:153] op_sel_hi:[1,0]
	v_cvt_pk_bf16_f32 v33, v36, v37
	v_add_f32_e32 v36, 1.0, v38
	v_add_f32_e32 v37, 1.0, v39
	v_mul_f32_e32 v38, 0xbfb8aa3b, v42
	v_mul_f32_e32 v39, 0xbfb8aa3b, v43
	v_exp_f32_e32 v38, v38
	v_exp_f32_e32 v39, v39
	v_rcp_f32_e32 v36, v36
	v_rcp_f32_e32 v37, v37
	v_add_f32_e32 v38, 1.0, v38
	v_add_f32_e32 v39, 1.0, v39
	v_rcp_f32_e32 v38, v38
	v_rcp_f32_e32 v39, v39
	v_pk_mul_f32 v[36:37], v[40:41], v[36:37]
	v_add_u32_e32 v52, 0x90, v146
	v_pk_mul_f32 v[34:35], v[34:35], v[36:37]
	v_pk_mul_f32 v[36:37], v[42:43], v[38:39]
	v_cvt_pk_bf16_f32 v34, v34, v35
	v_pk_mul_f32 v[36:37], v[48:49], v[36:37]
	v_pk_mul_f32 v[28:29], v[28:29], v[150:151] op_sel_hi:[1,0]
	v_cvt_pk_bf16_f32 v35, v36, v37
	v_mad_i64_i32 v[36:37], s[4:5], v52, s52, v[144:145]
	global_store_dwordx4 v[36:37], v[32:35], off
	v_pk_mul_f32 v[30:31], v[30:31], v[150:151] op_sel_hi:[1,0]
	v_pk_mul_f32 v[20:21], v[20:21], v[150:151] op_sel_hi:[1,0]
	v_pk_mul_f32 v[32:33], v[18:19], v[150:151] op_sel_hi:[1,0]
	v_mul_f32_e32 v18, 0xbfb8aa3b, v28
	v_exp_f32_e32 v34, v18
	v_mul_f32_e32 v18, 0xbfb8aa3b, v29
	v_exp_f32_e32 v35, v18
	v_pk_mul_f32 v[18:19], v[16:17], v[150:151] op_sel_hi:[1,0]
	v_add_f32_e32 v16, 1.0, v34
	v_mul_f32_e32 v34, 0xbfb8aa3b, v30
; DI unsigned pk_bf16(float lo, float hi) { f32x2 v = {lo, hi}; return __builtin_bit_cast(unsigned, __builtin_convertvector(v, bf16v2)); }
; DI float fast_silu(float x) { return x * fast_sigmoid(x); }
; #define PG8_WAIT_V(n) asm volatile("s_waitcnt vmcnt(" #n ")" ::: "memory")
; #define PG8_BAR __builtin_amdgcn_s_barrier()
; #define PG8_WAIT_V(n) asm volatile("s_waitcnt vmcnt(" #n ")" ::: "memory")
; #define PG8_BAR __builtin_amdgcn_s_barrier()
; template <class Epi>
; DI void gemm_phase(LAS unsigned char* lds, const Gemm g, const StaticOrder S, const Epi E) {
;     ...
;     PG8_WAIT_V(0);
;     if (wr == 0) PG8_BAR;
;     PG8_BAR;
;     DI void operator()(AccRef acc, const Unit& u, int wr, int wc, int fr, int fq) const {
;     ...
;             for (int m = 0; m < 4; ++m) {
;                 const int row = row0 + ai * 128 + m * 16;
;                 const float r = RS ? rsc.r[ai][m] : 1.0f;
;                 const f32x4 a0 = acc[ai][0][m][0] * r, a1 = acc[ai][0][m][1] * r, b0 = acc[ai][1][m][0] * r, b1 = acc[ai][1][m][1] * r;
;                 u32x4 w;
;                 w.x = pk_bf16(fast_silu(a0[0]) * b0[0], fast_silu(a0[1]) * b0[1]); w.y = pk_bf16(fast_silu(a0[2]) * b0[2], fast_silu(a0[3]) * b0[3]);
;                 w.z = pk_bf16(fast_silu(a1[0]) * b1[0], fast_silu(a1[1]) * b1[1]); w.w = pk_bf16(fast_silu(a1[2]) * b1[2], fast_silu(a1[3]) * b1[3]);
;                 *(u32x4*)(G + (size_t)row * DFF + col) = w;
;             }
	v_add_f32_e32 v17, 1.0, v35
	v_mul_f32_e32 v35, 0xbfb8aa3b, v31
	v_exp_f32_e32 v34, v34
	v_exp_f32_e32 v35, v35
	v_rcp_f32_e32 v16, v16
	v_rcp_f32_e32 v17, v17
	v_add_f32_e32 v34, 1.0, v34
	v_add_f32_e32 v35, 1.0, v35
	v_rcp_f32_e32 v34, v34
	v_rcp_f32_e32 v35, v35
	v_pk_mul_f32 v[16:17], v[28:29], v[16:17]
	v_pk_mul_f32 v[24:25], v[24:25], v[150:151] op_sel_hi:[1,0]
	v_pk_mul_f32 v[16:17], v[20:21], v[16:17]
	v_pk_mul_f32 v[22:23], v[22:23], v[150:151] op_sel_hi:[1,0]
	v_cvt_pk_bf16_f32 v16, v16, v17
	v_pk_mul_f32 v[20:21], v[30:31], v[34:35]
	v_mul_f32_e32 v17, 0xbfb8aa3b, v24
	v_pk_mul_f32 v[20:21], v[22:23], v[20:21]
	v_exp_f32_e32 v22, v17
	v_mul_f32_e32 v17, 0xbfb8aa3b, v25
	v_exp_f32_e32 v23, v17
	v_pk_mul_f32 v[26:27], v[26:27], v[150:151] op_sel_hi:[1,0]
	v_cvt_pk_bf16_f32 v17, v20, v21
	v_add_f32_e32 v20, 1.0, v22
	v_add_f32_e32 v21, 1.0, v23
	v_mul_f32_e32 v22, 0xbfb8aa3b, v26
	v_mul_f32_e32 v23, 0xbfb8aa3b, v27
	v_exp_f32_e32 v22, v22
	v_exp_f32_e32 v23, v23
	v_rcp_f32_e32 v20, v20
	v_rcp_f32_e32 v21, v21
	v_add_f32_e32 v22, 1.0, v22
	v_add_f32_e32 v23, 1.0, v23
	v_rcp_f32_e32 v22, v22
	v_rcp_f32_e32 v23, v23
	v_pk_mul_f32 v[20:21], v[24:25], v[20:21]
	v_add_u32_e32 v36, 0xa0, v146
	v_pk_mul_f32 v[18:19], v[18:19], v[20:21]
	v_pk_mul_f32 v[20:21], v[26:27], v[22:23]
	v_cvt_pk_bf16_f32 v18, v18, v19
	v_pk_mul_f32 v[20:21], v[32:33], v[20:21]
	v_pk_mul_f32 v[12:13], v[12:13], v[148:149] op_sel_hi:[1,0]
	v_cvt_pk_bf16_f32 v19, v20, v21
	v_mad_i64_i32 v[20:21], s[4:5], v36, s52, v[144:145]
	global_store_dwordx4 v[20:21], v[16:19], off
	v_pk_mul_f32 v[14:15], v[14:15], v[148:149] op_sel_hi:[1,0]
	v_pk_mul_f32 v[4:5], v[4:5], v[148:149] op_sel_hi:[1,0]
	v_pk_mul_f32 v[16:17], v[2:3], v[148:149] op_sel_hi:[1,0]
	v_mul_f32_e32 v2, 0xbfb8aa3b, v12
	v_exp_f32_e32 v18, v2
	v_mul_f32_e32 v2, 0xbfb8aa3b, v13
	v_exp_f32_e32 v19, v2
	v_pk_mul_f32 v[2:3], v[0:1], v[148:149] op_sel_hi:[1,0]
	v_add_f32_e32 v0, 1.0, v18
	v_mul_f32_e32 v18, 0xbfb8aa3b, v14
	v_add_f32_e32 v1, 1.0, v19
	v_mul_f32_e32 v19, 0xbfb8aa3b, v15
	v_exp_f32_e32 v18, v18
	v_exp_f32_e32 v19, v19
	v_rcp_f32_e32 v0, v0
	v_rcp_f32_e32 v1, v1
	v_add_f32_e32 v18, 1.0, v18
	v_add_f32_e32 v19, 1.0, v19
	v_rcp_f32_e32 v18, v18
	v_rcp_f32_e32 v19, v19
	v_pk_mul_f32 v[0:1], v[12:13], v[0:1]
	v_pk_mul_f32 v[8:9], v[8:9], v[148:149] op_sel_hi:[1,0]
	v_pk_mul_f32 v[0:1], v[4:5], v[0:1]
	v_pk_mul_f32 v[6:7], v[6:7], v[148:149] op_sel_hi:[1,0]
	v_cvt_pk_bf16_f32 v0, v0, v1
	v_pk_mul_f32 v[4:5], v[14:15], v[18:19]
	v_mul_f32_e32 v1, 0xbfb8aa3b, v8
	v_pk_mul_f32 v[4:5], v[6:7], v[4:5]
	v_exp_f32_e32 v6, v1
	v_mul_f32_e32 v1, 0xbfb8aa3b, v9
	v_exp_f32_e32 v7, v1
	v_pk_mul_f32 v[10:11], v[10:11], v[148:149] op_sel_hi:[1,0]
	v_cvt_pk_bf16_f32 v1, v4, v5
	v_add_f32_e32 v4, 1.0, v6
	v_add_f32_e32 v5, 1.0, v7
	v_mul_f32_e32 v6, 0xbfb8aa3b, v10
	v_mul_f32_e32 v7, 0xbfb8aa3b, v11
	v_exp_f32_e32 v6, v6
	v_exp_f32_e32 v7, v7
	v_rcp_f32_e32 v4, v4
	v_rcp_f32_e32 v5, v5
	v_add_f32_e32 v6, 1.0, v6
	v_add_f32_e32 v7, 1.0, v7
	v_rcp_f32_e32 v6, v6
	v_rcp_f32_e32 v7, v7
	v_pk_mul_f32 v[4:5], v[8:9], v[4:5]
	v_add_u32_e32 v20, 0xb0, v146
	v_pk_mul_f32 v[2:3], v[2:3], v[4:5]
	v_pk_mul_f32 v[4:5], v[10:11], v[6:7]
	v_cvt_pk_bf16_f32 v2, v2, v3
	v_pk_mul_f32 v[4:5], v[16:17], v[4:5]
	s_and_b64 vcc, exec, s[0:1]
	v_cvt_pk_bf16_f32 v3, v4, v5
	v_mad_i64_i32 v[4:5], s[4:5], v20, s52, v[144:145]
	s_mov_b32 s5, s24
	s_mov_b32 s4, s28
	s_mov_b64 s[10:11], s[38:39]
	s_mov_b64 s[8:9], s[36:37]
	global_store_dwordx4 v[4:5], v[0:3], off
	s_cbranch_vccz .LBB0_862
	s_waitcnt vmcnt(0)
	s_cmpk_gt_u32 s6, 0xff
	s_cbranch_scc1 .LBB0_869
	s_barrier

; #define PG8_STAGE(bufoff, gbase, voff) do { _Pragma("unroll") for (int _i = 0; _i < 2; ++_i) \
;         __builtin_amdgcn_global_load_lds((const unsigned*)((const char*)(gbase) + (voff)[_i]), (LAS unsigned*)(lds + (bufoff) + ldsw + _i * 8192), 16, 0, 0); } while (0)
; #define PG8_LDA(dst, b, h) do { _Pragma("unroll") for (int m = 0; m < 4; ++m) _Pragma("unroll") for (int k = 0; k < 2; ++k) dst[m][k] = *(const LAS bf16x8*)(lds + PG8_SA(b, h) + aoff + m * 2048 + k * 1024); } while (0)
; #define PG8_LDB(dst, b, h) do { _Pragma("unroll") for (int n = 0; n < 2; ++n) _Pragma("unroll") for (int k = 0; k < 2; ++k) dst[n][k] = *(const LAS bf16x8*)(lds + PG8_SB(b, h) + boff + n * 2048 + k * 1024); } while (0)
; #define PG8_MMA(ai, bj, At, Bt) do { __builtin_amdgcn_s_setprio(1); _Pragma("unroll") for (int m = 0; m < 4; ++m) _Pragma("unroll") for (int n = 0; n < 2; ++n) _Pragma("unroll") for (int k = 0; k < 2; ++k) \
;         acc[ai][bj][m][n] = __builtin_amdgcn_mfma_f32_16x16x32_bf16(Bt[n][k], At[m][k], acc[ai][bj][m][n], 0, 0, 0); __builtin_amdgcn_s_setprio(0); } while (0)
; #define PG8_WAIT_V(n) asm volatile("s_waitcnt vmcnt(" #n ")" ::: "memory")
; #define PG8_WAIT_L(n) asm volatile("s_waitcnt lgkmcnt(" #n ")" ::: "memory")
; #define PG8_BAR __builtin_amdgcn_s_barrier()
; #define PG8_SCHED __builtin_amdgcn_sched_barrier(0)
; template <class Epi>
; DI void gemm_phase(LAS unsigned char* lds, const Gemm g, const StaticOrder S, const Epi E) {
;     ...
;             const bool last = (t == nt - 2);
;             const char* a1 = cA + (size_t)(t + 1) * kstep;
;             const char* a2 = last ? nA : cA + (size_t)(t + 2) * kstep; const char* b2 = last ? nB : cB + (size_t)(t + 2) * kstep;
;             const char* a3 = a2 + kstep; const char* b3 = b2 + kstep;
;             PG8_LDB(B0, 0, 0); PG8_SCHED; PG8_LDA(At, 0, 0); PG8_STAGE(PG8_SA(1, 1), a1 + hstep, voffA);
;             PG8_WAIT_L(8); PG8_BAR; PG8_WAIT_L(0); PG8_MMA(0, 0, At, B0); PG8_BAR; PG8_SCHED;
;             PG8_LDB(B1, 0, 1); PG8_STAGE(PG8_SB(0, 0), b2, voffB);
;             PG8_BAR; PG8_WAIT_L(0); PG8_MMA(0, 1, At, B1); PG8_BAR;
;             PG8_LDA(At, 0, 1); PG8_STAGE(PG8_SA(0, 0), a2, voffA);
;             PG8_BAR; PG8_WAIT_L(0); PG8_MMA(1, 0, At, B0); PG8_BAR; PG8_SCHED;
;             PG8_STAGE(PG8_SB(0, 1), b2 + hstep, voffB);
;             PG8_WAIT_V(6); PG8_BAR; PG8_MMA(1, 1, At, B1); PG8_BAR;
.LBB0_941:
	ds_read_b128 v[144:147], v199
	ds_read_b128 v[148:151], v199 offset:1024
	ds_read_b128 v[152:155], v199 offset:2048
	ds_read_b128 v[156:159], v199 offset:3072
	s_add_u32 s22, s20, 0x100
	s_addc_u32 s23, s21, 0
	s_cmp_eq_u32 s58, 40
	s_cselect_b32 s27, s9, s23
	s_cselect_b32 s26, s8, s22
	s_cselect_b32 s25, s5, s53
	s_cselect_b32 s24, s4, s52
	v_lshl_add_u64 v[192:193], s[20:21], 0, v[136:137]
	s_add_i32 m0, s33, 0xc000
	ds_read_b128 v[160:163], v200
	ds_read_b128 v[164:167], v200 offset:1024
	ds_read_b128 v[168:171], v200 offset:2048
	ds_read_b128 v[172:175], v200 offset:3072
	ds_read_b128 v[176:179], v200 offset:4096
	ds_read_b128 v[180:183], v200 offset:5120
	ds_read_b128 v[184:187], v200 offset:6144
	ds_read_b128 v[188:191], v200 offset:7168
	global_load_lds_dwordx4 v[192:193], off
	v_lshl_add_u64 v[192:193], s[20:21], 0, v[138:139]
	s_add_i32 m0, s33, 0xe000
	s_nop 0
	global_load_lds_dwordx4 v[192:193], off
	s_waitcnt lgkmcnt(8)
	s_barrier
	s_waitcnt lgkmcnt(0)
	s_setprio 1
	s_waitcnt lgkmcnt(0)
	v_mfma_f32_16x16x32_bf16 v[124:127], v[144:147], v[160:163], v[124:127]
	v_mfma_f32_16x16x32_bf16 v[120:123], v[152:155], v[160:163], v[120:123]
	v_mfma_f32_16x16x32_bf16 v[108:111], v[144:147], v[168:171], v[108:111]
	v_mfma_f32_16x16x32_bf16 v[104:107], v[152:155], v[168:171], v[104:107]
	v_mfma_f32_16x16x32_bf16 v[92:95], v[144:147], v[176:179], v[92:95]
	v_mfma_f32_16x16x32_bf16 v[88:91], v[152:155], v[176:179], v[88:91]
	v_mfma_f32_16x16x32_bf16 v[84:87], v[144:147], v[184:187], v[84:87]
	v_mfma_f32_16x16x32_bf16 v[76:79], v[152:155], v[184:187], v[76:79]
	v_mfma_f32_16x16x32_bf16 v[124:127], v[148:151], v[164:167], v[124:127]
	v_mfma_f32_16x16x32_bf16 v[120:123], v[156:159], v[164:167], v[120:123]
	v_mfma_f32_16x16x32_bf16 v[108:111], v[148:151], v[172:175], v[108:111]
	v_mfma_f32_16x16x32_bf16 v[104:107], v[156:159], v[172:175], v[104:107]
	v_mfma_f32_16x16x32_bf16 v[92:95], v[148:151], v[180:183], v[92:95]
	v_mfma_f32_16x16x32_bf16 v[88:91], v[156:159], v[180:183], v[88:91]
	s_setprio 2
	s_barrier
	v_mfma_f32_16x16x32_bf16 v[84:87], v[148:151], v[188:191], v[84:87]
	v_mfma_f32_16x16x32_bf16 v[76:79], v[156:159], v[188:191], v[76:79]
	s_setprio 0
	s_add_i32 s20, s42, s29
	v_lshl_add_u64 v[214:215], s[24:25], 0, v[130:131]
	s_mov_b32 m0, s20
	ds_read_b128 v[192:195], v201
	ds_read_b128 v[202:205], v201 offset:1024
	ds_read_b128 v[206:209], v201 offset:2048
	ds_read_b128 v[210:213], v201 offset:3072
	global_load_lds_dwordx4 v[214:215], off
	v_lshl_add_u64 v[216:217], s[24:25], 0, v[134:135]
	s_add_i32 m0, s20, 0x2000
	s_nop 0
	global_load_lds_dwordx4 v[216:217], off
	s_barrier
	s_waitcnt lgkmcnt(0)
	s_setprio 1
	s_waitcnt lgkmcnt(0)
	v_mfma_f32_16x16x32_bf16 v[116:119], v[192:195], v[160:163], v[116:119]
	v_mfma_f32_16x16x32_bf16 v[112:115], v[206:209], v[160:163], v[112:115]
	v_mfma_f32_16x16x32_bf16 v[100:103], v[192:195], v[168:171], v[100:103]
	v_mfma_f32_16x16x32_bf16 v[96:99], v[206:209], v[168:171], v[96:99]
	v_mfma_f32_16x16x32_bf16 v[80:83], v[192:195], v[176:179], v[80:83]
	v_mfma_f32_16x16x32_bf16 v[72:75], v[206:209], v[176:179], v[72:75]
	v_mfma_f32_16x16x32_bf16 v[68:71], v[192:195], v[184:187], v[68:71]
	v_mfma_f32_16x16x32_bf16 v[64:67], v[206:209], v[184:187], v[64:67]
	v_mfma_f32_16x16x32_bf16 v[116:119], v[202:205], v[164:167], v[116:119]
	v_mfma_f32_16x16x32_bf16 v[112:115], v[210:213], v[164:167], v[112:115]
	v_mfma_f32_16x16x32_bf16 v[100:103], v[202:205], v[172:175], v[100:103]
	v_mfma_f32_16x16x32_bf16 v[96:99], v[210:213], v[172:175], v[96:99]
	v_mfma_f32_16x16x32_bf16 v[80:83], v[202:205], v[180:183], v[80:83]
	v_mfma_f32_16x16x32_bf16 v[72:75], v[210:213], v[180:183], v[72:75]
	s_setprio 2
	s_barrier
	v_mfma_f32_16x16x32_bf16 v[68:71], v[202:205], v[188:191], v[68:71]
	v_mfma_f32_16x16x32_bf16 v[64:67], v[210:213], v[188:191], v[64:67]
	s_setprio 0
	s_mov_b32 m0, s33
	v_lshl_add_u64 v[218:219], s[26:27], 0, v[128:129]
	ds_read_b128 v[160:163], v200 offset:16384
	ds_read_b128 v[164:167], v200 offset:17408
	ds_read_b128 v[168:171], v200 offset:18432
	ds_read_b128 v[172:175], v200 offset:19456
	ds_read_b128 v[176:179], v200 offset:20480
	ds_read_b128 v[180:183], v200 offset:21504
	ds_read_b128 v[184:187], v200 offset:22528
	ds_read_b128 v[188:191], v200 offset:23552
	global_load_lds_dwordx4 v[218:219], off
	v_lshl_add_u64 v[220:221], s[26:27], 0, v[132:133]
	s_mov_b32 m0, s34
	s_nop 0
	global_load_lds_dwordx4 v[220:221], off
	s_barrier
	s_waitcnt lgkmcnt(0)
	s_setprio 1
	s_waitcnt lgkmcnt(0)
	v_mfma_f32_16x16x32_bf16 v[60:63], v[144:147], v[160:163], v[60:63]
	v_mfma_f32_16x16x32_bf16 v[56:59], v[152:155], v[160:163], v[56:59]
	v_mfma_f32_16x16x32_bf16 v[48:51], v[144:147], v[168:171], v[48:51]
	v_mfma_f32_16x16x32_bf16 v[40:43], v[152:155], v[168:171], v[40:43]
	v_mfma_f32_16x16x32_bf16 v[32:35], v[144:147], v[176:179], v[32:35]
	v_mfma_f32_16x16x32_bf16 v[24:27], v[152:155], v[176:179], v[24:27]
	v_mfma_f32_16x16x32_bf16 v[16:19], v[144:147], v[184:187], v[16:19]
	v_mfma_f32_16x16x32_bf16 v[8:11], v[152:155], v[184:187], v[8:11]
	v_mfma_f32_16x16x32_bf16 v[60:63], v[148:151], v[164:167], v[60:63]
	v_mfma_f32_16x16x32_bf16 v[56:59], v[156:159], v[164:167], v[56:59]
	v_mfma_f32_16x16x32_bf16 v[48:51], v[148:151], v[172:175], v[48:51]
	v_mfma_f32_16x16x32_bf16 v[40:43], v[156:159], v[172:175], v[40:43]
	v_mfma_f32_16x16x32_bf16 v[32:35], v[148:151], v[180:183], v[32:35]
	v_mfma_f32_16x16x32_bf16 v[24:27], v[156:159], v[180:183], v[24:27]
	s_setprio 2
	s_barrier
; #define PG8_STAGE(bufoff, gbase, voff) do { _Pragma("unroll") for (int _i = 0; _i < 2; ++_i) \
;         __builtin_amdgcn_global_load_lds((const unsigned*)((const char*)(gbase) + (voff)[_i]), (LAS unsigned*)(lds + (bufoff) + ldsw + _i * 8192), 16, 0, 0); } while (0)
; #define PG8_LDA(dst, b, h) do { _Pragma("unroll") for (int m = 0; m < 4; ++m) _Pragma("unroll") for (int k = 0; k < 2; ++k) dst[m][k] = *(const LAS bf16x8*)(lds + PG8_SA(b, h) + aoff + m * 2048 + k * 1024); } while (0)
; #define PG8_LDB(dst, b, h) do { _Pragma("unroll") for (int n = 0; n < 2; ++n) _Pragma("unroll") for (int k = 0; k < 2; ++k) dst[n][k] = *(const LAS bf16x8*)(lds + PG8_SB(b, h) + boff + n * 2048 + k * 1024); } while (0)
; #define PG8_MMA(ai, bj, At, Bt) do { __builtin_amdgcn_s_setprio(1); _Pragma("unroll") for (int m = 0; m < 4; ++m) _Pragma("unroll") for (int n = 0; n < 2; ++n) _Pragma("unroll") for (int k = 0; k < 2; ++k) \
;         acc[ai][bj][m][n] = __builtin_amdgcn_mfma_f32_16x16x32_bf16(Bt[n][k], At[m][k], acc[ai][bj][m][n], 0, 0, 0); __builtin_amdgcn_s_setprio(0); } while (0)
; #define PG8_WAIT_V(n) asm volatile("s_waitcnt vmcnt(" #n ")" ::: "memory")
; #define PG8_WAIT_L(n) asm volatile("s_waitcnt lgkmcnt(" #n ")" ::: "memory")
; #define PG8_BAR __builtin_amdgcn_s_barrier()
; #define PG8_SCHED __builtin_amdgcn_sched_barrier(0)
; #define PG8_STAGE(bufoff, gbase, voff) do { _Pragma("unroll") for (int _i = 0; _i < 2; ++_i) \
;         __builtin_amdgcn_global_load_lds((const unsigned*)((const char*)(gbase) + (voff)[_i]), (LAS unsigned*)(lds + (bufoff) + ldsw + _i * 8192), 16, 0, 0); } while (0)
; #define PG8_WAIT_V(n) asm volatile("s_waitcnt vmcnt(" #n ")" ::: "memory")
; template <class Epi>
; DI void gemm_phase(LAS unsigned char* lds, const Gemm g, const StaticOrder S, const Epi E) {
;     ...
;             PG8_BAR; PG8_WAIT_L(0); PG8_MMA(1, 0, At, B0); PG8_BAR; PG8_SCHED;
;             PG8_STAGE(PG8_SB(0, 1), b2 + hstep, voffB);
;             PG8_WAIT_V(6); PG8_BAR; PG8_MMA(1, 1, At, B1); PG8_BAR;
;             PG8_LDB(B0, 1, 0); PG8_SCHED; PG8_LDA(At, 1, 0); PG8_STAGE(PG8_SA(0, 1), a2 + hstep, voffA);
;             PG8_WAIT_L(8); PG8_BAR; PG8_WAIT_L(0); PG8_MMA(0, 0, At, B0); PG8_BAR; PG8_SCHED;
;             PG8_LDB(B1, 1, 1); PG8_STAGE(PG8_SB(1, 0), b3, voffB);
;             PG8_BAR; PG8_WAIT_L(0); PG8_MMA(0, 1, At, B1); PG8_BAR;
	v_mfma_f32_16x16x32_bf16 v[16:19], v[148:151], v[188:191], v[16:19]
	v_mfma_f32_16x16x32_bf16 v[8:11], v[156:159], v[188:191], v[8:11]
	s_setprio 0
	s_add_u32 s20, s24, 0xb0000
	s_addc_u32 s21, s25, 0
	s_add_i32 s59, s43, s29
	v_lshl_add_u64 v[144:145], s[20:21], 0, v[130:131]
	s_mov_b32 m0, s59
	s_nop 0
	global_load_lds_dwordx4 v[144:145], off
	v_lshl_add_u64 v[144:145], s[20:21], 0, v[134:135]
	s_add_i32 m0, s59, 0x2000
	s_nop 0
	global_load_lds_dwordx4 v[144:145], off
	s_waitcnt vmcnt(6)
	s_barrier
	s_setprio 1
	v_mfma_f32_16x16x32_bf16 v[52:55], v[192:195], v[160:163], v[52:55]
	v_mfma_f32_16x16x32_bf16 v[44:47], v[206:209], v[160:163], v[44:47]
	v_mfma_f32_16x16x32_bf16 v[36:39], v[192:195], v[168:171], v[36:39]
	v_mfma_f32_16x16x32_bf16 v[28:31], v[206:209], v[168:171], v[28:31]
	v_mfma_f32_16x16x32_bf16 v[20:23], v[192:195], v[176:179], v[20:23]
	v_mfma_f32_16x16x32_bf16 v[12:15], v[206:209], v[176:179], v[12:15]
	v_mfma_f32_16x16x32_bf16 v[4:7], v[192:195], v[184:187], v[4:7]
	v_mfma_f32_16x16x32_bf16 v[0:3], v[206:209], v[184:187], v[0:3]
	v_mfma_f32_16x16x32_bf16 v[52:55], v[202:205], v[164:167], v[52:55]
	v_mfma_f32_16x16x32_bf16 v[44:47], v[210:213], v[164:167], v[44:47]
	v_mfma_f32_16x16x32_bf16 v[36:39], v[202:205], v[172:175], v[36:39]
	v_mfma_f32_16x16x32_bf16 v[28:31], v[210:213], v[172:175], v[28:31]
	v_mfma_f32_16x16x32_bf16 v[20:23], v[202:205], v[180:183], v[20:23]
	v_mfma_f32_16x16x32_bf16 v[12:15], v[210:213], v[180:183], v[12:15]
	s_setprio 2
	s_barrier
	v_mfma_f32_16x16x32_bf16 v[4:7], v[202:205], v[188:191], v[4:7]
	v_mfma_f32_16x16x32_bf16 v[0:3], v[210:213], v[188:191], v[0:3]
	s_setprio 0
	s_add_i32 s59, 0, 0x18000
	v_add_u32_e32 v156, s59, v197
	ds_read_b128 v[144:147], v156
	ds_read_b128 v[148:151], v156 offset:1024
	ds_read_b128 v[152:155], v156 offset:2048
	ds_read_b128 v[156:159], v156 offset:3072
	s_add_u32 s20, s26, 0xb0000
	s_addc_u32 s21, s27, 0
	s_mov_b32 m0, s35
	v_lshl_add_u64 v[192:193], s[20:21], 0, v[128:129]
	ds_read_b128 v[160:163], v200 offset:32768
	ds_read_b128 v[164:167], v200 offset:33792
	ds_read_b128 v[168:171], v200 offset:34816
	ds_read_b128 v[172:175], v200 offset:35840
	ds_read_b128 v[176:179], v200 offset:36864
	ds_read_b128 v[180:183], v200 offset:37888
	ds_read_b128 v[184:187], v200 offset:38912
	ds_read_b128 v[188:191], v200 offset:39936
	global_load_lds_dwordx4 v[192:193], off
	v_lshl_add_u64 v[192:193], s[20:21], 0, v[132:133]
	s_mov_b32 m0, s36
	s_nop 0
	global_load_lds_dwordx4 v[192:193], off
	s_waitcnt lgkmcnt(8)
	s_barrier
	s_waitcnt lgkmcnt(0)
	s_setprio 1
	s_waitcnt lgkmcnt(0)
	v_mfma_f32_16x16x32_bf16 v[124:127], v[144:147], v[160:163], v[124:127]
	v_mfma_f32_16x16x32_bf16 v[120:123], v[152:155], v[160:163], v[120:123]
	v_mfma_f32_16x16x32_bf16 v[108:111], v[144:147], v[168:171], v[108:111]
	v_mfma_f32_16x16x32_bf16 v[104:107], v[152:155], v[168:171], v[104:107]
	v_mfma_f32_16x16x32_bf16 v[92:95], v[144:147], v[176:179], v[92:95]
	v_mfma_f32_16x16x32_bf16 v[88:91], v[152:155], v[176:179], v[88:91]
	v_mfma_f32_16x16x32_bf16 v[84:87], v[144:147], v[184:187], v[84:87]
	v_mfma_f32_16x16x32_bf16 v[76:79], v[152:155], v[184:187], v[76:79]
	v_mfma_f32_16x16x32_bf16 v[124:127], v[148:151], v[164:167], v[124:127]
	v_mfma_f32_16x16x32_bf16 v[120:123], v[156:159], v[164:167], v[120:123]
	v_mfma_f32_16x16x32_bf16 v[108:111], v[148:151], v[172:175], v[108:111]
	v_mfma_f32_16x16x32_bf16 v[104:107], v[156:159], v[172:175], v[104:107]
	v_mfma_f32_16x16x32_bf16 v[92:95], v[148:151], v[180:183], v[92:95]
	v_mfma_f32_16x16x32_bf16 v[88:91], v[156:159], v[180:183], v[88:91]
	s_setprio 2
	s_barrier
	v_mfma_f32_16x16x32_bf16 v[84:87], v[148:151], v[188:191], v[84:87]
	v_mfma_f32_16x16x32_bf16 v[76:79], v[156:159], v[188:191], v[76:79]
	s_setprio 0
	s_add_i32 s26, 0, 0x1c000
	s_add_i32 s20, s59, s29
	v_add_u32_e32 v210, s26, v197
	v_lshl_add_u64 v[214:215], v[214:215], 0, s[10:11]
	s_mov_b32 m0, s20
	ds_read_b128 v[192:195], v210
	ds_read_b128 v[202:205], v210 offset:1024
	ds_read_b128 v[206:209], v210 offset:2048
	ds_read_b128 v[210:213], v210 offset:3072
	global_load_lds_dwordx4 v[214:215], off
	v_lshl_add_u64 v[214:215], v[216:217], 0, s[10:11]
	s_add_i32 m0, s20, 0x2000
	s_nop 0
	global_load_lds_dwordx4 v[214:215], off
	s_barrier
	s_waitcnt lgkmcnt(0)
	s_setprio 1
	s_waitcnt lgkmcnt(0)
	v_mfma_f32_16x16x32_bf16 v[116:119], v[192:195], v[160:163], v[116:119]
	v_mfma_f32_16x16x32_bf16 v[112:115], v[206:209], v[160:163], v[112:115]
	v_mfma_f32_16x16x32_bf16 v[100:103], v[192:195], v[168:171], v[100:103]
	v_mfma_f32_16x16x32_bf16 v[96:99], v[206:209], v[168:171], v[96:99]
	v_mfma_f32_16x16x32_bf16 v[80:83], v[192:195], v[176:179], v[80:83]
	v_mfma_f32_16x16x32_bf16 v[72:75], v[206:209], v[176:179], v[72:75]
	v_mfma_f32_16x16x32_bf16 v[68:71], v[192:195], v[184:187], v[68:71]
	v_mfma_f32_16x16x32_bf16 v[64:67], v[206:209], v[184:187], v[64:67]
	v_mfma_f32_16x16x32_bf16 v[116:119], v[202:205], v[164:167], v[116:119]
	v_mfma_f32_16x16x32_bf16 v[112:115], v[210:213], v[164:167], v[112:115]
	v_mfma_f32_16x16x32_bf16 v[100:103], v[202:205], v[172:175], v[100:103]
	v_mfma_f32_16x16x32_bf16 v[96:99], v[210:213], v[172:175], v[96:99]
	v_mfma_f32_16x16x32_bf16 v[80:83], v[202:205], v[180:183], v[80:83]
	v_mfma_f32_16x16x32_bf16 v[72:75], v[210:213], v[180:183], v[72:75]
	s_setprio 2
	s_barrier
; DI f32x4 bf_lo4(u32x4 w) { f32x4 r; r[0] = bf_lo(w.x); r[1] = bf_hi(w.x); r[2] = bf_lo(w.y); r[3] = bf_hi(w.y); return r; }
; DI f32x4 bf_hi4(u32x4 w) { f32x4 r; r[0] = bf_lo(w.z); r[1] = bf_hi(w.z); r[2] = bf_lo(w.w); r[3] = bf_hi(w.w); return r; }
; #define PG8_STAGE(bufoff, gbase, voff) do { _Pragma("unroll") for (int _i = 0; _i < 2; ++_i) \
;         __builtin_amdgcn_global_load_lds((const unsigned*)((const char*)(gbase) + (voff)[_i]), (LAS unsigned*)(lds + (bufoff) + ldsw + _i * 8192), 16, 0, 0); } while (0)
; #define PG8_LDA(dst, b, h) do { _Pragma("unroll") for (int m = 0; m < 4; ++m) _Pragma("unroll") for (int k = 0; k < 2; ++k) dst[m][k] = *(const LAS bf16x8*)(lds + PG8_SA(b, h) + aoff + m * 2048 + k * 1024); } while (0)
; #define PG8_WAIT_V(n) asm volatile("s_waitcnt vmcnt(" #n ")" ::: "memory")
; #define PG8_WAIT_L(n) asm volatile("s_waitcnt lgkmcnt(" #n ")" ::: "memory")
; #define PG8_BAR __builtin_amdgcn_s_barrier()
; #define PG8_SCHED __builtin_amdgcn_sched_barrier(0)
; #define PG8_WAIT_V(n) asm volatile("s_waitcnt vmcnt(" #n ")" ::: "memory")
; template <class Epi>
; DI void gemm_phase(LAS unsigned char* lds, const Gemm g, const StaticOrder S, const Epi E) {
;     ...
;             PG8_BAR; PG8_WAIT_L(0); PG8_MMA(0, 1, At, B1); PG8_BAR;
;             PG8_LDA(At, 1, 1); PG8_STAGE(PG8_SA(1, 0), a3, voffA);
;             PG8_BAR; PG8_WAIT_L(0); PG8_MMA(1, 0, At, B0); PG8_BAR; PG8_SCHED;
;             PG8_STAGE(PG8_SB(1, 1), b3 + hstep, voffB);
;             PG8_WAIT_V(6); PG8_BAR; PG8_MMA(1, 1, At, B1); PG8_BAR;
;     DI void operator()(AccRef acc, const Unit& u, int wr, int wc, int fr, int fq) const {
;         const float scale = HALFSTEP ? 0.5f : 1.0f;
;         const int row0 = u.pm * 256 + wr * 64 + fr, col0 = u.pn * 256 + wc * 32 + 8 * fq;
; #pragma unroll
;         for (int ai = 0; ai < 2; ++ai) {
;             f32x4 bv[4][2][2];
; #pragma unroll
;             for (int m = 0; m < 4; ++m)
; #pragma unroll
;                 for (int bj = 0; bj < 2; ++bj) {
;                     const size_t o = (size_t)(row0 + ai * 128 + m * 16) * DM + col0 + bj * 128;
;                     if (BASEF32) { bv[m][bj][0] = *(const f32x4*)(basef + o); bv[m][bj][1] = *(const f32x4*)(basef + o + 4); }
;                     else { const u32x4 h = *(const u32x4*)(xnb + o); bv[m][bj][0] = bf_lo4(h); bv[m][bj][1] = bf_hi4(h); }
;                 }
	v_mfma_f32_16x16x32_bf16 v[68:71], v[202:205], v[188:191], v[68:71]
	v_mfma_f32_16x16x32_bf16 v[64:67], v[210:213], v[188:191], v[64:67]
	s_setprio 0
	s_mov_b32 m0, s38
	v_lshl_add_u64 v[214:215], v[218:219], 0, s[10:11]
	ds_read_b128 v[160:163], v200 offset:49152
	ds_read_b128 v[164:167], v200 offset:50176
	ds_read_b128 v[168:171], v200 offset:51200
	ds_read_b128 v[172:175], v200 offset:52224
	ds_read_b128 v[176:179], v200 offset:53248
	ds_read_b128 v[180:183], v200 offset:54272
	ds_read_b128 v[184:187], v200 offset:55296
	ds_read_b128 v[188:191], v200 offset:56320
	global_load_lds_dwordx4 v[214:215], off
	v_lshl_add_u64 v[214:215], v[220:221], 0, s[10:11]
	s_mov_b32 m0, s39
	s_nop 0
	global_load_lds_dwordx4 v[214:215], off
	s_barrier
	s_waitcnt lgkmcnt(0)
	s_setprio 1
	s_waitcnt lgkmcnt(0)
	v_mfma_f32_16x16x32_bf16 v[60:63], v[144:147], v[160:163], v[60:63]
	v_mfma_f32_16x16x32_bf16 v[56:59], v[152:155], v[160:163], v[56:59]
	v_mfma_f32_16x16x32_bf16 v[48:51], v[144:147], v[168:171], v[48:51]
	v_mfma_f32_16x16x32_bf16 v[40:43], v[152:155], v[168:171], v[40:43]
	v_mfma_f32_16x16x32_bf16 v[32:35], v[144:147], v[176:179], v[32:35]
	v_mfma_f32_16x16x32_bf16 v[24:27], v[152:155], v[176:179], v[24:27]
	v_mfma_f32_16x16x32_bf16 v[16:19], v[144:147], v[184:187], v[16:19]
	v_mfma_f32_16x16x32_bf16 v[8:11], v[152:155], v[184:187], v[8:11]
	v_mfma_f32_16x16x32_bf16 v[60:63], v[148:151], v[164:167], v[60:63]
	v_mfma_f32_16x16x32_bf16 v[56:59], v[156:159], v[164:167], v[56:59]
	v_mfma_f32_16x16x32_bf16 v[48:51], v[148:151], v[172:175], v[48:51]
	v_mfma_f32_16x16x32_bf16 v[40:43], v[156:159], v[172:175], v[40:43]
	v_mfma_f32_16x16x32_bf16 v[32:35], v[148:151], v[180:183], v[32:35]
	v_mfma_f32_16x16x32_bf16 v[24:27], v[156:159], v[180:183], v[24:27]
	s_setprio 2
	s_barrier
	v_mfma_f32_16x16x32_bf16 v[16:19], v[148:151], v[188:191], v[16:19]
	v_mfma_f32_16x16x32_bf16 v[8:11], v[156:159], v[188:191], v[8:11]
	s_setprio 0
	s_add_u32 s20, s24, 0xb0080
	s_addc_u32 s21, s25, 0
	s_add_i32 s24, s26, s29
	v_lshl_add_u64 v[144:145], s[20:21], 0, v[130:131]
	s_mov_b32 m0, s24
	s_nop 0
	global_load_lds_dwordx4 v[144:145], off
	v_lshl_add_u64 v[144:145], s[20:21], 0, v[134:135]
	s_add_i32 m0, s24, 0x2000
	s_nop 0
	global_load_lds_dwordx4 v[144:145], off
	s_waitcnt vmcnt(6)
	s_barrier
	s_setprio 1
	v_mfma_f32_16x16x32_bf16 v[52:55], v[192:195], v[160:163], v[52:55]
	v_mfma_f32_16x16x32_bf16 v[44:47], v[206:209], v[160:163], v[44:47]
	v_mfma_f32_16x16x32_bf16 v[36:39], v[192:195], v[168:171], v[36:39]
	v_mfma_f32_16x16x32_bf16 v[28:31], v[206:209], v[168:171], v[28:31]
	v_mfma_f32_16x16x32_bf16 v[20:23], v[192:195], v[176:179], v[20:23]
	v_mfma_f32_16x16x32_bf16 v[12:15], v[206:209], v[176:179], v[12:15]
	v_mfma_f32_16x16x32_bf16 v[4:7], v[192:195], v[184:187], v[4:7]
	v_mfma_f32_16x16x32_bf16 v[0:3], v[206:209], v[184:187], v[0:3]
	v_mfma_f32_16x16x32_bf16 v[52:55], v[202:205], v[164:167], v[52:55]
	v_mfma_f32_16x16x32_bf16 v[44:47], v[210:213], v[164:167], v[44:47]
	v_mfma_f32_16x16x32_bf16 v[36:39], v[202:205], v[172:175], v[36:39]
	v_mfma_f32_16x16x32_bf16 v[28:31], v[210:213], v[172:175], v[28:31]
	v_mfma_f32_16x16x32_bf16 v[20:23], v[202:205], v[180:183], v[20:23]
	v_mfma_f32_16x16x32_bf16 v[12:15], v[210:213], v[180:183], v[12:15]
	s_setprio 2
	s_barrier
	v_mfma_f32_16x16x32_bf16 v[4:7], v[202:205], v[188:191], v[4:7]
	v_mfma_f32_16x16x32_bf16 v[0:3], v[210:213], v[188:191], v[0:3]
	s_setprio 0
	s_add_i32 s58, s58, 2
	s_add_u32 s52, s52, 0x100
	s_addc_u32 s53, s53, 0
	s_cmp_gt_u32 s58, 41
	s_mov_b64 s[20:21], s[22:23]
	s_cbranch_scc0 .LBB0_941
	v_lshl_add_u32 v148, s50, 8, v196
	v_lshl_or_b32 v144, s51, 8, v198
	v_or_b32_e32 v146, 16, v148
	v_ashrrev_i32_e32 v145, 31, v144
	v_ashrrev_i32_e32 v147, 31, v146
	v_lshl_add_u64 v[176:177], v[144:145], 1, s[56:57]
	v_ashrrev_i32_e32 v149, 31, v148
	v_lshlrev_b64 v[146:147], 11, v[146:147]
	v_lshlrev_b64 v[144:145], 11, v[148:149]
	v_lshl_add_u64 v[150:151], v[176:177], 0, v[146:147]
	v_or_b32_e32 v146, 32, v148
	v_or_b32_e32 v148, 48, v148
	v_ashrrev_i32_e32 v147, 31, v146
	v_ashrrev_i32_e32 v149, 31, v148
	v_lshl_add_u64 v[144:145], v[176:177], 0, v[144:145]
	v_lshlrev_b64 v[146:147], 11, v[146:147]
	v_lshlrev_b64 v[148:149], 11, v[148:149]
	global_load_dwordx4 v[152:155], v[144:145], off
	global_load_dwordx4 v[156:159], v[144:145], off offset:256
	v_lshl_add_u64 v[146:147], v[176:177], 0, v[146:147]
	v_lshl_add_u64 v[148:149], v[176:177], 0, v[148:149]
	global_load_dwordx4 v[160:163], v[150:151], off
	global_load_dwordx4 v[164:167], v[150:151], off offset:256
	global_load_dwordx4 v[168:171], v[146:147], off
	global_load_dwordx4 v[172:175], v[146:147], off offset:256
	global_load_dwordx4 v[202:205], v[148:149], off
	global_load_dwordx4 v[206:209], v[148:149], off offset:256
	s_mov_b32 s51, s48
	s_mov_b32 s50, s49
	s_mov_b64 s[22:23], s[4:5]
	s_mov_b64 s[20:21], s[8:9]
	s_waitcnt vmcnt(0)
; DI unsigned pk_bf16(float lo, float hi) { f32x2 v = {lo, hi}; return __builtin_bit_cast(unsigned, __builtin_convertvector(v, bf16v2)); }
; DI f32x4 bf_lo4(u32x4 w) { f32x4 r; r[0] = bf_lo(w.x); r[1] = bf_hi(w.x); r[2] = bf_lo(w.y); r[3] = bf_hi(w.y); return r; }
; DI f32x4 bf_hi4(u32x4 w) { f32x4 r; r[0] = bf_lo(w.z); r[1] = bf_hi(w.z); r[2] = bf_lo(w.w); r[3] = bf_hi(w.w); return r; }
;     DI void operator()(AccRef acc, const Unit& u, int wr, int wc, int fr, int fq) const {
;     ...
; #pragma unroll
;         for (int ai = 0; ai < 2; ++ai) {
;             f32x4 bv[4][2][2];
; #pragma unroll
;             for (int m = 0; m < 4; ++m)
; #pragma unroll
;                 for (int bj = 0; bj < 2; ++bj) {
;                     const size_t o = (size_t)(row0 + ai * 128 + m * 16) * DM + col0 + bj * 128;
;                     if (BASEF32) { bv[m][bj][0] = *(const f32x4*)(basef + o); bv[m][bj][1] = *(const f32x4*)(basef + o + 4); }
;                     else { const u32x4 h = *(const u32x4*)(xnb + o); bv[m][bj][0] = bf_lo4(h); bv[m][bj][1] = bf_hi4(h); }
;                 }
; #pragma unroll
;             for (int m = 0; m < 4; ++m) {
;                 const int row = row0 + ai * 128 + m * 16;
;                 float q = 0.f;
; #pragma unroll
;                 for (int bj = 0; bj < 2; ++bj) {
;                     const size_t o = (size_t)row * DM + col0 + bj * 128;
;                     const f32x4 r0 = bv[m][bj][0] + scale * acc[ai][bj][m][0], r1 = bv[m][bj][1] + scale * acc[ai][bj][m][1];
;                     u32x4 w; w.x = pk_bf16(r0[0], r0[1]); w.y = pk_bf16(r0[2], r0[3]); w.z = pk_bf16(r1[0], r1[1]); w.w = pk_bf16(r1[2], r1[3]);
;                     *(u32x4*)(xnb + o) = w;
	v_lshlrev_b32_e32 v214, 16, v154
	v_and_b32_e32 v215, 0xffff0000, v154
	v_lshlrev_b32_e32 v216, 16, v155
	v_and_b32_e32 v217, 0xffff0000, v155
	v_lshlrev_b32_e32 v210, 16, v152
	v_and_b32_e32 v211, 0xffff0000, v152
	v_lshlrev_b32_e32 v212, 16, v153
	v_and_b32_e32 v213, 0xffff0000, v153
	v_lshlrev_b32_e32 v194, 16, v162
	v_and_b32_e32 v195, 0xffff0000, v162
	v_lshlrev_b32_e32 v230, 16, v163
	v_and_b32_e32 v231, 0xffff0000, v163
	v_lshlrev_b32_e32 v154, 16, v202
	v_and_b32_e32 v155, 0xffff0000, v202
	v_lshlrev_b32_e32 v162, 16, v203
	v_and_b32_e32 v163, 0xffff0000, v203
	v_pk_fma_f32 v[202:203], v[122:123], 0.5, v[216:217] op_sel_hi:[1,0,1]
	v_pk_fma_f32 v[122:123], v[120:121], 0.5, v[214:215] op_sel_hi:[1,0,1]
	v_lshlrev_b32_e32 v218, 16, v156
	v_and_b32_e32 v219, 0xffff0000, v156
	v_lshlrev_b32_e32 v220, 16, v157
	v_and_b32_e32 v221, 0xffff0000, v157
	v_pk_fma_f32 v[126:127], v[126:127], 0.5, v[212:213] op_sel_hi:[1,0,1]
	v_pk_fma_f32 v[124:125], v[124:125], 0.5, v[210:211] op_sel_hi:[1,0,1]
	v_cvt_pk_bf16_f32 v122, v122, v123
	v_cvt_pk_bf16_f32 v123, v202, v203
	v_add_co_u32_e32 v202, vcc, s44, v144
	v_lshlrev_b32_e32 v224, 16, v158
	v_and_b32_e32 v225, 0xffff0000, v158
	v_lshlrev_b32_e32 v226, 16, v159
	v_and_b32_e32 v227, 0xffff0000, v159
	v_cvt_pk_bf16_f32 v120, v124, v125
	v_cvt_pk_bf16_f32 v121, v126, v127
	v_pk_fma_f32 v[118:119], v[118:119], 0.5, v[220:221] op_sel_hi:[1,0,1]
	v_pk_fma_f32 v[116:117], v[116:117], 0.5, v[218:219] op_sel_hi:[1,0,1]
	v_addc_co_u32_e32 v203, vcc, 0, v145, vcc
	v_lshlrev_b32_e32 v192, 16, v160
	v_and_b32_e32 v193, 0xffff0000, v160
	global_store_dwordx4 v[144:145], v[120:123], off
	v_pk_fma_f32 v[108:109], v[108:109], 0.5, v[192:193] op_sel_hi:[1,0,1]
	v_lshl_add_u64 v[192:193], v[144:145], 0, s[12:13]
	v_pk_fma_f32 v[120:121], v[114:115], 0.5, v[226:227] op_sel_hi:[1,0,1]
	v_pk_fma_f32 v[114:115], v[112:113], 0.5, v[224:225] op_sel_hi:[1,0,1]
	v_cvt_pk_bf16_f32 v112, v116, v117
	v_cvt_pk_bf16_f32 v113, v118, v119
	global_load_dwordx4 v[116:119], v[202:203], off
	v_cvt_pk_bf16_f32 v114, v114, v115
	v_cvt_pk_bf16_f32 v115, v120, v121
	v_lshlrev_b32_e32 v228, 16, v161
	v_and_b32_e32 v229, 0xffff0000, v161
	global_store_dwordx4 v[144:145], v[112:115], off offset:256
	v_pk_fma_f32 v[120:121], v[106:107], 0.5, v[230:231] op_sel_hi:[1,0,1]
	v_pk_fma_f32 v[110:111], v[110:111], 0.5, v[228:229] op_sel_hi:[1,0,1]
	v_pk_fma_f32 v[112:113], v[104:105], 0.5, v[194:195] op_sel_hi:[1,0,1]
	global_load_dwordx4 v[104:107], v[192:193], off offset:256
	v_add_co_u32_e32 v194, vcc, s45, v144
	v_lshlrev_b32_e32 v184, 16, v164
	s_nop 0
	v_addc_co_u32_e32 v195, vcc, 0, v145, vcc
	v_and_b32_e32 v185, 0xffff0000, v164
	v_lshlrev_b32_e32 v188, 16, v165
	v_and_b32_e32 v189, 0xffff0000, v165
	v_lshlrev_b32_e32 v186, 16, v166
	v_and_b32_e32 v187, 0xffff0000, v166
	v_lshlrev_b32_e32 v190, 16, v167
	v_and_b32_e32 v191, 0xffff0000, v167
	v_cvt_pk_bf16_f32 v108, v108, v109
	v_cvt_pk_bf16_f32 v109, v110, v111
	v_cvt_pk_bf16_f32 v110, v112, v113
	global_load_dwordx4 v[112:115], v[194:195], off
	v_cvt_pk_bf16_f32 v111, v120, v121
	global_store_dwordx4 v[150:151], v[108:111], off
	v_pk_fma_f32 v[124:125], v[98:99], 0.5, v[190:191] op_sel_hi:[1,0,1]
	v_pk_fma_f32 v[96:97], v[96:97], 0.5, v[186:187] op_sel_hi:[1,0,1]
	v_pk_fma_f32 v[110:111], v[102:103], 0.5, v[188:189] op_sel_hi:[1,0,1]
	v_pk_fma_f32 v[108:109], v[100:101], 0.5, v[184:185] op_sel_hi:[1,0,1]
	v_lshl_add_u64 v[98:99], v[144:145], 0, s[14:15]
	global_load_dwordx4 v[100:103], v[98:99], off offset:256
	v_cvt_pk_bf16_f32 v108, v108, v109
	v_cvt_pk_bf16_f32 v109, v110, v111
	v_cvt_pk_bf16_f32 v110, v96, v97
	v_add_co_u32_e32 v96, vcc, s46, v144
	v_lshlrev_b32_e32 v176, 16, v168
	s_nop 0
	v_addc_co_u32_e32 v97, vcc, 0, v145, vcc
	v_and_b32_e32 v177, 0xffff0000, v168
	v_lshlrev_b32_e32 v180, 16, v169
	v_and_b32_e32 v181, 0xffff0000, v169
	v_lshlrev_b32_e32 v178, 16, v170
	v_and_b32_e32 v179, 0xffff0000, v170
	v_lshlrev_b32_e32 v182, 16, v171
	v_and_b32_e32 v183, 0xffff0000, v171
	global_load_dwordx4 v[120:123], v[96:97], off
	v_cvt_pk_bf16_f32 v111, v124, v125
	global_store_dwordx4 v[150:151], v[108:111], off offset:256
	v_pk_fma_f32 v[150:151], v[90:91], 0.5, v[182:183] op_sel_hi:[1,0,1]
	v_pk_fma_f32 v[88:89], v[88:89], 0.5, v[178:179] op_sel_hi:[1,0,1]
	v_pk_fma_f32 v[110:111], v[94:95], 0.5, v[180:181] op_sel_hi:[1,0,1]
	v_pk_fma_f32 v[108:109], v[92:93], 0.5, v[176:177] op_sel_hi:[1,0,1]
	v_lshl_add_u64 v[90:91], v[144:145], 0, s[16:17]
	global_load_dwordx4 v[92:95], v[90:91], off offset:256
	v_cvt_pk_bf16_f32 v108, v108, v109
	v_cvt_pk_bf16_f32 v109, v110, v111
	v_cvt_pk_bf16_f32 v110, v88, v89
	v_add_co_u32_e32 v88, vcc, s47, v144
	v_lshlrev_b32_e32 v170, 16, v174
	s_nop 0
	v_addc_co_u32_e32 v89, vcc, 0, v145, vcc
	v_and_b32_e32 v171, 0xffff0000, v174
	global_load_dwordx4 v[124:127], v[88:89], off
	v_lshlrev_b32_e32 v168, 16, v172
	v_and_b32_e32 v169, 0xffff0000, v172
	v_lshlrev_b32_e32 v172, 16, v173
	v_and_b32_e32 v173, 0xffff0000, v173
	v_cvt_pk_bf16_f32 v111, v150, v151
	v_pk_fma_f32 v[150:151], v[72:73], 0.5, v[170:171] op_sel_hi:[1,0,1]
	v_lshl_add_u64 v[72:73], v[144:145], 0, s[18:19]
	global_store_dwordx4 v[146:147], v[108:111], off
	v_lshlrev_b32_e32 v174, 16, v175
	v_and_b32_e32 v175, 0xffff0000, v175
	v_pk_fma_f32 v[110:111], v[82:83], 0.5, v[172:173] op_sel_hi:[1,0,1]
	v_pk_fma_f32 v[108:109], v[80:81], 0.5, v[168:169] op_sel_hi:[1,0,1]
	global_load_dwordx4 v[80:83], v[72:73], off offset:256
	v_lshlrev_b32_e32 v160, 16, v204
	v_and_b32_e32 v161, 0xffff0000, v204
	v_lshlrev_b32_e32 v166, 16, v205
	v_and_b32_e32 v167, 0xffff0000, v205
	v_pk_fma_f32 v[74:75], v[74:75], 0.5, v[174:175] op_sel_hi:[1,0,1]
	v_cvt_pk_bf16_f32 v108, v108, v109
	v_cvt_pk_bf16_f32 v109, v110, v111
	v_cvt_pk_bf16_f32 v111, v74, v75
	v_pk_fma_f32 v[86:87], v[86:87], 0.5, v[162:163] op_sel_hi:[1,0,1]
	v_pk_fma_f32 v[74:75], v[84:85], 0.5, v[154:155] op_sel_hi:[1,0,1]
	v_pk_fma_f32 v[78:79], v[78:79], 0.5, v[166:167] op_sel_hi:[1,0,1]
	v_pk_fma_f32 v[76:77], v[76:77], 0.5, v[160:161] op_sel_hi:[1,0,1]
	v_lshlrev_b32_e32 v152, 16, v206
	v_and_b32_e32 v153, 0xffff0000, v206
	v_lshlrev_b32_e32 v158, 16, v207
	v_and_b32_e32 v159, 0xffff0000, v207
	v_lshlrev_b32_e32 v156, 16, v208
	v_and_b32_e32 v157, 0xffff0000, v208
	v_lshlrev_b32_e32 v164, 16, v209
	v_and_b32_e32 v165, 0xffff0000, v209
	v_cvt_pk_bf16_f32 v74, v74, v75
	v_cvt_pk_bf16_f32 v75, v86, v87
	v_cvt_pk_bf16_f32 v76, v76, v77
	v_cvt_pk_bf16_f32 v77, v78, v79
	global_store_dwordx4 v[148:149], v[74:77], off
	v_pk_fma_f32 v[70:71], v[70:71], 0.5, v[158:159] op_sel_hi:[1,0,1]
	v_pk_fma_f32 v[68:69], v[68:69], 0.5, v[152:153] op_sel_hi:[1,0,1]
	v_pk_fma_f32 v[74:75], v[66:67], 0.5, v[164:165] op_sel_hi:[1,0,1]
	v_pk_fma_f32 v[66:67], v[64:65], 0.5, v[156:157] op_sel_hi:[1,0,1]
	v_cvt_pk_bf16_f32 v64, v68, v69
	v_cvt_pk_bf16_f32 v65, v70, v71
	v_cvt_pk_bf16_f32 v66, v66, v67
	v_cvt_pk_bf16_f32 v67, v74, v75
	global_store_dwordx4 v[148:149], v[64:67], off offset:256
	s_waitcnt vmcnt(0)
; DI unsigned pk_bf16(float lo, float hi) { f32x2 v = {lo, hi}; return __builtin_bit_cast(unsigned, __builtin_convertvector(v, bf16v2)); }
; #define PG8_WAIT_V(n) asm volatile("s_waitcnt vmcnt(" #n ")" ::: "memory")
; #define PG8_BAR __builtin_amdgcn_s_barrier()
; #define PG8_WAIT_V(n) asm volatile("s_waitcnt vmcnt(" #n ")" ::: "memory")
; #define PG8_BAR __builtin_amdgcn_s_barrier()
; template <class Epi>
; DI void gemm_phase(LAS unsigned char* lds, const Gemm g, const StaticOrder S, const Epi E) {
;     ...
;     PG8_WAIT_V(0);
;     if (wr == 0) PG8_BAR;
;     PG8_BAR;
;     DI void operator()(AccRef acc, const Unit& u, int wr, int wc, int fr, int fq) const {
;     ...
;             for (int m = 0; m < 4; ++m) {
;                 const int row = row0 + ai * 128 + m * 16;
;                 float q = 0.f;
; #pragma unroll
;                 for (int bj = 0; bj < 2; ++bj) {
;                     const size_t o = (size_t)row * DM + col0 + bj * 128;
;                     const f32x4 r0 = bv[m][bj][0] + scale * acc[ai][bj][m][0], r1 = bv[m][bj][1] + scale * acc[ai][bj][m][1];
;                     u32x4 w; w.x = pk_bf16(r0[0], r0[1]); w.y = pk_bf16(r0[2], r0[3]); w.z = pk_bf16(r1[0], r1[1]); w.w = pk_bf16(r1[2], r1[3]);
;                     *(u32x4*)(xnb + o) = w;
	v_lshlrev_b32_e32 v68, 16, v118
	v_and_b32_e32 v69, 0xffff0000, v118
	v_lshlrev_b32_e32 v64, 16, v116
	v_and_b32_e32 v65, 0xffff0000, v116
	v_lshlrev_b32_e32 v66, 16, v117
	v_and_b32_e32 v67, 0xffff0000, v117
	v_lshlrev_b32_e32 v70, 16, v119
	v_and_b32_e32 v71, 0xffff0000, v119
	v_pk_fma_f32 v[62:63], v[62:63], 0.5, v[66:67] op_sel_hi:[1,0,1]
	v_pk_fma_f32 v[60:61], v[60:61], 0.5, v[64:65] op_sel_hi:[1,0,1]
	v_pk_fma_f32 v[64:65], v[58:59], 0.5, v[70:71] op_sel_hi:[1,0,1]
	v_pk_fma_f32 v[58:59], v[56:57], 0.5, v[68:69] op_sel_hi:[1,0,1]
	v_lshlrev_b32_e32 v74, 16, v104
	v_and_b32_e32 v75, 0xffff0000, v104
	v_lshlrev_b32_e32 v76, 16, v105
	v_and_b32_e32 v77, 0xffff0000, v105
	v_lshlrev_b32_e32 v78, 16, v106
	v_and_b32_e32 v79, 0xffff0000, v106
	v_lshlrev_b32_e32 v84, 16, v107
	v_and_b32_e32 v85, 0xffff0000, v107
	v_cvt_pk_bf16_f32 v56, v60, v61
	v_cvt_pk_bf16_f32 v57, v62, v63
	v_cvt_pk_bf16_f32 v58, v58, v59
	v_cvt_pk_bf16_f32 v59, v64, v65
	v_cvt_pk_bf16_f32 v110, v150, v151
	global_store_dwordx4 v[202:203], v[56:59], off
	v_pk_fma_f32 v[54:55], v[54:55], 0.5, v[76:77] op_sel_hi:[1,0,1]
	v_pk_fma_f32 v[52:53], v[52:53], 0.5, v[74:75] op_sel_hi:[1,0,1]
	v_pk_fma_f32 v[56:57], v[46:47], 0.5, v[84:85] op_sel_hi:[1,0,1]
	v_pk_fma_f32 v[46:47], v[44:45], 0.5, v[78:79] op_sel_hi:[1,0,1]
	global_store_dwordx4 v[146:147], v[108:111], off offset:256
	v_lshlrev_b32_e32 v86, 16, v112
	v_and_b32_e32 v87, 0xffff0000, v112
	v_lshlrev_b32_e32 v104, 16, v113
	v_and_b32_e32 v105, 0xffff0000, v113
	v_lshlrev_b32_e32 v106, 16, v114
	v_and_b32_e32 v107, 0xffff0000, v114
	v_lshlrev_b32_e32 v108, 16, v115
	v_and_b32_e32 v109, 0xffff0000, v115
	v_cvt_pk_bf16_f32 v44, v52, v53
	v_cvt_pk_bf16_f32 v45, v54, v55
	v_cvt_pk_bf16_f32 v46, v46, v47
	v_cvt_pk_bf16_f32 v47, v56, v57
	global_store_dwordx4 v[192:193], v[44:47], off offset:256
	v_lshlrev_b32_e32 v110, 16, v100
	v_and_b32_e32 v111, 0xffff0000, v100
	v_pk_fma_f32 v[44:45], v[50:51], 0.5, v[104:105] op_sel_hi:[1,0,1]
	v_pk_fma_f32 v[46:47], v[48:49], 0.5, v[86:87] op_sel_hi:[1,0,1]
	v_pk_fma_f32 v[48:49], v[42:43], 0.5, v[108:109] op_sel_hi:[1,0,1]
	v_pk_fma_f32 v[42:43], v[40:41], 0.5, v[106:107] op_sel_hi:[1,0,1]
	v_lshlrev_b32_e32 v100, 16, v101
	v_and_b32_e32 v101, 0xffff0000, v101
	v_lshlrev_b32_e32 v112, 16, v102
	v_and_b32_e32 v113, 0xffff0000, v102
	v_lshlrev_b32_e32 v102, 16, v103
	v_and_b32_e32 v103, 0xffff0000, v103
	v_cvt_pk_bf16_f32 v40, v46, v47
	v_cvt_pk_bf16_f32 v41, v44, v45
	v_cvt_pk_bf16_f32 v42, v42, v43
	v_cvt_pk_bf16_f32 v43, v48, v49
	global_store_dwordx4 v[194:195], v[40:43], off
	v_pk_fma_f32 v[38:39], v[38:39], 0.5, v[100:101] op_sel_hi:[1,0,1]
	v_pk_fma_f32 v[36:37], v[36:37], 0.5, v[110:111] op_sel_hi:[1,0,1]
	v_pk_fma_f32 v[40:41], v[30:31], 0.5, v[102:103] op_sel_hi:[1,0,1]
	v_pk_fma_f32 v[30:31], v[28:29], 0.5, v[112:113] op_sel_hi:[1,0,1]
	v_lshlrev_b32_e32 v114, 16, v120
	v_and_b32_e32 v115, 0xffff0000, v120
	v_lshlrev_b32_e32 v116, 16, v121
	v_and_b32_e32 v117, 0xffff0000, v121
	v_lshlrev_b32_e32 v118, 16, v122
	v_and_b32_e32 v119, 0xffff0000, v122
	v_lshlrev_b32_e32 v120, 16, v123
	v_and_b32_e32 v121, 0xffff0000, v123
	v_cvt_pk_bf16_f32 v28, v36, v37
	v_cvt_pk_bf16_f32 v29, v38, v39
	v_cvt_pk_bf16_f32 v30, v30, v31
	v_cvt_pk_bf16_f32 v31, v40, v41
	global_store_dwordx4 v[98:99], v[28:31], off offset:256
	v_lshlrev_b32_e32 v122, 16, v92
	v_and_b32_e32 v123, 0xffff0000, v92
	v_pk_fma_f32 v[28:29], v[34:35], 0.5, v[116:117] op_sel_hi:[1,0,1]
	v_pk_fma_f32 v[30:31], v[32:33], 0.5, v[114:115] op_sel_hi:[1,0,1]
	v_pk_fma_f32 v[32:33], v[26:27], 0.5, v[120:121] op_sel_hi:[1,0,1]
	v_pk_fma_f32 v[26:27], v[24:25], 0.5, v[118:119] op_sel_hi:[1,0,1]
	v_lshlrev_b32_e32 v92, 16, v93
	v_and_b32_e32 v93, 0xffff0000, v93
	v_lshlrev_b32_e32 v144, 16, v94
	v_and_b32_e32 v145, 0xffff0000, v94
	v_lshlrev_b32_e32 v94, 16, v95
	v_and_b32_e32 v95, 0xffff0000, v95
	v_cvt_pk_bf16_f32 v24, v30, v31
	v_cvt_pk_bf16_f32 v25, v28, v29
	v_cvt_pk_bf16_f32 v26, v26, v27
	v_cvt_pk_bf16_f32 v27, v32, v33
	global_store_dwordx4 v[96:97], v[24:27], off
	v_pk_fma_f32 v[22:23], v[22:23], 0.5, v[92:93] op_sel_hi:[1,0,1]
	v_pk_fma_f32 v[20:21], v[20:21], 0.5, v[122:123] op_sel_hi:[1,0,1]
	v_pk_fma_f32 v[24:25], v[14:15], 0.5, v[94:95] op_sel_hi:[1,0,1]
	v_pk_fma_f32 v[14:15], v[12:13], 0.5, v[144:145] op_sel_hi:[1,0,1]
	v_lshlrev_b32_e32 v146, 16, v124
	v_and_b32_e32 v147, 0xffff0000, v124
	v_lshlrev_b32_e32 v124, 16, v125
	v_and_b32_e32 v125, 0xffff0000, v125
	v_lshlrev_b32_e32 v148, 16, v126
	v_and_b32_e32 v149, 0xffff0000, v126
	v_lshlrev_b32_e32 v126, 16, v127
	v_and_b32_e32 v127, 0xffff0000, v127
	v_cvt_pk_bf16_f32 v12, v20, v21
	v_cvt_pk_bf16_f32 v13, v22, v23
	v_cvt_pk_bf16_f32 v14, v14, v15
	v_cvt_pk_bf16_f32 v15, v24, v25
	global_store_dwordx4 v[90:91], v[12:15], off offset:256
	v_lshlrev_b32_e32 v150, 16, v80
	v_and_b32_e32 v151, 0xffff0000, v80
	v_pk_fma_f32 v[12:13], v[18:19], 0.5, v[124:125] op_sel_hi:[1,0,1]
	v_pk_fma_f32 v[14:15], v[16:17], 0.5, v[146:147] op_sel_hi:[1,0,1]
	v_pk_fma_f32 v[16:17], v[10:11], 0.5, v[126:127] op_sel_hi:[1,0,1]
	v_pk_fma_f32 v[10:11], v[8:9], 0.5, v[148:149] op_sel_hi:[1,0,1]
	v_lshlrev_b32_e32 v80, 16, v81
	v_and_b32_e32 v81, 0xffff0000, v81
	v_lshlrev_b32_e32 v152, 16, v82
	v_and_b32_e32 v153, 0xffff0000, v82
	v_lshlrev_b32_e32 v82, 16, v83
	v_and_b32_e32 v83, 0xffff0000, v83
	v_cvt_pk_bf16_f32 v8, v14, v15
	v_cvt_pk_bf16_f32 v9, v12, v13
	v_cvt_pk_bf16_f32 v10, v10, v11
	v_cvt_pk_bf16_f32 v11, v16, v17
	global_store_dwordx4 v[88:89], v[8:11], off
	v_pk_fma_f32 v[6:7], v[6:7], 0.5, v[80:81] op_sel_hi:[1,0,1]
	v_pk_fma_f32 v[4:5], v[4:5], 0.5, v[150:151] op_sel_hi:[1,0,1]
	v_pk_fma_f32 v[8:9], v[2:3], 0.5, v[82:83] op_sel_hi:[1,0,1]
	v_pk_fma_f32 v[2:3], v[0:1], 0.5, v[152:153] op_sel_hi:[1,0,1]
	v_cvt_pk_bf16_f32 v0, v4, v5
	v_cvt_pk_bf16_f32 v1, v6, v7
	v_cvt_pk_bf16_f32 v2, v2, v3
	v_cvt_pk_bf16_f32 v3, v8, v9
	s_and_b64 vcc, exec, s[0:1]
	global_store_dwordx4 v[72:73], v[0:3], off offset:256
	s_cbranch_vccz .LBB0_930
	s_waitcnt vmcnt(0)
	s_cmpk_gt_u32 s6, 0xff
	s_cbranch_scc1 .LBB0_945
	s_barrier
